# v064: v056 + B-fragment LDS read addresses precomputed once per unit (no VALU add at the top of each load segment in the GEMM K-loops)
# speedup vs baseline: 1.0097x; 1.0080x over previous
.LBB0_338:
	s_ashr_i32 s29, s28, 31
	v_cmp_lt_i64_e64 s[42:43], s[34:35], 64
	s_lshl_b64 s[34:35], s[28:29], 19
	s_add_u32 s34, s48, s34
	s_addc_u32 s35, s49, s35
	s_and_b64 s[36:37], s[42:43], exec
	s_cselect_b32 s1, s35, s39
	s_cselect_b32 s7, s34, s38
	s_ashr_i32 s31, s30, 31
	s_lshl_b64 s[36:37], s[30:31], 19
	s_add_u32 s36, s50, s36
	s_addc_u32 s37, s51, s37
	s_and_b64 s[42:43], s[42:43], exec
	s_cselect_b32 s29, s37, s41
	s_cselect_b32 s31, s36, s40
	s_add_u32 s65, s40, 0x100
	v_mov_b32_e32 v2, 0
	s_addc_u32 s66, s41, 0
	s_mov_b32 s67, -2
	v_mov_b32_e32 v3, v2
	v_mov_b32_e32 v4, v2
	v_mov_b32_e32 v5, v2
	v_mov_b32_e32 v6, v2
	v_mov_b32_e32 v7, v2
	v_mov_b32_e32 v8, v2
	v_mov_b32_e32 v9, v2
	s_waitcnt vmcnt(0)
	v_mov_b32_e32 v18, v2
	v_mov_b32_e32 v19, v2
	v_mov_b32_e32 v20, v2
	v_mov_b32_e32 v21, v2
	v_mov_b32_e32 v22, v2
	v_mov_b32_e32 v23, v2
	v_mov_b32_e32 v24, v2
	v_mov_b32_e32 v25, v2
	v_mov_b32_e32 v34, v2
	v_mov_b32_e32 v35, v2
	v_mov_b32_e32 v36, v2
	v_mov_b32_e32 v37, v2
	v_mov_b32_e32 v38, v2
	v_mov_b32_e32 v39, v2
	v_mov_b32_e32 v40, v2
	v_mov_b32_e32 v41, v2
	v_mov_b32_e32 v50, v2
	v_mov_b32_e32 v51, v2
	v_mov_b32_e32 v52, v2
	v_mov_b32_e32 v53, v2
	v_mov_b32_e32 v54, v2
	v_mov_b32_e32 v55, v2
	v_mov_b32_e32 v56, v2
	v_mov_b32_e32 v57, v2
	v_mov_b32_e32 v10, v2
	v_mov_b32_e32 v11, v2
	v_mov_b32_e32 v12, v2
	v_mov_b32_e32 v13, v2
	v_mov_b32_e32 v14, v2
	v_mov_b32_e32 v15, v2
	v_mov_b32_e32 v16, v2
	v_mov_b32_e32 v17, v2
	v_mov_b32_e32 v26, v2
	v_mov_b32_e32 v27, v2
	v_mov_b32_e32 v28, v2
	v_mov_b32_e32 v29, v2
	v_mov_b32_e32 v30, v2
	v_mov_b32_e32 v31, v2
	v_mov_b32_e32 v32, v2
	v_mov_b32_e32 v33, v2
	v_mov_b32_e32 v42, v2
	v_mov_b32_e32 v43, v2
	v_mov_b32_e32 v44, v2
	v_mov_b32_e32 v45, v2
	v_mov_b32_e32 v46, v2
	v_mov_b32_e32 v47, v2
	v_mov_b32_e32 v48, v2
	v_mov_b32_e32 v49, v2
	v_mov_b32_e32 v58, v2
	v_mov_b32_e32 v59, v2
	v_mov_b32_e32 v60, v2
	v_mov_b32_e32 v61, v2
	v_mov_b32_e32 v62, v2
	v_mov_b32_e32 v63, v2
	v_mov_b32_e32 v64, v2
	v_mov_b32_e32 v65, v2
	v_mov_b32_e32 v66, v2
	v_mov_b32_e32 v67, v2
	v_mov_b32_e32 v68, v2
	v_mov_b32_e32 v69, v2
	v_mov_b32_e32 v70, v2
	v_mov_b32_e32 v71, v2
	v_mov_b32_e32 v72, v2
	v_mov_b32_e32 v73, v2
	v_mov_b32_e32 v82, v2
	v_mov_b32_e32 v83, v2
	v_mov_b32_e32 v84, v2
	v_mov_b32_e32 v85, v2
	v_mov_b32_e32 v86, v2
	v_mov_b32_e32 v87, v2
	v_mov_b32_e32 v88, v2
	v_mov_b32_e32 v89, v2
	v_mov_b32_e32 v98, v2
	v_mov_b32_e32 v99, v2
	v_mov_b32_e32 v100, v2
	v_mov_b32_e32 v101, v2
	v_mov_b32_e32 v102, v2
	v_mov_b32_e32 v103, v2
	v_mov_b32_e32 v104, v2
	v_mov_b32_e32 v105, v2
	v_mov_b32_e32 v114, v2
	v_mov_b32_e32 v115, v2
	v_mov_b32_e32 v116, v2
	v_mov_b32_e32 v117, v2
	v_mov_b32_e32 v118, v2
	v_mov_b32_e32 v119, v2
	v_mov_b32_e32 v120, v2
	v_mov_b32_e32 v121, v2
	v_mov_b32_e32 v74, v2
	v_mov_b32_e32 v75, v2
	v_mov_b32_e32 v76, v2
	v_mov_b32_e32 v77, v2
	v_mov_b32_e32 v78, v2
	v_mov_b32_e32 v79, v2
	v_mov_b32_e32 v80, v2
	v_mov_b32_e32 v81, v2
	v_mov_b32_e32 v90, v2
	v_mov_b32_e32 v91, v2
	v_mov_b32_e32 v92, v2
	v_mov_b32_e32 v93, v2
	v_mov_b32_e32 v94, v2
	v_mov_b32_e32 v95, v2
	v_mov_b32_e32 v96, v2
	v_mov_b32_e32 v97, v2
	v_mov_b32_e32 v106, v2
	v_mov_b32_e32 v107, v2
	v_mov_b32_e32 v108, v2
	v_mov_b32_e32 v109, v2
	v_mov_b32_e32 v110, v2
	v_mov_b32_e32 v111, v2
	v_mov_b32_e32 v112, v2
	v_mov_b32_e32 v113, v2
	v_mov_b32_e32 v122, v2
	v_mov_b32_e32 v123, v2
	v_mov_b32_e32 v124, v2
	v_mov_b32_e32 v125, v2
	v_mov_b32_e32 v126, v2
	v_mov_b32_e32 v127, v2
	v_mov_b32_e32 v128, v2
	v_mov_b32_e32 v129, v2
	v_add_u32_e32 v216, 0x10000, v1
.LBB0_339:
	ds_read_b128 v[136:139], v144
	ds_read_b128 v[140:143], v144 offset:1024
	ds_read_b128 v[150:153], v144 offset:2048
	ds_read_b128 v[154:157], v144 offset:3072
	s_add_u32 s40, s38, 0x100
	s_addc_u32 s41, s39, 0
	s_cmp_eq_u32 s67, 12
	s_cselect_b32 s46, s7, s40
	s_cselect_b32 s47, s1, s41
	s_cselect_b32 s42, s31, s65
	s_cselect_b32 s43, s29, s66
	s_add_u32 s44, s46, 0x80
	s_addc_u32 s45, s47, 0
	s_add_u32 s38, s38, 0x40080
	s_addc_u32 s39, s39, 0
	ds_read_b128 v[158:161], v145
	ds_read_b128 v[162:165], v145 offset:1024
	ds_read_b128 v[166:169], v145 offset:2048
	ds_read_b128 v[170:173], v145 offset:3072
	ds_read_b128 v[174:177], v145 offset:4096
	ds_read_b128 v[178:181], v145 offset:5120
	ds_read_b128 v[182:185], v145 offset:6144
	ds_read_b128 v[186:189], v145 offset:7168
	s_add_i32 m0, s53, 0xc000
	s_nop 0
	global_load_lds_dwordx4 v130, s[38:39]
	s_add_i32 m0, s53, 0xe000
	s_nop 0
	global_load_lds_dwordx4 v132, s[38:39]
	s_waitcnt lgkmcnt(8)
	s_barrier
	s_waitcnt lgkmcnt(0)
	s_setprio 1
	s_waitcnt lgkmcnt(0)
	v_mfma_f32_16x16x32_bf16 v[126:129], v[136:139], v[158:161], v[126:129]
	v_mfma_f32_16x16x32_bf16 v[122:125], v[150:153], v[158:161], v[122:125]
	v_mfma_f32_16x16x32_bf16 v[110:113], v[136:139], v[166:169], v[110:113]
	v_mfma_f32_16x16x32_bf16 v[106:109], v[150:153], v[166:169], v[106:109]
	v_mfma_f32_16x16x32_bf16 v[94:97], v[136:139], v[174:177], v[94:97]
	v_mfma_f32_16x16x32_bf16 v[90:93], v[150:153], v[174:177], v[90:93]
	v_mfma_f32_16x16x32_bf16 v[78:81], v[136:139], v[182:185], v[78:81]
	v_mfma_f32_16x16x32_bf16 v[74:77], v[150:153], v[182:185], v[74:77]
	v_mfma_f32_16x16x32_bf16 v[126:129], v[140:143], v[162:165], v[126:129]
	v_mfma_f32_16x16x32_bf16 v[122:125], v[154:157], v[162:165], v[122:125]
	v_mfma_f32_16x16x32_bf16 v[110:113], v[140:143], v[170:173], v[110:113]
	v_mfma_f32_16x16x32_bf16 v[106:109], v[154:157], v[170:173], v[106:109]
	v_mfma_f32_16x16x32_bf16 v[94:97], v[140:143], v[178:181], v[94:97]
	v_mfma_f32_16x16x32_bf16 v[90:93], v[154:157], v[178:181], v[90:93]
	v_mfma_f32_16x16x32_bf16 v[78:81], v[140:143], v[186:189], v[78:81]
	v_mfma_f32_16x16x32_bf16 v[74:77], v[154:157], v[186:189], v[74:77]
	s_setprio 0
	s_barrier
	s_mov_b64 s[38:39], s[42:43]
	s_add_i32 s68, s62, s52
	ds_read_b128 v[190:193], v146
	ds_read_b128 v[194:197], v146 offset:1024
	ds_read_b128 v[198:201], v146 offset:2048
	ds_read_b128 v[202:205], v146 offset:3072
	s_mov_b32 m0, s68
	s_nop 0
	global_load_lds_dwordx4 v130, s[38:39]
	s_add_i32 m0, s68, 0x2000
	s_nop 0
	global_load_lds_dwordx4 v132, s[38:39]
	s_barrier
	s_waitcnt lgkmcnt(0)
	s_setprio 1
	s_waitcnt lgkmcnt(0)
	v_mfma_f32_16x16x32_bf16 v[118:121], v[190:193], v[158:161], v[118:121]
	v_mfma_f32_16x16x32_bf16 v[114:117], v[198:201], v[158:161], v[114:117]
	v_mfma_f32_16x16x32_bf16 v[102:105], v[190:193], v[166:169], v[102:105]
	v_mfma_f32_16x16x32_bf16 v[98:101], v[198:201], v[166:169], v[98:101]
	v_mfma_f32_16x16x32_bf16 v[86:89], v[190:193], v[174:177], v[86:89]
	v_mfma_f32_16x16x32_bf16 v[82:85], v[198:201], v[174:177], v[82:85]
	v_mfma_f32_16x16x32_bf16 v[70:73], v[190:193], v[182:185], v[70:73]
	v_mfma_f32_16x16x32_bf16 v[66:69], v[198:201], v[182:185], v[66:69]
	v_mfma_f32_16x16x32_bf16 v[118:121], v[194:197], v[162:165], v[118:121]
	v_mfma_f32_16x16x32_bf16 v[114:117], v[202:205], v[162:165], v[114:117]
	v_mfma_f32_16x16x32_bf16 v[102:105], v[194:197], v[170:173], v[102:105]
	v_mfma_f32_16x16x32_bf16 v[98:101], v[202:205], v[170:173], v[98:101]
	v_mfma_f32_16x16x32_bf16 v[86:89], v[194:197], v[178:181], v[86:89]
	v_mfma_f32_16x16x32_bf16 v[82:85], v[202:205], v[178:181], v[82:85]
	v_mfma_f32_16x16x32_bf16 v[70:73], v[194:197], v[186:189], v[70:73]
	v_mfma_f32_16x16x32_bf16 v[66:69], v[202:205], v[186:189], v[66:69]
	s_setprio 0
	s_mov_b64 s[38:39], s[46:47]
	s_mov_b32 m0, s53
	s_barrier
	ds_read_b128 v[158:161], v145 offset:16384
	ds_read_b128 v[162:165], v145 offset:17408
	ds_read_b128 v[166:169], v145 offset:18432
	ds_read_b128 v[170:173], v145 offset:19456
	ds_read_b128 v[174:177], v145 offset:20480
	ds_read_b128 v[178:181], v145 offset:21504
	ds_read_b128 v[182:185], v145 offset:22528
	ds_read_b128 v[186:189], v145 offset:23552
	s_nop 0
	global_load_lds_dwordx4 v130, s[38:39]
	s_mov_b32 m0, s54
	s_nop 0
	global_load_lds_dwordx4 v132, s[38:39]
	s_barrier
	s_waitcnt lgkmcnt(0)
	s_setprio 1
	s_waitcnt lgkmcnt(0)
	v_mfma_f32_16x16x32_bf16 v[62:65], v[136:139], v[158:161], v[62:65]
	v_mfma_f32_16x16x32_bf16 v[58:61], v[150:153], v[158:161], v[58:61]
	v_mfma_f32_16x16x32_bf16 v[46:49], v[136:139], v[166:169], v[46:49]
	v_mfma_f32_16x16x32_bf16 v[42:45], v[150:153], v[166:169], v[42:45]
	v_mfma_f32_16x16x32_bf16 v[30:33], v[136:139], v[174:177], v[30:33]
	v_mfma_f32_16x16x32_bf16 v[26:29], v[150:153], v[174:177], v[26:29]
	v_mfma_f32_16x16x32_bf16 v[14:17], v[136:139], v[182:185], v[14:17]
	v_mfma_f32_16x16x32_bf16 v[10:13], v[150:153], v[182:185], v[10:13]
	v_mfma_f32_16x16x32_bf16 v[62:65], v[140:143], v[162:165], v[62:65]
	v_mfma_f32_16x16x32_bf16 v[58:61], v[154:157], v[162:165], v[58:61]
	v_mfma_f32_16x16x32_bf16 v[46:49], v[140:143], v[170:173], v[46:49]
	v_mfma_f32_16x16x32_bf16 v[42:45], v[154:157], v[170:173], v[42:45]
	v_mfma_f32_16x16x32_bf16 v[30:33], v[140:143], v[178:181], v[30:33]
	v_mfma_f32_16x16x32_bf16 v[26:29], v[154:157], v[178:181], v[26:29]
	v_mfma_f32_16x16x32_bf16 v[14:17], v[140:143], v[186:189], v[14:17]
	v_mfma_f32_16x16x32_bf16 v[10:13], v[154:157], v[186:189], v[10:13]
	s_setprio 0
	s_barrier
	s_add_u32 s38, s42, 0x40000
	s_addc_u32 s39, s43, 0
	s_add_i32 s68, s63, s52
	s_mov_b32 m0, s68
	s_nop 0
	global_load_lds_dwordx4 v130, s[38:39]
	s_add_i32 m0, s68, 0x2000
	s_nop 0
	global_load_lds_dwordx4 v132, s[38:39]
	s_waitcnt vmcnt(6)
	s_barrier
	s_setprio 1
	v_mfma_f32_16x16x32_bf16 v[54:57], v[190:193], v[158:161], v[54:57]
	v_mfma_f32_16x16x32_bf16 v[50:53], v[198:201], v[158:161], v[50:53]
	v_mfma_f32_16x16x32_bf16 v[38:41], v[190:193], v[166:169], v[38:41]
	v_mfma_f32_16x16x32_bf16 v[34:37], v[198:201], v[166:169], v[34:37]
	v_mfma_f32_16x16x32_bf16 v[22:25], v[190:193], v[174:177], v[22:25]
	v_mfma_f32_16x16x32_bf16 v[18:21], v[198:201], v[174:177], v[18:21]
	v_mfma_f32_16x16x32_bf16 v[6:9], v[190:193], v[182:185], v[6:9]
	v_mfma_f32_16x16x32_bf16 v[2:5], v[198:201], v[182:185], v[2:5]
	v_mfma_f32_16x16x32_bf16 v[54:57], v[194:197], v[162:165], v[54:57]
	v_mfma_f32_16x16x32_bf16 v[50:53], v[202:205], v[162:165], v[50:53]
	v_mfma_f32_16x16x32_bf16 v[38:41], v[194:197], v[170:173], v[38:41]
	v_mfma_f32_16x16x32_bf16 v[34:37], v[202:205], v[170:173], v[34:37]
	v_mfma_f32_16x16x32_bf16 v[22:25], v[194:197], v[178:181], v[22:25]
	v_mfma_f32_16x16x32_bf16 v[18:21], v[202:205], v[178:181], v[18:21]
	v_mfma_f32_16x16x32_bf16 v[6:9], v[194:197], v[186:189], v[6:9]
	v_mfma_f32_16x16x32_bf16 v[2:5], v[202:205], v[186:189], v[2:5]
	s_setprio 0
	s_add_i32 s68, 0, 0x18000
	s_barrier
	ds_read_b128 v[136:139], v216 offset:32768
	ds_read_b128 v[140:143], v216 offset:33792
	ds_read_b128 v[150:153], v216 offset:34816
	ds_read_b128 v[154:157], v216 offset:35840
	s_add_u32 s38, s46, 0x40000
	s_addc_u32 s39, s47, 0
	s_mov_b32 m0, s55
	ds_read_b128 v[158:161], v145 offset:32768
	ds_read_b128 v[162:165], v145 offset:33792
	ds_read_b128 v[166:169], v145 offset:34816
	ds_read_b128 v[170:173], v145 offset:35840
	ds_read_b128 v[174:177], v145 offset:36864
	ds_read_b128 v[178:181], v145 offset:37888
	ds_read_b128 v[182:185], v145 offset:38912
	ds_read_b128 v[186:189], v145 offset:39936
	s_nop 0
	global_load_lds_dwordx4 v130, s[38:39]
	s_mov_b32 m0, s56
	s_nop 0
	global_load_lds_dwordx4 v132, s[38:39]
	s_waitcnt lgkmcnt(8)
	s_barrier
	s_waitcnt lgkmcnt(0)
	s_setprio 1
	s_waitcnt lgkmcnt(0)
	v_mfma_f32_16x16x32_bf16 v[126:129], v[136:139], v[158:161], v[126:129]
	v_mfma_f32_16x16x32_bf16 v[122:125], v[150:153], v[158:161], v[122:125]
	v_mfma_f32_16x16x32_bf16 v[110:113], v[136:139], v[166:169], v[110:113]
	v_mfma_f32_16x16x32_bf16 v[106:109], v[150:153], v[166:169], v[106:109]
	v_mfma_f32_16x16x32_bf16 v[94:97], v[136:139], v[174:177], v[94:97]
	v_mfma_f32_16x16x32_bf16 v[90:93], v[150:153], v[174:177], v[90:93]
	v_mfma_f32_16x16x32_bf16 v[78:81], v[136:139], v[182:185], v[78:81]
	v_mfma_f32_16x16x32_bf16 v[74:77], v[150:153], v[182:185], v[74:77]
	v_mfma_f32_16x16x32_bf16 v[126:129], v[140:143], v[162:165], v[126:129]
	v_mfma_f32_16x16x32_bf16 v[122:125], v[154:157], v[162:165], v[122:125]
	v_mfma_f32_16x16x32_bf16 v[110:113], v[140:143], v[170:173], v[110:113]
	v_mfma_f32_16x16x32_bf16 v[106:109], v[154:157], v[170:173], v[106:109]
	v_mfma_f32_16x16x32_bf16 v[94:97], v[140:143], v[178:181], v[94:97]
	v_mfma_f32_16x16x32_bf16 v[90:93], v[154:157], v[178:181], v[90:93]
	v_mfma_f32_16x16x32_bf16 v[78:81], v[140:143], v[186:189], v[78:81]
	v_mfma_f32_16x16x32_bf16 v[74:77], v[154:157], v[186:189], v[74:77]
	s_setprio 0
	s_barrier
	s_add_i32 s46, 0, 0x1c000
	s_add_u32 s38, s42, 0x80
	s_addc_u32 s39, s43, 0
	s_add_i32 s47, s68, s52
	ds_read_b128 v[190:193], v216 offset:49152
	ds_read_b128 v[194:197], v216 offset:50176
	ds_read_b128 v[198:201], v216 offset:51200
	ds_read_b128 v[202:205], v216 offset:52224
	s_mov_b32 m0, s47
	s_nop 0
	global_load_lds_dwordx4 v130, s[38:39]
	s_add_i32 m0, s47, 0x2000
	s_nop 0
	global_load_lds_dwordx4 v132, s[38:39]
	s_barrier
	s_waitcnt lgkmcnt(0)
	s_setprio 1
	s_waitcnt lgkmcnt(0)
	v_mfma_f32_16x16x32_bf16 v[118:121], v[190:193], v[158:161], v[118:121]
	v_mfma_f32_16x16x32_bf16 v[114:117], v[198:201], v[158:161], v[114:117]
	v_mfma_f32_16x16x32_bf16 v[102:105], v[190:193], v[166:169], v[102:105]
	v_mfma_f32_16x16x32_bf16 v[98:101], v[198:201], v[166:169], v[98:101]
	v_mfma_f32_16x16x32_bf16 v[86:89], v[190:193], v[174:177], v[86:89]
	v_mfma_f32_16x16x32_bf16 v[82:85], v[198:201], v[174:177], v[82:85]
	v_mfma_f32_16x16x32_bf16 v[70:73], v[190:193], v[182:185], v[70:73]
	v_mfma_f32_16x16x32_bf16 v[66:69], v[198:201], v[182:185], v[66:69]
	v_mfma_f32_16x16x32_bf16 v[118:121], v[194:197], v[162:165], v[118:121]
	v_mfma_f32_16x16x32_bf16 v[114:117], v[202:205], v[162:165], v[114:117]
	v_mfma_f32_16x16x32_bf16 v[102:105], v[194:197], v[170:173], v[102:105]
	v_mfma_f32_16x16x32_bf16 v[98:101], v[202:205], v[170:173], v[98:101]
	v_mfma_f32_16x16x32_bf16 v[86:89], v[194:197], v[178:181], v[86:89]
	v_mfma_f32_16x16x32_bf16 v[82:85], v[202:205], v[178:181], v[82:85]
	v_mfma_f32_16x16x32_bf16 v[70:73], v[194:197], v[186:189], v[70:73]
	v_mfma_f32_16x16x32_bf16 v[66:69], v[202:205], v[186:189], v[66:69]
	s_setprio 0
	s_mov_b32 m0, s58
	s_barrier
	ds_read_b128 v[158:161], v145 offset:49152
	ds_read_b128 v[162:165], v145 offset:50176
	ds_read_b128 v[166:169], v145 offset:51200
	ds_read_b128 v[170:173], v145 offset:52224
	ds_read_b128 v[174:177], v145 offset:53248
	ds_read_b128 v[178:181], v145 offset:54272
	ds_read_b128 v[182:185], v145 offset:55296
	ds_read_b128 v[186:189], v145 offset:56320
	s_nop 0
	global_load_lds_dwordx4 v130, s[44:45]
	s_mov_b32 m0, s59
	s_nop 0
	global_load_lds_dwordx4 v132, s[44:45]
	s_barrier
	s_waitcnt lgkmcnt(0)
	s_setprio 1
	s_waitcnt lgkmcnt(0)
	v_mfma_f32_16x16x32_bf16 v[62:65], v[136:139], v[158:161], v[62:65]
	v_mfma_f32_16x16x32_bf16 v[58:61], v[150:153], v[158:161], v[58:61]
	v_mfma_f32_16x16x32_bf16 v[46:49], v[136:139], v[166:169], v[46:49]
	v_mfma_f32_16x16x32_bf16 v[42:45], v[150:153], v[166:169], v[42:45]
	v_mfma_f32_16x16x32_bf16 v[30:33], v[136:139], v[174:177], v[30:33]
	v_mfma_f32_16x16x32_bf16 v[26:29], v[150:153], v[174:177], v[26:29]
	v_mfma_f32_16x16x32_bf16 v[14:17], v[136:139], v[182:185], v[14:17]
	v_mfma_f32_16x16x32_bf16 v[10:13], v[150:153], v[182:185], v[10:13]
	v_mfma_f32_16x16x32_bf16 v[62:65], v[140:143], v[162:165], v[62:65]
	v_mfma_f32_16x16x32_bf16 v[58:61], v[154:157], v[162:165], v[58:61]
	v_mfma_f32_16x16x32_bf16 v[46:49], v[140:143], v[170:173], v[46:49]
	v_mfma_f32_16x16x32_bf16 v[42:45], v[154:157], v[170:173], v[42:45]
	v_mfma_f32_16x16x32_bf16 v[30:33], v[140:143], v[178:181], v[30:33]
	v_mfma_f32_16x16x32_bf16 v[26:29], v[154:157], v[178:181], v[26:29]
	v_mfma_f32_16x16x32_bf16 v[14:17], v[140:143], v[186:189], v[14:17]
	v_mfma_f32_16x16x32_bf16 v[10:13], v[154:157], v[186:189], v[10:13]
	s_setprio 0
	s_barrier
	s_add_u32 s38, s42, 0x40080
	s_addc_u32 s39, s43, 0
	s_add_i32 s42, s46, s52
	s_mov_b32 m0, s42
	s_nop 0
	global_load_lds_dwordx4 v130, s[38:39]
	s_add_i32 m0, s42, 0x2000
	s_nop 0
	global_load_lds_dwordx4 v132, s[38:39]
	s_waitcnt vmcnt(6)
	s_barrier
	s_setprio 1
	v_mfma_f32_16x16x32_bf16 v[54:57], v[190:193], v[158:161], v[54:57]
	v_mfma_f32_16x16x32_bf16 v[50:53], v[198:201], v[158:161], v[50:53]
	v_mfma_f32_16x16x32_bf16 v[38:41], v[190:193], v[166:169], v[38:41]
	v_mfma_f32_16x16x32_bf16 v[34:37], v[198:201], v[166:169], v[34:37]
	v_mfma_f32_16x16x32_bf16 v[22:25], v[190:193], v[174:177], v[22:25]
	v_mfma_f32_16x16x32_bf16 v[18:21], v[198:201], v[174:177], v[18:21]
	v_mfma_f32_16x16x32_bf16 v[6:9], v[190:193], v[182:185], v[6:9]
	v_mfma_f32_16x16x32_bf16 v[2:5], v[198:201], v[182:185], v[2:5]
	v_mfma_f32_16x16x32_bf16 v[54:57], v[194:197], v[162:165], v[54:57]
	v_mfma_f32_16x16x32_bf16 v[50:53], v[202:205], v[162:165], v[50:53]
	v_mfma_f32_16x16x32_bf16 v[38:41], v[194:197], v[170:173], v[38:41]
	v_mfma_f32_16x16x32_bf16 v[34:37], v[202:205], v[170:173], v[34:37]
	v_mfma_f32_16x16x32_bf16 v[22:25], v[194:197], v[178:181], v[22:25]
	v_mfma_f32_16x16x32_bf16 v[18:21], v[202:205], v[178:181], v[18:21]
	v_mfma_f32_16x16x32_bf16 v[6:9], v[194:197], v[186:189], v[6:9]
	v_mfma_f32_16x16x32_bf16 v[2:5], v[202:205], v[186:189], v[2:5]
	s_setprio 0
	s_add_i32 s67, s67, 2
	s_add_u32 s65, s65, 0x100
	s_addc_u32 s66, s66, 0
	s_cmp_gt_u32 s67, 13
	s_mov_b64 s[38:39], s[40:41]
	s_barrier
	s_cbranch_scc0 .LBB0_339
	v_mov_b32_e32 v134, v0
	s_ashr_i32 s38, s0, 1
	v_readfirstlane_b32 s1, v134
	s_and_b32 s7, s1, 0xc0
	s_ashr_i32 s1, s1, 2
	s_andn2_b32 s1, s1, 63
	v_and_or_b32 v136, v134, 15, s1
	s_ashr_i32 s39, s38, 31
	s_lshl_b64 s[40:41], s[38:39], 19
	v_lshl_add_u32 v140, s6, 8, v136
	s_or_b32 s40, s40, s7
	v_lshrrev_b32_e32 v134, 1, v134
	v_ashrrev_i32_e32 v141, 31, v140
	s_and_b32 s29, s0, 1
	v_and_b32_e32 v139, 24, v134
	v_lshlrev_b64 v[136:137], 8, v[140:141]
	s_bitcmp1_b32 s0, 0
	v_lshl_add_u64 v[142:143], v[136:137], 0, s[40:41]
	s_mov_b64 s[6:7], -1
	s_cselect_b64 s[0:1], -1, 0
	s_cmp_eq_u32 s29, 0
	v_lshlrev_b32_e32 v134, 2, v139
	v_lshlrev_b32_e32 v138, 1, v139
	v_or_b32_e32 v136, 32, v139
	s_cbranch_scc1 .LBB0_342
	v_lshl_add_u64 v[150:151], v[142:143], 2, s[16:17]
	v_lshl_add_u64 v[154:155], v[150:151], 0, v[134:135]
	v_lshl_add_u64 v[150:151], v[142:143], 1, s[20:21]
	v_mov_b32_e32 v139, v135
	v_lshl_add_u64 v[156:157], v[150:151], 0, v[138:139]
	v_cvt_pk_bf16_f32 v150, v126, v127
	v_cvt_pk_bf16_f32 v151, v128, v129
	v_cvt_pk_bf16_f32 v152, v122, v123
	v_cvt_pk_bf16_f32 v153, v124, v125
	v_mov_b32_e32 v137, v135
	s_mov_b64 s[6:7], 0
	global_store_dwordx4 v[154:155], v[126:129], off
	global_store_dwordx4 v[154:155], v[122:125], off offset:16
	global_store_dwordx4 v[156:157], v[150:153], off
	global_store_dwordx4 v[154:155], v[118:121], off offset:128

.LBB0_393:
	s_ashr_i32 s13, s12, 31
	s_lshl_b64 s[18:19], s[12:13], 17
	s_add_u32 s18, s45, s18
	s_addc_u32 s19, s46, s19
	s_and_b64 s[22:23], s[22:23], exec
	v_mov_b32_e32 v2, 0
	s_cselect_b32 s1, s19, s7
	s_cselect_b32 s13, s18, s6
	s_mov_b64 s[24:25], 0
	s_mov_b64 s[22:23], -1
	s_mov_b64 s[28:29], 0
	s_waitcnt lgkmcnt(0)
	v_mov_b32_e32 v3, v2
	v_mov_b32_e32 v4, v2
	v_mov_b32_e32 v5, v2
	v_mov_b32_e32 v6, v2
	v_mov_b32_e32 v7, v2
	v_mov_b32_e32 v8, v2
	v_mov_b32_e32 v9, v2
	v_mov_b32_e32 v18, v2
	v_mov_b32_e32 v19, v2
	v_mov_b32_e32 v20, v2
	v_mov_b32_e32 v21, v2
	v_mov_b32_e32 v22, v2
	v_mov_b32_e32 v23, v2
	v_mov_b32_e32 v24, v2
	v_mov_b32_e32 v25, v2
	v_mov_b32_e32 v34, v2
	v_mov_b32_e32 v35, v2
	v_mov_b32_e32 v36, v2
	v_mov_b32_e32 v37, v2
	v_mov_b32_e32 v38, v2
	v_mov_b32_e32 v39, v2
	v_mov_b32_e32 v40, v2
	v_mov_b32_e32 v41, v2
	v_mov_b32_e32 v50, v2
	v_mov_b32_e32 v51, v2
	v_mov_b32_e32 v52, v2
	v_mov_b32_e32 v53, v2
	v_mov_b32_e32 v54, v2
	v_mov_b32_e32 v55, v2
	v_mov_b32_e32 v56, v2
	v_mov_b32_e32 v57, v2
	v_mov_b32_e32 v10, v2
	v_mov_b32_e32 v11, v2
	v_mov_b32_e32 v12, v2
	v_mov_b32_e32 v13, v2
	v_mov_b32_e32 v14, v2
	v_mov_b32_e32 v15, v2
	v_mov_b32_e32 v16, v2
	v_mov_b32_e32 v17, v2
	v_mov_b32_e32 v26, v2
	v_mov_b32_e32 v27, v2
	v_mov_b32_e32 v28, v2
	v_mov_b32_e32 v29, v2
	v_mov_b32_e32 v30, v2
	v_mov_b32_e32 v31, v2
	v_mov_b32_e32 v32, v2
	v_mov_b32_e32 v33, v2
	v_mov_b32_e32 v42, v2
	v_mov_b32_e32 v43, v2
	v_mov_b32_e32 v44, v2
	v_mov_b32_e32 v45, v2
	v_mov_b32_e32 v46, v2
	v_mov_b32_e32 v47, v2
	v_mov_b32_e32 v48, v2
	v_mov_b32_e32 v49, v2
	v_mov_b32_e32 v58, v2
	v_mov_b32_e32 v59, v2
	v_mov_b32_e32 v60, v2
	v_mov_b32_e32 v61, v2
	v_mov_b32_e32 v62, v2
	v_mov_b32_e32 v63, v2
	v_mov_b32_e32 v64, v2
	v_mov_b32_e32 v65, v2
	v_mov_b32_e32 v66, v2
	v_mov_b32_e32 v67, v2
	v_mov_b32_e32 v68, v2
	v_mov_b32_e32 v69, v2
	v_mov_b32_e32 v70, v2
	v_mov_b32_e32 v71, v2
	v_mov_b32_e32 v72, v2
	v_mov_b32_e32 v73, v2
	v_mov_b32_e32 v82, v2
	v_mov_b32_e32 v83, v2
	v_mov_b32_e32 v84, v2
	v_mov_b32_e32 v85, v2
	v_mov_b32_e32 v86, v2
	v_mov_b32_e32 v87, v2
	v_mov_b32_e32 v88, v2
	v_mov_b32_e32 v89, v2
	v_mov_b32_e32 v98, v2
	v_mov_b32_e32 v99, v2
	v_mov_b32_e32 v100, v2
	v_mov_b32_e32 v101, v2
	v_mov_b32_e32 v102, v2
	v_mov_b32_e32 v103, v2
	v_mov_b32_e32 v104, v2
	v_mov_b32_e32 v105, v2
	v_mov_b32_e32 v114, v2
	v_mov_b32_e32 v115, v2
	v_mov_b32_e32 v116, v2
	v_mov_b32_e32 v117, v2
	v_mov_b32_e32 v118, v2
	v_mov_b32_e32 v119, v2
	v_mov_b32_e32 v120, v2
	v_mov_b32_e32 v121, v2
	v_mov_b32_e32 v74, v2
	v_mov_b32_e32 v75, v2
	v_mov_b32_e32 v76, v2
	v_mov_b32_e32 v77, v2
	v_mov_b32_e32 v78, v2
	v_mov_b32_e32 v79, v2
	v_mov_b32_e32 v80, v2
	v_mov_b32_e32 v81, v2
	v_mov_b32_e32 v90, v2
	v_mov_b32_e32 v91, v2
	v_mov_b32_e32 v92, v2
	v_mov_b32_e32 v93, v2
	v_mov_b32_e32 v94, v2
	v_mov_b32_e32 v95, v2
	v_mov_b32_e32 v96, v2
	v_mov_b32_e32 v97, v2
	v_mov_b32_e32 v106, v2
	v_mov_b32_e32 v107, v2
	v_mov_b32_e32 v108, v2
	v_mov_b32_e32 v109, v2
	v_mov_b32_e32 v110, v2
	v_mov_b32_e32 v111, v2
	v_mov_b32_e32 v112, v2
	v_mov_b32_e32 v113, v2
	v_mov_b32_e32 v122, v2
	v_mov_b32_e32 v123, v2
	v_mov_b32_e32 v124, v2
	v_mov_b32_e32 v125, v2
	v_mov_b32_e32 v126, v2
	v_mov_b32_e32 v127, v2
	v_mov_b32_e32 v128, v2
	v_mov_b32_e32 v129, v2
	v_add_u32_e32 v216, 0x10000, v1
	s_waitcnt vmcnt(0)
.LBB0_394:
	s_add_u32 s34, s20, s24
	s_addc_u32 s35, s21, s25
	s_add_u32 s36, s34, 0x100
	s_addc_u32 s37, s35, 0
	s_and_b64 s[30:31], s[28:29], exec
	s_cselect_b32 s39, s15, s37
	s_cselect_b32 s38, s14, s36
	s_add_u32 s24, s6, s24
	s_addc_u32 s25, s7, s25
	s_add_u32 s30, s24, 0x100
	s_addc_u32 s31, s25, 0
	s_add_u32 s24, s38, 0x80
	s_addc_u32 s25, s39, 0
	s_and_b64 s[28:29], s[28:29], exec
	s_cselect_b32 s41, s1, s31
	s_cselect_b32 s40, s13, s30
	s_add_u32 s42, s34, 0x12080
	s_addc_u32 s43, s35, 0
	s_add_i32 s78, s63, s49
	s_add_i32 m0, s50, 0xc000
	s_add_i32 s79, s50, 0xe000
	s_add_i32 s77, s78, 0x2000
	s_add_u32 s36, s40, 0x10000
	s_addc_u32 s37, s41, 0
	s_add_i32 s75, s64, s49
	s_add_i32 s73, s75, 0x2000
	s_add_i32 s72, 0, 0x18000
	s_add_u32 s34, s38, 0x12000
	ds_read_b128 v[146:149], v140
	ds_read_b128 v[150:153], v140 offset:1024
	ds_read_b128 v[154:157], v140 offset:2048
	ds_read_b128 v[158:161], v140 offset:3072
	s_addc_u32 s35, s39, 0
	s_add_i32 s70, 0, 0x1c000
	s_add_u32 s30, s40, 0x80
	s_addc_u32 s31, s41, 0
	s_add_i32 s71, s72, s49
	s_add_i32 s69, s71, 0x2000
	s_add_u32 s28, s40, 0x10080
	s_addc_u32 s29, s41, 0
	s_add_i32 s76, s70, s49
	s_add_i32 s74, s76, 0x2000
	ds_read_b128 v[162:165], v141
	ds_read_b128 v[166:169], v141 offset:1024
	ds_read_b128 v[170:173], v141 offset:2048
	ds_read_b128 v[174:177], v141 offset:3072
	ds_read_b128 v[178:181], v141 offset:4096
	ds_read_b128 v[182:185], v141 offset:5120
	ds_read_b128 v[186:189], v141 offset:6144
	ds_read_b128 v[190:193], v141 offset:7168
	s_nop 0
	global_load_lds_dwordx4 v130, s[42:43]
	s_mov_b32 m0, s79
	s_nop 0
	global_load_lds_dwordx4 v134, s[42:43]
	s_waitcnt lgkmcnt(8)
	s_barrier
	s_waitcnt lgkmcnt(0)
	s_setprio 1
	s_waitcnt lgkmcnt(0)
	v_mfma_f32_16x16x32_bf16 v[126:129], v[146:149], v[162:165], v[126:129]
	v_mfma_f32_16x16x32_bf16 v[122:125], v[154:157], v[162:165], v[122:125]
	v_mfma_f32_16x16x32_bf16 v[110:113], v[146:149], v[170:173], v[110:113]
	v_mfma_f32_16x16x32_bf16 v[106:109], v[154:157], v[170:173], v[106:109]
	v_mfma_f32_16x16x32_bf16 v[94:97], v[146:149], v[178:181], v[94:97]
	v_mfma_f32_16x16x32_bf16 v[90:93], v[154:157], v[178:181], v[90:93]
	v_mfma_f32_16x16x32_bf16 v[78:81], v[146:149], v[186:189], v[78:81]
	v_mfma_f32_16x16x32_bf16 v[74:77], v[154:157], v[186:189], v[74:77]
	v_mfma_f32_16x16x32_bf16 v[126:129], v[150:153], v[166:169], v[126:129]
	v_mfma_f32_16x16x32_bf16 v[122:125], v[158:161], v[166:169], v[122:125]
	v_mfma_f32_16x16x32_bf16 v[110:113], v[150:153], v[174:177], v[110:113]
	v_mfma_f32_16x16x32_bf16 v[106:109], v[158:161], v[174:177], v[106:109]
	v_mfma_f32_16x16x32_bf16 v[94:97], v[150:153], v[182:185], v[94:97]
	v_mfma_f32_16x16x32_bf16 v[90:93], v[158:161], v[182:185], v[90:93]
	v_mfma_f32_16x16x32_bf16 v[78:81], v[150:153], v[190:193], v[78:81]
	v_mfma_f32_16x16x32_bf16 v[74:77], v[158:161], v[190:193], v[74:77]
	s_setprio 0
	s_barrier
	s_mov_b32 m0, s78
	ds_read_b128 v[194:197], v142
	ds_read_b128 v[198:201], v142 offset:1024
	ds_read_b128 v[202:205], v142 offset:2048
	ds_read_b128 v[206:209], v142 offset:3072
	s_nop 0
	global_load_lds_dwordx4 v132, s[40:41]
	s_mov_b32 m0, s77
	s_nop 0
	global_load_lds_dwordx4 v136, s[40:41]
	s_barrier
	s_waitcnt lgkmcnt(0)
	s_setprio 1
	s_waitcnt lgkmcnt(0)
	v_mfma_f32_16x16x32_bf16 v[118:121], v[194:197], v[162:165], v[118:121]
	v_mfma_f32_16x16x32_bf16 v[114:117], v[202:205], v[162:165], v[114:117]
	v_mfma_f32_16x16x32_bf16 v[102:105], v[194:197], v[170:173], v[102:105]
	v_mfma_f32_16x16x32_bf16 v[98:101], v[202:205], v[170:173], v[98:101]
	v_mfma_f32_16x16x32_bf16 v[86:89], v[194:197], v[178:181], v[86:89]
	v_mfma_f32_16x16x32_bf16 v[82:85], v[202:205], v[178:181], v[82:85]
	v_mfma_f32_16x16x32_bf16 v[70:73], v[194:197], v[186:189], v[70:73]
	v_mfma_f32_16x16x32_bf16 v[66:69], v[202:205], v[186:189], v[66:69]
	v_mfma_f32_16x16x32_bf16 v[118:121], v[198:201], v[166:169], v[118:121]
	v_mfma_f32_16x16x32_bf16 v[114:117], v[206:209], v[166:169], v[114:117]
	v_mfma_f32_16x16x32_bf16 v[102:105], v[198:201], v[174:177], v[102:105]
	v_mfma_f32_16x16x32_bf16 v[98:101], v[206:209], v[174:177], v[98:101]
	v_mfma_f32_16x16x32_bf16 v[86:89], v[198:201], v[182:185], v[86:89]
	v_mfma_f32_16x16x32_bf16 v[82:85], v[206:209], v[182:185], v[82:85]
	v_mfma_f32_16x16x32_bf16 v[70:73], v[198:201], v[190:193], v[70:73]
	v_mfma_f32_16x16x32_bf16 v[66:69], v[206:209], v[190:193], v[66:69]
	s_setprio 0
	s_mov_b32 m0, s50
	s_barrier
	ds_read_b128 v[162:165], v141 offset:16384
	ds_read_b128 v[166:169], v141 offset:17408
	ds_read_b128 v[170:173], v141 offset:18432
	ds_read_b128 v[174:177], v141 offset:19456
	ds_read_b128 v[178:181], v141 offset:20480
	ds_read_b128 v[182:185], v141 offset:21504
	ds_read_b128 v[186:189], v141 offset:22528
	ds_read_b128 v[190:193], v141 offset:23552
	s_nop 0
	global_load_lds_dwordx4 v130, s[38:39]
	s_mov_b32 m0, s51
	s_nop 0
	global_load_lds_dwordx4 v134, s[38:39]
	s_barrier
	s_waitcnt lgkmcnt(0)
	s_setprio 1
	s_waitcnt lgkmcnt(0)
	v_mfma_f32_16x16x32_bf16 v[62:65], v[146:149], v[162:165], v[62:65]
	v_mfma_f32_16x16x32_bf16 v[58:61], v[154:157], v[162:165], v[58:61]
	v_mfma_f32_16x16x32_bf16 v[46:49], v[146:149], v[170:173], v[46:49]
	v_mfma_f32_16x16x32_bf16 v[42:45], v[154:157], v[170:173], v[42:45]
	v_mfma_f32_16x16x32_bf16 v[30:33], v[146:149], v[178:181], v[30:33]
	v_mfma_f32_16x16x32_bf16 v[26:29], v[154:157], v[178:181], v[26:29]
	v_mfma_f32_16x16x32_bf16 v[14:17], v[146:149], v[186:189], v[14:17]
	v_mfma_f32_16x16x32_bf16 v[10:13], v[154:157], v[186:189], v[10:13]
	v_mfma_f32_16x16x32_bf16 v[62:65], v[150:153], v[166:169], v[62:65]
	v_mfma_f32_16x16x32_bf16 v[58:61], v[158:161], v[166:169], v[58:61]
	v_mfma_f32_16x16x32_bf16 v[46:49], v[150:153], v[174:177], v[46:49]
	v_mfma_f32_16x16x32_bf16 v[42:45], v[158:161], v[174:177], v[42:45]
	v_mfma_f32_16x16x32_bf16 v[30:33], v[150:153], v[182:185], v[30:33]
	v_mfma_f32_16x16x32_bf16 v[26:29], v[158:161], v[182:185], v[26:29]
	v_mfma_f32_16x16x32_bf16 v[14:17], v[150:153], v[190:193], v[14:17]
	v_mfma_f32_16x16x32_bf16 v[10:13], v[158:161], v[190:193], v[10:13]
	s_setprio 0
	s_barrier
	s_mov_b32 m0, s75
	s_nop 0
	global_load_lds_dwordx4 v132, s[36:37]
	s_mov_b32 m0, s73
	s_nop 0
	global_load_lds_dwordx4 v136, s[36:37]
	s_waitcnt vmcnt(6)
	s_barrier
	s_setprio 1
	v_mfma_f32_16x16x32_bf16 v[54:57], v[194:197], v[162:165], v[54:57]
	v_mfma_f32_16x16x32_bf16 v[50:53], v[202:205], v[162:165], v[50:53]
	v_mfma_f32_16x16x32_bf16 v[38:41], v[194:197], v[170:173], v[38:41]
	v_mfma_f32_16x16x32_bf16 v[34:37], v[202:205], v[170:173], v[34:37]
	v_mfma_f32_16x16x32_bf16 v[22:25], v[194:197], v[178:181], v[22:25]
	v_mfma_f32_16x16x32_bf16 v[18:21], v[202:205], v[178:181], v[18:21]
	v_mfma_f32_16x16x32_bf16 v[6:9], v[194:197], v[186:189], v[6:9]
	v_mfma_f32_16x16x32_bf16 v[2:5], v[202:205], v[186:189], v[2:5]
	v_mfma_f32_16x16x32_bf16 v[54:57], v[198:201], v[166:169], v[54:57]
	v_mfma_f32_16x16x32_bf16 v[50:53], v[206:209], v[166:169], v[50:53]
	v_mfma_f32_16x16x32_bf16 v[38:41], v[198:201], v[174:177], v[38:41]
	v_mfma_f32_16x16x32_bf16 v[34:37], v[206:209], v[174:177], v[34:37]
	v_mfma_f32_16x16x32_bf16 v[22:25], v[198:201], v[182:185], v[22:25]
	v_mfma_f32_16x16x32_bf16 v[18:21], v[206:209], v[182:185], v[18:21]
	v_mfma_f32_16x16x32_bf16 v[6:9], v[198:201], v[190:193], v[6:9]
	v_mfma_f32_16x16x32_bf16 v[2:5], v[206:209], v[190:193], v[2:5]
	s_setprio 0
	s_barrier
	ds_read_b128 v[146:149], v216 offset:32768
	ds_read_b128 v[150:153], v216 offset:33792
	ds_read_b128 v[154:157], v216 offset:34816
	ds_read_b128 v[158:161], v216 offset:35840
	s_mov_b32 m0, s52
	ds_read_b128 v[162:165], v141 offset:32768
	ds_read_b128 v[166:169], v141 offset:33792
	ds_read_b128 v[170:173], v141 offset:34816
	ds_read_b128 v[174:177], v141 offset:35840
	ds_read_b128 v[178:181], v141 offset:36864
	ds_read_b128 v[182:185], v141 offset:37888
	ds_read_b128 v[186:189], v141 offset:38912
	ds_read_b128 v[190:193], v141 offset:39936
	s_nop 0
	global_load_lds_dwordx4 v130, s[34:35]
	s_mov_b32 m0, s53
	s_nop 0
	global_load_lds_dwordx4 v134, s[34:35]
	s_waitcnt lgkmcnt(8)
	s_barrier
	s_waitcnt lgkmcnt(0)
	s_setprio 1
	s_waitcnt lgkmcnt(0)
	v_mfma_f32_16x16x32_bf16 v[126:129], v[146:149], v[162:165], v[126:129]
	v_mfma_f32_16x16x32_bf16 v[122:125], v[154:157], v[162:165], v[122:125]
	v_mfma_f32_16x16x32_bf16 v[110:113], v[146:149], v[170:173], v[110:113]
	v_mfma_f32_16x16x32_bf16 v[106:109], v[154:157], v[170:173], v[106:109]
	v_mfma_f32_16x16x32_bf16 v[94:97], v[146:149], v[178:181], v[94:97]
	v_mfma_f32_16x16x32_bf16 v[90:93], v[154:157], v[178:181], v[90:93]
	v_mfma_f32_16x16x32_bf16 v[78:81], v[146:149], v[186:189], v[78:81]
	v_mfma_f32_16x16x32_bf16 v[74:77], v[154:157], v[186:189], v[74:77]
	v_mfma_f32_16x16x32_bf16 v[126:129], v[150:153], v[166:169], v[126:129]
	v_mfma_f32_16x16x32_bf16 v[122:125], v[158:161], v[166:169], v[122:125]
	v_mfma_f32_16x16x32_bf16 v[110:113], v[150:153], v[174:177], v[110:113]
	v_mfma_f32_16x16x32_bf16 v[106:109], v[158:161], v[174:177], v[106:109]
	v_mfma_f32_16x16x32_bf16 v[94:97], v[150:153], v[182:185], v[94:97]
	v_mfma_f32_16x16x32_bf16 v[90:93], v[158:161], v[182:185], v[90:93]
	v_mfma_f32_16x16x32_bf16 v[78:81], v[150:153], v[190:193], v[78:81]
	v_mfma_f32_16x16x32_bf16 v[74:77], v[158:161], v[190:193], v[74:77]
	s_setprio 0
	s_barrier
	s_mov_b32 m0, s71
	ds_read_b128 v[194:197], v216 offset:49152
	ds_read_b128 v[198:201], v216 offset:50176
	ds_read_b128 v[202:205], v216 offset:51200
	ds_read_b128 v[206:209], v216 offset:52224
	s_nop 0
	global_load_lds_dwordx4 v132, s[30:31]
	s_mov_b32 m0, s69
	s_nop 0
	global_load_lds_dwordx4 v136, s[30:31]
	s_barrier
	s_waitcnt lgkmcnt(0)
	s_setprio 1
	s_waitcnt lgkmcnt(0)
	v_mfma_f32_16x16x32_bf16 v[118:121], v[194:197], v[162:165], v[118:121]
	v_mfma_f32_16x16x32_bf16 v[114:117], v[202:205], v[162:165], v[114:117]
	v_mfma_f32_16x16x32_bf16 v[102:105], v[194:197], v[170:173], v[102:105]
	v_mfma_f32_16x16x32_bf16 v[98:101], v[202:205], v[170:173], v[98:101]
	v_mfma_f32_16x16x32_bf16 v[86:89], v[194:197], v[178:181], v[86:89]
	v_mfma_f32_16x16x32_bf16 v[82:85], v[202:205], v[178:181], v[82:85]
	v_mfma_f32_16x16x32_bf16 v[70:73], v[194:197], v[186:189], v[70:73]
	v_mfma_f32_16x16x32_bf16 v[66:69], v[202:205], v[186:189], v[66:69]
	v_mfma_f32_16x16x32_bf16 v[118:121], v[198:201], v[166:169], v[118:121]
	v_mfma_f32_16x16x32_bf16 v[114:117], v[206:209], v[166:169], v[114:117]
	v_mfma_f32_16x16x32_bf16 v[102:105], v[198:201], v[174:177], v[102:105]
	v_mfma_f32_16x16x32_bf16 v[98:101], v[206:209], v[174:177], v[98:101]
	v_mfma_f32_16x16x32_bf16 v[86:89], v[198:201], v[182:185], v[86:89]
	v_mfma_f32_16x16x32_bf16 v[82:85], v[206:209], v[182:185], v[82:85]
	v_mfma_f32_16x16x32_bf16 v[70:73], v[198:201], v[190:193], v[70:73]
	v_mfma_f32_16x16x32_bf16 v[66:69], v[206:209], v[190:193], v[66:69]
	s_setprio 0
	s_mov_b32 m0, s58
	s_barrier
	ds_read_b128 v[162:165], v141 offset:49152
	ds_read_b128 v[166:169], v141 offset:50176
	ds_read_b128 v[170:173], v141 offset:51200
	ds_read_b128 v[174:177], v141 offset:52224
	ds_read_b128 v[178:181], v141 offset:53248
	ds_read_b128 v[182:185], v141 offset:54272
	ds_read_b128 v[186:189], v141 offset:55296
	ds_read_b128 v[190:193], v141 offset:56320
	s_nop 0
	global_load_lds_dwordx4 v130, s[24:25]
	s_mov_b32 m0, s59
	s_nop 0
	global_load_lds_dwordx4 v134, s[24:25]
	s_barrier
	s_waitcnt lgkmcnt(0)
	s_setprio 1
	s_waitcnt lgkmcnt(0)
	v_mfma_f32_16x16x32_bf16 v[62:65], v[146:149], v[162:165], v[62:65]
	v_mfma_f32_16x16x32_bf16 v[58:61], v[154:157], v[162:165], v[58:61]
	v_mfma_f32_16x16x32_bf16 v[46:49], v[146:149], v[170:173], v[46:49]
	v_mfma_f32_16x16x32_bf16 v[42:45], v[154:157], v[170:173], v[42:45]
	v_mfma_f32_16x16x32_bf16 v[30:33], v[146:149], v[178:181], v[30:33]
	v_mfma_f32_16x16x32_bf16 v[26:29], v[154:157], v[178:181], v[26:29]
	v_mfma_f32_16x16x32_bf16 v[14:17], v[146:149], v[186:189], v[14:17]
	v_mfma_f32_16x16x32_bf16 v[10:13], v[154:157], v[186:189], v[10:13]
	v_mfma_f32_16x16x32_bf16 v[62:65], v[150:153], v[166:169], v[62:65]
	v_mfma_f32_16x16x32_bf16 v[58:61], v[158:161], v[166:169], v[58:61]
	v_mfma_f32_16x16x32_bf16 v[46:49], v[150:153], v[174:177], v[46:49]
	v_mfma_f32_16x16x32_bf16 v[42:45], v[158:161], v[174:177], v[42:45]
	v_mfma_f32_16x16x32_bf16 v[30:33], v[150:153], v[182:185], v[30:33]
	v_mfma_f32_16x16x32_bf16 v[26:29], v[158:161], v[182:185], v[26:29]
	v_mfma_f32_16x16x32_bf16 v[14:17], v[150:153], v[190:193], v[14:17]
	v_mfma_f32_16x16x32_bf16 v[10:13], v[158:161], v[190:193], v[10:13]
	s_setprio 0
	s_barrier
	s_mov_b32 m0, s76
	s_nop 0
	global_load_lds_dwordx4 v132, s[28:29]
	s_mov_b32 m0, s74
	s_nop 0
	global_load_lds_dwordx4 v136, s[28:29]
	s_waitcnt vmcnt(6)
	s_barrier
	s_setprio 1
	v_mfma_f32_16x16x32_bf16 v[54:57], v[194:197], v[162:165], v[54:57]
	v_mfma_f32_16x16x32_bf16 v[50:53], v[202:205], v[162:165], v[50:53]
	v_mfma_f32_16x16x32_bf16 v[38:41], v[194:197], v[170:173], v[38:41]
	v_mfma_f32_16x16x32_bf16 v[34:37], v[202:205], v[170:173], v[34:37]
	v_mfma_f32_16x16x32_bf16 v[22:25], v[194:197], v[178:181], v[22:25]
	v_mfma_f32_16x16x32_bf16 v[18:21], v[202:205], v[178:181], v[18:21]
	v_mfma_f32_16x16x32_bf16 v[6:9], v[194:197], v[186:189], v[6:9]
	v_mfma_f32_16x16x32_bf16 v[2:5], v[202:205], v[186:189], v[2:5]
	v_mfma_f32_16x16x32_bf16 v[54:57], v[198:201], v[166:169], v[54:57]
	v_mfma_f32_16x16x32_bf16 v[50:53], v[206:209], v[166:169], v[50:53]
	v_mfma_f32_16x16x32_bf16 v[38:41], v[198:201], v[174:177], v[38:41]
	v_mfma_f32_16x16x32_bf16 v[34:37], v[206:209], v[174:177], v[34:37]
	v_mfma_f32_16x16x32_bf16 v[22:25], v[198:201], v[182:185], v[22:25]
	v_mfma_f32_16x16x32_bf16 v[18:21], v[206:209], v[182:185], v[18:21]
	v_mfma_f32_16x16x32_bf16 v[6:9], v[198:201], v[190:193], v[6:9]
	v_mfma_f32_16x16x32_bf16 v[2:5], v[206:209], v[190:193], v[2:5]
	s_setprio 0
	s_andn2_b64 vcc, exec, s[22:23]
	s_mov_b64 s[28:29], -1
	s_mov_b64 s[22:23], 0
	s_mov_b64 s[24:25], 0x100
	s_barrier
	s_cbranch_vccz .LBB0_394
	v_mov_b32_e32 v154, v0
	s_ashr_i32 s1, s0, 31
	v_readfirstlane_b32 s6, v154
	s_bfe_u32 s13, s6, 0x20006
	s_ashr_i32 s6, s6, 2
	s_andn2_b32 s6, s6, 63
	s_ashr_i32 s7, s6, 31
	s_lshl_b64 s[20:21], s[0:1], 10
	s_add_u32 s22, s54, s20
	s_addc_u32 s23, s55, s21
	s_lshl_b64 s[20:21], s[6:7], 2
	v_and_b32_e32 v145, 15, v154
	s_add_u32 s20, s22, s20
	s_addc_u32 s21, s23, s21
	v_lshlrev_b32_e32 v138, 2, v145
	global_load_dword v153, v138, s[20:21] offset:64
	global_load_dword v152, v138, s[20:21] offset:128
	global_load_dword v151, v138, s[20:21] offset:192
	global_load_dword v150, v138, s[20:21] offset:512
	global_load_dword v149, v138, s[20:21] offset:576
	global_load_dword v148, v138, s[20:21] offset:640
	global_load_dword v147, v138, s[20:21] offset:704
	v_mul_f32_e32 v127, v127, v127
	v_mul_f32_e32 v123, v123, v123
	v_mul_f32_e32 v119, v119, v119
	v_mul_f32_e32 v115, v115, v115
	v_fmac_f32_e32 v127, v126, v126
	v_mul_f32_e32 v126, v129, v129
	v_fmac_f32_e32 v123, v122, v122
	v_mul_f32_e32 v122, v125, v125
	v_fmac_f32_e32 v119, v118, v118
	v_mul_f32_e32 v118, v121, v121
	v_fmac_f32_e32 v115, v114, v114
	v_mul_f32_e32 v114, v117, v117
	v_fmac_f32_e32 v126, v128, v128
	v_fmac_f32_e32 v122, v124, v124
	v_fmac_f32_e32 v118, v120, v120
	v_fmac_f32_e32 v114, v116, v116
	v_add_f32_e32 v126, v127, v126
	v_add_f32_e32 v122, v123, v122
	v_add_f32_e32 v118, v119, v118
	v_add_f32_e32 v114, v115, v114
	v_add_f32_e32 v122, v126, v122
	v_add_f32_e32 v114, v118, v114
	v_add_f32_e32 v115, v122, v114
	ds_swizzle_b32 v116, v115 offset:swizzle(SWAP,16)
	v_and_b32_e32 v156, 64, v143
	v_xor_b32_e32 v155, 32, v143
	v_add_u32_e32 v156, 64, v156
	v_cmp_lt_i32_e32 vcc, v155, v156
	s_lshl_b32 s22, s68, 2
	s_or_b32 s22, s13, s22
	v_cndmask_b32_e32 v114, v143, v155, vcc
	s_lshl_b64 s[0:1], s[0:1], 8
	v_lshlrev_b32_e32 v114, 2, v114
	s_waitcnt lgkmcnt(0)
	v_add_f32_e32 v115, v115, v116
	s_add_u32 s0, s0, s6
	ds_bpermute_b32 v116, v114, v115
	s_addc_u32 s1, s1, s7
	s_ashr_i32 s23, s22, 31
	v_or_b32_e32 v146, s0, v145
	v_mov_b32_e32 v145, s1
	s_lshl_b64 s[0:1], s[22:23], 2
	v_and_b32_e32 v117, 48, v154
	s_add_u32 s0, s56, s0
	v_cmp_eq_u32_e64 s[6:7], 0, v117
	s_addc_u32 s1, s57, s1
	s_and_saveexec_b64 s[22:23], s[6:7]
	s_cbranch_execz .LBB0_397
	v_lshl_add_u64 v[118:119], s[20:21], 0, v[138:139]
	global_load_dword v118, v[118:119], off
	s_waitcnt lgkmcnt(0)
	v_add_f32_e32 v115, v115, v116
	v_mad_u64_u32 v[116:117], s[20:21], v146, 48, s[0:1]
	s_waitcnt vmcnt(0)
	v_add_f32_e32 v115, v115, v118
	v_fmamk_f32 v115, v115, 0x3c2aaaab, v144
	v_mul_f32_e32 v118, 0x4b800000, v115
	v_cmp_gt_f32_e32 vcc, s65, v115
	s_nop 1
	v_cndmask_b32_e32 v115, v115, v118, vcc
	v_rsq_f32_e32 v115, v115
	v_mov_b32_e32 v118, v117
	v_mad_u64_u32 v[118:119], s[20:21], v145, 48, v[118:119]
	v_mul_f32_e32 v117, 0x45800000, v115
	v_cndmask_b32_e32 v115, v115, v117, vcc
	v_mov_b32_e32 v117, v118
	global_store_dword v[116:117], v115, off

.LBB0_504:
	s_ashr_i32 s43, s42, 31
	v_cmp_lt_i64_e32 vcc, s[20:21], v[140:141]
	s_lshl_b64 s[20:21], s[42:43], 19
	s_add_u32 s44, s56, s20
	s_addc_u32 s45, s57, s21
	s_and_b64 s[20:21], vcc, exec
	s_cselect_b32 s1, s45, s17
	s_cselect_b32 s9, s44, s16
	s_ashr_i32 s41, s40, 31
	s_lshl_b64 s[20:21], s[40:41], 19
	s_add_u32 s46, s63, s20
	s_addc_u32 s47, s72, s21
	s_and_b64 s[20:21], vcc, exec
	s_cselect_b32 s41, s47, s19
	s_cselect_b32 s43, s46, s18
	s_add_u32 s52, s18, 0x100
	v_mov_b32_e32 v4, 0
	s_addc_u32 s53, s19, 0
	s_mov_b32 s62, -2
	s_waitcnt lgkmcnt(0)
	v_mov_b32_e32 v5, v4
	v_mov_b32_e32 v6, v4
	v_mov_b32_e32 v7, v4
	v_mov_b32_e32 v8, v4
	v_mov_b32_e32 v9, v4
	v_mov_b32_e32 v10, v4
	v_mov_b32_e32 v11, v4
	v_mov_b32_e32 v20, v4
	v_mov_b32_e32 v21, v4
	v_mov_b32_e32 v22, v4
	v_mov_b32_e32 v23, v4
	v_mov_b32_e32 v24, v4
	v_mov_b32_e32 v25, v4
	v_mov_b32_e32 v26, v4
	v_mov_b32_e32 v27, v4
	v_mov_b32_e32 v36, v4
	v_mov_b32_e32 v37, v4
	v_mov_b32_e32 v38, v4
	v_mov_b32_e32 v39, v4
	v_mov_b32_e32 v40, v4
	v_mov_b32_e32 v41, v4
	v_mov_b32_e32 v42, v4
	v_mov_b32_e32 v43, v4
	v_mov_b32_e32 v52, v4
	v_mov_b32_e32 v53, v4
	v_mov_b32_e32 v54, v4
	v_mov_b32_e32 v55, v4
	v_mov_b32_e32 v56, v4
	v_mov_b32_e32 v57, v4
	v_mov_b32_e32 v58, v4
	v_mov_b32_e32 v59, v4
	v_mov_b32_e32 v12, v4
	v_mov_b32_e32 v13, v4
	v_mov_b32_e32 v14, v4
	v_mov_b32_e32 v15, v4
	v_mov_b32_e32 v16, v4
	v_mov_b32_e32 v17, v4
	v_mov_b32_e32 v18, v4
	v_mov_b32_e32 v19, v4
	v_mov_b32_e32 v28, v4
	v_mov_b32_e32 v29, v4
	v_mov_b32_e32 v30, v4
	v_mov_b32_e32 v31, v4
	v_mov_b32_e32 v32, v4
	v_mov_b32_e32 v33, v4
	v_mov_b32_e32 v34, v4
	v_mov_b32_e32 v35, v4
	v_mov_b32_e32 v44, v4
	v_mov_b32_e32 v45, v4
	v_mov_b32_e32 v46, v4
	v_mov_b32_e32 v47, v4
	v_mov_b32_e32 v48, v4
	v_mov_b32_e32 v49, v4
	v_mov_b32_e32 v50, v4
	v_mov_b32_e32 v51, v4
	v_mov_b32_e32 v60, v4
	v_mov_b32_e32 v61, v4
	v_mov_b32_e32 v62, v4
	v_mov_b32_e32 v63, v4
	v_mov_b32_e32 v64, v4
	v_mov_b32_e32 v65, v4
	v_mov_b32_e32 v66, v4
	v_mov_b32_e32 v67, v4
	v_mov_b32_e32 v68, v4
	v_mov_b32_e32 v69, v4
	v_mov_b32_e32 v70, v4
	v_mov_b32_e32 v71, v4
	v_mov_b32_e32 v72, v4
	v_mov_b32_e32 v73, v4
	v_mov_b32_e32 v74, v4
	v_mov_b32_e32 v75, v4
	v_mov_b32_e32 v84, v4
	v_mov_b32_e32 v85, v4
	v_mov_b32_e32 v86, v4
	v_mov_b32_e32 v87, v4
	v_mov_b32_e32 v88, v4
	v_mov_b32_e32 v89, v4
	v_mov_b32_e32 v90, v4
	v_mov_b32_e32 v91, v4
	v_mov_b32_e32 v100, v4
	v_mov_b32_e32 v101, v4
	v_mov_b32_e32 v102, v4
	v_mov_b32_e32 v103, v4
	v_mov_b32_e32 v104, v4
	v_mov_b32_e32 v105, v4
	v_mov_b32_e32 v106, v4
	v_mov_b32_e32 v107, v4
	v_mov_b32_e32 v116, v4
	v_mov_b32_e32 v117, v4
	v_mov_b32_e32 v118, v4
	v_mov_b32_e32 v119, v4
	v_mov_b32_e32 v120, v4
	v_mov_b32_e32 v121, v4
	v_mov_b32_e32 v122, v4
	v_mov_b32_e32 v123, v4
	v_mov_b32_e32 v76, v4
	v_mov_b32_e32 v77, v4
	v_mov_b32_e32 v78, v4
	v_mov_b32_e32 v79, v4
	v_mov_b32_e32 v80, v4
	v_mov_b32_e32 v81, v4
	v_mov_b32_e32 v82, v4
	v_mov_b32_e32 v83, v4
	v_mov_b32_e32 v92, v4
	v_mov_b32_e32 v93, v4
	v_mov_b32_e32 v94, v4
	v_mov_b32_e32 v95, v4
	v_mov_b32_e32 v96, v4
	v_mov_b32_e32 v97, v4
	v_mov_b32_e32 v98, v4
	v_mov_b32_e32 v99, v4
	v_mov_b32_e32 v108, v4
	v_mov_b32_e32 v109, v4
	v_mov_b32_e32 v110, v4
	v_mov_b32_e32 v111, v4
	v_mov_b32_e32 v112, v4
	v_mov_b32_e32 v113, v4
	v_mov_b32_e32 v114, v4
	v_mov_b32_e32 v115, v4
	v_mov_b32_e32 v124, v4
	v_mov_b32_e32 v125, v4
	v_mov_b32_e32 v126, v4
	v_mov_b32_e32 v127, v4
	v_mov_b32_e32 v128, v4
	v_mov_b32_e32 v129, v4
	v_mov_b32_e32 v130, v4
	v_mov_b32_e32 v131, v4
	v_add_u32_e32 v218, 0x10000, v1
.LBB0_505:
	s_add_u32 s18, s16, 0x100
	s_addc_u32 s19, s17, 0
	s_cmp_eq_u32 s62, 12
	s_cselect_b32 s50, s9, s18
	s_cselect_b32 s51, s1, s19
	s_cselect_b32 s20, s43, s52
	s_cselect_b32 s21, s41, s53
	s_add_u32 s48, s50, 0x80
	s_addc_u32 s49, s51, 0
	s_add_i32 s64, 0, 0x10000
	ds_read_b128 v[132:135], v218
	ds_read_b128 v[142:145], v218 offset:1024
	ds_read_b128 v[146:149], v218 offset:2048
	ds_read_b128 v[150:153], v218 offset:3072
	s_add_u32 s16, s16, 0x40080
	s_addc_u32 s17, s17, 0
	ds_read_b128 v[154:157], v3
	ds_read_b128 v[158:161], v3 offset:1024
	ds_read_b128 v[162:165], v3 offset:2048
	ds_read_b128 v[166:169], v3 offset:3072
	ds_read_b128 v[170:173], v3 offset:4096
	ds_read_b128 v[174:177], v3 offset:5120
	ds_read_b128 v[178:181], v3 offset:6144
	ds_read_b128 v[182:185], v3 offset:7168
	s_add_i32 m0, s74, 0xc000
	s_nop 0
	global_load_lds_dwordx4 v136, s[16:17]
	s_add_i32 m0, s74, 0xe000
	s_nop 0
	global_load_lds_dwordx4 v138, s[16:17]
	s_waitcnt lgkmcnt(8)
	s_barrier
	s_waitcnt lgkmcnt(0)
	s_setprio 1
	s_waitcnt lgkmcnt(0)
	v_mfma_f32_16x16x32_bf16 v[128:131], v[132:135], v[154:157], v[128:131]
	v_mfma_f32_16x16x32_bf16 v[124:127], v[146:149], v[154:157], v[124:127]
	v_mfma_f32_16x16x32_bf16 v[112:115], v[132:135], v[162:165], v[112:115]
	v_mfma_f32_16x16x32_bf16 v[108:111], v[146:149], v[162:165], v[108:111]
	v_mfma_f32_16x16x32_bf16 v[96:99], v[132:135], v[170:173], v[96:99]
	v_mfma_f32_16x16x32_bf16 v[92:95], v[146:149], v[170:173], v[92:95]
	v_mfma_f32_16x16x32_bf16 v[80:83], v[132:135], v[178:181], v[80:83]
	v_mfma_f32_16x16x32_bf16 v[76:79], v[146:149], v[178:181], v[76:79]
	v_mfma_f32_16x16x32_bf16 v[128:131], v[142:145], v[158:161], v[128:131]
	v_mfma_f32_16x16x32_bf16 v[124:127], v[150:153], v[158:161], v[124:127]
	v_mfma_f32_16x16x32_bf16 v[112:115], v[142:145], v[166:169], v[112:115]
	v_mfma_f32_16x16x32_bf16 v[108:111], v[150:153], v[166:169], v[108:111]
	v_mfma_f32_16x16x32_bf16 v[96:99], v[142:145], v[174:177], v[96:99]
	v_mfma_f32_16x16x32_bf16 v[92:95], v[150:153], v[174:177], v[92:95]
	v_mfma_f32_16x16x32_bf16 v[80:83], v[142:145], v[182:185], v[80:83]
	v_mfma_f32_16x16x32_bf16 v[76:79], v[150:153], v[182:185], v[76:79]
	s_setprio 0
	s_barrier
	s_add_i32 s65, 0, 0x14000
	s_mov_b64 s[16:17], s[20:21]
	s_add_i32 s64, s64, s73
	ds_read_b128 v[186:189], v218 offset:16384
	ds_read_b128 v[190:193], v218 offset:17408
	ds_read_b128 v[210:213], v218 offset:18432
	ds_read_b128 v[214:217], v218 offset:19456
	s_mov_b32 m0, s64
	s_nop 0
	global_load_lds_dwordx4 v136, s[16:17]
	s_add_i32 m0, s64, 0x2000
	s_nop 0
	global_load_lds_dwordx4 v138, s[16:17]
	s_barrier
	s_waitcnt lgkmcnt(0)
	s_setprio 1
	s_waitcnt lgkmcnt(0)
	v_mfma_f32_16x16x32_bf16 v[120:123], v[186:189], v[154:157], v[120:123]
	v_mfma_f32_16x16x32_bf16 v[116:119], v[210:213], v[154:157], v[116:119]
	v_mfma_f32_16x16x32_bf16 v[104:107], v[186:189], v[162:165], v[104:107]
	v_mfma_f32_16x16x32_bf16 v[100:103], v[210:213], v[162:165], v[100:103]
	v_mfma_f32_16x16x32_bf16 v[88:91], v[186:189], v[170:173], v[88:91]
	v_mfma_f32_16x16x32_bf16 v[84:87], v[210:213], v[170:173], v[84:87]
	v_mfma_f32_16x16x32_bf16 v[72:75], v[186:189], v[178:181], v[72:75]
	v_mfma_f32_16x16x32_bf16 v[68:71], v[210:213], v[178:181], v[68:71]
	v_mfma_f32_16x16x32_bf16 v[120:123], v[190:193], v[158:161], v[120:123]
	v_mfma_f32_16x16x32_bf16 v[116:119], v[214:217], v[158:161], v[116:119]
	v_mfma_f32_16x16x32_bf16 v[104:107], v[190:193], v[166:169], v[104:107]
	v_mfma_f32_16x16x32_bf16 v[100:103], v[214:217], v[166:169], v[100:103]
	v_mfma_f32_16x16x32_bf16 v[88:91], v[190:193], v[174:177], v[88:91]
	v_mfma_f32_16x16x32_bf16 v[84:87], v[214:217], v[174:177], v[84:87]
	v_mfma_f32_16x16x32_bf16 v[72:75], v[190:193], v[182:185], v[72:75]
	v_mfma_f32_16x16x32_bf16 v[68:71], v[214:217], v[182:185], v[68:71]
	s_setprio 0
	s_mov_b64 s[16:17], s[50:51]
	s_mov_b32 m0, s74
	s_barrier
	ds_read_b128 v[154:157], v3 offset:16384
	ds_read_b128 v[158:161], v3 offset:17408
	ds_read_b128 v[162:165], v3 offset:18432
	ds_read_b128 v[166:169], v3 offset:19456
	ds_read_b128 v[170:173], v3 offset:20480
	ds_read_b128 v[174:177], v3 offset:21504
	ds_read_b128 v[178:181], v3 offset:22528
	ds_read_b128 v[182:185], v3 offset:23552
	s_nop 0
	global_load_lds_dwordx4 v136, s[16:17]
	s_mov_b32 m0, s75
	s_nop 0
	global_load_lds_dwordx4 v138, s[16:17]
	s_barrier
	s_waitcnt lgkmcnt(0)
	s_setprio 1
	s_waitcnt lgkmcnt(0)
	v_mfma_f32_16x16x32_bf16 v[64:67], v[132:135], v[154:157], v[64:67]
	v_mfma_f32_16x16x32_bf16 v[60:63], v[146:149], v[154:157], v[60:63]
	v_mfma_f32_16x16x32_bf16 v[48:51], v[132:135], v[162:165], v[48:51]
	v_mfma_f32_16x16x32_bf16 v[44:47], v[146:149], v[162:165], v[44:47]
	v_mfma_f32_16x16x32_bf16 v[32:35], v[132:135], v[170:173], v[32:35]
	v_mfma_f32_16x16x32_bf16 v[28:31], v[146:149], v[170:173], v[28:31]
	v_mfma_f32_16x16x32_bf16 v[16:19], v[132:135], v[178:181], v[16:19]
	v_mfma_f32_16x16x32_bf16 v[12:15], v[146:149], v[178:181], v[12:15]
	v_mfma_f32_16x16x32_bf16 v[64:67], v[142:145], v[158:161], v[64:67]
	v_mfma_f32_16x16x32_bf16 v[60:63], v[150:153], v[158:161], v[60:63]
	v_mfma_f32_16x16x32_bf16 v[48:51], v[142:145], v[166:169], v[48:51]
	v_mfma_f32_16x16x32_bf16 v[44:47], v[150:153], v[166:169], v[44:47]
	v_mfma_f32_16x16x32_bf16 v[32:35], v[142:145], v[174:177], v[32:35]
	v_mfma_f32_16x16x32_bf16 v[28:31], v[150:153], v[174:177], v[28:31]
	v_mfma_f32_16x16x32_bf16 v[16:19], v[142:145], v[182:185], v[16:19]
	v_mfma_f32_16x16x32_bf16 v[12:15], v[150:153], v[182:185], v[12:15]
	s_setprio 0
	s_barrier
	s_add_u32 s16, s20, 0x40000
	s_addc_u32 s17, s21, 0
	s_add_i32 s64, s65, s73
	s_mov_b32 m0, s64
	s_nop 0
	global_load_lds_dwordx4 v136, s[16:17]
	s_add_i32 m0, s64, 0x2000
	s_nop 0
	global_load_lds_dwordx4 v138, s[16:17]
	s_waitcnt vmcnt(6)
	s_barrier
	s_setprio 1
	v_mfma_f32_16x16x32_bf16 v[56:59], v[186:189], v[154:157], v[56:59]
	v_mfma_f32_16x16x32_bf16 v[52:55], v[210:213], v[154:157], v[52:55]
	v_mfma_f32_16x16x32_bf16 v[40:43], v[186:189], v[162:165], v[40:43]
	v_mfma_f32_16x16x32_bf16 v[36:39], v[210:213], v[162:165], v[36:39]
	v_mfma_f32_16x16x32_bf16 v[24:27], v[186:189], v[170:173], v[24:27]
	v_mfma_f32_16x16x32_bf16 v[20:23], v[210:213], v[170:173], v[20:23]
	v_mfma_f32_16x16x32_bf16 v[8:11], v[186:189], v[178:181], v[8:11]
	v_mfma_f32_16x16x32_bf16 v[4:7], v[210:213], v[178:181], v[4:7]
	v_mfma_f32_16x16x32_bf16 v[56:59], v[190:193], v[158:161], v[56:59]
	v_mfma_f32_16x16x32_bf16 v[52:55], v[214:217], v[158:161], v[52:55]
	v_mfma_f32_16x16x32_bf16 v[40:43], v[190:193], v[166:169], v[40:43]
	v_mfma_f32_16x16x32_bf16 v[36:39], v[214:217], v[166:169], v[36:39]
	v_mfma_f32_16x16x32_bf16 v[24:27], v[190:193], v[174:177], v[24:27]
	v_mfma_f32_16x16x32_bf16 v[20:23], v[214:217], v[174:177], v[20:23]
	v_mfma_f32_16x16x32_bf16 v[8:11], v[190:193], v[182:185], v[8:11]
	v_mfma_f32_16x16x32_bf16 v[4:7], v[214:217], v[182:185], v[4:7]
	s_setprio 0
	s_add_i32 s64, 0, 0x18000
	s_barrier
	ds_read_b128 v[132:135], v218 offset:32768
	ds_read_b128 v[142:145], v218 offset:33792
	ds_read_b128 v[146:149], v218 offset:34816
	ds_read_b128 v[150:153], v218 offset:35840
	s_add_u32 s16, s50, 0x40000
	s_addc_u32 s17, s51, 0
	s_mov_b32 m0, s78
	ds_read_b128 v[154:157], v3 offset:32768
	ds_read_b128 v[158:161], v3 offset:33792
	ds_read_b128 v[162:165], v3 offset:34816
	ds_read_b128 v[166:169], v3 offset:35840
	ds_read_b128 v[170:173], v3 offset:36864
	ds_read_b128 v[174:177], v3 offset:37888
	ds_read_b128 v[178:181], v3 offset:38912
	ds_read_b128 v[182:185], v3 offset:39936
	s_nop 0
	global_load_lds_dwordx4 v136, s[16:17]
	s_mov_b32 m0, s79
	s_nop 0
	global_load_lds_dwordx4 v138, s[16:17]
	s_waitcnt lgkmcnt(8)
	s_barrier
	s_waitcnt lgkmcnt(0)
	s_setprio 1
	s_waitcnt lgkmcnt(0)
	v_mfma_f32_16x16x32_bf16 v[128:131], v[132:135], v[154:157], v[128:131]
	v_mfma_f32_16x16x32_bf16 v[124:127], v[146:149], v[154:157], v[124:127]
	v_mfma_f32_16x16x32_bf16 v[112:115], v[132:135], v[162:165], v[112:115]
	v_mfma_f32_16x16x32_bf16 v[108:111], v[146:149], v[162:165], v[108:111]
	v_mfma_f32_16x16x32_bf16 v[96:99], v[132:135], v[170:173], v[96:99]
	v_mfma_f32_16x16x32_bf16 v[92:95], v[146:149], v[170:173], v[92:95]
	v_mfma_f32_16x16x32_bf16 v[80:83], v[132:135], v[178:181], v[80:83]
	v_mfma_f32_16x16x32_bf16 v[76:79], v[146:149], v[178:181], v[76:79]
	v_mfma_f32_16x16x32_bf16 v[128:131], v[142:145], v[158:161], v[128:131]
	v_mfma_f32_16x16x32_bf16 v[124:127], v[150:153], v[158:161], v[124:127]
	v_mfma_f32_16x16x32_bf16 v[112:115], v[142:145], v[166:169], v[112:115]
	v_mfma_f32_16x16x32_bf16 v[108:111], v[150:153], v[166:169], v[108:111]
	v_mfma_f32_16x16x32_bf16 v[96:99], v[142:145], v[174:177], v[96:99]
	v_mfma_f32_16x16x32_bf16 v[92:95], v[150:153], v[174:177], v[92:95]
	v_mfma_f32_16x16x32_bf16 v[80:83], v[142:145], v[182:185], v[80:83]
	v_mfma_f32_16x16x32_bf16 v[76:79], v[150:153], v[182:185], v[76:79]
	s_setprio 0
	s_barrier
	s_add_i32 s50, 0, 0x1c000
	s_add_u32 s16, s20, 0x80
	s_addc_u32 s17, s21, 0
	s_add_i32 s51, s64, s73
	ds_read_b128 v[186:189], v218 offset:49152
	ds_read_b128 v[190:193], v218 offset:50176
	ds_read_b128 v[210:213], v218 offset:51200
	ds_read_b128 v[214:217], v218 offset:52224
	s_mov_b32 m0, s51
	s_nop 0
	global_load_lds_dwordx4 v136, s[16:17]
	s_add_i32 m0, s51, 0x2000
	s_nop 0
	global_load_lds_dwordx4 v138, s[16:17]
	s_barrier
	s_waitcnt lgkmcnt(0)
	s_setprio 1
	s_waitcnt lgkmcnt(0)
	v_mfma_f32_16x16x32_bf16 v[120:123], v[186:189], v[154:157], v[120:123]
	v_mfma_f32_16x16x32_bf16 v[116:119], v[210:213], v[154:157], v[116:119]
	v_mfma_f32_16x16x32_bf16 v[104:107], v[186:189], v[162:165], v[104:107]
	v_mfma_f32_16x16x32_bf16 v[100:103], v[210:213], v[162:165], v[100:103]
	v_mfma_f32_16x16x32_bf16 v[88:91], v[186:189], v[170:173], v[88:91]
	v_mfma_f32_16x16x32_bf16 v[84:87], v[210:213], v[170:173], v[84:87]
	v_mfma_f32_16x16x32_bf16 v[72:75], v[186:189], v[178:181], v[72:75]
	v_mfma_f32_16x16x32_bf16 v[68:71], v[210:213], v[178:181], v[68:71]
	v_mfma_f32_16x16x32_bf16 v[120:123], v[190:193], v[158:161], v[120:123]
	v_mfma_f32_16x16x32_bf16 v[116:119], v[214:217], v[158:161], v[116:119]
	v_mfma_f32_16x16x32_bf16 v[104:107], v[190:193], v[166:169], v[104:107]
	v_mfma_f32_16x16x32_bf16 v[100:103], v[214:217], v[166:169], v[100:103]
	v_mfma_f32_16x16x32_bf16 v[88:91], v[190:193], v[174:177], v[88:91]
	v_mfma_f32_16x16x32_bf16 v[84:87], v[214:217], v[174:177], v[84:87]
	v_mfma_f32_16x16x32_bf16 v[72:75], v[190:193], v[182:185], v[72:75]
	v_mfma_f32_16x16x32_bf16 v[68:71], v[214:217], v[182:185], v[68:71]
	s_setprio 0
	s_mov_b32 m0, s80
	s_barrier
	ds_read_b128 v[154:157], v3 offset:49152
	ds_read_b128 v[158:161], v3 offset:50176
	ds_read_b128 v[162:165], v3 offset:51200
	ds_read_b128 v[166:169], v3 offset:52224
	ds_read_b128 v[170:173], v3 offset:53248
	ds_read_b128 v[174:177], v3 offset:54272
	ds_read_b128 v[178:181], v3 offset:55296
	ds_read_b128 v[182:185], v3 offset:56320
	s_nop 0
	global_load_lds_dwordx4 v136, s[48:49]
	s_mov_b32 m0, s81
	s_nop 0
	global_load_lds_dwordx4 v138, s[48:49]
	s_barrier
	s_waitcnt lgkmcnt(0)
	s_setprio 1
	s_waitcnt lgkmcnt(0)
	v_mfma_f32_16x16x32_bf16 v[64:67], v[132:135], v[154:157], v[64:67]
	v_mfma_f32_16x16x32_bf16 v[60:63], v[146:149], v[154:157], v[60:63]
	v_mfma_f32_16x16x32_bf16 v[48:51], v[132:135], v[162:165], v[48:51]
	v_mfma_f32_16x16x32_bf16 v[44:47], v[146:149], v[162:165], v[44:47]
	v_mfma_f32_16x16x32_bf16 v[32:35], v[132:135], v[170:173], v[32:35]
	v_mfma_f32_16x16x32_bf16 v[28:31], v[146:149], v[170:173], v[28:31]
	v_mfma_f32_16x16x32_bf16 v[16:19], v[132:135], v[178:181], v[16:19]
	v_mfma_f32_16x16x32_bf16 v[12:15], v[146:149], v[178:181], v[12:15]
	v_mfma_f32_16x16x32_bf16 v[64:67], v[142:145], v[158:161], v[64:67]
	v_mfma_f32_16x16x32_bf16 v[60:63], v[150:153], v[158:161], v[60:63]
	v_mfma_f32_16x16x32_bf16 v[48:51], v[142:145], v[166:169], v[48:51]
	v_mfma_f32_16x16x32_bf16 v[44:47], v[150:153], v[166:169], v[44:47]
	v_mfma_f32_16x16x32_bf16 v[32:35], v[142:145], v[174:177], v[32:35]
	v_mfma_f32_16x16x32_bf16 v[28:31], v[150:153], v[174:177], v[28:31]
	v_mfma_f32_16x16x32_bf16 v[16:19], v[142:145], v[182:185], v[16:19]
	v_mfma_f32_16x16x32_bf16 v[12:15], v[150:153], v[182:185], v[12:15]
	s_setprio 0
	s_barrier
	s_add_u32 s16, s20, 0x40080
	s_addc_u32 s17, s21, 0
	s_add_i32 s20, s50, s73
	s_mov_b32 m0, s20
	s_nop 0
	global_load_lds_dwordx4 v136, s[16:17]
	s_add_i32 m0, s20, 0x2000
	s_nop 0
	global_load_lds_dwordx4 v138, s[16:17]
	s_waitcnt vmcnt(6)
	s_barrier
	s_setprio 1
	v_mfma_f32_16x16x32_bf16 v[56:59], v[186:189], v[154:157], v[56:59]
	v_mfma_f32_16x16x32_bf16 v[52:55], v[210:213], v[154:157], v[52:55]
	v_mfma_f32_16x16x32_bf16 v[40:43], v[186:189], v[162:165], v[40:43]
	v_mfma_f32_16x16x32_bf16 v[36:39], v[210:213], v[162:165], v[36:39]
	v_mfma_f32_16x16x32_bf16 v[24:27], v[186:189], v[170:173], v[24:27]
	v_mfma_f32_16x16x32_bf16 v[20:23], v[210:213], v[170:173], v[20:23]
	v_mfma_f32_16x16x32_bf16 v[8:11], v[186:189], v[178:181], v[8:11]
	v_mfma_f32_16x16x32_bf16 v[4:7], v[210:213], v[178:181], v[4:7]
	v_mfma_f32_16x16x32_bf16 v[56:59], v[190:193], v[158:161], v[56:59]
	v_mfma_f32_16x16x32_bf16 v[52:55], v[214:217], v[158:161], v[52:55]
	v_mfma_f32_16x16x32_bf16 v[40:43], v[190:193], v[166:169], v[40:43]
	v_mfma_f32_16x16x32_bf16 v[36:39], v[214:217], v[166:169], v[36:39]
	v_mfma_f32_16x16x32_bf16 v[24:27], v[190:193], v[174:177], v[24:27]
	v_mfma_f32_16x16x32_bf16 v[20:23], v[214:217], v[174:177], v[20:23]
	v_mfma_f32_16x16x32_bf16 v[8:11], v[190:193], v[182:185], v[8:11]
	v_mfma_f32_16x16x32_bf16 v[4:7], v[214:217], v[182:185], v[4:7]
	s_setprio 0
	s_add_i32 s62, s62, 2
	s_add_u32 s52, s52, 0x100
	s_addc_u32 s53, s53, 0
	s_cmp_gt_u32 s62, 13
	s_mov_b64 s[16:17], s[18:19]
	s_barrier
	s_cbranch_scc0 .LBB0_505
	v_mov_b32_e32 v132, v0
	s_lshl_b32 s16, s0, 2
	v_readfirstlane_b32 s1, v132
	s_bfe_u32 s9, s1, 0x20006
	s_ashr_i32 s1, s1, 2
	s_lshl_b32 s0, s8, 8
	s_andn2_b32 s1, s1, 63
	s_add_i32 s1, s1, s0
	v_and_or_b32 v142, v132, 15, s1
	v_ashrrev_i32_e32 v143, 31, v142
	v_bfe_u32 v134, v132, 4, 2
	v_lshl_add_u64 v[132:133], v[142:143], 2, s[24:25]
	global_load_dword v135, v[132:133], off
	global_load_dword v147, v[132:133], off offset:64
	global_load_dword v173, v[132:133], off offset:128
	global_load_dword v172, v[132:133], off offset:192
	global_load_dword v171, v[132:133], off offset:512
	global_load_dword v170, v[132:133], off offset:576
	global_load_dword v169, v[132:133], off offset:640
	global_load_dword v168, v[132:133], off offset:704
	s_or_b32 s17, s9, s16
	s_cmp_gt_i32 s17, 5
	s_cselect_b64 s[0:1], -1, 0
	s_cmp_gt_u32 s17, 9
	s_cselect_b64 s[8:9], -1, 0
	s_cmp_lg_u32 s17, 10
	s_cselect_b64 s[50:51], -1, 0
	s_cmp_gt_u32 s16, 11
	s_cselect_b64 s[48:49], -1, 0
	s_lshl_b32 s68, s17, 6
	s_add_i32 s16, s68, 0xfffffd00
	v_lshlrev_b32_e32 v157, 3, v134
	v_or_b32_e32 v144, s16, v157
	v_cmp_eq_u32_e64 s[16:17], 0, v134
	s_mov_b64 s[18:19], -1
	s_waitcnt vmcnt(0)
	v_fmamk_f32 v132, v135, 0x3a800000, v231
	v_cmp_gt_f32_e32 vcc, s11, v132
	v_mul_f32_e32 v133, 0x4b800000, v132
	s_nop 0
	v_cndmask_b32_e32 v132, v132, v133, vcc
	v_rsq_f32_e32 v132, v132
	s_nop 0
	v_mul_f32_e32 v133, 0x45800000, v132
	v_cndmask_b32_e32 v146, v132, v133, vcc
	s_and_b64 vcc, exec, s[0:1]
	s_cbranch_vccz .LBB0_519
	s_and_b64 vcc, exec, s[8:9]
	s_cbranch_vccz .LBB0_516
	s_and_b64 vcc, exec, s[50:51]
	s_cbranch_vccz .LBB0_512
	s_andn2_b64 vcc, exec, s[48:49]
	s_cbranch_vccnz .LBB0_511
	v_mov_b64_e32 v[148:149], s[38:39]
	s_movk_i32 s18, 0x480
	v_mad_i64_i32 v[148:149], s[18:19], v142, s18, v[148:149]
	v_mov_b32_e32 v145, v2
	v_pk_mul_f32 v[134:135], v[130:131], v[146:147] op_sel_hi:[1,0]
	v_pk_mul_f32 v[132:133], v[128:129], v[146:147] op_sel_hi:[1,0]
	v_lshl_add_u64 v[150:151], v[144:145], 2, v[148:149]
	global_store_dwordx4 v[150:151], v[132:135], off
	v_ashrrev_i32_e32 v145, 31, v144
	v_lshl_add_u64 v[148:149], v[144:145], 2, v[148:149]
	v_pk_mul_f32 v[134:135], v[126:127], v[146:147] op_sel_hi:[1,0]
	v_pk_mul_f32 v[132:133], v[124:125], v[146:147] op_sel_hi:[1,0]
	global_store_dwordx4 v[150:151], v[132:135], off offset:16
	s_nop 1
	v_pk_mul_f32 v[134:135], v[122:123], v[146:147] op_sel_hi:[1,0]
	v_pk_mul_f32 v[132:133], v[120:121], v[146:147] op_sel_hi:[1,0]
	global_store_dwordx4 v[148:149], v[132:135], off offset:128
	s_nop 1
	v_pk_mul_f32 v[134:135], v[118:119], v[146:147] op_sel_hi:[1,0]
	v_pk_mul_f32 v[132:133], v[116:117], v[146:147] op_sel_hi:[1,0]
	global_store_dwordx4 v[148:149], v[132:135], off offset:144

.LBB0_653:
	s_ashr_i32 s17, s16, 31
	s_lshl_b64 s[20:21], s[16:17], 17
	s_add_u32 s20, s48, s20
	s_addc_u32 s21, s49, s21
	s_and_b64 s[24:25], s[24:25], exec
	v_mov_b32_e32 v4, 0
	s_cselect_b32 s17, s21, s1
	s_cselect_b32 s23, s20, s0
	s_mov_b64 s[26:27], 0
	s_mov_b64 s[24:25], -1
	s_mov_b64 s[28:29], 0
	s_waitcnt lgkmcnt(0)
	v_mov_b32_e32 v5, v4
	v_mov_b32_e32 v6, v4
	v_mov_b32_e32 v7, v4
	v_mov_b32_e32 v8, v4
	v_mov_b32_e32 v9, v4
	v_mov_b32_e32 v10, v4
	v_mov_b32_e32 v11, v4
	v_mov_b32_e32 v20, v4
	v_mov_b32_e32 v21, v4
	v_mov_b32_e32 v22, v4
	v_mov_b32_e32 v23, v4
	v_mov_b32_e32 v24, v4
	v_mov_b32_e32 v25, v4
	v_mov_b32_e32 v26, v4
	v_mov_b32_e32 v27, v4
	v_mov_b32_e32 v36, v4
	v_mov_b32_e32 v37, v4
	v_mov_b32_e32 v38, v4
	v_mov_b32_e32 v39, v4
	v_mov_b32_e32 v40, v4
	v_mov_b32_e32 v41, v4
	v_mov_b32_e32 v42, v4
	v_mov_b32_e32 v43, v4
	v_mov_b32_e32 v52, v4
	v_mov_b32_e32 v53, v4
	v_mov_b32_e32 v54, v4
	v_mov_b32_e32 v55, v4
	v_mov_b32_e32 v56, v4
	v_mov_b32_e32 v57, v4
	v_mov_b32_e32 v58, v4
	v_mov_b32_e32 v59, v4
	v_mov_b32_e32 v12, v4
	v_mov_b32_e32 v13, v4
	v_mov_b32_e32 v14, v4
	v_mov_b32_e32 v15, v4
	v_mov_b32_e32 v16, v4
	v_mov_b32_e32 v17, v4
	v_mov_b32_e32 v18, v4
	v_mov_b32_e32 v19, v4
	v_mov_b32_e32 v28, v4
	v_mov_b32_e32 v29, v4
	v_mov_b32_e32 v30, v4
	v_mov_b32_e32 v31, v4
	v_mov_b32_e32 v32, v4
	v_mov_b32_e32 v33, v4
	v_mov_b32_e32 v34, v4
	v_mov_b32_e32 v35, v4
	v_mov_b32_e32 v44, v4
	v_mov_b32_e32 v45, v4
	v_mov_b32_e32 v46, v4
	v_mov_b32_e32 v47, v4
	v_mov_b32_e32 v48, v4
	v_mov_b32_e32 v49, v4
	v_mov_b32_e32 v50, v4
	v_mov_b32_e32 v51, v4
	v_mov_b32_e32 v60, v4
	v_mov_b32_e32 v61, v4
	v_mov_b32_e32 v62, v4
	v_mov_b32_e32 v63, v4
	v_mov_b32_e32 v64, v4
	v_mov_b32_e32 v65, v4
	v_mov_b32_e32 v66, v4
	v_mov_b32_e32 v67, v4
	v_mov_b32_e32 v68, v4
	v_mov_b32_e32 v69, v4
	v_mov_b32_e32 v70, v4
	v_mov_b32_e32 v71, v4
	v_mov_b32_e32 v72, v4
	v_mov_b32_e32 v73, v4
	v_mov_b32_e32 v74, v4
	v_mov_b32_e32 v75, v4
	v_mov_b32_e32 v84, v4
	v_mov_b32_e32 v85, v4
	v_mov_b32_e32 v86, v4
	v_mov_b32_e32 v87, v4
	v_mov_b32_e32 v88, v4
	v_mov_b32_e32 v89, v4
	v_mov_b32_e32 v90, v4
	v_mov_b32_e32 v91, v4
	v_mov_b32_e32 v100, v4
	v_mov_b32_e32 v101, v4
	v_mov_b32_e32 v102, v4
	v_mov_b32_e32 v103, v4
	v_mov_b32_e32 v104, v4
	v_mov_b32_e32 v105, v4
	v_mov_b32_e32 v106, v4
	v_mov_b32_e32 v107, v4
	v_mov_b32_e32 v116, v4
	v_mov_b32_e32 v117, v4
	v_mov_b32_e32 v118, v4
	v_mov_b32_e32 v119, v4
	v_mov_b32_e32 v120, v4
	v_mov_b32_e32 v121, v4
	v_mov_b32_e32 v122, v4
	v_mov_b32_e32 v123, v4
	v_mov_b32_e32 v76, v4
	v_mov_b32_e32 v77, v4
	v_mov_b32_e32 v78, v4
	v_mov_b32_e32 v79, v4
	v_mov_b32_e32 v80, v4
	v_mov_b32_e32 v81, v4
	v_mov_b32_e32 v82, v4
	v_mov_b32_e32 v83, v4
	v_mov_b32_e32 v92, v4
	v_mov_b32_e32 v93, v4
	v_mov_b32_e32 v94, v4
	v_mov_b32_e32 v95, v4
	v_mov_b32_e32 v96, v4
	v_mov_b32_e32 v97, v4
	v_mov_b32_e32 v98, v4
	v_mov_b32_e32 v99, v4
	v_mov_b32_e32 v108, v4
	v_mov_b32_e32 v109, v4
	v_mov_b32_e32 v110, v4
	v_mov_b32_e32 v111, v4
	v_mov_b32_e32 v112, v4
	v_mov_b32_e32 v113, v4
	v_mov_b32_e32 v114, v4
	v_mov_b32_e32 v115, v4
	v_mov_b32_e32 v124, v4
	v_mov_b32_e32 v125, v4
	v_mov_b32_e32 v126, v4
	v_mov_b32_e32 v127, v4
	v_mov_b32_e32 v128, v4
	v_mov_b32_e32 v129, v4
	v_mov_b32_e32 v130, v4
	v_mov_b32_e32 v131, v4
	v_add_u32_e32 v218, 0x10000, v1
	s_waitcnt vmcnt(0)
.LBB0_654:
	s_add_u32 s36, s14, s26
	s_addc_u32 s37, s15, s27
	s_add_u32 s38, s36, 0x100
	s_addc_u32 s39, s37, 0
	s_and_b64 s[30:31], s[28:29], exec
	s_cselect_b32 s41, s19, s39
	s_cselect_b32 s40, s18, s38
	s_add_u32 s26, s0, s26
	s_addc_u32 s27, s1, s27
	s_add_u32 s30, s26, 0x100
	s_addc_u32 s31, s27, 0
	s_add_u32 s26, s40, 0x80
	s_addc_u32 s27, s41, 0
	s_add_i32 s81, 0, 0x10000
	s_and_b64 s[28:29], s[28:29], exec
	s_cselect_b32 s43, s17, s31
	s_cselect_b32 s42, s23, s30
	s_add_u32 s44, s36, 0x12080
	s_addc_u32 s45, s37, 0
	s_add_i32 s86, s81, s51
	s_add_i32 m0, s52, 0xc000
	s_add_i32 s87, s52, 0xe000
	s_add_i32 s85, 0, 0x14000
	s_add_i32 s84, s86, 0x2000
	s_add_u32 s38, s42, 0x10000
	s_addc_u32 s39, s43, 0
	s_add_i32 s82, s85, s51
	s_add_i32 s80, s82, 0x2000
	s_add_i32 s79, 0, 0x18000
	s_add_u32 s36, s40, 0x12000
	ds_read_b128 v[140:143], v218
	ds_read_b128 v[144:147], v218 offset:1024
	ds_read_b128 v[148:151], v218 offset:2048
	ds_read_b128 v[152:155], v218 offset:3072
	s_addc_u32 s37, s41, 0
	s_add_i32 s75, 0, 0x1c000
	s_add_u32 s30, s42, 0x80
	s_addc_u32 s31, s43, 0
	s_add_i32 s78, s79, s51
	s_add_i32 s74, s78, 0x2000
	s_add_u32 s28, s42, 0x10080
	s_addc_u32 s29, s43, 0
	s_add_i32 s83, s75, s51
	s_add_i32 s81, s83, 0x2000
	ds_read_b128 v[156:159], v3
	ds_read_b128 v[160:163], v3 offset:1024
	ds_read_b128 v[164:167], v3 offset:2048
	ds_read_b128 v[168:171], v3 offset:3072
	ds_read_b128 v[172:175], v3 offset:4096
	ds_read_b128 v[176:179], v3 offset:5120
	ds_read_b128 v[180:183], v3 offset:6144
	ds_read_b128 v[184:187], v3 offset:7168
	s_nop 0
	global_load_lds_dwordx4 v132, s[44:45]
	s_mov_b32 m0, s87
	s_nop 0
	global_load_lds_dwordx4 v136, s[44:45]
	s_waitcnt lgkmcnt(8)
	s_barrier
	s_waitcnt lgkmcnt(0)
	s_setprio 1
	s_waitcnt lgkmcnt(0)
	v_mfma_f32_16x16x32_bf16 v[128:131], v[140:143], v[156:159], v[128:131]
	v_mfma_f32_16x16x32_bf16 v[124:127], v[148:151], v[156:159], v[124:127]
	v_mfma_f32_16x16x32_bf16 v[112:115], v[140:143], v[164:167], v[112:115]
	v_mfma_f32_16x16x32_bf16 v[108:111], v[148:151], v[164:167], v[108:111]
	v_mfma_f32_16x16x32_bf16 v[96:99], v[140:143], v[172:175], v[96:99]
	v_mfma_f32_16x16x32_bf16 v[92:95], v[148:151], v[172:175], v[92:95]
	v_mfma_f32_16x16x32_bf16 v[80:83], v[140:143], v[180:183], v[80:83]
	v_mfma_f32_16x16x32_bf16 v[76:79], v[148:151], v[180:183], v[76:79]
	v_mfma_f32_16x16x32_bf16 v[128:131], v[144:147], v[160:163], v[128:131]
	v_mfma_f32_16x16x32_bf16 v[124:127], v[152:155], v[160:163], v[124:127]
	v_mfma_f32_16x16x32_bf16 v[112:115], v[144:147], v[168:171], v[112:115]
	v_mfma_f32_16x16x32_bf16 v[108:111], v[152:155], v[168:171], v[108:111]
	v_mfma_f32_16x16x32_bf16 v[96:99], v[144:147], v[176:179], v[96:99]
	v_mfma_f32_16x16x32_bf16 v[92:95], v[152:155], v[176:179], v[92:95]
	v_mfma_f32_16x16x32_bf16 v[80:83], v[144:147], v[184:187], v[80:83]
	v_mfma_f32_16x16x32_bf16 v[76:79], v[152:155], v[184:187], v[76:79]
	s_setprio 0
	s_barrier
	s_mov_b32 m0, s86
	ds_read_b128 v[188:191], v218 offset:16384
	ds_read_b128 v[192:195], v218 offset:17408
	ds_read_b128 v[210:213], v218 offset:18432
	ds_read_b128 v[214:217], v218 offset:19456
	s_nop 0
	global_load_lds_dwordx4 v134, s[42:43]
	s_mov_b32 m0, s84
	s_nop 0
	global_load_lds_dwordx4 v138, s[42:43]
	s_barrier
	s_waitcnt lgkmcnt(0)
	s_setprio 1
	s_waitcnt lgkmcnt(0)
	v_mfma_f32_16x16x32_bf16 v[120:123], v[188:191], v[156:159], v[120:123]
	v_mfma_f32_16x16x32_bf16 v[116:119], v[210:213], v[156:159], v[116:119]
	v_mfma_f32_16x16x32_bf16 v[104:107], v[188:191], v[164:167], v[104:107]
	v_mfma_f32_16x16x32_bf16 v[100:103], v[210:213], v[164:167], v[100:103]
	v_mfma_f32_16x16x32_bf16 v[88:91], v[188:191], v[172:175], v[88:91]
	v_mfma_f32_16x16x32_bf16 v[84:87], v[210:213], v[172:175], v[84:87]
	v_mfma_f32_16x16x32_bf16 v[72:75], v[188:191], v[180:183], v[72:75]
	v_mfma_f32_16x16x32_bf16 v[68:71], v[210:213], v[180:183], v[68:71]
	v_mfma_f32_16x16x32_bf16 v[120:123], v[192:195], v[160:163], v[120:123]
	v_mfma_f32_16x16x32_bf16 v[116:119], v[214:217], v[160:163], v[116:119]
	v_mfma_f32_16x16x32_bf16 v[104:107], v[192:195], v[168:171], v[104:107]
	v_mfma_f32_16x16x32_bf16 v[100:103], v[214:217], v[168:171], v[100:103]
	v_mfma_f32_16x16x32_bf16 v[88:91], v[192:195], v[176:179], v[88:91]
	v_mfma_f32_16x16x32_bf16 v[84:87], v[214:217], v[176:179], v[84:87]
	v_mfma_f32_16x16x32_bf16 v[72:75], v[192:195], v[184:187], v[72:75]
	v_mfma_f32_16x16x32_bf16 v[68:71], v[214:217], v[184:187], v[68:71]
	s_setprio 0
	s_mov_b32 m0, s52
	s_barrier
	ds_read_b128 v[156:159], v3 offset:16384
	ds_read_b128 v[160:163], v3 offset:17408
	ds_read_b128 v[164:167], v3 offset:18432
	ds_read_b128 v[168:171], v3 offset:19456
	ds_read_b128 v[172:175], v3 offset:20480
	ds_read_b128 v[176:179], v3 offset:21504
	ds_read_b128 v[180:183], v3 offset:22528
	ds_read_b128 v[184:187], v3 offset:23552
	s_nop 0
	global_load_lds_dwordx4 v132, s[40:41]
	s_mov_b32 m0, s53
	s_nop 0
	global_load_lds_dwordx4 v136, s[40:41]
	s_barrier
	s_waitcnt lgkmcnt(0)
	s_setprio 1
	s_waitcnt lgkmcnt(0)
	v_mfma_f32_16x16x32_bf16 v[64:67], v[140:143], v[156:159], v[64:67]
	v_mfma_f32_16x16x32_bf16 v[60:63], v[148:151], v[156:159], v[60:63]
	v_mfma_f32_16x16x32_bf16 v[48:51], v[140:143], v[164:167], v[48:51]
	v_mfma_f32_16x16x32_bf16 v[44:47], v[148:151], v[164:167], v[44:47]
	v_mfma_f32_16x16x32_bf16 v[32:35], v[140:143], v[172:175], v[32:35]
	v_mfma_f32_16x16x32_bf16 v[28:31], v[148:151], v[172:175], v[28:31]
	v_mfma_f32_16x16x32_bf16 v[16:19], v[140:143], v[180:183], v[16:19]
	v_mfma_f32_16x16x32_bf16 v[12:15], v[148:151], v[180:183], v[12:15]
	v_mfma_f32_16x16x32_bf16 v[64:67], v[144:147], v[160:163], v[64:67]
	v_mfma_f32_16x16x32_bf16 v[60:63], v[152:155], v[160:163], v[60:63]
	v_mfma_f32_16x16x32_bf16 v[48:51], v[144:147], v[168:171], v[48:51]
	v_mfma_f32_16x16x32_bf16 v[44:47], v[152:155], v[168:171], v[44:47]
	v_mfma_f32_16x16x32_bf16 v[32:35], v[144:147], v[176:179], v[32:35]
	v_mfma_f32_16x16x32_bf16 v[28:31], v[152:155], v[176:179], v[28:31]
	v_mfma_f32_16x16x32_bf16 v[16:19], v[144:147], v[184:187], v[16:19]
	v_mfma_f32_16x16x32_bf16 v[12:15], v[152:155], v[184:187], v[12:15]
	s_setprio 0
	s_barrier
	s_mov_b32 m0, s82
	s_nop 0
	global_load_lds_dwordx4 v134, s[38:39]
	s_mov_b32 m0, s80
	s_nop 0
	global_load_lds_dwordx4 v138, s[38:39]
	s_waitcnt vmcnt(6)
	s_barrier
	s_setprio 1
	v_mfma_f32_16x16x32_bf16 v[56:59], v[188:191], v[156:159], v[56:59]
	v_mfma_f32_16x16x32_bf16 v[52:55], v[210:213], v[156:159], v[52:55]
	v_mfma_f32_16x16x32_bf16 v[40:43], v[188:191], v[164:167], v[40:43]
	v_mfma_f32_16x16x32_bf16 v[36:39], v[210:213], v[164:167], v[36:39]
	v_mfma_f32_16x16x32_bf16 v[24:27], v[188:191], v[172:175], v[24:27]
	v_mfma_f32_16x16x32_bf16 v[20:23], v[210:213], v[172:175], v[20:23]
	v_mfma_f32_16x16x32_bf16 v[8:11], v[188:191], v[180:183], v[8:11]
	v_mfma_f32_16x16x32_bf16 v[4:7], v[210:213], v[180:183], v[4:7]
	v_mfma_f32_16x16x32_bf16 v[56:59], v[192:195], v[160:163], v[56:59]
	v_mfma_f32_16x16x32_bf16 v[52:55], v[214:217], v[160:163], v[52:55]
	v_mfma_f32_16x16x32_bf16 v[40:43], v[192:195], v[168:171], v[40:43]
	v_mfma_f32_16x16x32_bf16 v[36:39], v[214:217], v[168:171], v[36:39]
	v_mfma_f32_16x16x32_bf16 v[24:27], v[192:195], v[176:179], v[24:27]
	v_mfma_f32_16x16x32_bf16 v[20:23], v[214:217], v[176:179], v[20:23]
	v_mfma_f32_16x16x32_bf16 v[8:11], v[192:195], v[184:187], v[8:11]
	v_mfma_f32_16x16x32_bf16 v[4:7], v[214:217], v[184:187], v[4:7]
	s_setprio 0
	s_barrier
	ds_read_b128 v[140:143], v218 offset:32768
	ds_read_b128 v[144:147], v218 offset:33792
	ds_read_b128 v[148:151], v218 offset:34816
	ds_read_b128 v[152:155], v218 offset:35840
	s_mov_b32 m0, s55
	ds_read_b128 v[156:159], v3 offset:32768
	ds_read_b128 v[160:163], v3 offset:33792
	ds_read_b128 v[164:167], v3 offset:34816
	ds_read_b128 v[168:171], v3 offset:35840
	ds_read_b128 v[172:175], v3 offset:36864
	ds_read_b128 v[176:179], v3 offset:37888
	ds_read_b128 v[180:183], v3 offset:38912
	ds_read_b128 v[184:187], v3 offset:39936
	s_nop 0
	global_load_lds_dwordx4 v132, s[36:37]
	s_mov_b32 m0, s56
	s_nop 0
	global_load_lds_dwordx4 v136, s[36:37]
	s_waitcnt lgkmcnt(8)
	s_barrier
	s_waitcnt lgkmcnt(0)
	s_setprio 1
	s_waitcnt lgkmcnt(0)
	v_mfma_f32_16x16x32_bf16 v[128:131], v[140:143], v[156:159], v[128:131]
	v_mfma_f32_16x16x32_bf16 v[124:127], v[148:151], v[156:159], v[124:127]
	v_mfma_f32_16x16x32_bf16 v[112:115], v[140:143], v[164:167], v[112:115]
	v_mfma_f32_16x16x32_bf16 v[108:111], v[148:151], v[164:167], v[108:111]
	v_mfma_f32_16x16x32_bf16 v[96:99], v[140:143], v[172:175], v[96:99]
	v_mfma_f32_16x16x32_bf16 v[92:95], v[148:151], v[172:175], v[92:95]
	v_mfma_f32_16x16x32_bf16 v[80:83], v[140:143], v[180:183], v[80:83]
	v_mfma_f32_16x16x32_bf16 v[76:79], v[148:151], v[180:183], v[76:79]
	v_mfma_f32_16x16x32_bf16 v[128:131], v[144:147], v[160:163], v[128:131]
	v_mfma_f32_16x16x32_bf16 v[124:127], v[152:155], v[160:163], v[124:127]
	v_mfma_f32_16x16x32_bf16 v[112:115], v[144:147], v[168:171], v[112:115]
	v_mfma_f32_16x16x32_bf16 v[108:111], v[152:155], v[168:171], v[108:111]
	v_mfma_f32_16x16x32_bf16 v[96:99], v[144:147], v[176:179], v[96:99]
	v_mfma_f32_16x16x32_bf16 v[92:95], v[152:155], v[176:179], v[92:95]
	v_mfma_f32_16x16x32_bf16 v[80:83], v[144:147], v[184:187], v[80:83]
	v_mfma_f32_16x16x32_bf16 v[76:79], v[152:155], v[184:187], v[76:79]
	s_setprio 0
	s_barrier
	s_mov_b32 m0, s78
	ds_read_b128 v[188:191], v218 offset:49152
	ds_read_b128 v[192:195], v218 offset:50176
	ds_read_b128 v[210:213], v218 offset:51200
	ds_read_b128 v[214:217], v218 offset:52224
	s_nop 0
	global_load_lds_dwordx4 v134, s[30:31]
	s_mov_b32 m0, s74
	s_nop 0
	global_load_lds_dwordx4 v138, s[30:31]
	s_barrier
	s_waitcnt lgkmcnt(0)
	s_setprio 1
	s_waitcnt lgkmcnt(0)
	v_mfma_f32_16x16x32_bf16 v[120:123], v[188:191], v[156:159], v[120:123]
	v_mfma_f32_16x16x32_bf16 v[116:119], v[210:213], v[156:159], v[116:119]
	v_mfma_f32_16x16x32_bf16 v[104:107], v[188:191], v[164:167], v[104:107]
	v_mfma_f32_16x16x32_bf16 v[100:103], v[210:213], v[164:167], v[100:103]
	v_mfma_f32_16x16x32_bf16 v[88:91], v[188:191], v[172:175], v[88:91]
	v_mfma_f32_16x16x32_bf16 v[84:87], v[210:213], v[172:175], v[84:87]
	v_mfma_f32_16x16x32_bf16 v[72:75], v[188:191], v[180:183], v[72:75]
	v_mfma_f32_16x16x32_bf16 v[68:71], v[210:213], v[180:183], v[68:71]
	v_mfma_f32_16x16x32_bf16 v[120:123], v[192:195], v[160:163], v[120:123]
	v_mfma_f32_16x16x32_bf16 v[116:119], v[214:217], v[160:163], v[116:119]
	v_mfma_f32_16x16x32_bf16 v[104:107], v[192:195], v[168:171], v[104:107]
	v_mfma_f32_16x16x32_bf16 v[100:103], v[214:217], v[168:171], v[100:103]
	v_mfma_f32_16x16x32_bf16 v[88:91], v[192:195], v[176:179], v[88:91]
	v_mfma_f32_16x16x32_bf16 v[84:87], v[214:217], v[176:179], v[84:87]
	v_mfma_f32_16x16x32_bf16 v[72:75], v[192:195], v[184:187], v[72:75]
	v_mfma_f32_16x16x32_bf16 v[68:71], v[214:217], v[184:187], v[68:71]
	s_setprio 0
	s_mov_b32 m0, s65
	s_barrier
	ds_read_b128 v[156:159], v3 offset:49152
	ds_read_b128 v[160:163], v3 offset:50176
	ds_read_b128 v[164:167], v3 offset:51200
	ds_read_b128 v[168:171], v3 offset:52224
	ds_read_b128 v[172:175], v3 offset:53248
	ds_read_b128 v[176:179], v3 offset:54272
	ds_read_b128 v[180:183], v3 offset:55296
	ds_read_b128 v[184:187], v3 offset:56320
	s_nop 0
	global_load_lds_dwordx4 v132, s[26:27]
	s_mov_b32 m0, s67
	s_nop 0
	global_load_lds_dwordx4 v136, s[26:27]
	s_barrier
	s_waitcnt lgkmcnt(0)
	s_setprio 1
	s_waitcnt lgkmcnt(0)
	v_mfma_f32_16x16x32_bf16 v[64:67], v[140:143], v[156:159], v[64:67]
	v_mfma_f32_16x16x32_bf16 v[60:63], v[148:151], v[156:159], v[60:63]
	v_mfma_f32_16x16x32_bf16 v[48:51], v[140:143], v[164:167], v[48:51]
	v_mfma_f32_16x16x32_bf16 v[44:47], v[148:151], v[164:167], v[44:47]
	v_mfma_f32_16x16x32_bf16 v[32:35], v[140:143], v[172:175], v[32:35]
	v_mfma_f32_16x16x32_bf16 v[28:31], v[148:151], v[172:175], v[28:31]
	v_mfma_f32_16x16x32_bf16 v[16:19], v[140:143], v[180:183], v[16:19]
	v_mfma_f32_16x16x32_bf16 v[12:15], v[148:151], v[180:183], v[12:15]
	v_mfma_f32_16x16x32_bf16 v[64:67], v[144:147], v[160:163], v[64:67]
	v_mfma_f32_16x16x32_bf16 v[60:63], v[152:155], v[160:163], v[60:63]
	v_mfma_f32_16x16x32_bf16 v[48:51], v[144:147], v[168:171], v[48:51]
	v_mfma_f32_16x16x32_bf16 v[44:47], v[152:155], v[168:171], v[44:47]
	v_mfma_f32_16x16x32_bf16 v[32:35], v[144:147], v[176:179], v[32:35]
	v_mfma_f32_16x16x32_bf16 v[28:31], v[152:155], v[176:179], v[28:31]
	v_mfma_f32_16x16x32_bf16 v[16:19], v[144:147], v[184:187], v[16:19]
	v_mfma_f32_16x16x32_bf16 v[12:15], v[152:155], v[184:187], v[12:15]
	s_setprio 0
	s_barrier
	s_mov_b32 m0, s83
	s_nop 0
	global_load_lds_dwordx4 v134, s[28:29]
	s_mov_b32 m0, s81
	s_nop 0
	global_load_lds_dwordx4 v138, s[28:29]
	s_waitcnt vmcnt(6)
	s_barrier
	s_setprio 1
	v_mfma_f32_16x16x32_bf16 v[56:59], v[188:191], v[156:159], v[56:59]
	v_mfma_f32_16x16x32_bf16 v[52:55], v[210:213], v[156:159], v[52:55]
	v_mfma_f32_16x16x32_bf16 v[40:43], v[188:191], v[164:167], v[40:43]
	v_mfma_f32_16x16x32_bf16 v[36:39], v[210:213], v[164:167], v[36:39]
	v_mfma_f32_16x16x32_bf16 v[24:27], v[188:191], v[172:175], v[24:27]
	v_mfma_f32_16x16x32_bf16 v[20:23], v[210:213], v[172:175], v[20:23]
	v_mfma_f32_16x16x32_bf16 v[8:11], v[188:191], v[180:183], v[8:11]
	v_mfma_f32_16x16x32_bf16 v[4:7], v[210:213], v[180:183], v[4:7]
	v_mfma_f32_16x16x32_bf16 v[56:59], v[192:195], v[160:163], v[56:59]
	v_mfma_f32_16x16x32_bf16 v[52:55], v[214:217], v[160:163], v[52:55]
	v_mfma_f32_16x16x32_bf16 v[40:43], v[192:195], v[168:171], v[40:43]
	v_mfma_f32_16x16x32_bf16 v[36:39], v[214:217], v[168:171], v[36:39]
	v_mfma_f32_16x16x32_bf16 v[24:27], v[192:195], v[176:179], v[24:27]
	v_mfma_f32_16x16x32_bf16 v[20:23], v[214:217], v[176:179], v[20:23]
	v_mfma_f32_16x16x32_bf16 v[8:11], v[192:195], v[184:187], v[8:11]
	v_mfma_f32_16x16x32_bf16 v[4:7], v[214:217], v[184:187], v[4:7]
	s_setprio 0
	s_andn2_b64 vcc, exec, s[24:25]
	s_mov_b64 s[28:29], -1
	s_mov_b64 s[24:25], 0
	s_mov_b64 s[26:27], 0x100
	s_barrier
	s_cbranch_vccz .LBB0_654
	v_mov_b32_e32 v141, v0
	s_ashr_i32 s23, s22, 31
	v_readfirstlane_b32 s0, v141
	s_bfe_u32 s17, s0, 0x20006
	s_ashr_i32 s0, s0, 2
	s_andn2_b32 s0, s0, 63
	s_ashr_i32 s1, s0, 31
	s_lshl_b64 s[14:15], s[22:23], 10
	s_add_u32 s24, s57, s14
	s_addc_u32 s25, s62, s15
	s_lshl_b64 s[14:15], s[0:1], 2
	v_and_b32_e32 v142, 15, v141
	s_add_u32 s24, s24, s14
	s_addc_u32 s25, s25, s15
	v_lshlrev_b32_e32 v140, 2, v142
	global_load_dword v150, v140, s[24:25] offset:64
	global_load_dword v149, v140, s[24:25] offset:128
	global_load_dword v148, v140, s[24:25] offset:192
	global_load_dword v147, v140, s[24:25] offset:512
	global_load_dword v146, v140, s[24:25] offset:576
	global_load_dword v145, v140, s[24:25] offset:640
	global_load_dword v144, v140, s[24:25] offset:704
	v_mul_f32_e32 v129, v129, v129
	v_mul_f32_e32 v125, v125, v125
	v_mul_f32_e32 v121, v121, v121
	v_mul_f32_e32 v117, v117, v117
	v_fmac_f32_e32 v129, v128, v128
	v_mul_f32_e32 v128, v131, v131
	v_fmac_f32_e32 v125, v124, v124
	v_mul_f32_e32 v124, v127, v127
	v_fmac_f32_e32 v121, v120, v120
	v_mul_f32_e32 v120, v123, v123
	v_fmac_f32_e32 v117, v116, v116
	v_mul_f32_e32 v116, v119, v119
	v_fmac_f32_e32 v128, v130, v130
	v_fmac_f32_e32 v124, v126, v126
	v_fmac_f32_e32 v120, v122, v122
	v_fmac_f32_e32 v116, v118, v118
	v_add_f32_e32 v128, v129, v128
	v_add_f32_e32 v124, v125, v124
	v_add_f32_e32 v120, v121, v120
	v_add_f32_e32 v116, v117, v116
	v_add_f32_e32 v124, v128, v124
	v_add_f32_e32 v116, v120, v116
	v_add_f32_e32 v117, v124, v116
	ds_swizzle_b32 v118, v117 offset:swizzle(SWAP,16)
	v_and_b32_e32 v152, 64, v236
	v_xor_b32_e32 v151, 32, v236
	v_add_u32_e32 v152, 64, v152
	v_cmp_lt_i32_e32 vcc, v151, v152
	s_lshl_b32 s14, s73, 2
	s_or_b32 s26, s17, s14
	v_cndmask_b32_e32 v116, v236, v151, vcc
	s_lshl_b64 s[14:15], s[22:23], 8
	v_lshlrev_b32_e32 v116, 2, v116
	s_waitcnt lgkmcnt(0)
	v_add_f32_e32 v117, v117, v118
	s_add_u32 s0, s14, s0
	ds_bpermute_b32 v118, v116, v117
	s_addc_u32 s1, s15, s1
	s_ashr_i32 s27, s26, 31
	v_or_b32_e32 v143, s0, v142
	v_mov_b32_e32 v142, s1
	s_lshl_b64 s[0:1], s[26:27], 2
	v_and_b32_e32 v119, 48, v141
	s_add_u32 s0, s63, s0
	v_cmp_eq_u32_e64 s[14:15], 0, v119
	s_addc_u32 s1, s64, s1
	s_and_saveexec_b64 s[22:23], s[14:15]
	s_cbranch_execz .LBB0_657
	v_mov_b32_e32 v141, v2
	v_lshl_add_u64 v[120:121], s[24:25], 0, v[140:141]
	global_load_dword v119, v[120:121], off
	s_waitcnt lgkmcnt(0)
	v_add_f32_e32 v117, v117, v118
	s_waitcnt vmcnt(0)
	v_add_f32_e32 v117, v117, v119
	v_fmamk_f32 v117, v117, 0x3c2aaaab, v231
	v_cmp_gt_f32_e32 vcc, s11, v117
	v_mul_f32_e32 v118, 0x4b800000, v117
	s_nop 0
	v_cndmask_b32_e32 v117, v117, v118, vcc
	v_rsq_f32_e32 v117, v117
	s_nop 0
	v_mul_f32_e32 v118, 0x45800000, v117
	v_cndmask_b32_e32 v117, v117, v118, vcc
	v_mad_u64_u32 v[118:119], s[24:25], v143, 48, s[0:1]
	v_mov_b32_e32 v120, v119
	v_mad_u64_u32 v[120:121], s[24:25], v142, 48, v[120:121]
	v_mov_b32_e32 v119, v120
	global_store_dword v[118:119], v117, off

.LBB0_768:
	s_add_u32 s47, s22, 0x100
	v_mov_b32_e32 v4, 0
	s_addc_u32 s49, s23, 0
	s_mov_b32 s62, -2
	v_mov_b32_e32 v5, v4
	v_mov_b32_e32 v6, v4
	v_mov_b32_e32 v7, v4
	v_mov_b32_e32 v8, v4
	v_mov_b32_e32 v9, v4
	v_mov_b32_e32 v10, v4
	v_mov_b32_e32 v11, v4
	v_mov_b32_e32 v20, v4
	v_mov_b32_e32 v21, v4
	v_mov_b32_e32 v22, v4
	v_mov_b32_e32 v23, v4
	v_mov_b32_e32 v24, v4
	v_mov_b32_e32 v25, v4
	v_mov_b32_e32 v26, v4
	v_mov_b32_e32 v27, v4
	v_mov_b32_e32 v36, v4
	v_mov_b32_e32 v37, v4
	v_mov_b32_e32 v38, v4
	v_mov_b32_e32 v39, v4
	v_mov_b32_e32 v40, v4
	v_mov_b32_e32 v41, v4
	v_mov_b32_e32 v42, v4
	v_mov_b32_e32 v43, v4
	v_mov_b32_e32 v52, v4
	v_mov_b32_e32 v53, v4
	v_mov_b32_e32 v54, v4
	v_mov_b32_e32 v55, v4
	v_mov_b32_e32 v56, v4
	v_mov_b32_e32 v57, v4
	v_mov_b32_e32 v58, v4
	v_mov_b32_e32 v59, v4
	v_mov_b32_e32 v12, v4
	v_mov_b32_e32 v13, v4
	v_mov_b32_e32 v14, v4
	v_mov_b32_e32 v15, v4
	v_mov_b32_e32 v16, v4
	v_mov_b32_e32 v17, v4
	v_mov_b32_e32 v18, v4
	v_mov_b32_e32 v19, v4
	v_mov_b32_e32 v28, v4
	v_mov_b32_e32 v29, v4
	v_mov_b32_e32 v30, v4
	v_mov_b32_e32 v31, v4
	v_mov_b32_e32 v32, v4
	v_mov_b32_e32 v33, v4
	v_mov_b32_e32 v34, v4
	v_mov_b32_e32 v35, v4
	v_mov_b32_e32 v44, v4
	v_mov_b32_e32 v45, v4
	v_mov_b32_e32 v46, v4
	v_mov_b32_e32 v47, v4
	v_mov_b32_e32 v48, v4
	v_mov_b32_e32 v49, v4
	v_mov_b32_e32 v50, v4
	v_mov_b32_e32 v51, v4
	v_mov_b32_e32 v60, v4
	v_mov_b32_e32 v61, v4
	v_mov_b32_e32 v62, v4
	v_mov_b32_e32 v63, v4
	v_mov_b32_e32 v64, v4
	v_mov_b32_e32 v65, v4
	v_mov_b32_e32 v66, v4
	v_mov_b32_e32 v67, v4
	v_mov_b32_e32 v68, v4
	v_mov_b32_e32 v69, v4
	v_mov_b32_e32 v70, v4
	v_mov_b32_e32 v71, v4
	v_mov_b32_e32 v72, v4
	v_mov_b32_e32 v73, v4
	v_mov_b32_e32 v74, v4
	v_mov_b32_e32 v75, v4
	v_mov_b32_e32 v84, v4
	v_mov_b32_e32 v85, v4
	v_mov_b32_e32 v86, v4
	v_mov_b32_e32 v87, v4
	v_mov_b32_e32 v88, v4
	v_mov_b32_e32 v89, v4
	v_mov_b32_e32 v90, v4
	v_mov_b32_e32 v91, v4
	v_mov_b32_e32 v100, v4
	v_mov_b32_e32 v101, v4
	v_mov_b32_e32 v102, v4
	v_mov_b32_e32 v103, v4
	v_mov_b32_e32 v104, v4
	v_mov_b32_e32 v105, v4
	v_mov_b32_e32 v106, v4
	v_mov_b32_e32 v107, v4
	v_mov_b32_e32 v116, v4
	v_mov_b32_e32 v117, v4
	v_mov_b32_e32 v118, v4
	v_mov_b32_e32 v119, v4
	v_mov_b32_e32 v120, v4
	v_mov_b32_e32 v121, v4
	v_mov_b32_e32 v122, v4
	v_mov_b32_e32 v123, v4
	v_mov_b32_e32 v76, v4
	v_mov_b32_e32 v77, v4
	v_mov_b32_e32 v78, v4
	v_mov_b32_e32 v79, v4
	v_mov_b32_e32 v80, v4
	v_mov_b32_e32 v81, v4
	v_mov_b32_e32 v82, v4
	v_mov_b32_e32 v83, v4
	v_mov_b32_e32 v92, v4
	v_mov_b32_e32 v93, v4
	v_mov_b32_e32 v94, v4
	v_mov_b32_e32 v95, v4
	v_mov_b32_e32 v96, v4
	v_mov_b32_e32 v97, v4
	v_mov_b32_e32 v98, v4
	v_mov_b32_e32 v99, v4
	v_mov_b32_e32 v108, v4
	v_mov_b32_e32 v109, v4
	v_mov_b32_e32 v110, v4
	v_mov_b32_e32 v111, v4
	v_mov_b32_e32 v112, v4
	v_mov_b32_e32 v113, v4
	v_mov_b32_e32 v114, v4
	v_mov_b32_e32 v115, v4
	v_mov_b32_e32 v124, v4
	v_mov_b32_e32 v125, v4
	v_mov_b32_e32 v126, v4
	v_mov_b32_e32 v127, v4
	v_mov_b32_e32 v128, v4
	v_mov_b32_e32 v129, v4
	v_mov_b32_e32 v130, v4
	v_mov_b32_e32 v131, v4
	v_add_u32_e32 v216, 0x10000, v1
.LBB0_769:
	s_add_u32 s0, s8, 0x100
	s_addc_u32 s1, s9, 0
	s_cmp_eq_u32 s62, 2
	s_cselect_b32 s22, s42, s0
	s_cselect_b32 s23, s43, s1
	s_cselect_b32 s18, s44, s47
	s_cselect_b32 s19, s45, s49
	s_add_u32 s20, s22, 0x80
	s_addc_u32 s21, s23, 0
	s_add_i32 s64, 0, 0x10000
	ds_read_b128 v[132:135], v216
	ds_read_b128 v[136:139], v216 offset:1024
	ds_read_b128 v[140:143], v216 offset:2048
	ds_read_b128 v[144:147], v216 offset:3072
	s_add_u32 s8, s8, 0x18080
	s_addc_u32 s9, s9, 0
	ds_read_b128 v[152:155], v3
	ds_read_b128 v[156:159], v3 offset:1024
	ds_read_b128 v[160:163], v3 offset:2048
	ds_read_b128 v[164:167], v3 offset:3072
	ds_read_b128 v[168:171], v3 offset:4096
	ds_read_b128 v[172:175], v3 offset:5120
	ds_read_b128 v[176:179], v3 offset:6144
	ds_read_b128 v[180:183], v3 offset:7168
	s_add_i32 m0, s57, 0xc000
	s_nop 0
	global_load_lds_dwordx4 v148, s[8:9]
	s_add_i32 m0, s57, 0xe000
	s_nop 0
	global_load_lds_dwordx4 v150, s[8:9]
	s_waitcnt lgkmcnt(8)
	s_barrier
	s_waitcnt lgkmcnt(0)
	s_setprio 1
	s_waitcnt lgkmcnt(0)
	v_mfma_f32_16x16x32_bf16 v[128:131], v[132:135], v[152:155], v[128:131]
	v_mfma_f32_16x16x32_bf16 v[124:127], v[140:143], v[152:155], v[124:127]
	v_mfma_f32_16x16x32_bf16 v[112:115], v[132:135], v[160:163], v[112:115]
	v_mfma_f32_16x16x32_bf16 v[108:111], v[140:143], v[160:163], v[108:111]
	v_mfma_f32_16x16x32_bf16 v[96:99], v[132:135], v[168:171], v[96:99]
	v_mfma_f32_16x16x32_bf16 v[92:95], v[140:143], v[168:171], v[92:95]
	v_mfma_f32_16x16x32_bf16 v[80:83], v[132:135], v[176:179], v[80:83]
	v_mfma_f32_16x16x32_bf16 v[76:79], v[140:143], v[176:179], v[76:79]
	v_mfma_f32_16x16x32_bf16 v[128:131], v[136:139], v[156:159], v[128:131]
	v_mfma_f32_16x16x32_bf16 v[124:127], v[144:147], v[156:159], v[124:127]
	v_mfma_f32_16x16x32_bf16 v[112:115], v[136:139], v[164:167], v[112:115]
	v_mfma_f32_16x16x32_bf16 v[108:111], v[144:147], v[164:167], v[108:111]
	v_mfma_f32_16x16x32_bf16 v[96:99], v[136:139], v[172:175], v[96:99]
	v_mfma_f32_16x16x32_bf16 v[92:95], v[144:147], v[172:175], v[92:95]
	v_mfma_f32_16x16x32_bf16 v[80:83], v[136:139], v[180:183], v[80:83]
	v_mfma_f32_16x16x32_bf16 v[76:79], v[144:147], v[180:183], v[76:79]
	s_setprio 0
	s_barrier
	s_add_i32 s65, 0, 0x14000
	s_mov_b64 s[8:9], s[18:19]
	s_add_i32 s64, s64, s56
	ds_read_b128 v[184:187], v216 offset:16384
	ds_read_b128 v[188:191], v216 offset:17408
	ds_read_b128 v[192:195], v216 offset:18432
	ds_read_b128 v[210:213], v216 offset:19456
	s_mov_b32 m0, s64
	s_nop 0
	global_load_lds_dwordx4 v148, s[8:9]
	s_add_i32 m0, s64, 0x2000
	s_nop 0
	global_load_lds_dwordx4 v150, s[8:9]
	s_barrier
	s_waitcnt lgkmcnt(0)
	s_setprio 1
	s_waitcnt lgkmcnt(0)
	v_mfma_f32_16x16x32_bf16 v[120:123], v[184:187], v[152:155], v[120:123]
	v_mfma_f32_16x16x32_bf16 v[116:119], v[192:195], v[152:155], v[116:119]
	v_mfma_f32_16x16x32_bf16 v[104:107], v[184:187], v[160:163], v[104:107]
	v_mfma_f32_16x16x32_bf16 v[100:103], v[192:195], v[160:163], v[100:103]
	v_mfma_f32_16x16x32_bf16 v[88:91], v[184:187], v[168:171], v[88:91]
	v_mfma_f32_16x16x32_bf16 v[84:87], v[192:195], v[168:171], v[84:87]
	v_mfma_f32_16x16x32_bf16 v[72:75], v[184:187], v[176:179], v[72:75]
	v_mfma_f32_16x16x32_bf16 v[68:71], v[192:195], v[176:179], v[68:71]
	v_mfma_f32_16x16x32_bf16 v[120:123], v[188:191], v[156:159], v[120:123]
	v_mfma_f32_16x16x32_bf16 v[116:119], v[210:213], v[156:159], v[116:119]
	v_mfma_f32_16x16x32_bf16 v[104:107], v[188:191], v[164:167], v[104:107]
	v_mfma_f32_16x16x32_bf16 v[100:103], v[210:213], v[164:167], v[100:103]
	v_mfma_f32_16x16x32_bf16 v[88:91], v[188:191], v[172:175], v[88:91]
	v_mfma_f32_16x16x32_bf16 v[84:87], v[210:213], v[172:175], v[84:87]
	v_mfma_f32_16x16x32_bf16 v[72:75], v[188:191], v[180:183], v[72:75]
	v_mfma_f32_16x16x32_bf16 v[68:71], v[210:213], v[180:183], v[68:71]
	s_setprio 0
	s_mov_b64 s[8:9], s[22:23]
	s_mov_b32 m0, s57
	s_barrier
	ds_read_b128 v[152:155], v3 offset:16384
	ds_read_b128 v[156:159], v3 offset:17408
	ds_read_b128 v[160:163], v3 offset:18432
	ds_read_b128 v[164:167], v3 offset:19456
	ds_read_b128 v[168:171], v3 offset:20480
	ds_read_b128 v[172:175], v3 offset:21504
	ds_read_b128 v[176:179], v3 offset:22528
	ds_read_b128 v[180:183], v3 offset:23552
	s_nop 0
	global_load_lds_dwordx4 v148, s[8:9]
	s_mov_b32 m0, s63
	s_nop 0
	global_load_lds_dwordx4 v150, s[8:9]
	s_barrier
	s_waitcnt lgkmcnt(0)
	s_setprio 1
	s_waitcnt lgkmcnt(0)
	v_mfma_f32_16x16x32_bf16 v[64:67], v[132:135], v[152:155], v[64:67]
	v_mfma_f32_16x16x32_bf16 v[60:63], v[140:143], v[152:155], v[60:63]
	v_mfma_f32_16x16x32_bf16 v[48:51], v[132:135], v[160:163], v[48:51]
	v_mfma_f32_16x16x32_bf16 v[44:47], v[140:143], v[160:163], v[44:47]
	v_mfma_f32_16x16x32_bf16 v[32:35], v[132:135], v[168:171], v[32:35]
	v_mfma_f32_16x16x32_bf16 v[28:31], v[140:143], v[168:171], v[28:31]
	v_mfma_f32_16x16x32_bf16 v[16:19], v[132:135], v[176:179], v[16:19]
	v_mfma_f32_16x16x32_bf16 v[12:15], v[140:143], v[176:179], v[12:15]
	v_mfma_f32_16x16x32_bf16 v[64:67], v[136:139], v[156:159], v[64:67]
	v_mfma_f32_16x16x32_bf16 v[60:63], v[144:147], v[156:159], v[60:63]
	v_mfma_f32_16x16x32_bf16 v[48:51], v[136:139], v[164:167], v[48:51]
	v_mfma_f32_16x16x32_bf16 v[44:47], v[144:147], v[164:167], v[44:47]
	v_mfma_f32_16x16x32_bf16 v[32:35], v[136:139], v[172:175], v[32:35]
	v_mfma_f32_16x16x32_bf16 v[28:31], v[144:147], v[172:175], v[28:31]
	v_mfma_f32_16x16x32_bf16 v[16:19], v[136:139], v[180:183], v[16:19]
	v_mfma_f32_16x16x32_bf16 v[12:15], v[144:147], v[180:183], v[12:15]
	s_setprio 0
	s_barrier
	s_add_u32 s8, s18, 0x18000
	s_addc_u32 s9, s19, 0
	s_add_i32 s64, s65, s56
	s_mov_b32 m0, s64
	s_nop 0
	global_load_lds_dwordx4 v148, s[8:9]
	s_add_i32 m0, s64, 0x2000
	s_nop 0
	global_load_lds_dwordx4 v150, s[8:9]
	s_waitcnt vmcnt(6)
	s_barrier
	s_setprio 1
	v_mfma_f32_16x16x32_bf16 v[56:59], v[184:187], v[152:155], v[56:59]
	v_mfma_f32_16x16x32_bf16 v[52:55], v[192:195], v[152:155], v[52:55]
	v_mfma_f32_16x16x32_bf16 v[40:43], v[184:187], v[160:163], v[40:43]
	v_mfma_f32_16x16x32_bf16 v[36:39], v[192:195], v[160:163], v[36:39]
	v_mfma_f32_16x16x32_bf16 v[24:27], v[184:187], v[168:171], v[24:27]
	v_mfma_f32_16x16x32_bf16 v[20:23], v[192:195], v[168:171], v[20:23]
	v_mfma_f32_16x16x32_bf16 v[8:11], v[184:187], v[176:179], v[8:11]
	v_mfma_f32_16x16x32_bf16 v[4:7], v[192:195], v[176:179], v[4:7]
	v_mfma_f32_16x16x32_bf16 v[56:59], v[188:191], v[156:159], v[56:59]
	v_mfma_f32_16x16x32_bf16 v[52:55], v[210:213], v[156:159], v[52:55]
	v_mfma_f32_16x16x32_bf16 v[40:43], v[188:191], v[164:167], v[40:43]
	v_mfma_f32_16x16x32_bf16 v[36:39], v[210:213], v[164:167], v[36:39]
	v_mfma_f32_16x16x32_bf16 v[24:27], v[188:191], v[172:175], v[24:27]
	v_mfma_f32_16x16x32_bf16 v[20:23], v[210:213], v[172:175], v[20:23]
	v_mfma_f32_16x16x32_bf16 v[8:11], v[188:191], v[180:183], v[8:11]
	v_mfma_f32_16x16x32_bf16 v[4:7], v[210:213], v[180:183], v[4:7]
	s_setprio 0
	s_add_i32 s64, 0, 0x18000
	s_barrier
	ds_read_b128 v[132:135], v216 offset:32768
	ds_read_b128 v[136:139], v216 offset:33792
	ds_read_b128 v[140:143], v216 offset:34816
	ds_read_b128 v[144:147], v216 offset:35840
	s_add_u32 s8, s22, 0x18000
	s_addc_u32 s9, s23, 0
	s_mov_b32 m0, s72
	ds_read_b128 v[152:155], v3 offset:32768
	ds_read_b128 v[156:159], v3 offset:33792
	ds_read_b128 v[160:163], v3 offset:34816
	ds_read_b128 v[164:167], v3 offset:35840
	ds_read_b128 v[168:171], v3 offset:36864
	ds_read_b128 v[172:175], v3 offset:37888
	ds_read_b128 v[176:179], v3 offset:38912
	ds_read_b128 v[180:183], v3 offset:39936
	s_nop 0
	global_load_lds_dwordx4 v148, s[8:9]
	s_mov_b32 m0, s73
	s_nop 0
	global_load_lds_dwordx4 v150, s[8:9]
	s_waitcnt lgkmcnt(8)
	s_barrier
	s_waitcnt lgkmcnt(0)
	s_setprio 1
	s_waitcnt lgkmcnt(0)
	v_mfma_f32_16x16x32_bf16 v[128:131], v[132:135], v[152:155], v[128:131]
	v_mfma_f32_16x16x32_bf16 v[124:127], v[140:143], v[152:155], v[124:127]
	v_mfma_f32_16x16x32_bf16 v[112:115], v[132:135], v[160:163], v[112:115]
	v_mfma_f32_16x16x32_bf16 v[108:111], v[140:143], v[160:163], v[108:111]
	v_mfma_f32_16x16x32_bf16 v[96:99], v[132:135], v[168:171], v[96:99]
	v_mfma_f32_16x16x32_bf16 v[92:95], v[140:143], v[168:171], v[92:95]
	v_mfma_f32_16x16x32_bf16 v[80:83], v[132:135], v[176:179], v[80:83]
	v_mfma_f32_16x16x32_bf16 v[76:79], v[140:143], v[176:179], v[76:79]
	v_mfma_f32_16x16x32_bf16 v[128:131], v[136:139], v[156:159], v[128:131]
	v_mfma_f32_16x16x32_bf16 v[124:127], v[144:147], v[156:159], v[124:127]
	v_mfma_f32_16x16x32_bf16 v[112:115], v[136:139], v[164:167], v[112:115]
	v_mfma_f32_16x16x32_bf16 v[108:111], v[144:147], v[164:167], v[108:111]
	v_mfma_f32_16x16x32_bf16 v[96:99], v[136:139], v[172:175], v[96:99]
	v_mfma_f32_16x16x32_bf16 v[92:95], v[144:147], v[172:175], v[92:95]
	v_mfma_f32_16x16x32_bf16 v[80:83], v[136:139], v[180:183], v[80:83]
	v_mfma_f32_16x16x32_bf16 v[76:79], v[144:147], v[180:183], v[76:79]
	s_setprio 0
	s_barrier
	s_add_i32 s22, 0, 0x1c000
	s_add_u32 s8, s18, 0x80
	s_addc_u32 s9, s19, 0
	s_add_i32 s23, s64, s56
	ds_read_b128 v[184:187], v216 offset:49152
	ds_read_b128 v[188:191], v216 offset:50176
	ds_read_b128 v[192:195], v216 offset:51200
	ds_read_b128 v[210:213], v216 offset:52224
	s_mov_b32 m0, s23
	s_nop 0
	global_load_lds_dwordx4 v148, s[8:9]
	s_add_i32 m0, s23, 0x2000
	s_nop 0
	global_load_lds_dwordx4 v150, s[8:9]
	s_barrier
	s_waitcnt lgkmcnt(0)
	s_setprio 1
	s_waitcnt lgkmcnt(0)
	v_mfma_f32_16x16x32_bf16 v[120:123], v[184:187], v[152:155], v[120:123]
	v_mfma_f32_16x16x32_bf16 v[116:119], v[192:195], v[152:155], v[116:119]
	v_mfma_f32_16x16x32_bf16 v[104:107], v[184:187], v[160:163], v[104:107]
	v_mfma_f32_16x16x32_bf16 v[100:103], v[192:195], v[160:163], v[100:103]
	v_mfma_f32_16x16x32_bf16 v[88:91], v[184:187], v[168:171], v[88:91]
	v_mfma_f32_16x16x32_bf16 v[84:87], v[192:195], v[168:171], v[84:87]
	v_mfma_f32_16x16x32_bf16 v[72:75], v[184:187], v[176:179], v[72:75]
	v_mfma_f32_16x16x32_bf16 v[68:71], v[192:195], v[176:179], v[68:71]
	v_mfma_f32_16x16x32_bf16 v[120:123], v[188:191], v[156:159], v[120:123]
	v_mfma_f32_16x16x32_bf16 v[116:119], v[210:213], v[156:159], v[116:119]
	v_mfma_f32_16x16x32_bf16 v[104:107], v[188:191], v[164:167], v[104:107]
	v_mfma_f32_16x16x32_bf16 v[100:103], v[210:213], v[164:167], v[100:103]
	v_mfma_f32_16x16x32_bf16 v[88:91], v[188:191], v[172:175], v[88:91]
	v_mfma_f32_16x16x32_bf16 v[84:87], v[210:213], v[172:175], v[84:87]
	v_mfma_f32_16x16x32_bf16 v[72:75], v[188:191], v[180:183], v[72:75]
	v_mfma_f32_16x16x32_bf16 v[68:71], v[210:213], v[180:183], v[68:71]
	s_setprio 0
	s_mov_b32 m0, s68
	s_barrier
	ds_read_b128 v[152:155], v3 offset:49152
	ds_read_b128 v[156:159], v3 offset:50176
	ds_read_b128 v[160:163], v3 offset:51200
	ds_read_b128 v[164:167], v3 offset:52224
	ds_read_b128 v[168:171], v3 offset:53248
	ds_read_b128 v[172:175], v3 offset:54272
	ds_read_b128 v[176:179], v3 offset:55296
	ds_read_b128 v[180:183], v3 offset:56320
	s_nop 0
	global_load_lds_dwordx4 v148, s[20:21]
	s_mov_b32 m0, s74
	s_nop 0
	global_load_lds_dwordx4 v150, s[20:21]
	s_barrier
	s_waitcnt lgkmcnt(0)
	s_setprio 1
	s_waitcnt lgkmcnt(0)
	v_mfma_f32_16x16x32_bf16 v[64:67], v[132:135], v[152:155], v[64:67]
	v_mfma_f32_16x16x32_bf16 v[60:63], v[140:143], v[152:155], v[60:63]
	v_mfma_f32_16x16x32_bf16 v[48:51], v[132:135], v[160:163], v[48:51]
	v_mfma_f32_16x16x32_bf16 v[44:47], v[140:143], v[160:163], v[44:47]
	v_mfma_f32_16x16x32_bf16 v[32:35], v[132:135], v[168:171], v[32:35]
	v_mfma_f32_16x16x32_bf16 v[28:31], v[140:143], v[168:171], v[28:31]
	v_mfma_f32_16x16x32_bf16 v[16:19], v[132:135], v[176:179], v[16:19]
	v_mfma_f32_16x16x32_bf16 v[12:15], v[140:143], v[176:179], v[12:15]
	v_mfma_f32_16x16x32_bf16 v[64:67], v[136:139], v[156:159], v[64:67]
	v_mfma_f32_16x16x32_bf16 v[60:63], v[144:147], v[156:159], v[60:63]
	v_mfma_f32_16x16x32_bf16 v[48:51], v[136:139], v[164:167], v[48:51]
	v_mfma_f32_16x16x32_bf16 v[44:47], v[144:147], v[164:167], v[44:47]
	v_mfma_f32_16x16x32_bf16 v[32:35], v[136:139], v[172:175], v[32:35]
	v_mfma_f32_16x16x32_bf16 v[28:31], v[144:147], v[172:175], v[28:31]
	v_mfma_f32_16x16x32_bf16 v[16:19], v[136:139], v[180:183], v[16:19]
	v_mfma_f32_16x16x32_bf16 v[12:15], v[144:147], v[180:183], v[12:15]
	s_setprio 0
	s_barrier
	s_add_u32 s8, s18, 0x18080
	s_addc_u32 s9, s19, 0
	s_add_i32 s18, s22, s56
	s_mov_b32 m0, s18
	s_nop 0
	global_load_lds_dwordx4 v148, s[8:9]
	s_add_i32 m0, s18, 0x2000
	s_nop 0
	global_load_lds_dwordx4 v150, s[8:9]
	s_waitcnt vmcnt(6)
	s_barrier
	s_setprio 1
	v_mfma_f32_16x16x32_bf16 v[56:59], v[184:187], v[152:155], v[56:59]
	v_mfma_f32_16x16x32_bf16 v[52:55], v[192:195], v[152:155], v[52:55]
	v_mfma_f32_16x16x32_bf16 v[40:43], v[184:187], v[160:163], v[40:43]
	v_mfma_f32_16x16x32_bf16 v[36:39], v[192:195], v[160:163], v[36:39]
	v_mfma_f32_16x16x32_bf16 v[24:27], v[184:187], v[168:171], v[24:27]
	v_mfma_f32_16x16x32_bf16 v[20:23], v[192:195], v[168:171], v[20:23]
	v_mfma_f32_16x16x32_bf16 v[8:11], v[184:187], v[176:179], v[8:11]
	v_mfma_f32_16x16x32_bf16 v[4:7], v[192:195], v[176:179], v[4:7]
	v_mfma_f32_16x16x32_bf16 v[56:59], v[188:191], v[156:159], v[56:59]
	v_mfma_f32_16x16x32_bf16 v[52:55], v[210:213], v[156:159], v[52:55]
	v_mfma_f32_16x16x32_bf16 v[40:43], v[188:191], v[164:167], v[40:43]
	v_mfma_f32_16x16x32_bf16 v[36:39], v[210:213], v[164:167], v[36:39]
	v_mfma_f32_16x16x32_bf16 v[24:27], v[188:191], v[172:175], v[24:27]
	v_mfma_f32_16x16x32_bf16 v[20:23], v[210:213], v[172:175], v[20:23]
	v_mfma_f32_16x16x32_bf16 v[8:11], v[188:191], v[180:183], v[8:11]
	v_mfma_f32_16x16x32_bf16 v[4:7], v[210:213], v[180:183], v[4:7]
	s_setprio 0
	s_add_i32 s62, s62, 2
	s_add_u32 s47, s47, 0x100
	s_addc_u32 s49, s49, 0
	s_cmp_gt_u32 s62, 3
	s_mov_b64 s[8:9], s[0:1]
	s_barrier
	s_cbranch_scc0 .LBB0_769
	v_mov_b32_e32 v132, v0
	s_nop 0
	v_readfirstlane_b32 s0, v132
	s_lshr_b32 s1, s0, 6
	s_and_b32 s49, s1, 3
	s_cmp_eq_u32 s48, 4
	s_cselect_b64 s[8:9], -1, 0
	s_cmp_gt_u32 s49, 1
	s_cselect_b64 s[18:19], -1, 0
	s_and_b64 s[8:9], s[8:9], s[18:19]
	s_and_b64 vcc, exec, s[8:9]
	s_cbranch_vccnz .LBB0_757
	s_ashr_i32 s0, s0, 2
	s_lshl_b32 s1, s46, 8
	s_andn2_b32 s0, s0, 63
	s_add_i32 s0, s0, s1
	v_and_or_b32 v152, v132, 15, s0
	v_ashrrev_i32_e32 v153, 31, v152
	v_bfe_u32 v134, v132, 4, 2
	v_lshl_add_u64 v[132:133], v[152:153], 2, s[6:7]
	global_load_dword v135, v[132:133], off
	global_load_dword v178, v[132:133], off offset:64
	global_load_dword v177, v[132:133], off offset:128
	global_load_dword v176, v[132:133], off offset:192
	global_load_dword v175, v[132:133], off offset:512
	global_load_dword v174, v[132:133], off offset:576
	global_load_dword v173, v[132:133], off offset:640
	global_load_dword v172, v[132:133], off offset:704
	s_cmp_gt_i32 s48, 2
	s_cselect_b64 s[0:1], -1, 0
	v_lshlrev_b32_e32 v179, 3, v134
	s_lshl_b32 s8, s48, 3
	s_lshl_b32 s9, s49, 1
	s_or_b32 s8, s8, s9
	s_sub_i32 s46, s8, 24
	v_cmp_eq_u32_e64 s[18:19], 0, v134
	v_cmp_ne_u32_e64 s[20:21], 0, v134
	s_mov_b64 s[8:9], -1
	v_lshlrev_b32_e32 v154, 2, v179
	s_waitcnt vmcnt(0)
	v_fmamk_f32 v132, v135, 0x3b2aaaab, v231
	v_cmp_gt_f32_e32 vcc, s11, v132
	v_mul_f32_e32 v133, 0x4b800000, v132
	s_nop 0
	v_cndmask_b32_e32 v132, v132, v133, vcc
	v_rsq_f32_e32 v132, v132
	s_nop 0
	v_mul_f32_e32 v133, 0x45800000, v132
	v_cndmask_b32_e32 v158, v132, v133, vcc
	v_and_b32_e32 v132, 8, v179
	v_mov_b32_e32 v159, v158
	s_and_b64 vcc, exec, s[0:1]
	v_lshlrev_b32_e32 v156, 2, v132
	v_pk_mul_f32 v[128:129], v[128:129], v[158:159]
	v_pk_mul_f32 v[124:125], v[124:125], v[158:159]
	s_cbranch_vccz .LBB0_781
	v_and_b32_e32 v133, 64, v236
	v_xor_b32_e32 v132, 32, v236
	v_add_u32_e32 v133, 64, v133
	v_cmp_lt_i32_e32 vcc, v132, v133
	v_mov_b32_e32 v162, v158
	v_mov_b32_e32 v163, v158
	v_cndmask_b32_e32 v132, v236, v132, vcc
	v_pk_mul_f32 v[160:161], v[130:131], v[162:163]
	v_lshlrev_b32_e32 v170, 2, v132
	v_mul_f32_e32 v132, v129, v129
	v_mul_f32_e32 v133, v161, v161
	v_fmac_f32_e32 v132, v128, v128
	v_fmac_f32_e32 v133, v160, v160
	v_add_f32_e32 v155, v132, v133
	global_load_dwordx4 v[136:139], v154, s[40:41] offset:272
	global_load_dwordx4 v[144:147], v154, s[40:41] offset:256
	global_load_dwordx4 v[132:135], v156, s[26:27] offset:16
	global_load_dwordx4 v[140:143], v156, s[26:27]
	v_pk_mul_f32 v[162:163], v[126:127], v[162:163]
	v_mul_f32_e32 v157, v125, v125
	v_mul_f32_e32 v164, v163, v163
	v_fmac_f32_e32 v157, v124, v124
	v_fmac_f32_e32 v164, v162, v162
	v_add_f32_e32 v157, v157, v164
	v_add_f32_e32 v155, v155, v157
	ds_swizzle_b32 v157, v155 offset:swizzle(SWAP,16)
	s_waitcnt lgkmcnt(0)
	v_add_f32_e32 v155, v155, v157
	ds_bpermute_b32 v157, v170, v155
	s_and_saveexec_b64 s[8:9], s[20:21]
	s_xor_b64 s[8:9], exec, s[8:9]
	s_ashr_i32 s47, s46, 31
	s_or_saveexec_b64 s[8:9], s[8:9]
	v_mov_b64_e32 v[164:165], s[46:47]
	s_xor_b64 exec, exec, s[8:9]
	s_cbranch_execz .LBB0_776
	s_ashr_i32 s47, s46, 31
	s_mul_i32 s22, s46, 0x10400
	s_mul_hi_i32 s23, s46, 0x10400
	s_add_u32 s22, s35, s22
	s_addc_u32 s23, s54, s23
	s_waitcnt lgkmcnt(0)
	v_add_f32_e32 v155, v155, v157
	v_lshl_add_u64 v[164:165], v[152:153], 2, s[22:23]
	global_atomic_add_f32 v[164:165], v155, off
	v_mov_b64_e32 v[164:165], s[46:47]

.LBB0_1011:
	s_ashr_i32 s29, s28, 31
	s_lshl_b64 s[34:35], s[28:29], 17
	s_add_u32 s34, s53, s34
	s_addc_u32 s35, s54, s35
	s_and_b64 s[16:17], s[16:17], exec
	v_mov_b32_e32 v4, 0
	s_cselect_b32 s9, s35, s1
	s_cselect_b32 s19, s34, s0
	s_mov_b64 s[36:37], 0
	s_mov_b64 s[16:17], -1
	s_mov_b64 s[38:39], 0
	v_mov_b32_e32 v5, v4
	v_mov_b32_e32 v6, v4
	v_mov_b32_e32 v7, v4
	v_mov_b32_e32 v8, v4
	v_mov_b32_e32 v9, v4
	v_mov_b32_e32 v10, v4
	v_mov_b32_e32 v11, v4
	v_mov_b32_e32 v20, v4
	v_mov_b32_e32 v21, v4
	v_mov_b32_e32 v22, v4
	v_mov_b32_e32 v23, v4
	v_mov_b32_e32 v24, v4
	v_mov_b32_e32 v25, v4
	v_mov_b32_e32 v26, v4
	v_mov_b32_e32 v27, v4
	v_mov_b32_e32 v36, v4
	v_mov_b32_e32 v37, v4
	v_mov_b32_e32 v38, v4
	v_mov_b32_e32 v39, v4
	v_mov_b32_e32 v40, v4
	v_mov_b32_e32 v41, v4
	v_mov_b32_e32 v42, v4
	v_mov_b32_e32 v43, v4
	v_mov_b32_e32 v52, v4
	v_mov_b32_e32 v53, v4
	v_mov_b32_e32 v54, v4
	v_mov_b32_e32 v55, v4
	v_mov_b32_e32 v56, v4
	v_mov_b32_e32 v57, v4
	v_mov_b32_e32 v58, v4
	v_mov_b32_e32 v59, v4
	v_mov_b32_e32 v12, v4
	v_mov_b32_e32 v13, v4
	v_mov_b32_e32 v14, v4
	v_mov_b32_e32 v15, v4
	v_mov_b32_e32 v16, v4
	v_mov_b32_e32 v17, v4
	v_mov_b32_e32 v18, v4
	v_mov_b32_e32 v19, v4
	v_mov_b32_e32 v28, v4
	v_mov_b32_e32 v29, v4
	v_mov_b32_e32 v30, v4
	v_mov_b32_e32 v31, v4
	v_mov_b32_e32 v32, v4
	v_mov_b32_e32 v33, v4
	v_mov_b32_e32 v34, v4
	v_mov_b32_e32 v35, v4
	v_mov_b32_e32 v44, v4
	v_mov_b32_e32 v45, v4
	v_mov_b32_e32 v46, v4
	v_mov_b32_e32 v47, v4
	v_mov_b32_e32 v48, v4
	v_mov_b32_e32 v49, v4
	v_mov_b32_e32 v50, v4
	v_mov_b32_e32 v51, v4
	v_mov_b32_e32 v60, v4
	v_mov_b32_e32 v61, v4
	v_mov_b32_e32 v62, v4
	v_mov_b32_e32 v63, v4
	v_mov_b32_e32 v64, v4
	v_mov_b32_e32 v65, v4
	v_mov_b32_e32 v66, v4
	v_mov_b32_e32 v67, v4
	v_mov_b32_e32 v72, v4
	v_mov_b32_e32 v73, v4
	v_mov_b32_e32 v74, v4
	v_mov_b32_e32 v75, v4
	v_mov_b32_e32 v76, v4
	v_mov_b32_e32 v77, v4
	v_mov_b32_e32 v78, v4
	v_mov_b32_e32 v79, v4
	v_mov_b32_e32 v92, v4
	v_mov_b32_e32 v93, v4
	v_mov_b32_e32 v94, v4
	v_mov_b32_e32 v95, v4
	v_mov_b32_e32 v96, v4
	v_mov_b32_e32 v97, v4
	v_mov_b32_e32 v98, v4
	v_mov_b32_e32 v99, v4
	v_mov_b32_e32 v112, v4
	v_mov_b32_e32 v113, v4
	v_mov_b32_e32 v114, v4
	v_mov_b32_e32 v115, v4
	v_mov_b32_e32 v116, v4
	v_mov_b32_e32 v117, v4
	v_mov_b32_e32 v118, v4
	v_mov_b32_e32 v119, v4
	v_mov_b32_e32 v132, v4
	v_mov_b32_e32 v133, v4
	v_mov_b32_e32 v134, v4
	v_mov_b32_e32 v135, v4
	v_mov_b32_e32 v136, v4
	v_mov_b32_e32 v137, v4
	v_mov_b32_e32 v138, v4
	v_mov_b32_e32 v139, v4
	v_mov_b32_e32 v80, v4
	v_mov_b32_e32 v81, v4
	v_mov_b32_e32 v82, v4
	v_mov_b32_e32 v83, v4
	v_mov_b32_e32 v84, v4
	v_mov_b32_e32 v85, v4
	v_mov_b32_e32 v86, v4
	v_mov_b32_e32 v87, v4
	v_mov_b32_e32 v100, v4
	v_mov_b32_e32 v101, v4
	v_mov_b32_e32 v102, v4
	v_mov_b32_e32 v103, v4
	v_mov_b32_e32 v104, v4
	v_mov_b32_e32 v105, v4
	v_mov_b32_e32 v106, v4
	v_mov_b32_e32 v107, v4
	v_mov_b32_e32 v120, v4
	v_mov_b32_e32 v121, v4
	v_mov_b32_e32 v122, v4
	v_mov_b32_e32 v123, v4
	v_mov_b32_e32 v124, v4
	v_mov_b32_e32 v125, v4
	v_mov_b32_e32 v126, v4
	v_mov_b32_e32 v127, v4
	v_mov_b32_e32 v140, v4
	v_mov_b32_e32 v141, v4
	v_mov_b32_e32 v142, v4
	v_mov_b32_e32 v143, v4
	v_mov_b32_e32 v144, v4
	v_mov_b32_e32 v145, v4
	v_mov_b32_e32 v146, v4
	v_mov_b32_e32 v147, v4
	v_add_u32_e32 v218, 0x10000, v1
	s_waitcnt vmcnt(0)
.LBB0_1012:
	s_add_u32 s29, s20, s36
	s_addc_u32 s42, s21, s37
	s_add_u32 s43, s29, 0x100
	s_addc_u32 s44, s42, 0
	s_and_b64 s[40:41], s[38:39], exec
	s_cselect_b32 s47, s31, s44
	s_cselect_b32 s46, s30, s43
	s_add_u32 s36, s0, s36
	s_addc_u32 s37, s1, s37
	s_add_u32 s40, s36, 0x100
	s_addc_u32 s41, s37, 0
	s_add_u32 s36, s46, 0x80
	s_addc_u32 s37, s47, 0
	s_add_i32 s78, 0, 0x10000
	s_and_b64 s[38:39], s[38:39], exec
	s_cselect_b32 s49, s9, s41
	s_cselect_b32 s48, s19, s40
	s_add_u32 s50, s29, 0x12080
	s_addc_u32 s51, s42, 0
	s_add_i32 s83, s78, s55
	s_add_i32 m0, s56, 0xc000
	s_add_i32 s84, s56, 0xe000
	s_add_i32 s82, 0, 0x14000
	s_add_i32 s81, s83, 0x2000
	s_add_u32 s44, s48, 0x10000
	s_addc_u32 s45, s49, 0
	s_add_i32 s79, s82, s55
	s_add_i32 s75, s79, 0x2000
	s_add_i32 s74, 0, 0x18000
	s_add_u32 s42, s46, 0x12000
	ds_read_b128 v[68:71], v218
	ds_read_b128 v[88:91], v218 offset:1024
	ds_read_b128 v[108:111], v218 offset:2048
	ds_read_b128 v[128:131], v218 offset:3072
	s_addc_u32 s43, s47, 0
	s_add_i32 s67, 0, 0x1c000
	s_add_u32 s40, s48, 0x80
	s_addc_u32 s41, s49, 0
	s_add_i32 s68, s74, s55
	s_add_i32 s29, s68, 0x2000
	s_add_u32 s38, s48, 0x10080
	s_addc_u32 s39, s49, 0
	s_add_i32 s80, s67, s55
	s_add_i32 s78, s80, 0x2000
	ds_read_b128 v[148:151], v3
	ds_read_b128 v[152:155], v3 offset:1024
	ds_read_b128 v[156:159], v3 offset:2048
	ds_read_b128 v[160:163], v3 offset:3072
	ds_read_b128 v[172:175], v3 offset:4096
	ds_read_b128 v[176:179], v3 offset:5120
	ds_read_b128 v[180:183], v3 offset:6144
	ds_read_b128 v[184:187], v3 offset:7168
	s_nop 0
	global_load_lds_dwordx4 v164, s[50:51]
	s_mov_b32 m0, s84
	s_nop 0
	global_load_lds_dwordx4 v168, s[50:51]
	s_waitcnt lgkmcnt(8)
	s_barrier
	s_waitcnt lgkmcnt(0)
	s_setprio 1
	s_waitcnt lgkmcnt(0)
	v_mfma_f32_16x16x32_bf16 v[144:147], v[68:71], v[148:151], v[144:147]
	v_mfma_f32_16x16x32_bf16 v[140:143], v[108:111], v[148:151], v[140:143]
	v_mfma_f32_16x16x32_bf16 v[124:127], v[68:71], v[156:159], v[124:127]
	v_mfma_f32_16x16x32_bf16 v[120:123], v[108:111], v[156:159], v[120:123]
	v_mfma_f32_16x16x32_bf16 v[104:107], v[68:71], v[172:175], v[104:107]
	v_mfma_f32_16x16x32_bf16 v[100:103], v[108:111], v[172:175], v[100:103]
	v_mfma_f32_16x16x32_bf16 v[84:87], v[68:71], v[180:183], v[84:87]
	v_mfma_f32_16x16x32_bf16 v[80:83], v[108:111], v[180:183], v[80:83]
	v_mfma_f32_16x16x32_bf16 v[144:147], v[88:91], v[152:155], v[144:147]
	v_mfma_f32_16x16x32_bf16 v[140:143], v[128:131], v[152:155], v[140:143]
	v_mfma_f32_16x16x32_bf16 v[124:127], v[88:91], v[160:163], v[124:127]
	v_mfma_f32_16x16x32_bf16 v[120:123], v[128:131], v[160:163], v[120:123]
	v_mfma_f32_16x16x32_bf16 v[104:107], v[88:91], v[176:179], v[104:107]
	v_mfma_f32_16x16x32_bf16 v[100:103], v[128:131], v[176:179], v[100:103]
	v_mfma_f32_16x16x32_bf16 v[84:87], v[88:91], v[184:187], v[84:87]
	v_mfma_f32_16x16x32_bf16 v[80:83], v[128:131], v[184:187], v[80:83]
	s_setprio 0
	s_barrier
	s_mov_b32 m0, s83
	ds_read_b128 v[188:191], v218 offset:16384
	ds_read_b128 v[192:195], v218 offset:17408
	ds_read_b128 v[210:213], v218 offset:18432
	ds_read_b128 v[214:217], v218 offset:19456
	s_nop 0
	global_load_lds_dwordx4 v166, s[48:49]
	s_mov_b32 m0, s81
	s_nop 0
	global_load_lds_dwordx4 v170, s[48:49]
	s_barrier
	s_waitcnt lgkmcnt(0)
	s_setprio 1
	s_waitcnt lgkmcnt(0)
	v_mfma_f32_16x16x32_bf16 v[136:139], v[188:191], v[148:151], v[136:139]
	v_mfma_f32_16x16x32_bf16 v[132:135], v[210:213], v[148:151], v[132:135]
	v_mfma_f32_16x16x32_bf16 v[116:119], v[188:191], v[156:159], v[116:119]
	v_mfma_f32_16x16x32_bf16 v[112:115], v[210:213], v[156:159], v[112:115]
	v_mfma_f32_16x16x32_bf16 v[96:99], v[188:191], v[172:175], v[96:99]
	v_mfma_f32_16x16x32_bf16 v[92:95], v[210:213], v[172:175], v[92:95]
	v_mfma_f32_16x16x32_bf16 v[76:79], v[188:191], v[180:183], v[76:79]
	v_mfma_f32_16x16x32_bf16 v[72:75], v[210:213], v[180:183], v[72:75]
	v_mfma_f32_16x16x32_bf16 v[136:139], v[192:195], v[152:155], v[136:139]
	v_mfma_f32_16x16x32_bf16 v[132:135], v[214:217], v[152:155], v[132:135]
	v_mfma_f32_16x16x32_bf16 v[116:119], v[192:195], v[160:163], v[116:119]
	v_mfma_f32_16x16x32_bf16 v[112:115], v[214:217], v[160:163], v[112:115]
	v_mfma_f32_16x16x32_bf16 v[96:99], v[192:195], v[176:179], v[96:99]
	v_mfma_f32_16x16x32_bf16 v[92:95], v[214:217], v[176:179], v[92:95]
	v_mfma_f32_16x16x32_bf16 v[76:79], v[192:195], v[184:187], v[76:79]
	v_mfma_f32_16x16x32_bf16 v[72:75], v[214:217], v[184:187], v[72:75]
	s_setprio 0
	s_mov_b32 m0, s56
	s_barrier
	ds_read_b128 v[148:151], v3 offset:16384
	ds_read_b128 v[152:155], v3 offset:17408
	ds_read_b128 v[156:159], v3 offset:18432
	ds_read_b128 v[160:163], v3 offset:19456
	ds_read_b128 v[172:175], v3 offset:20480
	ds_read_b128 v[176:179], v3 offset:21504
	ds_read_b128 v[180:183], v3 offset:22528
	ds_read_b128 v[184:187], v3 offset:23552
	s_nop 0
	global_load_lds_dwordx4 v164, s[46:47]
	s_mov_b32 m0, s57
	s_nop 0
	global_load_lds_dwordx4 v168, s[46:47]
	s_barrier
	s_waitcnt lgkmcnt(0)
	s_setprio 1
	s_waitcnt lgkmcnt(0)
	v_mfma_f32_16x16x32_bf16 v[64:67], v[68:71], v[148:151], v[64:67]
	v_mfma_f32_16x16x32_bf16 v[60:63], v[108:111], v[148:151], v[60:63]
	v_mfma_f32_16x16x32_bf16 v[48:51], v[68:71], v[156:159], v[48:51]
	v_mfma_f32_16x16x32_bf16 v[44:47], v[108:111], v[156:159], v[44:47]
	v_mfma_f32_16x16x32_bf16 v[32:35], v[68:71], v[172:175], v[32:35]
	v_mfma_f32_16x16x32_bf16 v[28:31], v[108:111], v[172:175], v[28:31]
	v_mfma_f32_16x16x32_bf16 v[16:19], v[68:71], v[180:183], v[16:19]
	v_mfma_f32_16x16x32_bf16 v[12:15], v[108:111], v[180:183], v[12:15]
	v_mfma_f32_16x16x32_bf16 v[64:67], v[88:91], v[152:155], v[64:67]
	v_mfma_f32_16x16x32_bf16 v[60:63], v[128:131], v[152:155], v[60:63]
	v_mfma_f32_16x16x32_bf16 v[48:51], v[88:91], v[160:163], v[48:51]
	v_mfma_f32_16x16x32_bf16 v[44:47], v[128:131], v[160:163], v[44:47]
	v_mfma_f32_16x16x32_bf16 v[32:35], v[88:91], v[176:179], v[32:35]
	v_mfma_f32_16x16x32_bf16 v[28:31], v[128:131], v[176:179], v[28:31]
	v_mfma_f32_16x16x32_bf16 v[16:19], v[88:91], v[184:187], v[16:19]
	v_mfma_f32_16x16x32_bf16 v[12:15], v[128:131], v[184:187], v[12:15]
	s_setprio 0
	s_barrier
	s_mov_b32 m0, s79
	s_nop 0
	global_load_lds_dwordx4 v166, s[44:45]
	s_mov_b32 m0, s75
	s_nop 0
	global_load_lds_dwordx4 v170, s[44:45]
	s_waitcnt vmcnt(6)
	s_barrier
	s_setprio 1
	v_mfma_f32_16x16x32_bf16 v[56:59], v[188:191], v[148:151], v[56:59]
	v_mfma_f32_16x16x32_bf16 v[52:55], v[210:213], v[148:151], v[52:55]
	v_mfma_f32_16x16x32_bf16 v[40:43], v[188:191], v[156:159], v[40:43]
	v_mfma_f32_16x16x32_bf16 v[36:39], v[210:213], v[156:159], v[36:39]
	v_mfma_f32_16x16x32_bf16 v[24:27], v[188:191], v[172:175], v[24:27]
	v_mfma_f32_16x16x32_bf16 v[20:23], v[210:213], v[172:175], v[20:23]
	v_mfma_f32_16x16x32_bf16 v[8:11], v[188:191], v[180:183], v[8:11]
	v_mfma_f32_16x16x32_bf16 v[4:7], v[210:213], v[180:183], v[4:7]
	v_mfma_f32_16x16x32_bf16 v[56:59], v[192:195], v[152:155], v[56:59]
	v_mfma_f32_16x16x32_bf16 v[52:55], v[214:217], v[152:155], v[52:55]
	v_mfma_f32_16x16x32_bf16 v[40:43], v[192:195], v[160:163], v[40:43]
	v_mfma_f32_16x16x32_bf16 v[36:39], v[214:217], v[160:163], v[36:39]
	v_mfma_f32_16x16x32_bf16 v[24:27], v[192:195], v[176:179], v[24:27]
	v_mfma_f32_16x16x32_bf16 v[20:23], v[214:217], v[176:179], v[20:23]
	v_mfma_f32_16x16x32_bf16 v[8:11], v[192:195], v[184:187], v[8:11]
	v_mfma_f32_16x16x32_bf16 v[4:7], v[214:217], v[184:187], v[4:7]
	s_setprio 0
	s_barrier
	ds_read_b128 v[68:71], v218 offset:32768
	ds_read_b128 v[88:91], v218 offset:33792
	ds_read_b128 v[108:111], v218 offset:34816
	ds_read_b128 v[128:131], v218 offset:35840
	s_mov_b32 m0, s62
	ds_read_b128 v[148:151], v3 offset:32768
	ds_read_b128 v[152:155], v3 offset:33792
	ds_read_b128 v[156:159], v3 offset:34816
	ds_read_b128 v[160:163], v3 offset:35840
	ds_read_b128 v[172:175], v3 offset:36864
	ds_read_b128 v[176:179], v3 offset:37888
	ds_read_b128 v[180:183], v3 offset:38912
	ds_read_b128 v[184:187], v3 offset:39936
	s_nop 0
	global_load_lds_dwordx4 v164, s[42:43]
	s_mov_b32 m0, s63
	s_nop 0
	global_load_lds_dwordx4 v168, s[42:43]
	s_waitcnt lgkmcnt(8)
	s_barrier
	s_waitcnt lgkmcnt(0)
	s_setprio 1
	s_waitcnt lgkmcnt(0)
	v_mfma_f32_16x16x32_bf16 v[144:147], v[68:71], v[148:151], v[144:147]
	v_mfma_f32_16x16x32_bf16 v[140:143], v[108:111], v[148:151], v[140:143]
	v_mfma_f32_16x16x32_bf16 v[124:127], v[68:71], v[156:159], v[124:127]
	v_mfma_f32_16x16x32_bf16 v[120:123], v[108:111], v[156:159], v[120:123]
	v_mfma_f32_16x16x32_bf16 v[104:107], v[68:71], v[172:175], v[104:107]
	v_mfma_f32_16x16x32_bf16 v[100:103], v[108:111], v[172:175], v[100:103]
	v_mfma_f32_16x16x32_bf16 v[84:87], v[68:71], v[180:183], v[84:87]
	v_mfma_f32_16x16x32_bf16 v[80:83], v[108:111], v[180:183], v[80:83]
	v_mfma_f32_16x16x32_bf16 v[144:147], v[88:91], v[152:155], v[144:147]
	v_mfma_f32_16x16x32_bf16 v[140:143], v[128:131], v[152:155], v[140:143]
	v_mfma_f32_16x16x32_bf16 v[124:127], v[88:91], v[160:163], v[124:127]
	v_mfma_f32_16x16x32_bf16 v[120:123], v[128:131], v[160:163], v[120:123]
	v_mfma_f32_16x16x32_bf16 v[104:107], v[88:91], v[176:179], v[104:107]
	v_mfma_f32_16x16x32_bf16 v[100:103], v[128:131], v[176:179], v[100:103]
	v_mfma_f32_16x16x32_bf16 v[84:87], v[88:91], v[184:187], v[84:87]
	v_mfma_f32_16x16x32_bf16 v[80:83], v[128:131], v[184:187], v[80:83]
	s_setprio 0
	s_barrier
	s_mov_b32 m0, s68
	ds_read_b128 v[188:191], v218 offset:49152
	ds_read_b128 v[192:195], v218 offset:50176
	ds_read_b128 v[210:213], v218 offset:51200
	ds_read_b128 v[214:217], v218 offset:52224
	s_nop 0
	global_load_lds_dwordx4 v166, s[40:41]
	s_mov_b32 m0, s29
	s_nop 0
	global_load_lds_dwordx4 v170, s[40:41]
	s_barrier
	s_waitcnt lgkmcnt(0)
	s_setprio 1
	s_waitcnt lgkmcnt(0)
	v_mfma_f32_16x16x32_bf16 v[136:139], v[188:191], v[148:151], v[136:139]
	v_mfma_f32_16x16x32_bf16 v[132:135], v[210:213], v[148:151], v[132:135]
	v_mfma_f32_16x16x32_bf16 v[116:119], v[188:191], v[156:159], v[116:119]
	v_mfma_f32_16x16x32_bf16 v[112:115], v[210:213], v[156:159], v[112:115]
	v_mfma_f32_16x16x32_bf16 v[96:99], v[188:191], v[172:175], v[96:99]
	v_mfma_f32_16x16x32_bf16 v[92:95], v[210:213], v[172:175], v[92:95]
	v_mfma_f32_16x16x32_bf16 v[76:79], v[188:191], v[180:183], v[76:79]
	v_mfma_f32_16x16x32_bf16 v[72:75], v[210:213], v[180:183], v[72:75]
	v_mfma_f32_16x16x32_bf16 v[136:139], v[192:195], v[152:155], v[136:139]
	v_mfma_f32_16x16x32_bf16 v[132:135], v[214:217], v[152:155], v[132:135]
	v_mfma_f32_16x16x32_bf16 v[116:119], v[192:195], v[160:163], v[116:119]
	v_mfma_f32_16x16x32_bf16 v[112:115], v[214:217], v[160:163], v[112:115]
	v_mfma_f32_16x16x32_bf16 v[96:99], v[192:195], v[176:179], v[96:99]
	v_mfma_f32_16x16x32_bf16 v[92:95], v[214:217], v[176:179], v[92:95]
	v_mfma_f32_16x16x32_bf16 v[76:79], v[192:195], v[184:187], v[76:79]
	v_mfma_f32_16x16x32_bf16 v[72:75], v[214:217], v[184:187], v[72:75]
	s_setprio 0
	s_mov_b32 m0, s64
	s_barrier
	ds_read_b128 v[148:151], v3 offset:49152
	ds_read_b128 v[152:155], v3 offset:50176
	ds_read_b128 v[156:159], v3 offset:51200
	ds_read_b128 v[160:163], v3 offset:52224
	ds_read_b128 v[172:175], v3 offset:53248
	ds_read_b128 v[176:179], v3 offset:54272
	ds_read_b128 v[180:183], v3 offset:55296
	ds_read_b128 v[184:187], v3 offset:56320
	s_nop 0
	global_load_lds_dwordx4 v164, s[36:37]
	s_mov_b32 m0, s65
	s_nop 0
	global_load_lds_dwordx4 v168, s[36:37]
	s_barrier
	s_waitcnt lgkmcnt(0)
	s_setprio 1
	s_waitcnt lgkmcnt(0)
	v_mfma_f32_16x16x32_bf16 v[64:67], v[68:71], v[148:151], v[64:67]
	v_mfma_f32_16x16x32_bf16 v[60:63], v[108:111], v[148:151], v[60:63]
	v_mfma_f32_16x16x32_bf16 v[48:51], v[68:71], v[156:159], v[48:51]
	v_mfma_f32_16x16x32_bf16 v[44:47], v[108:111], v[156:159], v[44:47]
	v_mfma_f32_16x16x32_bf16 v[32:35], v[68:71], v[172:175], v[32:35]
	v_mfma_f32_16x16x32_bf16 v[28:31], v[108:111], v[172:175], v[28:31]
	v_mfma_f32_16x16x32_bf16 v[16:19], v[68:71], v[180:183], v[16:19]
	v_mfma_f32_16x16x32_bf16 v[12:15], v[108:111], v[180:183], v[12:15]
	v_mfma_f32_16x16x32_bf16 v[64:67], v[88:91], v[152:155], v[64:67]
	v_mfma_f32_16x16x32_bf16 v[60:63], v[128:131], v[152:155], v[60:63]
	v_mfma_f32_16x16x32_bf16 v[48:51], v[88:91], v[160:163], v[48:51]
	v_mfma_f32_16x16x32_bf16 v[44:47], v[128:131], v[160:163], v[44:47]
	v_mfma_f32_16x16x32_bf16 v[32:35], v[88:91], v[176:179], v[32:35]
	v_mfma_f32_16x16x32_bf16 v[28:31], v[128:131], v[176:179], v[28:31]
	v_mfma_f32_16x16x32_bf16 v[16:19], v[88:91], v[184:187], v[16:19]
	v_mfma_f32_16x16x32_bf16 v[12:15], v[128:131], v[184:187], v[12:15]
	s_setprio 0
	s_barrier
	s_mov_b32 m0, s80
	s_nop 0
	global_load_lds_dwordx4 v166, s[38:39]
	s_mov_b32 m0, s78
	s_nop 0
	global_load_lds_dwordx4 v170, s[38:39]
	s_waitcnt vmcnt(6)
	s_barrier
	s_setprio 1
	v_mfma_f32_16x16x32_bf16 v[56:59], v[188:191], v[148:151], v[56:59]
	v_mfma_f32_16x16x32_bf16 v[52:55], v[210:213], v[148:151], v[52:55]
	v_mfma_f32_16x16x32_bf16 v[40:43], v[188:191], v[156:159], v[40:43]
	v_mfma_f32_16x16x32_bf16 v[36:39], v[210:213], v[156:159], v[36:39]
	v_mfma_f32_16x16x32_bf16 v[24:27], v[188:191], v[172:175], v[24:27]
	v_mfma_f32_16x16x32_bf16 v[20:23], v[210:213], v[172:175], v[20:23]
	v_mfma_f32_16x16x32_bf16 v[8:11], v[188:191], v[180:183], v[8:11]
	v_mfma_f32_16x16x32_bf16 v[4:7], v[210:213], v[180:183], v[4:7]
	v_mfma_f32_16x16x32_bf16 v[56:59], v[192:195], v[152:155], v[56:59]
	v_mfma_f32_16x16x32_bf16 v[52:55], v[214:217], v[152:155], v[52:55]
	v_mfma_f32_16x16x32_bf16 v[40:43], v[192:195], v[160:163], v[40:43]
	v_mfma_f32_16x16x32_bf16 v[36:39], v[214:217], v[160:163], v[36:39]
	v_mfma_f32_16x16x32_bf16 v[24:27], v[192:195], v[176:179], v[24:27]
	v_mfma_f32_16x16x32_bf16 v[20:23], v[214:217], v[176:179], v[20:23]
	v_mfma_f32_16x16x32_bf16 v[8:11], v[192:195], v[184:187], v[8:11]
	v_mfma_f32_16x16x32_bf16 v[4:7], v[214:217], v[184:187], v[4:7]
	s_setprio 0
	s_andn2_b64 vcc, exec, s[16:17]
	s_mov_b64 s[38:39], -1
	s_mov_b64 s[16:17], 0
	s_mov_b64 s[36:37], 0x100
	s_barrier
	s_cbranch_vccz .LBB0_1012
	v_mov_b32_e32 v68, v0
	s_cmp_gt_i32 s8, 2
	s_cselect_b64 s[0:1], -1, 0
	v_readfirstlane_b32 s9, v68
	s_ashr_i32 s19, s18, 31
	s_lshl_b64 s[16:17], s[18:19], 8
	s_ashr_i32 s18, s9, 2
	s_andn2_b32 s18, s18, 63
	s_ashr_i32 s19, s18, 31
	s_add_u32 s18, s16, s18
	v_bfe_u32 v174, v68, 4, 2
	s_addc_u32 s19, s17, s19
	v_and_or_b32 v172, v68, 15, s18
	v_mov_b32_e32 v173, s19
	v_lshlrev_b32_e32 v179, 3, v174
	s_and_b64 vcc, exec, s[0:1]
	s_cbranch_vccnz .LBB0_1015
	v_mov_b64_e32 v[68:69], s[6:7]
	s_movk_i32 s20, 0x240
	v_mad_u64_u32 v[68:69], s[16:17], v172, s20, v[68:69]
	v_mov_b32_e32 v70, v69
	v_mad_u64_u32 v[70:71], s[16:17], v173, s20, v[70:71]
	v_mov_b32_e32 v69, v70
	v_lshlrev_b32_e32 v70, 1, v179
	v_mov_b32_e32 v71, v2
	v_lshl_add_u64 v[68:69], v[68:69], 0, v[70:71]
	v_add_co_u32_e32 v70, vcc, 0x2000, v68
	s_movk_i32 s16, 0x4000
	s_nop 0
	v_addc_co_u32_e32 v71, vcc, 0, v69, vcc
	global_load_dwordx4 v[160:163], v[68:69], off offset:512
	global_load_dwordx4 v[156:159], v[70:71], off offset:1536
	v_add_co_u32_e32 v70, vcc, s16, v68
	s_nop 1
	v_addc_co_u32_e32 v71, vcc, 0, v69, vcc
	v_add_co_u32_e32 v88, vcc, 0x6000, v68
	s_nop 1
	v_addc_co_u32_e32 v89, vcc, 0, v69, vcc
	global_load_dwordx4 v[152:155], v[70:71], off offset:2560
	global_load_dwordx4 v[148:151], v[88:89], off offset:3584
	v_add_co_u32_e32 v70, vcc, 0x12000, v68
	s_nop 1
	v_addc_co_u32_e32 v71, vcc, 0, v69, vcc
	v_add_co_u32_e32 v88, vcc, 0x14000, v68
	s_nop 1
	v_addc_co_u32_e32 v89, vcc, 0, v69, vcc
	global_load_dwordx4 v[128:131], v[70:71], off offset:512
	global_load_dwordx4 v[108:111], v[88:89], off offset:1536
	v_add_co_u32_e32 v70, vcc, 0x16000, v68
	s_nop 1
	v_addc_co_u32_e32 v71, vcc, 0, v69, vcc
	v_add_co_u32_e32 v68, vcc, 0x18000, v68
	s_nop 1
	v_addc_co_u32_e32 v69, vcc, 0, v69, vcc
	global_load_dwordx4 v[88:91], v[70:71], off offset:2560
	s_nop 0
	global_load_dwordx4 v[68:71], v[68:69], off offset:3584

.LBB0_1764:
	s_ashr_i32 s41, s40, 31
	v_cmp_lt_i64_e32 vcc, s[14:15], v[202:203]
	s_lshl_b64 s[14:15], s[40:41], 19
	s_add_u32 s42, s52, s14
	s_addc_u32 s43, s53, s15
	s_and_b64 s[14:15], vcc, exec
	s_cselect_b32 s41, s43, s1
	s_cselect_b32 s65, s42, s0
	s_ashr_i32 s39, s38, 31
	s_lshl_b64 s[14:15], s[38:39], 19
	s_add_u32 s44, s54, s14
	s_addc_u32 s45, s55, s15
	s_and_b64 s[14:15], vcc, exec
	s_cselect_b32 s39, s45, s9
	s_cselect_b32 s67, s44, s8
	s_add_u32 s68, s8, 0x100
	v_mov_b32_e32 v4, 0
	s_addc_u32 s79, s9, 0
	s_mov_b32 s80, -2
	v_mov_b32_e32 v5, v4
	v_mov_b32_e32 v6, v4
	v_mov_b32_e32 v7, v4
	v_mov_b32_e32 v8, v4
	v_mov_b32_e32 v9, v4
	v_mov_b32_e32 v10, v4
	v_mov_b32_e32 v11, v4
	v_mov_b32_e32 v20, v4
	v_mov_b32_e32 v21, v4
	v_mov_b32_e32 v22, v4
	v_mov_b32_e32 v23, v4
	v_mov_b32_e32 v24, v4
	v_mov_b32_e32 v25, v4
	v_mov_b32_e32 v26, v4
	v_mov_b32_e32 v27, v4
	v_mov_b32_e32 v36, v4
	v_mov_b32_e32 v37, v4
	v_mov_b32_e32 v38, v4
	v_mov_b32_e32 v39, v4
	v_mov_b32_e32 v40, v4
	v_mov_b32_e32 v41, v4
	v_mov_b32_e32 v42, v4
	v_mov_b32_e32 v43, v4
	s_waitcnt vmcnt(0)
	v_mov_b32_e32 v52, v4
	v_mov_b32_e32 v53, v4
	v_mov_b32_e32 v54, v4
	v_mov_b32_e32 v55, v4
	v_mov_b32_e32 v56, v4
	v_mov_b32_e32 v57, v4
	v_mov_b32_e32 v58, v4
	v_mov_b32_e32 v59, v4
	v_mov_b32_e32 v12, v4
	v_mov_b32_e32 v13, v4
	v_mov_b32_e32 v14, v4
	v_mov_b32_e32 v15, v4
	v_mov_b32_e32 v16, v4
	v_mov_b32_e32 v17, v4
	v_mov_b32_e32 v18, v4
	v_mov_b32_e32 v19, v4
	v_mov_b32_e32 v28, v4
	v_mov_b32_e32 v29, v4
	v_mov_b32_e32 v30, v4
	v_mov_b32_e32 v31, v4
	v_mov_b32_e32 v32, v4
	v_mov_b32_e32 v33, v4
	v_mov_b32_e32 v34, v4
	v_mov_b32_e32 v35, v4
	v_mov_b32_e32 v44, v4
	v_mov_b32_e32 v45, v4
	v_mov_b32_e32 v46, v4
	v_mov_b32_e32 v47, v4
	v_mov_b32_e32 v48, v4
	v_mov_b32_e32 v49, v4
	v_mov_b32_e32 v50, v4
	v_mov_b32_e32 v51, v4
	v_mov_b32_e32 v60, v4
	v_mov_b32_e32 v61, v4
	v_mov_b32_e32 v62, v4
	v_mov_b32_e32 v63, v4
	v_mov_b32_e32 v64, v4
	v_mov_b32_e32 v65, v4
	v_mov_b32_e32 v66, v4
	v_mov_b32_e32 v67, v4
	v_mov_b32_e32 v68, v4
	v_mov_b32_e32 v69, v4
	v_mov_b32_e32 v70, v4
	v_mov_b32_e32 v71, v4
	v_mov_b32_e32 v72, v4
	v_mov_b32_e32 v73, v4
	v_mov_b32_e32 v74, v4
	v_mov_b32_e32 v75, v4
	v_mov_b32_e32 v84, v4
	v_mov_b32_e32 v85, v4
	v_mov_b32_e32 v86, v4
	v_mov_b32_e32 v87, v4
	v_mov_b32_e32 v88, v4
	v_mov_b32_e32 v89, v4
	v_mov_b32_e32 v90, v4
	v_mov_b32_e32 v91, v4
	v_mov_b32_e32 v100, v4
	v_mov_b32_e32 v101, v4
	v_mov_b32_e32 v102, v4
	v_mov_b32_e32 v103, v4
	v_mov_b32_e32 v104, v4
	v_mov_b32_e32 v105, v4
	v_mov_b32_e32 v106, v4
	v_mov_b32_e32 v107, v4
	v_mov_b32_e32 v116, v4
	v_mov_b32_e32 v117, v4
	v_mov_b32_e32 v118, v4
	v_mov_b32_e32 v119, v4
	v_mov_b32_e32 v120, v4
	v_mov_b32_e32 v121, v4
	v_mov_b32_e32 v122, v4
	v_mov_b32_e32 v123, v4
	v_mov_b32_e32 v76, v4
	v_mov_b32_e32 v77, v4
	v_mov_b32_e32 v78, v4
	v_mov_b32_e32 v79, v4
	v_mov_b32_e32 v80, v4
	v_mov_b32_e32 v81, v4
	v_mov_b32_e32 v82, v4
	v_mov_b32_e32 v83, v4
	v_mov_b32_e32 v92, v4
	v_mov_b32_e32 v93, v4
	v_mov_b32_e32 v94, v4
	v_mov_b32_e32 v95, v4
	v_mov_b32_e32 v96, v4
	v_mov_b32_e32 v97, v4
	v_mov_b32_e32 v98, v4
	v_mov_b32_e32 v99, v4
	v_mov_b32_e32 v108, v4
	v_mov_b32_e32 v109, v4
	v_mov_b32_e32 v110, v4
	v_mov_b32_e32 v111, v4
	v_mov_b32_e32 v112, v4
	v_mov_b32_e32 v113, v4
	v_mov_b32_e32 v114, v4
	v_mov_b32_e32 v115, v4
	v_mov_b32_e32 v124, v4
	v_mov_b32_e32 v125, v4
	v_mov_b32_e32 v126, v4
	v_mov_b32_e32 v127, v4
	v_mov_b32_e32 v128, v4
	v_mov_b32_e32 v129, v4
	v_mov_b32_e32 v130, v4
	v_mov_b32_e32 v131, v4
	v_add_u32_e32 v216, 0x10000, v1
.LBB0_1765:
	s_add_u32 s8, s0, 0x100
	s_addc_u32 s9, s1, 0
	s_cmp_eq_u32 s80, 12
	s_cselect_b32 s46, s65, s8
	s_cselect_b32 s47, s41, s9
	s_cselect_b32 s14, s67, s68
	s_cselect_b32 s15, s39, s79
	s_add_u32 s18, s46, 0x80
	s_addc_u32 s19, s47, 0
	s_add_i32 s81, 0, 0x10000
	ds_read_b128 v[132:135], v216
	ds_read_b128 v[140:143], v216 offset:1024
	ds_read_b128 v[144:147], v216 offset:2048
	ds_read_b128 v[148:151], v216 offset:3072
	s_add_u32 s0, s0, 0x40080
	s_addc_u32 s1, s1, 0
	ds_read_b128 v[152:155], v3
	ds_read_b128 v[156:159], v3 offset:1024
	ds_read_b128 v[160:163], v3 offset:2048
	ds_read_b128 v[164:167], v3 offset:3072
	ds_read_b128 v[168:171], v3 offset:4096
	ds_read_b128 v[172:175], v3 offset:5120
	ds_read_b128 v[176:179], v3 offset:6144
	ds_read_b128 v[180:183], v3 offset:7168
	s_add_i32 m0, s57, 0xc000
	s_nop 0
	global_load_lds_dwordx4 v138, s[0:1]
	s_add_i32 m0, s57, 0xe000
	s_nop 0
	global_load_lds_dwordx4 v136, s[0:1]
	s_waitcnt lgkmcnt(8)
	s_barrier
	s_waitcnt lgkmcnt(0)
	s_setprio 1
	s_waitcnt lgkmcnt(0)
	v_mfma_f32_16x16x32_bf16 v[128:131], v[132:135], v[152:155], v[128:131]
	v_mfma_f32_16x16x32_bf16 v[124:127], v[144:147], v[152:155], v[124:127]
	v_mfma_f32_16x16x32_bf16 v[112:115], v[132:135], v[160:163], v[112:115]
	v_mfma_f32_16x16x32_bf16 v[108:111], v[144:147], v[160:163], v[108:111]
	v_mfma_f32_16x16x32_bf16 v[96:99], v[132:135], v[168:171], v[96:99]
	v_mfma_f32_16x16x32_bf16 v[92:95], v[144:147], v[168:171], v[92:95]
	v_mfma_f32_16x16x32_bf16 v[80:83], v[132:135], v[176:179], v[80:83]
	v_mfma_f32_16x16x32_bf16 v[76:79], v[144:147], v[176:179], v[76:79]
	v_mfma_f32_16x16x32_bf16 v[128:131], v[140:143], v[156:159], v[128:131]
	v_mfma_f32_16x16x32_bf16 v[124:127], v[148:151], v[156:159], v[124:127]
	v_mfma_f32_16x16x32_bf16 v[112:115], v[140:143], v[164:167], v[112:115]
	v_mfma_f32_16x16x32_bf16 v[108:111], v[148:151], v[164:167], v[108:111]
	v_mfma_f32_16x16x32_bf16 v[96:99], v[140:143], v[172:175], v[96:99]
	v_mfma_f32_16x16x32_bf16 v[92:95], v[148:151], v[172:175], v[92:95]
	v_mfma_f32_16x16x32_bf16 v[80:83], v[140:143], v[180:183], v[80:83]
	v_mfma_f32_16x16x32_bf16 v[76:79], v[148:151], v[180:183], v[76:79]
	s_setprio 0
	s_barrier
	s_add_i32 s82, 0, 0x14000
	s_mov_b64 s[0:1], s[14:15]
	s_add_i32 s81, s81, s56
	ds_read_b128 v[184:187], v216 offset:16384
	ds_read_b128 v[188:191], v216 offset:17408
	ds_read_b128 v[192:195], v216 offset:18432
	ds_read_b128 v[210:213], v216 offset:19456
	s_mov_b32 m0, s81
	s_nop 0
	global_load_lds_dwordx4 v138, s[0:1]
	s_add_i32 m0, s81, 0x2000
	s_nop 0
	global_load_lds_dwordx4 v136, s[0:1]
	s_barrier
	s_waitcnt lgkmcnt(0)
	s_setprio 1
	s_waitcnt lgkmcnt(0)
	v_mfma_f32_16x16x32_bf16 v[120:123], v[184:187], v[152:155], v[120:123]
	v_mfma_f32_16x16x32_bf16 v[116:119], v[192:195], v[152:155], v[116:119]
	v_mfma_f32_16x16x32_bf16 v[104:107], v[184:187], v[160:163], v[104:107]
	v_mfma_f32_16x16x32_bf16 v[100:103], v[192:195], v[160:163], v[100:103]
	v_mfma_f32_16x16x32_bf16 v[88:91], v[184:187], v[168:171], v[88:91]
	v_mfma_f32_16x16x32_bf16 v[84:87], v[192:195], v[168:171], v[84:87]
	v_mfma_f32_16x16x32_bf16 v[72:75], v[184:187], v[176:179], v[72:75]
	v_mfma_f32_16x16x32_bf16 v[68:71], v[192:195], v[176:179], v[68:71]
	v_mfma_f32_16x16x32_bf16 v[120:123], v[188:191], v[156:159], v[120:123]
	v_mfma_f32_16x16x32_bf16 v[116:119], v[210:213], v[156:159], v[116:119]
	v_mfma_f32_16x16x32_bf16 v[104:107], v[188:191], v[164:167], v[104:107]
	v_mfma_f32_16x16x32_bf16 v[100:103], v[210:213], v[164:167], v[100:103]
	v_mfma_f32_16x16x32_bf16 v[88:91], v[188:191], v[172:175], v[88:91]
	v_mfma_f32_16x16x32_bf16 v[84:87], v[210:213], v[172:175], v[84:87]
	v_mfma_f32_16x16x32_bf16 v[72:75], v[188:191], v[180:183], v[72:75]
	v_mfma_f32_16x16x32_bf16 v[68:71], v[210:213], v[180:183], v[68:71]
	s_setprio 0
	s_mov_b64 s[0:1], s[46:47]
	s_mov_b32 m0, s57
	s_barrier
	ds_read_b128 v[152:155], v3 offset:16384
	ds_read_b128 v[156:159], v3 offset:17408
	ds_read_b128 v[160:163], v3 offset:18432
	ds_read_b128 v[164:167], v3 offset:19456
	ds_read_b128 v[168:171], v3 offset:20480
	ds_read_b128 v[172:175], v3 offset:21504
	ds_read_b128 v[176:179], v3 offset:22528
	ds_read_b128 v[180:183], v3 offset:23552
	s_nop 0
	global_load_lds_dwordx4 v138, s[0:1]
	s_mov_b32 m0, s62
	s_nop 0
	global_load_lds_dwordx4 v136, s[0:1]
	s_barrier
	s_waitcnt lgkmcnt(0)
	s_setprio 1
	s_waitcnt lgkmcnt(0)
	v_mfma_f32_16x16x32_bf16 v[64:67], v[132:135], v[152:155], v[64:67]
	v_mfma_f32_16x16x32_bf16 v[60:63], v[144:147], v[152:155], v[60:63]
	v_mfma_f32_16x16x32_bf16 v[48:51], v[132:135], v[160:163], v[48:51]
	v_mfma_f32_16x16x32_bf16 v[44:47], v[144:147], v[160:163], v[44:47]
	v_mfma_f32_16x16x32_bf16 v[32:35], v[132:135], v[168:171], v[32:35]
	v_mfma_f32_16x16x32_bf16 v[28:31], v[144:147], v[168:171], v[28:31]
	v_mfma_f32_16x16x32_bf16 v[16:19], v[132:135], v[176:179], v[16:19]
	v_mfma_f32_16x16x32_bf16 v[12:15], v[144:147], v[176:179], v[12:15]
	v_mfma_f32_16x16x32_bf16 v[64:67], v[140:143], v[156:159], v[64:67]
	v_mfma_f32_16x16x32_bf16 v[60:63], v[148:151], v[156:159], v[60:63]
	v_mfma_f32_16x16x32_bf16 v[48:51], v[140:143], v[164:167], v[48:51]
	v_mfma_f32_16x16x32_bf16 v[44:47], v[148:151], v[164:167], v[44:47]
	v_mfma_f32_16x16x32_bf16 v[32:35], v[140:143], v[172:175], v[32:35]
	v_mfma_f32_16x16x32_bf16 v[28:31], v[148:151], v[172:175], v[28:31]
	v_mfma_f32_16x16x32_bf16 v[16:19], v[140:143], v[180:183], v[16:19]
	v_mfma_f32_16x16x32_bf16 v[12:15], v[148:151], v[180:183], v[12:15]
	s_setprio 0
	s_barrier
	s_add_u32 s0, s14, 0x40000
	s_addc_u32 s1, s15, 0
	s_add_i32 s81, s82, s56
	s_mov_b32 m0, s81
	s_nop 0
	global_load_lds_dwordx4 v138, s[0:1]
	s_add_i32 m0, s81, 0x2000
	s_nop 0
	global_load_lds_dwordx4 v136, s[0:1]
	s_waitcnt vmcnt(6)
	s_barrier
	s_setprio 1
	v_mfma_f32_16x16x32_bf16 v[56:59], v[184:187], v[152:155], v[56:59]
	v_mfma_f32_16x16x32_bf16 v[52:55], v[192:195], v[152:155], v[52:55]
	v_mfma_f32_16x16x32_bf16 v[40:43], v[184:187], v[160:163], v[40:43]
	v_mfma_f32_16x16x32_bf16 v[36:39], v[192:195], v[160:163], v[36:39]
	v_mfma_f32_16x16x32_bf16 v[24:27], v[184:187], v[168:171], v[24:27]
	v_mfma_f32_16x16x32_bf16 v[20:23], v[192:195], v[168:171], v[20:23]
	v_mfma_f32_16x16x32_bf16 v[8:11], v[184:187], v[176:179], v[8:11]
	v_mfma_f32_16x16x32_bf16 v[4:7], v[192:195], v[176:179], v[4:7]
	v_mfma_f32_16x16x32_bf16 v[56:59], v[188:191], v[156:159], v[56:59]
	v_mfma_f32_16x16x32_bf16 v[52:55], v[210:213], v[156:159], v[52:55]
	v_mfma_f32_16x16x32_bf16 v[40:43], v[188:191], v[164:167], v[40:43]
	v_mfma_f32_16x16x32_bf16 v[36:39], v[210:213], v[164:167], v[36:39]
	v_mfma_f32_16x16x32_bf16 v[24:27], v[188:191], v[172:175], v[24:27]
	v_mfma_f32_16x16x32_bf16 v[20:23], v[210:213], v[172:175], v[20:23]
	v_mfma_f32_16x16x32_bf16 v[8:11], v[188:191], v[180:183], v[8:11]
	v_mfma_f32_16x16x32_bf16 v[4:7], v[210:213], v[180:183], v[4:7]
	s_setprio 0
	s_add_i32 s81, 0, 0x18000
	s_barrier
	ds_read_b128 v[132:135], v216 offset:32768
	ds_read_b128 v[140:143], v216 offset:33792
	ds_read_b128 v[144:147], v216 offset:34816
	ds_read_b128 v[148:151], v216 offset:35840
	s_add_u32 s0, s46, 0x40000
	s_addc_u32 s1, s47, 0
	s_mov_b32 m0, s63
	ds_read_b128 v[152:155], v3 offset:32768
	ds_read_b128 v[156:159], v3 offset:33792
	ds_read_b128 v[160:163], v3 offset:34816
	ds_read_b128 v[164:167], v3 offset:35840
	ds_read_b128 v[168:171], v3 offset:36864
	ds_read_b128 v[172:175], v3 offset:37888
	ds_read_b128 v[176:179], v3 offset:38912
	ds_read_b128 v[180:183], v3 offset:39936
	s_nop 0
	global_load_lds_dwordx4 v138, s[0:1]
	s_mov_b32 m0, s72
	s_nop 0
	global_load_lds_dwordx4 v136, s[0:1]
	s_waitcnt lgkmcnt(8)
	s_barrier
	s_waitcnt lgkmcnt(0)
	s_setprio 1
	s_waitcnt lgkmcnt(0)
	v_mfma_f32_16x16x32_bf16 v[128:131], v[132:135], v[152:155], v[128:131]
	v_mfma_f32_16x16x32_bf16 v[124:127], v[144:147], v[152:155], v[124:127]
	v_mfma_f32_16x16x32_bf16 v[112:115], v[132:135], v[160:163], v[112:115]
	v_mfma_f32_16x16x32_bf16 v[108:111], v[144:147], v[160:163], v[108:111]
	v_mfma_f32_16x16x32_bf16 v[96:99], v[132:135], v[168:171], v[96:99]
	v_mfma_f32_16x16x32_bf16 v[92:95], v[144:147], v[168:171], v[92:95]
	v_mfma_f32_16x16x32_bf16 v[80:83], v[132:135], v[176:179], v[80:83]
	v_mfma_f32_16x16x32_bf16 v[76:79], v[144:147], v[176:179], v[76:79]
	v_mfma_f32_16x16x32_bf16 v[128:131], v[140:143], v[156:159], v[128:131]
	v_mfma_f32_16x16x32_bf16 v[124:127], v[148:151], v[156:159], v[124:127]
	v_mfma_f32_16x16x32_bf16 v[112:115], v[140:143], v[164:167], v[112:115]
	v_mfma_f32_16x16x32_bf16 v[108:111], v[148:151], v[164:167], v[108:111]
	v_mfma_f32_16x16x32_bf16 v[96:99], v[140:143], v[172:175], v[96:99]
	v_mfma_f32_16x16x32_bf16 v[92:95], v[148:151], v[172:175], v[92:95]
	v_mfma_f32_16x16x32_bf16 v[80:83], v[140:143], v[180:183], v[80:83]
	v_mfma_f32_16x16x32_bf16 v[76:79], v[148:151], v[180:183], v[76:79]
	s_setprio 0
	s_barrier
	s_add_i32 s46, 0, 0x1c000
	s_add_u32 s0, s14, 0x80
	s_addc_u32 s1, s15, 0
	s_add_i32 s47, s81, s56
	ds_read_b128 v[184:187], v216 offset:49152
	ds_read_b128 v[188:191], v216 offset:50176
	ds_read_b128 v[192:195], v216 offset:51200
	ds_read_b128 v[210:213], v216 offset:52224
	s_mov_b32 m0, s47
	s_nop 0
	global_load_lds_dwordx4 v138, s[0:1]
	s_add_i32 m0, s47, 0x2000
	s_nop 0
	global_load_lds_dwordx4 v136, s[0:1]
	s_barrier
	s_waitcnt lgkmcnt(0)
	s_setprio 1
	s_waitcnt lgkmcnt(0)
	v_mfma_f32_16x16x32_bf16 v[120:123], v[184:187], v[152:155], v[120:123]
	v_mfma_f32_16x16x32_bf16 v[116:119], v[192:195], v[152:155], v[116:119]
	v_mfma_f32_16x16x32_bf16 v[104:107], v[184:187], v[160:163], v[104:107]
	v_mfma_f32_16x16x32_bf16 v[100:103], v[192:195], v[160:163], v[100:103]
	v_mfma_f32_16x16x32_bf16 v[88:91], v[184:187], v[168:171], v[88:91]
	v_mfma_f32_16x16x32_bf16 v[84:87], v[192:195], v[168:171], v[84:87]
	v_mfma_f32_16x16x32_bf16 v[72:75], v[184:187], v[176:179], v[72:75]
	v_mfma_f32_16x16x32_bf16 v[68:71], v[192:195], v[176:179], v[68:71]
	v_mfma_f32_16x16x32_bf16 v[120:123], v[188:191], v[156:159], v[120:123]
	v_mfma_f32_16x16x32_bf16 v[116:119], v[210:213], v[156:159], v[116:119]
	v_mfma_f32_16x16x32_bf16 v[104:107], v[188:191], v[164:167], v[104:107]
	v_mfma_f32_16x16x32_bf16 v[100:103], v[210:213], v[164:167], v[100:103]
	v_mfma_f32_16x16x32_bf16 v[88:91], v[188:191], v[172:175], v[88:91]
	v_mfma_f32_16x16x32_bf16 v[84:87], v[210:213], v[172:175], v[84:87]
	v_mfma_f32_16x16x32_bf16 v[72:75], v[188:191], v[180:183], v[72:75]
	v_mfma_f32_16x16x32_bf16 v[68:71], v[210:213], v[180:183], v[68:71]
	s_setprio 0
	s_mov_b32 m0, s73
	s_barrier
	ds_read_b128 v[152:155], v3 offset:49152
	ds_read_b128 v[156:159], v3 offset:50176
	ds_read_b128 v[160:163], v3 offset:51200
	ds_read_b128 v[164:167], v3 offset:52224
	ds_read_b128 v[168:171], v3 offset:53248
	ds_read_b128 v[172:175], v3 offset:54272
	ds_read_b128 v[176:179], v3 offset:55296
	ds_read_b128 v[180:183], v3 offset:56320
	s_nop 0
	global_load_lds_dwordx4 v138, s[18:19]
	s_mov_b32 m0, s74
	s_nop 0
	global_load_lds_dwordx4 v136, s[18:19]
	s_barrier
	s_waitcnt lgkmcnt(0)
	s_setprio 1
	s_waitcnt lgkmcnt(0)
	v_mfma_f32_16x16x32_bf16 v[64:67], v[132:135], v[152:155], v[64:67]
	v_mfma_f32_16x16x32_bf16 v[60:63], v[144:147], v[152:155], v[60:63]
	v_mfma_f32_16x16x32_bf16 v[48:51], v[132:135], v[160:163], v[48:51]
	v_mfma_f32_16x16x32_bf16 v[44:47], v[144:147], v[160:163], v[44:47]
	v_mfma_f32_16x16x32_bf16 v[32:35], v[132:135], v[168:171], v[32:35]
	v_mfma_f32_16x16x32_bf16 v[28:31], v[144:147], v[168:171], v[28:31]
	v_mfma_f32_16x16x32_bf16 v[16:19], v[132:135], v[176:179], v[16:19]
	v_mfma_f32_16x16x32_bf16 v[12:15], v[144:147], v[176:179], v[12:15]
	v_mfma_f32_16x16x32_bf16 v[64:67], v[140:143], v[156:159], v[64:67]
	v_mfma_f32_16x16x32_bf16 v[60:63], v[148:151], v[156:159], v[60:63]
	v_mfma_f32_16x16x32_bf16 v[48:51], v[140:143], v[164:167], v[48:51]
	v_mfma_f32_16x16x32_bf16 v[44:47], v[148:151], v[164:167], v[44:47]
	v_mfma_f32_16x16x32_bf16 v[32:35], v[140:143], v[172:175], v[32:35]
	v_mfma_f32_16x16x32_bf16 v[28:31], v[148:151], v[172:175], v[28:31]
	v_mfma_f32_16x16x32_bf16 v[16:19], v[140:143], v[180:183], v[16:19]
	v_mfma_f32_16x16x32_bf16 v[12:15], v[148:151], v[180:183], v[12:15]
	s_setprio 0
	s_barrier
	s_add_u32 s0, s14, 0x40080
	s_addc_u32 s1, s15, 0
	s_add_i32 s14, s46, s56
	s_mov_b32 m0, s14
	s_nop 0
	global_load_lds_dwordx4 v138, s[0:1]
	s_add_i32 m0, s14, 0x2000
	s_nop 0
	global_load_lds_dwordx4 v136, s[0:1]
	s_waitcnt vmcnt(6)
	s_barrier
	s_setprio 1
	v_mfma_f32_16x16x32_bf16 v[56:59], v[184:187], v[152:155], v[56:59]
	v_mfma_f32_16x16x32_bf16 v[52:55], v[192:195], v[152:155], v[52:55]
	v_mfma_f32_16x16x32_bf16 v[40:43], v[184:187], v[160:163], v[40:43]
	v_mfma_f32_16x16x32_bf16 v[36:39], v[192:195], v[160:163], v[36:39]
	v_mfma_f32_16x16x32_bf16 v[24:27], v[184:187], v[168:171], v[24:27]
	v_mfma_f32_16x16x32_bf16 v[20:23], v[192:195], v[168:171], v[20:23]
	v_mfma_f32_16x16x32_bf16 v[8:11], v[184:187], v[176:179], v[8:11]
	v_mfma_f32_16x16x32_bf16 v[4:7], v[192:195], v[176:179], v[4:7]
	v_mfma_f32_16x16x32_bf16 v[56:59], v[188:191], v[156:159], v[56:59]
	v_mfma_f32_16x16x32_bf16 v[52:55], v[210:213], v[156:159], v[52:55]
	v_mfma_f32_16x16x32_bf16 v[40:43], v[188:191], v[164:167], v[40:43]
	v_mfma_f32_16x16x32_bf16 v[36:39], v[210:213], v[164:167], v[36:39]
	v_mfma_f32_16x16x32_bf16 v[24:27], v[188:191], v[172:175], v[24:27]
	v_mfma_f32_16x16x32_bf16 v[20:23], v[210:213], v[172:175], v[20:23]
	v_mfma_f32_16x16x32_bf16 v[8:11], v[188:191], v[180:183], v[8:11]
	v_mfma_f32_16x16x32_bf16 v[4:7], v[210:213], v[180:183], v[4:7]
	s_setprio 0
	s_add_i32 s80, s80, 2
	s_add_u32 s68, s68, 0x100
	s_addc_u32 s79, s79, 0
	s_cmp_gt_u32 s80, 13
	s_mov_b64 s[0:1], s[8:9]
	s_barrier
	s_cbranch_scc0 .LBB0_1765
	v_mov_b32_e32 v145, v0
	s_lshl_b32 s1, s64, 8
	v_readfirstlane_b32 s0, v145
	s_and_b32 s14, s0, 0xc0
	s_ashr_i32 s0, s0, 2
	v_and_b32_e32 v170, 15, v145
	s_and_b32 s15, s0, 0xffffffc0
	v_or_b32_e32 v132, s15, v170
	v_add_u32_e32 v132, s1, v132
	v_ashrrev_i32_e32 v133, 31, v132
	v_lshl_add_u64 v[132:133], v[132:133], 2, s[20:21]
	global_load_dword v134, v[132:133], off
	global_load_dword v174, v[132:133], off offset:64
	global_load_dword v173, v[132:133], off offset:128
	global_load_dword v172, v[132:133], off offset:192
	global_load_dword v171, v[132:133], off offset:512
	global_load_dword v169, v[132:133], off offset:576
	global_load_dword v168, v[132:133], off offset:640
	global_load_dword v167, v[132:133], off offset:704
	s_add_i32 s15, s15, s1
	s_cmp_gt_i32 s78, 2
	s_cselect_b64 s[0:1], -1, 0
	v_or_b32_e32 v142, s15, v170
	s_mov_b64 s[8:9], -1
	s_waitcnt vmcnt(0)
	v_fmamk_f32 v132, v134, 0x3a800000, v231
	v_cmp_gt_f32_e32 vcc, s11, v132
	v_mul_f32_e32 v133, 0x4b800000, v132
	s_nop 0
	v_cndmask_b32_e32 v132, v132, v133, vcc
	v_rsq_f32_e32 v132, v132
	s_nop 0
	v_mul_f32_e32 v133, 0x45800000, v132
	v_cndmask_b32_e32 v144, v132, v133, vcc
	v_lshrrev_b32_e32 v132, 1, v145
	v_and_b32_e32 v155, 24, v132
	s_and_b64 vcc, exec, s[0:1]
	v_lshlrev_b32_e32 v166, 2, v155
	v_lshlrev_b32_e32 v140, 1, v155
	s_cbranch_vccz .LBB0_1768
	v_ashrrev_i32_e32 v143, 31, v142
	v_lshlrev_b64 v[132:133], 9, v[142:143]
	v_lshl_add_u64 v[132:133], s[24:25], 0, v[132:133]
	s_lshl_b32 s68, s14, 1
	v_pk_mul_f32 v[160:161], v[130:131], v[144:145] op_sel_hi:[1,0]
	v_pk_mul_f32 v[162:163], v[128:129], v[144:145] op_sel_hi:[1,0]
	v_lshl_add_u64 v[164:165], v[132:133], 0, s[68:69]
	v_pk_mul_f32 v[132:133], v[160:161], v[160:161]
	v_pk_mul_f32 v[134:135], v[162:163], v[162:163]
	v_pk_mul_f32 v[156:157], v[126:127], v[144:145] op_sel_hi:[1,0]
	v_pk_mov_b32 v[146:147], v[134:135], v[132:133] op_sel:[1,0]
	v_mov_b32_e32 v135, v133
	v_pk_add_f32 v[132:133], v[146:147], v[134:135]
	v_pk_mul_f32 v[158:159], v[124:125], v[144:145] op_sel_hi:[1,0]
	v_pk_add_f32 v[132:133], v[132:133], v[132:133] op_sel_hi:[0,1]
	v_pk_mul_f32 v[134:135], v[156:157], v[156:157]
	v_pk_mul_f32 v[146:147], v[158:159], v[158:159]
	v_pk_mul_f32 v[152:153], v[120:121], v[144:145] op_sel_hi:[1,0]
	v_pk_mov_b32 v[148:149], v[146:147], v[134:135] op_sel:[1,0]
	v_mov_b32_e32 v147, v135
	v_pk_mul_f32 v[150:151], v[122:123], v[144:145] op_sel_hi:[1,0]
	v_mul_f32_e32 v132, v152, v152
	v_pk_add_f32 v[134:135], v[148:149], v[146:147]
	v_pk_fma_f32 v[176:177], v[152:153], v[152:153], v[132:133] op_sel_hi:[1,1,0]
	v_mul_f32_e32 v132, v150, v150
	v_pk_add_f32 v[134:135], v[134:135], v[134:135] op_sel_hi:[0,1]
	v_pk_fma_f32 v[178:179], v[150:151], v[150:151], v[132:133] op_sel_hi:[1,1,0]
	v_pk_mul_f32 v[146:147], v[118:119], v[144:145] op_sel_hi:[1,0]
	v_pk_mul_f32 v[148:149], v[116:117], v[144:145] op_sel_hi:[1,0]
	v_mul_f32_e32 v132, v146, v146
	v_mul_f32_e32 v176, v148, v148
	v_mul_f32_e32 v178, v149, v149
	v_mul_f32_e32 v134, v147, v147
	v_pk_add_f32 v[176:177], v[176:177], v[178:179]
	v_pk_add_f32 v[132:133], v[132:133], v[134:135]
	v_and_b32_e32 v134, 64, v236
	v_pk_add_f32 v[132:133], v[176:177], v[132:133]
	v_add_u32_e32 v134, 64, v134
	v_add_f32_e32 v132, v132, v133
	ds_swizzle_b32 v133, v132 offset:swizzle(SWAP,16)
	v_mov_b32_e32 v141, v2
	v_lshl_add_u64 v[164:165], v[164:165], 0, v[140:141]
	s_mov_b64 s[8:9], 0
	s_waitcnt lgkmcnt(0)
	v_add_f32_e32 v132, v132, v133
	v_xor_b32_e32 v133, 32, v236
	v_cmp_lt_i32_e32 vcc, v133, v134
	s_nop 1
	v_cndmask_b32_e32 v133, v236, v133, vcc
	v_lshlrev_b32_e32 v133, 2, v133
	ds_bpermute_b32 v133, v133, v132
	s_waitcnt lgkmcnt(0)
	v_add_f32_e32 v132, v132, v133
	v_fmamk_f32 v132, v132, 0x3c800000, v231
	v_cmp_gt_f32_e32 vcc, s11, v132
	v_mul_f32_e32 v133, 0x4b800000, v132
	s_nop 0
	v_cndmask_b32_e32 v132, v132, v133, vcc
	v_rsq_f32_e32 v132, v132
	s_nop 0
	v_mul_f32_e32 v133, 0x45800000, v132
	v_cndmask_b32_e32 v132, v132, v133, vcc
	v_mul_f32_e32 v154, 0x3e38aa3b, v132
	global_load_dwordx4 v[132:135], v166, s[26:27] offset:16
	global_load_dwordx4 v[176:179], v166, s[26:27]
	v_pk_mul_f32 v[162:163], v[162:163], v[154:155] op_sel_hi:[1,0]
	v_pk_mul_f32 v[160:161], v[160:161], v[154:155] op_sel_hi:[1,0]
	v_pk_mul_f32 v[158:159], v[158:159], v[154:155] op_sel_hi:[1,0]
	v_pk_mul_f32 v[156:157], v[156:157], v[154:155] op_sel_hi:[1,0]
	v_pk_mul_f32 v[152:153], v[152:153], v[154:155] op_sel_hi:[1,0]
	v_pk_mul_f32 v[150:151], v[150:151], v[154:155] op_sel_hi:[1,0]
	v_pk_mul_f32 v[148:149], v[148:149], v[154:155] op_sel_hi:[1,0]
	v_pk_mul_f32 v[146:147], v[146:147], v[154:155] op_sel_hi:[1,0]
	s_waitcnt vmcnt(1)
	v_pk_mul_f32 v[156:157], v[134:135], v[156:157]
	s_waitcnt vmcnt(0)
	v_pk_mul_f32 v[160:161], v[178:179], v[160:161]
	v_pk_mul_f32 v[162:163], v[176:177], v[162:163]
	v_pk_mul_f32 v[134:135], v[132:133], v[158:159]
	v_cvt_pk_bf16_f32 v132, v162, v163
	v_cvt_pk_bf16_f32 v133, v160, v161
	v_cvt_pk_bf16_f32 v134, v134, v135
	v_cvt_pk_bf16_f32 v135, v156, v157
	global_store_dwordx4 v[164:165], v[132:135], off
	global_load_dwordx4 v[132:135], v166, s[26:27] offset:144
	s_nop 0
	global_load_dwordx4 v[156:159], v166, s[26:27] offset:128
	s_waitcnt vmcnt(1)
	v_pk_mul_f32 v[146:147], v[134:135], v[146:147]
	s_waitcnt vmcnt(0)
	v_pk_mul_f32 v[150:151], v[158:159], v[150:151]
	v_pk_mul_f32 v[152:153], v[156:157], v[152:153]
	v_pk_mul_f32 v[134:135], v[132:133], v[148:149]
	v_cvt_pk_bf16_f32 v132, v152, v153
	v_cvt_pk_bf16_f32 v133, v150, v151
	v_cvt_pk_bf16_f32 v134, v134, v135
	v_cvt_pk_bf16_f32 v135, v146, v147
	global_store_dwordx4 v[164:165], v[132:135], off offset:64

.LBB0_1911:
	v_and_b32_e32 v3, 15, v1
	v_and_b32_e32 v4, 48, v1
	v_lshlrev_b32_e32 v3, 6, v3
	v_lshlrev_b32_e32 v1, 2, v1
	v_or_b32_e32 v5, v3, v4
	v_and_b32_e32 v1, 32, v1
	s_lshl_b32 s17, s17, 12
	s_lshl_b32 s16, s16, 13
	v_bitop3_b32 v3, v3, v1, v4 bitop3:0x36
	v_bitop3_b32 v6, v5, s16, v1 bitop3:0xde
	s_and_b32 s16, s17, 0x3000
	v_or_b32_e32 v1, s16, v3
	s_add_u32 s16, s14, 0x80
	v_mov_b32_e32 v133, v2
	s_addc_u32 s17, s15, 0
	s_waitcnt vmcnt(4)
	s_barrier
	s_add_i32 m0, s42, 0x18000
	v_lshl_add_u64 v[4:5], s[16:17], 0, v[132:133]
	v_mov_b32_e32 v135, v2
	global_load_lds_dwordx4 v[4:5], off
	s_add_i32 m0, s42, 0x1a000
	v_lshl_add_u64 v[4:5], s[16:17], 0, v[134:135]
	s_add_u32 s16, s24, 0x7bfdc80
	s_addc_u32 s17, s25, 0
	s_add_i32 s46, s42, 0x8000
	global_load_lds_dwordx4 v[4:5], off
	s_mov_b32 m0, s46
	v_lshl_add_u64 v[4:5], s[16:17], 0, v[132:133]
	s_add_i32 s47, s42, 0xa000
	global_load_lds_dwordx4 v[4:5], off
	v_lshl_add_u64 v[4:5], s[16:17], 0, v[134:135]
	s_add_u32 s16, s14, 0x40080
	s_mov_b32 m0, s47
	s_addc_u32 s17, s15, 0
	global_load_lds_dwordx4 v[4:5], off
	s_add_i32 m0, s42, 0x1c000
	v_lshl_add_u64 v[4:5], s[16:17], 0, v[132:133]
	global_load_lds_dwordx4 v[4:5], off
	v_lshl_add_u64 v[4:5], s[16:17], 0, v[134:135]
	s_add_i32 m0, s42, 0x1e000
	s_mov_b32 s51, -2
	global_load_lds_dwordx4 v[4:5], off
	s_waitcnt vmcnt(6)
	v_mov_b32_e32 v4, 0
	v_add_u32_e32 v3, 0, v6
	s_mov_b64 s[16:17], s[24:25]
	v_mov_b32_e32 v5, v4
	v_mov_b32_e32 v6, v4
	v_mov_b32_e32 v7, v4
	v_mov_b32_e32 v8, v4
	v_mov_b32_e32 v9, v4
	v_mov_b32_e32 v10, v4
	v_mov_b32_e32 v11, v4
	v_mov_b32_e32 v20, v4
	v_mov_b32_e32 v21, v4
	v_mov_b32_e32 v22, v4
	v_mov_b32_e32 v23, v4
	v_mov_b32_e32 v24, v4
	v_mov_b32_e32 v25, v4
	v_mov_b32_e32 v26, v4
	v_mov_b32_e32 v27, v4
	v_mov_b32_e32 v36, v4
	v_mov_b32_e32 v37, v4
	v_mov_b32_e32 v38, v4
	v_mov_b32_e32 v39, v4
	v_mov_b32_e32 v40, v4
	v_mov_b32_e32 v41, v4
	v_mov_b32_e32 v42, v4
	v_mov_b32_e32 v43, v4
	s_waitcnt vmcnt(0)
	v_mov_b32_e32 v52, v4
	v_mov_b32_e32 v53, v4
	v_mov_b32_e32 v54, v4
	v_mov_b32_e32 v55, v4
	v_mov_b32_e32 v56, v4
	v_mov_b32_e32 v57, v4
	v_mov_b32_e32 v58, v4
	v_mov_b32_e32 v59, v4
	v_mov_b32_e32 v12, v4
	v_mov_b32_e32 v13, v4
	v_mov_b32_e32 v14, v4
	v_mov_b32_e32 v15, v4
	v_mov_b32_e32 v16, v4
	v_mov_b32_e32 v17, v4
	v_mov_b32_e32 v18, v4
	v_mov_b32_e32 v19, v4
	v_mov_b32_e32 v28, v4
	v_mov_b32_e32 v29, v4
	v_mov_b32_e32 v30, v4
	v_mov_b32_e32 v31, v4
	v_mov_b32_e32 v32, v4
	v_mov_b32_e32 v33, v4
	v_mov_b32_e32 v34, v4
	v_mov_b32_e32 v35, v4
	v_mov_b32_e32 v44, v4
	v_mov_b32_e32 v45, v4
	v_mov_b32_e32 v46, v4
	v_mov_b32_e32 v47, v4
	v_mov_b32_e32 v48, v4
	v_mov_b32_e32 v49, v4
	v_mov_b32_e32 v50, v4
	v_mov_b32_e32 v51, v4
	v_mov_b32_e32 v60, v4
	v_mov_b32_e32 v61, v4
	v_mov_b32_e32 v62, v4
	v_mov_b32_e32 v63, v4
	v_mov_b32_e32 v64, v4
	v_mov_b32_e32 v65, v4
	v_mov_b32_e32 v66, v4
	v_mov_b32_e32 v67, v4
	v_mov_b32_e32 v68, v4
	v_mov_b32_e32 v69, v4
	v_mov_b32_e32 v70, v4
	v_mov_b32_e32 v71, v4
	v_mov_b32_e32 v72, v4
	v_mov_b32_e32 v73, v4
	v_mov_b32_e32 v74, v4
	v_mov_b32_e32 v75, v4
	v_mov_b32_e32 v84, v4
	v_mov_b32_e32 v85, v4
	v_mov_b32_e32 v86, v4
	v_mov_b32_e32 v87, v4
	v_mov_b32_e32 v88, v4
	v_mov_b32_e32 v89, v4
	v_mov_b32_e32 v90, v4
	v_mov_b32_e32 v91, v4
	v_mov_b32_e32 v100, v4
	v_mov_b32_e32 v101, v4
	v_mov_b32_e32 v102, v4
	v_mov_b32_e32 v103, v4
	v_mov_b32_e32 v104, v4
	v_mov_b32_e32 v105, v4
	v_mov_b32_e32 v106, v4
	v_mov_b32_e32 v107, v4
	v_mov_b32_e32 v116, v4
	v_mov_b32_e32 v117, v4
	v_mov_b32_e32 v118, v4
	v_mov_b32_e32 v119, v4
	v_mov_b32_e32 v120, v4
	v_mov_b32_e32 v121, v4
	v_mov_b32_e32 v122, v4
	v_mov_b32_e32 v123, v4
	v_mov_b32_e32 v76, v4
	v_mov_b32_e32 v77, v4
	v_mov_b32_e32 v78, v4
	v_mov_b32_e32 v79, v4
	v_mov_b32_e32 v80, v4
	v_mov_b32_e32 v81, v4
	v_mov_b32_e32 v82, v4
	v_mov_b32_e32 v83, v4
	v_mov_b32_e32 v92, v4
	v_mov_b32_e32 v93, v4
	v_mov_b32_e32 v94, v4
	v_mov_b32_e32 v95, v4
	v_mov_b32_e32 v96, v4
	v_mov_b32_e32 v97, v4
	v_mov_b32_e32 v98, v4
	v_mov_b32_e32 v99, v4
	v_mov_b32_e32 v108, v4
	v_mov_b32_e32 v109, v4
	v_mov_b32_e32 v110, v4
	v_mov_b32_e32 v111, v4
	v_mov_b32_e32 v112, v4
	v_mov_b32_e32 v113, v4
	v_mov_b32_e32 v114, v4
	v_mov_b32_e32 v115, v4
	v_mov_b32_e32 v124, v4
	v_mov_b32_e32 v125, v4
	v_mov_b32_e32 v126, v4
	v_mov_b32_e32 v127, v4
	v_mov_b32_e32 v128, v4
	v_mov_b32_e32 v129, v4
	v_mov_b32_e32 v130, v4
	v_mov_b32_e32 v131, v4
	v_add_u32_e32 v216, 0x10000, v1
	v_readlane_b32 s56, v255, 22
	v_readlane_b32 s57, v255, 21
	s_barrier
.LBB0_1912:
	s_add_u32 s18, s16, s56
	s_addc_u32 s19, s17, s57
	s_add_u32 s26, s16, 0x7bfdd00
	s_addc_u32 s27, s17, 0
	s_cmp_eq_u32 s51, 12
	s_cselect_b32 s18, s14, s18
	s_cselect_b32 s19, s15, s19
	s_cselect_b32 s38, s8, s26
	s_cselect_b32 s39, s9, s27
	s_add_u32 s28, s18, 0x80
	s_addc_u32 s29, s19, 0
	s_add_u32 s26, s38, 0x80
	s_addc_u32 s27, s39, 0
	s_add_i32 s54, 0, 0x10000
	ds_read_b128 v[136:139], v216
	ds_read_b128 v[140:143], v216 offset:1024
	ds_read_b128 v[144:147], v216 offset:2048
	ds_read_b128 v[148:151], v216 offset:3072
	s_add_u32 s52, s16, 0x7c3dc80
	s_addc_u32 s53, s17, 0
	ds_read_b128 v[152:155], v3
	ds_read_b128 v[156:159], v3 offset:1024
	ds_read_b128 v[160:163], v3 offset:2048
	ds_read_b128 v[164:167], v3 offset:3072
	ds_read_b128 v[168:171], v3 offset:4096
	ds_read_b128 v[172:175], v3 offset:5120
	ds_read_b128 v[176:179], v3 offset:6144
	ds_read_b128 v[180:183], v3 offset:7168
	s_add_i32 m0, s42, 0xc000
	s_nop 0
	global_load_lds_dwordx4 v132, s[52:53]
	s_add_i32 m0, s42, 0xe000
	s_nop 0
	global_load_lds_dwordx4 v134, s[52:53]
	s_waitcnt lgkmcnt(8)
	s_barrier
	s_waitcnt lgkmcnt(0)
	s_setprio 1
	s_waitcnt lgkmcnt(0)
	v_mfma_f32_16x16x32_bf16 v[128:131], v[136:139], v[152:155], v[128:131]
	v_mfma_f32_16x16x32_bf16 v[124:127], v[144:147], v[152:155], v[124:127]
	v_mfma_f32_16x16x32_bf16 v[112:115], v[136:139], v[160:163], v[112:115]
	v_mfma_f32_16x16x32_bf16 v[108:111], v[144:147], v[160:163], v[108:111]
	v_mfma_f32_16x16x32_bf16 v[96:99], v[136:139], v[168:171], v[96:99]
	v_mfma_f32_16x16x32_bf16 v[92:95], v[144:147], v[168:171], v[92:95]
	v_mfma_f32_16x16x32_bf16 v[80:83], v[136:139], v[176:179], v[80:83]
	v_mfma_f32_16x16x32_bf16 v[76:79], v[144:147], v[176:179], v[76:79]
	v_mfma_f32_16x16x32_bf16 v[128:131], v[140:143], v[156:159], v[128:131]
	v_mfma_f32_16x16x32_bf16 v[124:127], v[148:151], v[156:159], v[124:127]
	v_mfma_f32_16x16x32_bf16 v[112:115], v[140:143], v[164:167], v[112:115]
	v_mfma_f32_16x16x32_bf16 v[108:111], v[148:151], v[164:167], v[108:111]
	v_mfma_f32_16x16x32_bf16 v[96:99], v[140:143], v[172:175], v[96:99]
	v_mfma_f32_16x16x32_bf16 v[92:95], v[148:151], v[172:175], v[92:95]
	v_mfma_f32_16x16x32_bf16 v[80:83], v[140:143], v[180:183], v[80:83]
	v_mfma_f32_16x16x32_bf16 v[76:79], v[148:151], v[180:183], v[76:79]
	s_setprio 0
	s_barrier
	s_add_i32 s55, 0, 0x14000
	s_mov_b64 s[52:53], s[18:19]
	s_add_i32 s54, s54, s41
	ds_read_b128 v[184:187], v216 offset:16384
	ds_read_b128 v[188:191], v216 offset:17408
	ds_read_b128 v[192:195], v216 offset:18432
	ds_read_b128 v[210:213], v216 offset:19456
	s_mov_b32 m0, s54
	s_nop 0
	global_load_lds_dwordx4 v132, s[52:53]
	s_add_i32 m0, s54, 0x2000
	s_nop 0
	global_load_lds_dwordx4 v134, s[52:53]
	s_barrier
	s_waitcnt lgkmcnt(0)
	s_setprio 1
	s_waitcnt lgkmcnt(0)
	v_mfma_f32_16x16x32_bf16 v[120:123], v[184:187], v[152:155], v[120:123]
	v_mfma_f32_16x16x32_bf16 v[116:119], v[192:195], v[152:155], v[116:119]
	v_mfma_f32_16x16x32_bf16 v[104:107], v[184:187], v[160:163], v[104:107]
	v_mfma_f32_16x16x32_bf16 v[100:103], v[192:195], v[160:163], v[100:103]
	v_mfma_f32_16x16x32_bf16 v[88:91], v[184:187], v[168:171], v[88:91]
	v_mfma_f32_16x16x32_bf16 v[84:87], v[192:195], v[168:171], v[84:87]
	v_mfma_f32_16x16x32_bf16 v[72:75], v[184:187], v[176:179], v[72:75]
	v_mfma_f32_16x16x32_bf16 v[68:71], v[192:195], v[176:179], v[68:71]
	v_mfma_f32_16x16x32_bf16 v[120:123], v[188:191], v[156:159], v[120:123]
	v_mfma_f32_16x16x32_bf16 v[116:119], v[210:213], v[156:159], v[116:119]
	v_mfma_f32_16x16x32_bf16 v[104:107], v[188:191], v[164:167], v[104:107]
	v_mfma_f32_16x16x32_bf16 v[100:103], v[210:213], v[164:167], v[100:103]
	v_mfma_f32_16x16x32_bf16 v[88:91], v[188:191], v[172:175], v[88:91]
	v_mfma_f32_16x16x32_bf16 v[84:87], v[210:213], v[172:175], v[84:87]
	v_mfma_f32_16x16x32_bf16 v[72:75], v[188:191], v[180:183], v[72:75]
	v_mfma_f32_16x16x32_bf16 v[68:71], v[210:213], v[180:183], v[68:71]
	s_setprio 0
	s_mov_b64 s[52:53], s[38:39]
	s_mov_b32 m0, s42
	s_barrier
	ds_read_b128 v[152:155], v3 offset:16384
	ds_read_b128 v[156:159], v3 offset:17408
	ds_read_b128 v[160:163], v3 offset:18432
	ds_read_b128 v[164:167], v3 offset:19456
	ds_read_b128 v[168:171], v3 offset:20480
	ds_read_b128 v[172:175], v3 offset:21504
	ds_read_b128 v[176:179], v3 offset:22528
	ds_read_b128 v[180:183], v3 offset:23552
	s_nop 0
	global_load_lds_dwordx4 v132, s[52:53]
	s_mov_b32 m0, s43
	s_nop 0
	global_load_lds_dwordx4 v134, s[52:53]
	s_barrier
	s_waitcnt lgkmcnt(0)
	s_setprio 1
	s_waitcnt lgkmcnt(0)
	v_mfma_f32_16x16x32_bf16 v[64:67], v[136:139], v[152:155], v[64:67]
	v_mfma_f32_16x16x32_bf16 v[60:63], v[144:147], v[152:155], v[60:63]
	v_mfma_f32_16x16x32_bf16 v[48:51], v[136:139], v[160:163], v[48:51]
	v_mfma_f32_16x16x32_bf16 v[44:47], v[144:147], v[160:163], v[44:47]
	v_mfma_f32_16x16x32_bf16 v[32:35], v[136:139], v[168:171], v[32:35]
	v_mfma_f32_16x16x32_bf16 v[28:31], v[144:147], v[168:171], v[28:31]
	v_mfma_f32_16x16x32_bf16 v[16:19], v[136:139], v[176:179], v[16:19]
	v_mfma_f32_16x16x32_bf16 v[12:15], v[144:147], v[176:179], v[12:15]
	v_mfma_f32_16x16x32_bf16 v[64:67], v[140:143], v[156:159], v[64:67]
	v_mfma_f32_16x16x32_bf16 v[60:63], v[148:151], v[156:159], v[60:63]
	v_mfma_f32_16x16x32_bf16 v[48:51], v[140:143], v[164:167], v[48:51]
	v_mfma_f32_16x16x32_bf16 v[44:47], v[148:151], v[164:167], v[44:47]
	v_mfma_f32_16x16x32_bf16 v[32:35], v[140:143], v[172:175], v[32:35]
	v_mfma_f32_16x16x32_bf16 v[28:31], v[148:151], v[172:175], v[28:31]
	v_mfma_f32_16x16x32_bf16 v[16:19], v[140:143], v[180:183], v[16:19]
	v_mfma_f32_16x16x32_bf16 v[12:15], v[148:151], v[180:183], v[12:15]
	s_setprio 0
	s_barrier
	s_add_u32 s52, s18, 0x40000
	s_addc_u32 s53, s19, 0
	s_add_i32 s54, s55, s41
	s_mov_b32 m0, s54
	s_nop 0
	global_load_lds_dwordx4 v132, s[52:53]
	s_add_i32 m0, s54, 0x2000
	s_nop 0
	global_load_lds_dwordx4 v134, s[52:53]
	s_waitcnt vmcnt(6)
	s_barrier
	s_setprio 1
	v_mfma_f32_16x16x32_bf16 v[56:59], v[184:187], v[152:155], v[56:59]
	v_mfma_f32_16x16x32_bf16 v[52:55], v[192:195], v[152:155], v[52:55]
	v_mfma_f32_16x16x32_bf16 v[40:43], v[184:187], v[160:163], v[40:43]
	v_mfma_f32_16x16x32_bf16 v[36:39], v[192:195], v[160:163], v[36:39]
	v_mfma_f32_16x16x32_bf16 v[24:27], v[184:187], v[168:171], v[24:27]
	v_mfma_f32_16x16x32_bf16 v[20:23], v[192:195], v[168:171], v[20:23]
	v_mfma_f32_16x16x32_bf16 v[8:11], v[184:187], v[176:179], v[8:11]
	v_mfma_f32_16x16x32_bf16 v[4:7], v[192:195], v[176:179], v[4:7]
	v_mfma_f32_16x16x32_bf16 v[56:59], v[188:191], v[156:159], v[56:59]
	v_mfma_f32_16x16x32_bf16 v[52:55], v[210:213], v[156:159], v[52:55]
	v_mfma_f32_16x16x32_bf16 v[40:43], v[188:191], v[164:167], v[40:43]
	v_mfma_f32_16x16x32_bf16 v[36:39], v[210:213], v[164:167], v[36:39]
	v_mfma_f32_16x16x32_bf16 v[24:27], v[188:191], v[172:175], v[24:27]
	v_mfma_f32_16x16x32_bf16 v[20:23], v[210:213], v[172:175], v[20:23]
	v_mfma_f32_16x16x32_bf16 v[8:11], v[188:191], v[180:183], v[8:11]
	v_mfma_f32_16x16x32_bf16 v[4:7], v[210:213], v[180:183], v[4:7]
	s_setprio 0
	s_add_i32 s52, 0, 0x18000
	s_barrier
	ds_read_b128 v[136:139], v216 offset:32768
	ds_read_b128 v[140:143], v216 offset:33792
	ds_read_b128 v[144:147], v216 offset:34816
	ds_read_b128 v[148:151], v216 offset:35840
	s_add_u32 s38, s38, 0x40000
	s_addc_u32 s39, s39, 0
	s_mov_b32 m0, s44
	ds_read_b128 v[152:155], v3 offset:32768
	ds_read_b128 v[156:159], v3 offset:33792
	ds_read_b128 v[160:163], v3 offset:34816
	ds_read_b128 v[164:167], v3 offset:35840
	ds_read_b128 v[168:171], v3 offset:36864
	ds_read_b128 v[172:175], v3 offset:37888
	ds_read_b128 v[176:179], v3 offset:38912
	ds_read_b128 v[180:183], v3 offset:39936
	s_nop 0
	global_load_lds_dwordx4 v132, s[38:39]
	s_mov_b32 m0, s45
	s_nop 0
	global_load_lds_dwordx4 v134, s[38:39]
	s_waitcnt lgkmcnt(8)
	s_barrier
	s_waitcnt lgkmcnt(0)
	s_setprio 1
	s_waitcnt lgkmcnt(0)
	v_mfma_f32_16x16x32_bf16 v[128:131], v[136:139], v[152:155], v[128:131]
	v_mfma_f32_16x16x32_bf16 v[124:127], v[144:147], v[152:155], v[124:127]
	v_mfma_f32_16x16x32_bf16 v[112:115], v[136:139], v[160:163], v[112:115]
	v_mfma_f32_16x16x32_bf16 v[108:111], v[144:147], v[160:163], v[108:111]
	v_mfma_f32_16x16x32_bf16 v[96:99], v[136:139], v[168:171], v[96:99]
	v_mfma_f32_16x16x32_bf16 v[92:95], v[144:147], v[168:171], v[92:95]
	v_mfma_f32_16x16x32_bf16 v[80:83], v[136:139], v[176:179], v[80:83]
	v_mfma_f32_16x16x32_bf16 v[76:79], v[144:147], v[176:179], v[76:79]
	v_mfma_f32_16x16x32_bf16 v[128:131], v[140:143], v[156:159], v[128:131]
	v_mfma_f32_16x16x32_bf16 v[124:127], v[148:151], v[156:159], v[124:127]
	v_mfma_f32_16x16x32_bf16 v[112:115], v[140:143], v[164:167], v[112:115]
	v_mfma_f32_16x16x32_bf16 v[108:111], v[148:151], v[164:167], v[108:111]
	v_mfma_f32_16x16x32_bf16 v[96:99], v[140:143], v[172:175], v[96:99]
	v_mfma_f32_16x16x32_bf16 v[92:95], v[148:151], v[172:175], v[92:95]
	v_mfma_f32_16x16x32_bf16 v[80:83], v[140:143], v[180:183], v[80:83]
	v_mfma_f32_16x16x32_bf16 v[76:79], v[148:151], v[180:183], v[76:79]
	s_setprio 0
	s_barrier
	s_add_i32 s38, 0, 0x1c000
	s_add_i32 s39, s52, s41
	ds_read_b128 v[184:187], v216 offset:49152
	ds_read_b128 v[188:191], v216 offset:50176
	ds_read_b128 v[192:195], v216 offset:51200
	ds_read_b128 v[210:213], v216 offset:52224
	s_mov_b32 m0, s39
	s_nop 0
	global_load_lds_dwordx4 v132, s[28:29]
	s_add_i32 m0, s39, 0x2000
	s_nop 0
	global_load_lds_dwordx4 v134, s[28:29]
	s_barrier
	s_waitcnt lgkmcnt(0)
	s_setprio 1
	s_waitcnt lgkmcnt(0)
	v_mfma_f32_16x16x32_bf16 v[120:123], v[184:187], v[152:155], v[120:123]
	v_mfma_f32_16x16x32_bf16 v[116:119], v[192:195], v[152:155], v[116:119]
	v_mfma_f32_16x16x32_bf16 v[104:107], v[184:187], v[160:163], v[104:107]
	v_mfma_f32_16x16x32_bf16 v[100:103], v[192:195], v[160:163], v[100:103]
	v_mfma_f32_16x16x32_bf16 v[88:91], v[184:187], v[168:171], v[88:91]
	v_mfma_f32_16x16x32_bf16 v[84:87], v[192:195], v[168:171], v[84:87]
	v_mfma_f32_16x16x32_bf16 v[72:75], v[184:187], v[176:179], v[72:75]
	v_mfma_f32_16x16x32_bf16 v[68:71], v[192:195], v[176:179], v[68:71]
	v_mfma_f32_16x16x32_bf16 v[120:123], v[188:191], v[156:159], v[120:123]
	v_mfma_f32_16x16x32_bf16 v[116:119], v[210:213], v[156:159], v[116:119]
	v_mfma_f32_16x16x32_bf16 v[104:107], v[188:191], v[164:167], v[104:107]
	v_mfma_f32_16x16x32_bf16 v[100:103], v[210:213], v[164:167], v[100:103]
	v_mfma_f32_16x16x32_bf16 v[88:91], v[188:191], v[172:175], v[88:91]
	v_mfma_f32_16x16x32_bf16 v[84:87], v[210:213], v[172:175], v[84:87]
	v_mfma_f32_16x16x32_bf16 v[72:75], v[188:191], v[180:183], v[72:75]
	v_mfma_f32_16x16x32_bf16 v[68:71], v[210:213], v[180:183], v[68:71]
	s_setprio 0
	s_mov_b32 m0, s46
	s_barrier
	ds_read_b128 v[152:155], v3 offset:49152
	ds_read_b128 v[156:159], v3 offset:50176
	ds_read_b128 v[160:163], v3 offset:51200
	ds_read_b128 v[164:167], v3 offset:52224
	ds_read_b128 v[168:171], v3 offset:53248
	ds_read_b128 v[172:175], v3 offset:54272
	ds_read_b128 v[176:179], v3 offset:55296
	ds_read_b128 v[180:183], v3 offset:56320
	s_nop 0
	global_load_lds_dwordx4 v132, s[26:27]
	s_mov_b32 m0, s47
	s_nop 0
	global_load_lds_dwordx4 v134, s[26:27]
	s_barrier
	s_waitcnt lgkmcnt(0)
	s_setprio 1
	s_waitcnt lgkmcnt(0)
	v_mfma_f32_16x16x32_bf16 v[64:67], v[136:139], v[152:155], v[64:67]
	v_mfma_f32_16x16x32_bf16 v[60:63], v[144:147], v[152:155], v[60:63]
	v_mfma_f32_16x16x32_bf16 v[48:51], v[136:139], v[160:163], v[48:51]
	v_mfma_f32_16x16x32_bf16 v[44:47], v[144:147], v[160:163], v[44:47]
	v_mfma_f32_16x16x32_bf16 v[32:35], v[136:139], v[168:171], v[32:35]
	v_mfma_f32_16x16x32_bf16 v[28:31], v[144:147], v[168:171], v[28:31]
	v_mfma_f32_16x16x32_bf16 v[16:19], v[136:139], v[176:179], v[16:19]
	v_mfma_f32_16x16x32_bf16 v[12:15], v[144:147], v[176:179], v[12:15]
	v_mfma_f32_16x16x32_bf16 v[64:67], v[140:143], v[156:159], v[64:67]
	v_mfma_f32_16x16x32_bf16 v[60:63], v[148:151], v[156:159], v[60:63]
	v_mfma_f32_16x16x32_bf16 v[48:51], v[140:143], v[164:167], v[48:51]
	v_mfma_f32_16x16x32_bf16 v[44:47], v[148:151], v[164:167], v[44:47]
	v_mfma_f32_16x16x32_bf16 v[32:35], v[140:143], v[172:175], v[32:35]
	v_mfma_f32_16x16x32_bf16 v[28:31], v[148:151], v[172:175], v[28:31]
	v_mfma_f32_16x16x32_bf16 v[16:19], v[140:143], v[180:183], v[16:19]
	v_mfma_f32_16x16x32_bf16 v[12:15], v[148:151], v[180:183], v[12:15]
	s_setprio 0
	s_barrier
	s_add_u32 s18, s18, 0x40080
	s_addc_u32 s19, s19, 0
	s_add_i32 s26, s38, s41
	s_mov_b32 m0, s26
	s_nop 0
	global_load_lds_dwordx4 v132, s[18:19]
	s_add_i32 m0, s26, 0x2000
	s_nop 0
	global_load_lds_dwordx4 v134, s[18:19]
	s_waitcnt vmcnt(6)
	s_barrier
	s_setprio 1
	v_mfma_f32_16x16x32_bf16 v[56:59], v[184:187], v[152:155], v[56:59]
	v_mfma_f32_16x16x32_bf16 v[52:55], v[192:195], v[152:155], v[52:55]
	v_mfma_f32_16x16x32_bf16 v[40:43], v[184:187], v[160:163], v[40:43]
	v_mfma_f32_16x16x32_bf16 v[36:39], v[192:195], v[160:163], v[36:39]
	v_mfma_f32_16x16x32_bf16 v[24:27], v[184:187], v[168:171], v[24:27]
	v_mfma_f32_16x16x32_bf16 v[20:23], v[192:195], v[168:171], v[20:23]
	v_mfma_f32_16x16x32_bf16 v[8:11], v[184:187], v[176:179], v[8:11]
	v_mfma_f32_16x16x32_bf16 v[4:7], v[192:195], v[176:179], v[4:7]
	v_mfma_f32_16x16x32_bf16 v[56:59], v[188:191], v[156:159], v[56:59]
	v_mfma_f32_16x16x32_bf16 v[52:55], v[210:213], v[156:159], v[52:55]
	v_mfma_f32_16x16x32_bf16 v[40:43], v[188:191], v[164:167], v[40:43]
	v_mfma_f32_16x16x32_bf16 v[36:39], v[210:213], v[164:167], v[36:39]
	v_mfma_f32_16x16x32_bf16 v[24:27], v[188:191], v[172:175], v[24:27]
	v_mfma_f32_16x16x32_bf16 v[20:23], v[210:213], v[172:175], v[20:23]
	v_mfma_f32_16x16x32_bf16 v[8:11], v[188:191], v[180:183], v[8:11]
	v_mfma_f32_16x16x32_bf16 v[4:7], v[210:213], v[180:183], v[4:7]
	s_setprio 0
	s_add_i32 s51, s51, 2
	s_add_u32 s16, s16, 0x100
	s_addc_u32 s17, s17, 0
	s_cmp_gt_u32 s51, 13
	s_barrier
	s_cbranch_scc0 .LBB0_1912
	s_add_u32 s8, s24, s50
	s_addc_u32 s9, s25, 0
	s_add_u32 s18, s24, 0x7c7dc00
	s_addc_u32 s19, s25, 0
	s_add_u32 s28, s24, 0x94ddc00
	s_addc_u32 s29, s25, 0
	s_lshl_b64 s[6:7], s[6:7], 2
	s_add_u32 s26, s0, s6
	s_addc_u32 s27, s1, s7
	s_add_u32 s0, s30, s49
	s_addc_u32 s1, s31, s48
	v_mov_b32_e32 v141, v0
	s_add_u32 s6, s0, 0x53fc000
	s_addc_u32 s7, s1, 0
	v_readfirstlane_b32 s0, v141
	s_ashr_i32 s15, s0, 2
	v_and_b32_e32 v164, 15, v141
	s_andn2_b32 s15, s15, 63
	v_or_b32_e32 v132, s15, v164
	v_ashrrev_i32_e32 v133, 31, v132
	s_and_b32 s14, s0, 0xc0
	v_lshl_add_u64 v[132:133], v[132:133], 2, s[8:9]
	s_mov_b32 s0, 0x15000
	v_add_co_u32_e32 v132, vcc, s0, v132
	v_readlane_b32 s8, v253, 54
	s_nop 0
	v_addc_co_u32_e32 v133, vcc, 0, v133, vcc
	global_load_dword v1, v[132:133], off
	global_load_dword v168, v[132:133], off offset:64
	global_load_dword v167, v[132:133], off offset:128
	global_load_dword v166, v[132:133], off offset:192
	global_load_dword v165, v[132:133], off offset:512
	global_load_dword v163, v[132:133], off offset:576
	global_load_dword v162, v[132:133], off offset:640
	global_load_dword v151, v[132:133], off offset:704
	s_add_i32 s38, s15, 0x4000
	v_readlane_b32 s9, v253, 55
	v_or_b32_e32 v138, s38, v164
	s_mov_b64 s[0:1], -1
	s_waitcnt vmcnt(0)
	v_fmamk_f32 v1, v1, 0x3a800000, v231
	v_cmp_gt_f32_e32 vcc, s11, v1
	v_mul_f32_e32 v3, 0x4b800000, v1
	s_nop 0
	v_cndmask_b32_e32 v1, v1, v3, vcc
	v_rsq_f32_e32 v1, v1
	s_nop 0
	v_mul_f32_e32 v3, 0x45800000, v1
	v_cndmask_b32_e32 v140, v1, v3, vcc
	v_lshrrev_b32_e32 v1, 1, v141
	v_and_b32_e32 v1, 24, v1
	s_and_b64 vcc, exec, s[8:9]
	v_lshlrev_b32_e32 v3, 2, v1
	v_lshlrev_b32_e32 v136, 1, v1
	s_cbranch_vccz .LBB0_1915
	v_ashrrev_i32_e32 v139, 31, v138
	v_lshlrev_b64 v[132:133], 9, v[138:139]
	v_lshl_add_u64 v[132:133], s[28:29], 0, v[132:133]
	s_lshl_b32 s68, s14, 1
	v_pk_mul_f32 v[156:157], v[130:131], v[140:141] op_sel_hi:[1,0]
	v_pk_mul_f32 v[158:159], v[128:129], v[140:141] op_sel_hi:[1,0]
	v_lshl_add_u64 v[160:161], v[132:133], 0, s[68:69]
	v_pk_mul_f32 v[132:133], v[156:157], v[156:157]
	v_pk_mul_f32 v[134:135], v[158:159], v[158:159]
	v_pk_mul_f32 v[152:153], v[126:127], v[140:141] op_sel_hi:[1,0]
	v_pk_mov_b32 v[142:143], v[134:135], v[132:133] op_sel:[1,0]
	v_mov_b32_e32 v135, v133
	v_pk_add_f32 v[132:133], v[142:143], v[134:135]
	v_pk_mul_f32 v[154:155], v[124:125], v[140:141] op_sel_hi:[1,0]
	v_pk_add_f32 v[132:133], v[132:133], v[132:133] op_sel_hi:[0,1]
	v_pk_mul_f32 v[134:135], v[152:153], v[152:153]
	v_pk_mul_f32 v[142:143], v[154:155], v[154:155]
	v_pk_mul_f32 v[148:149], v[120:121], v[140:141] op_sel_hi:[1,0]
	v_pk_mov_b32 v[144:145], v[142:143], v[134:135] op_sel:[1,0]
	v_mov_b32_e32 v143, v135
	v_pk_mul_f32 v[146:147], v[122:123], v[140:141] op_sel_hi:[1,0]
	v_mul_f32_e32 v132, v148, v148
	v_pk_add_f32 v[134:135], v[144:145], v[142:143]
	v_pk_fma_f32 v[170:171], v[148:149], v[148:149], v[132:133] op_sel_hi:[1,1,0]
	v_mul_f32_e32 v132, v146, v146
	v_pk_add_f32 v[134:135], v[134:135], v[134:135] op_sel_hi:[0,1]
	v_pk_fma_f32 v[172:173], v[146:147], v[146:147], v[132:133] op_sel_hi:[1,1,0]
	v_pk_mul_f32 v[142:143], v[118:119], v[140:141] op_sel_hi:[1,0]
	v_pk_mul_f32 v[144:145], v[116:117], v[140:141] op_sel_hi:[1,0]
	v_mul_f32_e32 v132, v142, v142
	v_mul_f32_e32 v170, v144, v144
	v_mul_f32_e32 v172, v145, v145
	v_mul_f32_e32 v134, v143, v143
	v_pk_add_f32 v[170:171], v[170:171], v[172:173]
	v_pk_add_f32 v[132:133], v[132:133], v[134:135]
	v_and_b32_e32 v134, 64, v236
	v_pk_add_f32 v[132:133], v[170:171], v[132:133]
	v_add_u32_e32 v134, 64, v134
	v_add_f32_e32 v132, v132, v133
	ds_swizzle_b32 v133, v132 offset:swizzle(SWAP,16)
	v_mov_b32_e32 v137, v2
	v_lshl_add_u64 v[160:161], v[160:161], 0, v[136:137]
	s_mov_b64 s[0:1], 0
	s_waitcnt lgkmcnt(0)
	v_add_f32_e32 v132, v132, v133
	v_xor_b32_e32 v133, 32, v236
	v_cmp_lt_i32_e32 vcc, v133, v134
	s_nop 1
	v_cndmask_b32_e32 v133, v236, v133, vcc
	v_lshlrev_b32_e32 v133, 2, v133
	ds_bpermute_b32 v133, v133, v132
	s_waitcnt lgkmcnt(0)
	v_add_f32_e32 v132, v132, v133
	v_fmamk_f32 v132, v132, 0x3c800000, v231
	v_cmp_gt_f32_e32 vcc, s11, v132
	v_mul_f32_e32 v133, 0x4b800000, v132
	s_nop 0
	v_cndmask_b32_e32 v132, v132, v133, vcc
	v_rsq_f32_e32 v132, v132
	s_nop 0
	v_mul_f32_e32 v133, 0x45800000, v132
	v_cndmask_b32_e32 v132, v132, v133, vcc
	v_mul_f32_e32 v150, 0x3e38aa3b, v132
	global_load_dwordx4 v[132:135], v3, s[26:27] offset:16
	global_load_dwordx4 v[170:173], v3, s[26:27]
	v_pk_mul_f32 v[158:159], v[158:159], v[150:151] op_sel_hi:[1,0]
	v_pk_mul_f32 v[156:157], v[156:157], v[150:151] op_sel_hi:[1,0]
	v_pk_mul_f32 v[154:155], v[154:155], v[150:151] op_sel_hi:[1,0]
	v_pk_mul_f32 v[152:153], v[152:153], v[150:151] op_sel_hi:[1,0]
	v_pk_mul_f32 v[148:149], v[148:149], v[150:151] op_sel_hi:[1,0]
	v_pk_mul_f32 v[146:147], v[146:147], v[150:151] op_sel_hi:[1,0]
	v_pk_mul_f32 v[144:145], v[144:145], v[150:151] op_sel_hi:[1,0]
	v_pk_mul_f32 v[142:143], v[142:143], v[150:151] op_sel_hi:[1,0]
	s_waitcnt vmcnt(1)
	v_pk_mul_f32 v[152:153], v[134:135], v[152:153]
	s_waitcnt vmcnt(0)
	v_pk_mul_f32 v[156:157], v[172:173], v[156:157]
	v_pk_mul_f32 v[158:159], v[170:171], v[158:159]
	v_pk_mul_f32 v[134:135], v[132:133], v[154:155]
	v_cvt_pk_bf16_f32 v132, v158, v159
	v_cvt_pk_bf16_f32 v133, v156, v157
	v_cvt_pk_bf16_f32 v134, v134, v135
	v_cvt_pk_bf16_f32 v135, v152, v153
	global_store_dwordx4 v[160:161], v[132:135], off
	global_load_dwordx4 v[132:135], v3, s[26:27] offset:144
	s_nop 0
	global_load_dwordx4 v[152:155], v3, s[26:27] offset:128
	s_waitcnt vmcnt(1)
	v_pk_mul_f32 v[142:143], v[134:135], v[142:143]
	s_waitcnt vmcnt(0)
	v_pk_mul_f32 v[146:147], v[154:155], v[146:147]
	v_pk_mul_f32 v[148:149], v[152:153], v[148:149]
	v_pk_mul_f32 v[134:135], v[132:133], v[144:145]
	v_cvt_pk_bf16_f32 v132, v148, v149
	v_cvt_pk_bf16_f32 v133, v146, v147
	v_cvt_pk_bf16_f32 v134, v134, v135
	v_cvt_pk_bf16_f32 v135, v142, v143
	global_store_dwordx4 v[160:161], v[132:135], off offset:64

.LBB0_2212:
	s_ashr_i32 s7, s6, 31
	s_lshl_b64 s[18:19], s[6:7], 17
	s_add_u32 s18, s49, s18
	s_addc_u32 s19, s50, s19
	s_and_b64 s[22:23], s[22:23], exec
	v_mov_b32_e32 v4, 0
	s_cselect_b32 s1, s19, s17
	s_cselect_b32 s7, s18, s16
	s_mov_b64 s[24:25], 0
	s_mov_b64 s[22:23], -1
	s_mov_b64 s[26:27], 0
	s_waitcnt lgkmcnt(0)
	v_mov_b32_e32 v5, v4
	v_mov_b32_e32 v6, v4
	v_mov_b32_e32 v7, v4
	v_mov_b32_e32 v8, v4
	v_mov_b32_e32 v9, v4
	v_mov_b32_e32 v10, v4
	v_mov_b32_e32 v11, v4
	v_mov_b32_e32 v20, v4
	v_mov_b32_e32 v21, v4
	v_mov_b32_e32 v22, v4
	v_mov_b32_e32 v23, v4
	v_mov_b32_e32 v24, v4
	v_mov_b32_e32 v25, v4
	v_mov_b32_e32 v26, v4
	v_mov_b32_e32 v27, v4
	v_mov_b32_e32 v36, v4
	v_mov_b32_e32 v37, v4
	v_mov_b32_e32 v38, v4
	v_mov_b32_e32 v39, v4
	v_mov_b32_e32 v40, v4
	v_mov_b32_e32 v41, v4
	v_mov_b32_e32 v42, v4
	v_mov_b32_e32 v43, v4
	s_waitcnt vmcnt(0)
	v_mov_b32_e32 v52, v4
	v_mov_b32_e32 v53, v4
	v_mov_b32_e32 v54, v4
	v_mov_b32_e32 v55, v4
	v_mov_b32_e32 v56, v4
	v_mov_b32_e32 v57, v4
	v_mov_b32_e32 v58, v4
	v_mov_b32_e32 v59, v4
	v_mov_b32_e32 v12, v4
	v_mov_b32_e32 v13, v4
	v_mov_b32_e32 v14, v4
	v_mov_b32_e32 v15, v4
	v_mov_b32_e32 v16, v4
	v_mov_b32_e32 v17, v4
	v_mov_b32_e32 v18, v4
	v_mov_b32_e32 v19, v4
	v_mov_b32_e32 v28, v4
	v_mov_b32_e32 v29, v4
	v_mov_b32_e32 v30, v4
	v_mov_b32_e32 v31, v4
	v_mov_b32_e32 v32, v4
	v_mov_b32_e32 v33, v4
	v_mov_b32_e32 v34, v4
	v_mov_b32_e32 v35, v4
	v_mov_b32_e32 v44, v4
	v_mov_b32_e32 v45, v4
	v_mov_b32_e32 v46, v4
	v_mov_b32_e32 v47, v4
	v_mov_b32_e32 v48, v4
	v_mov_b32_e32 v49, v4
	v_mov_b32_e32 v50, v4
	v_mov_b32_e32 v51, v4
	v_mov_b32_e32 v60, v4
	v_mov_b32_e32 v61, v4
	v_mov_b32_e32 v62, v4
	v_mov_b32_e32 v63, v4
	v_mov_b32_e32 v64, v4
	v_mov_b32_e32 v65, v4
	v_mov_b32_e32 v66, v4
	v_mov_b32_e32 v67, v4
	v_mov_b32_e32 v68, v4
	v_mov_b32_e32 v69, v4
	v_mov_b32_e32 v70, v4
	v_mov_b32_e32 v71, v4
	v_mov_b32_e32 v72, v4
	v_mov_b32_e32 v73, v4
	v_mov_b32_e32 v74, v4
	v_mov_b32_e32 v75, v4
	v_mov_b32_e32 v84, v4
	v_mov_b32_e32 v85, v4
	v_mov_b32_e32 v86, v4
	v_mov_b32_e32 v87, v4
	v_mov_b32_e32 v88, v4
	v_mov_b32_e32 v89, v4
	v_mov_b32_e32 v90, v4
	v_mov_b32_e32 v91, v4
	v_mov_b32_e32 v100, v4
	v_mov_b32_e32 v101, v4
	v_mov_b32_e32 v102, v4
	v_mov_b32_e32 v103, v4
	v_mov_b32_e32 v104, v4
	v_mov_b32_e32 v105, v4
	v_mov_b32_e32 v106, v4
	v_mov_b32_e32 v107, v4
	v_mov_b32_e32 v116, v4
	v_mov_b32_e32 v117, v4
	v_mov_b32_e32 v118, v4
	v_mov_b32_e32 v119, v4
	v_mov_b32_e32 v120, v4
	v_mov_b32_e32 v121, v4
	v_mov_b32_e32 v122, v4
	v_mov_b32_e32 v123, v4
	v_mov_b32_e32 v76, v4
	v_mov_b32_e32 v77, v4
	v_mov_b32_e32 v78, v4
	v_mov_b32_e32 v79, v4
	v_mov_b32_e32 v80, v4
	v_mov_b32_e32 v81, v4
	v_mov_b32_e32 v82, v4
	v_mov_b32_e32 v83, v4
	v_mov_b32_e32 v92, v4
	v_mov_b32_e32 v93, v4
	v_mov_b32_e32 v94, v4
	v_mov_b32_e32 v95, v4
	v_mov_b32_e32 v96, v4
	v_mov_b32_e32 v97, v4
	v_mov_b32_e32 v98, v4
	v_mov_b32_e32 v99, v4
	v_mov_b32_e32 v108, v4
	v_mov_b32_e32 v109, v4
	v_mov_b32_e32 v110, v4
	v_mov_b32_e32 v111, v4
	v_mov_b32_e32 v112, v4
	v_mov_b32_e32 v113, v4
	v_mov_b32_e32 v114, v4
	v_mov_b32_e32 v115, v4
	v_mov_b32_e32 v124, v4
	v_mov_b32_e32 v125, v4
	v_mov_b32_e32 v126, v4
	v_mov_b32_e32 v127, v4
	v_mov_b32_e32 v128, v4
	v_mov_b32_e32 v129, v4
	v_mov_b32_e32 v130, v4
	v_mov_b32_e32 v131, v4
	v_add_u32_e32 v218, 0x10000, v1
.LBB0_2213:
	s_add_u32 s15, s20, s24
	s_addc_u32 s30, s21, s25
	s_add_u32 s31, s15, 0x100
	s_addc_u32 s38, s30, 0
	s_and_b64 s[28:29], s[26:27], exec
	s_cselect_b32 s41, s9, s38
	s_cselect_b32 s40, s8, s31
	s_add_u32 s24, s16, s24
	s_addc_u32 s25, s17, s25
	s_add_u32 s28, s24, 0x100
	s_addc_u32 s29, s25, 0
	s_add_u32 s24, s40, 0x80
	s_addc_u32 s25, s41, 0
	s_add_i32 s79, 0, 0x10000
	s_and_b64 s[26:27], s[26:27], exec
	s_cselect_b32 s43, s1, s29
	s_cselect_b32 s42, s7, s28
	s_add_u32 s44, s15, 0x12080
	s_addc_u32 s45, s30, 0
	s_add_i32 s84, s79, s51
	s_add_i32 m0, s52, 0xc000
	s_add_i32 s85, s52, 0xe000
	s_add_i32 s83, 0, 0x14000
	s_add_i32 s82, s84, 0x2000
	s_add_u32 s38, s42, 0x10000
	s_addc_u32 s39, s43, 0
	s_add_i32 s80, s83, s51
	s_add_i32 s78, s80, 0x2000
	s_add_i32 s75, 0, 0x18000
	s_add_u32 s30, s40, 0x12000
	ds_read_b128 v[140:143], v218
	ds_read_b128 v[144:147], v218 offset:1024
	ds_read_b128 v[148:151], v218 offset:2048
	ds_read_b128 v[152:155], v218 offset:3072
	s_addc_u32 s31, s41, 0
	s_add_i32 s73, 0, 0x1c000
	s_add_u32 s28, s42, 0x80
	s_addc_u32 s29, s43, 0
	s_add_i32 s74, s75, s51
	s_add_i32 s15, s74, 0x2000
	s_add_u32 s26, s42, 0x10080
	s_addc_u32 s27, s43, 0
	s_add_i32 s81, s73, s51
	s_add_i32 s79, s81, 0x2000
	ds_read_b128 v[156:159], v3
	ds_read_b128 v[160:163], v3 offset:1024
	ds_read_b128 v[164:167], v3 offset:2048
	ds_read_b128 v[168:171], v3 offset:3072
	ds_read_b128 v[172:175], v3 offset:4096
	ds_read_b128 v[176:179], v3 offset:5120
	ds_read_b128 v[180:183], v3 offset:6144
	ds_read_b128 v[184:187], v3 offset:7168
	s_nop 0
	global_load_lds_dwordx4 v132, s[44:45]
	s_mov_b32 m0, s85
	s_nop 0
	global_load_lds_dwordx4 v136, s[44:45]
	s_waitcnt lgkmcnt(8)
	s_barrier
	s_waitcnt lgkmcnt(0)
	s_setprio 1
	s_waitcnt lgkmcnt(0)
	v_mfma_f32_16x16x32_bf16 v[128:131], v[140:143], v[156:159], v[128:131]
	v_mfma_f32_16x16x32_bf16 v[124:127], v[148:151], v[156:159], v[124:127]
	v_mfma_f32_16x16x32_bf16 v[112:115], v[140:143], v[164:167], v[112:115]
	v_mfma_f32_16x16x32_bf16 v[108:111], v[148:151], v[164:167], v[108:111]
	v_mfma_f32_16x16x32_bf16 v[96:99], v[140:143], v[172:175], v[96:99]
	v_mfma_f32_16x16x32_bf16 v[92:95], v[148:151], v[172:175], v[92:95]
	v_mfma_f32_16x16x32_bf16 v[80:83], v[140:143], v[180:183], v[80:83]
	v_mfma_f32_16x16x32_bf16 v[76:79], v[148:151], v[180:183], v[76:79]
	v_mfma_f32_16x16x32_bf16 v[128:131], v[144:147], v[160:163], v[128:131]
	v_mfma_f32_16x16x32_bf16 v[124:127], v[152:155], v[160:163], v[124:127]
	v_mfma_f32_16x16x32_bf16 v[112:115], v[144:147], v[168:171], v[112:115]
	v_mfma_f32_16x16x32_bf16 v[108:111], v[152:155], v[168:171], v[108:111]
	v_mfma_f32_16x16x32_bf16 v[96:99], v[144:147], v[176:179], v[96:99]
	v_mfma_f32_16x16x32_bf16 v[92:95], v[152:155], v[176:179], v[92:95]
	v_mfma_f32_16x16x32_bf16 v[80:83], v[144:147], v[184:187], v[80:83]
	v_mfma_f32_16x16x32_bf16 v[76:79], v[152:155], v[184:187], v[76:79]
	s_setprio 0
	s_barrier
	s_mov_b32 m0, s84
	ds_read_b128 v[188:191], v218 offset:16384
	ds_read_b128 v[192:195], v218 offset:17408
	ds_read_b128 v[210:213], v218 offset:18432
	ds_read_b128 v[214:217], v218 offset:19456
	s_nop 0
	global_load_lds_dwordx4 v134, s[42:43]
	s_mov_b32 m0, s82
	s_nop 0
	global_load_lds_dwordx4 v138, s[42:43]
	s_barrier
	s_waitcnt lgkmcnt(0)
	s_setprio 1
	s_waitcnt lgkmcnt(0)
	v_mfma_f32_16x16x32_bf16 v[120:123], v[188:191], v[156:159], v[120:123]
	v_mfma_f32_16x16x32_bf16 v[116:119], v[210:213], v[156:159], v[116:119]
	v_mfma_f32_16x16x32_bf16 v[104:107], v[188:191], v[164:167], v[104:107]
	v_mfma_f32_16x16x32_bf16 v[100:103], v[210:213], v[164:167], v[100:103]
	v_mfma_f32_16x16x32_bf16 v[88:91], v[188:191], v[172:175], v[88:91]
	v_mfma_f32_16x16x32_bf16 v[84:87], v[210:213], v[172:175], v[84:87]
	v_mfma_f32_16x16x32_bf16 v[72:75], v[188:191], v[180:183], v[72:75]
	v_mfma_f32_16x16x32_bf16 v[68:71], v[210:213], v[180:183], v[68:71]
	v_mfma_f32_16x16x32_bf16 v[120:123], v[192:195], v[160:163], v[120:123]
	v_mfma_f32_16x16x32_bf16 v[116:119], v[214:217], v[160:163], v[116:119]
	v_mfma_f32_16x16x32_bf16 v[104:107], v[192:195], v[168:171], v[104:107]
	v_mfma_f32_16x16x32_bf16 v[100:103], v[214:217], v[168:171], v[100:103]
	v_mfma_f32_16x16x32_bf16 v[88:91], v[192:195], v[176:179], v[88:91]
	v_mfma_f32_16x16x32_bf16 v[84:87], v[214:217], v[176:179], v[84:87]
	v_mfma_f32_16x16x32_bf16 v[72:75], v[192:195], v[184:187], v[72:75]
	v_mfma_f32_16x16x32_bf16 v[68:71], v[214:217], v[184:187], v[68:71]
	s_setprio 0
	s_mov_b32 m0, s52
	s_barrier
	ds_read_b128 v[156:159], v3 offset:16384
	ds_read_b128 v[160:163], v3 offset:17408
	ds_read_b128 v[164:167], v3 offset:18432
	ds_read_b128 v[168:171], v3 offset:19456
	ds_read_b128 v[172:175], v3 offset:20480
	ds_read_b128 v[176:179], v3 offset:21504
	ds_read_b128 v[180:183], v3 offset:22528
	ds_read_b128 v[184:187], v3 offset:23552
	s_nop 0
	global_load_lds_dwordx4 v132, s[40:41]
	s_mov_b32 m0, s53
	s_nop 0
	global_load_lds_dwordx4 v136, s[40:41]
	s_barrier
	s_waitcnt lgkmcnt(0)
	s_setprio 1
	s_waitcnt lgkmcnt(0)
	v_mfma_f32_16x16x32_bf16 v[64:67], v[140:143], v[156:159], v[64:67]
	v_mfma_f32_16x16x32_bf16 v[60:63], v[148:151], v[156:159], v[60:63]
	v_mfma_f32_16x16x32_bf16 v[48:51], v[140:143], v[164:167], v[48:51]
	v_mfma_f32_16x16x32_bf16 v[44:47], v[148:151], v[164:167], v[44:47]
	v_mfma_f32_16x16x32_bf16 v[32:35], v[140:143], v[172:175], v[32:35]
	v_mfma_f32_16x16x32_bf16 v[28:31], v[148:151], v[172:175], v[28:31]
	v_mfma_f32_16x16x32_bf16 v[16:19], v[140:143], v[180:183], v[16:19]
	v_mfma_f32_16x16x32_bf16 v[12:15], v[148:151], v[180:183], v[12:15]
	v_mfma_f32_16x16x32_bf16 v[64:67], v[144:147], v[160:163], v[64:67]
	v_mfma_f32_16x16x32_bf16 v[60:63], v[152:155], v[160:163], v[60:63]
	v_mfma_f32_16x16x32_bf16 v[48:51], v[144:147], v[168:171], v[48:51]
	v_mfma_f32_16x16x32_bf16 v[44:47], v[152:155], v[168:171], v[44:47]
	v_mfma_f32_16x16x32_bf16 v[32:35], v[144:147], v[176:179], v[32:35]
	v_mfma_f32_16x16x32_bf16 v[28:31], v[152:155], v[176:179], v[28:31]
	v_mfma_f32_16x16x32_bf16 v[16:19], v[144:147], v[184:187], v[16:19]
	v_mfma_f32_16x16x32_bf16 v[12:15], v[152:155], v[184:187], v[12:15]
	s_setprio 0
	s_barrier
	s_mov_b32 m0, s80
	s_nop 0
	global_load_lds_dwordx4 v134, s[38:39]
	s_mov_b32 m0, s78
	s_nop 0
	global_load_lds_dwordx4 v138, s[38:39]
	s_waitcnt vmcnt(6)
	s_barrier
	s_setprio 1
	v_mfma_f32_16x16x32_bf16 v[56:59], v[188:191], v[156:159], v[56:59]
	v_mfma_f32_16x16x32_bf16 v[52:55], v[210:213], v[156:159], v[52:55]
	v_mfma_f32_16x16x32_bf16 v[40:43], v[188:191], v[164:167], v[40:43]
	v_mfma_f32_16x16x32_bf16 v[36:39], v[210:213], v[164:167], v[36:39]
	v_mfma_f32_16x16x32_bf16 v[24:27], v[188:191], v[172:175], v[24:27]
	v_mfma_f32_16x16x32_bf16 v[20:23], v[210:213], v[172:175], v[20:23]
	v_mfma_f32_16x16x32_bf16 v[8:11], v[188:191], v[180:183], v[8:11]
	v_mfma_f32_16x16x32_bf16 v[4:7], v[210:213], v[180:183], v[4:7]
	v_mfma_f32_16x16x32_bf16 v[56:59], v[192:195], v[160:163], v[56:59]
	v_mfma_f32_16x16x32_bf16 v[52:55], v[214:217], v[160:163], v[52:55]
	v_mfma_f32_16x16x32_bf16 v[40:43], v[192:195], v[168:171], v[40:43]
	v_mfma_f32_16x16x32_bf16 v[36:39], v[214:217], v[168:171], v[36:39]
	v_mfma_f32_16x16x32_bf16 v[24:27], v[192:195], v[176:179], v[24:27]
	v_mfma_f32_16x16x32_bf16 v[20:23], v[214:217], v[176:179], v[20:23]
	v_mfma_f32_16x16x32_bf16 v[8:11], v[192:195], v[184:187], v[8:11]
	v_mfma_f32_16x16x32_bf16 v[4:7], v[214:217], v[184:187], v[4:7]
	s_setprio 0
	s_barrier
	ds_read_b128 v[140:143], v218 offset:32768
	ds_read_b128 v[144:147], v218 offset:33792
	ds_read_b128 v[148:151], v218 offset:34816
	ds_read_b128 v[152:155], v218 offset:35840
	s_mov_b32 m0, s54
	ds_read_b128 v[156:159], v3 offset:32768
	ds_read_b128 v[160:163], v3 offset:33792
	ds_read_b128 v[164:167], v3 offset:34816
	ds_read_b128 v[168:171], v3 offset:35840
	ds_read_b128 v[172:175], v3 offset:36864
	ds_read_b128 v[176:179], v3 offset:37888
	ds_read_b128 v[180:183], v3 offset:38912
	ds_read_b128 v[184:187], v3 offset:39936
	s_nop 0
	global_load_lds_dwordx4 v132, s[30:31]
	s_mov_b32 m0, s55
	s_nop 0
	global_load_lds_dwordx4 v136, s[30:31]
	s_waitcnt lgkmcnt(8)
	s_barrier
	s_waitcnt lgkmcnt(0)
	s_setprio 1
	s_waitcnt lgkmcnt(0)
	v_mfma_f32_16x16x32_bf16 v[128:131], v[140:143], v[156:159], v[128:131]
	v_mfma_f32_16x16x32_bf16 v[124:127], v[148:151], v[156:159], v[124:127]
	v_mfma_f32_16x16x32_bf16 v[112:115], v[140:143], v[164:167], v[112:115]
	v_mfma_f32_16x16x32_bf16 v[108:111], v[148:151], v[164:167], v[108:111]
	v_mfma_f32_16x16x32_bf16 v[96:99], v[140:143], v[172:175], v[96:99]
	v_mfma_f32_16x16x32_bf16 v[92:95], v[148:151], v[172:175], v[92:95]
	v_mfma_f32_16x16x32_bf16 v[80:83], v[140:143], v[180:183], v[80:83]
	v_mfma_f32_16x16x32_bf16 v[76:79], v[148:151], v[180:183], v[76:79]
	v_mfma_f32_16x16x32_bf16 v[128:131], v[144:147], v[160:163], v[128:131]
	v_mfma_f32_16x16x32_bf16 v[124:127], v[152:155], v[160:163], v[124:127]
	v_mfma_f32_16x16x32_bf16 v[112:115], v[144:147], v[168:171], v[112:115]
	v_mfma_f32_16x16x32_bf16 v[108:111], v[152:155], v[168:171], v[108:111]
	v_mfma_f32_16x16x32_bf16 v[96:99], v[144:147], v[176:179], v[96:99]
	v_mfma_f32_16x16x32_bf16 v[92:95], v[152:155], v[176:179], v[92:95]
	v_mfma_f32_16x16x32_bf16 v[80:83], v[144:147], v[184:187], v[80:83]
	v_mfma_f32_16x16x32_bf16 v[76:79], v[152:155], v[184:187], v[76:79]
	s_setprio 0
	s_barrier
	s_mov_b32 m0, s74
	ds_read_b128 v[188:191], v218 offset:49152
	ds_read_b128 v[192:195], v218 offset:50176
	ds_read_b128 v[210:213], v218 offset:51200
	ds_read_b128 v[214:217], v218 offset:52224
	s_nop 0
	global_load_lds_dwordx4 v134, s[28:29]
	s_mov_b32 m0, s15
	s_nop 0
	global_load_lds_dwordx4 v138, s[28:29]
	s_barrier
	s_waitcnt lgkmcnt(0)
	s_setprio 1
	s_waitcnt lgkmcnt(0)
	v_mfma_f32_16x16x32_bf16 v[120:123], v[188:191], v[156:159], v[120:123]
	v_mfma_f32_16x16x32_bf16 v[116:119], v[210:213], v[156:159], v[116:119]
	v_mfma_f32_16x16x32_bf16 v[104:107], v[188:191], v[164:167], v[104:107]
	v_mfma_f32_16x16x32_bf16 v[100:103], v[210:213], v[164:167], v[100:103]
	v_mfma_f32_16x16x32_bf16 v[88:91], v[188:191], v[172:175], v[88:91]
	v_mfma_f32_16x16x32_bf16 v[84:87], v[210:213], v[172:175], v[84:87]
	v_mfma_f32_16x16x32_bf16 v[72:75], v[188:191], v[180:183], v[72:75]
	v_mfma_f32_16x16x32_bf16 v[68:71], v[210:213], v[180:183], v[68:71]
	v_mfma_f32_16x16x32_bf16 v[120:123], v[192:195], v[160:163], v[120:123]
	v_mfma_f32_16x16x32_bf16 v[116:119], v[214:217], v[160:163], v[116:119]
	v_mfma_f32_16x16x32_bf16 v[104:107], v[192:195], v[168:171], v[104:107]
	v_mfma_f32_16x16x32_bf16 v[100:103], v[214:217], v[168:171], v[100:103]
	v_mfma_f32_16x16x32_bf16 v[88:91], v[192:195], v[176:179], v[88:91]
	v_mfma_f32_16x16x32_bf16 v[84:87], v[214:217], v[176:179], v[84:87]
	v_mfma_f32_16x16x32_bf16 v[72:75], v[192:195], v[184:187], v[72:75]
	v_mfma_f32_16x16x32_bf16 v[68:71], v[214:217], v[184:187], v[68:71]
	s_setprio 0
	s_mov_b32 m0, s64
	s_barrier
	ds_read_b128 v[156:159], v3 offset:49152
	ds_read_b128 v[160:163], v3 offset:50176
	ds_read_b128 v[164:167], v3 offset:51200
	ds_read_b128 v[168:171], v3 offset:52224
	ds_read_b128 v[172:175], v3 offset:53248
	ds_read_b128 v[176:179], v3 offset:54272
	ds_read_b128 v[180:183], v3 offset:55296
	ds_read_b128 v[184:187], v3 offset:56320
	s_nop 0
	global_load_lds_dwordx4 v132, s[24:25]
	s_mov_b32 m0, s65
	s_nop 0
	global_load_lds_dwordx4 v136, s[24:25]
	s_barrier
	s_waitcnt lgkmcnt(0)
	s_setprio 1
	s_waitcnt lgkmcnt(0)
	v_mfma_f32_16x16x32_bf16 v[64:67], v[140:143], v[156:159], v[64:67]
	v_mfma_f32_16x16x32_bf16 v[60:63], v[148:151], v[156:159], v[60:63]
	v_mfma_f32_16x16x32_bf16 v[48:51], v[140:143], v[164:167], v[48:51]
	v_mfma_f32_16x16x32_bf16 v[44:47], v[148:151], v[164:167], v[44:47]
	v_mfma_f32_16x16x32_bf16 v[32:35], v[140:143], v[172:175], v[32:35]
	v_mfma_f32_16x16x32_bf16 v[28:31], v[148:151], v[172:175], v[28:31]
	v_mfma_f32_16x16x32_bf16 v[16:19], v[140:143], v[180:183], v[16:19]
	v_mfma_f32_16x16x32_bf16 v[12:15], v[148:151], v[180:183], v[12:15]
	v_mfma_f32_16x16x32_bf16 v[64:67], v[144:147], v[160:163], v[64:67]
	v_mfma_f32_16x16x32_bf16 v[60:63], v[152:155], v[160:163], v[60:63]
	v_mfma_f32_16x16x32_bf16 v[48:51], v[144:147], v[168:171], v[48:51]
	v_mfma_f32_16x16x32_bf16 v[44:47], v[152:155], v[168:171], v[44:47]
	v_mfma_f32_16x16x32_bf16 v[32:35], v[144:147], v[176:179], v[32:35]
	v_mfma_f32_16x16x32_bf16 v[28:31], v[152:155], v[176:179], v[28:31]
	v_mfma_f32_16x16x32_bf16 v[16:19], v[144:147], v[184:187], v[16:19]
	v_mfma_f32_16x16x32_bf16 v[12:15], v[152:155], v[184:187], v[12:15]
	s_setprio 0
	s_barrier
	s_mov_b32 m0, s81
	s_nop 0
	global_load_lds_dwordx4 v134, s[26:27]
	s_mov_b32 m0, s79
	s_nop 0
	global_load_lds_dwordx4 v138, s[26:27]
	s_waitcnt vmcnt(6)
	s_barrier
	s_setprio 1
	v_mfma_f32_16x16x32_bf16 v[56:59], v[188:191], v[156:159], v[56:59]
	v_mfma_f32_16x16x32_bf16 v[52:55], v[210:213], v[156:159], v[52:55]
	v_mfma_f32_16x16x32_bf16 v[40:43], v[188:191], v[164:167], v[40:43]
	v_mfma_f32_16x16x32_bf16 v[36:39], v[210:213], v[164:167], v[36:39]
	v_mfma_f32_16x16x32_bf16 v[24:27], v[188:191], v[172:175], v[24:27]
	v_mfma_f32_16x16x32_bf16 v[20:23], v[210:213], v[172:175], v[20:23]
	v_mfma_f32_16x16x32_bf16 v[8:11], v[188:191], v[180:183], v[8:11]
	v_mfma_f32_16x16x32_bf16 v[4:7], v[210:213], v[180:183], v[4:7]
	v_mfma_f32_16x16x32_bf16 v[56:59], v[192:195], v[160:163], v[56:59]
	v_mfma_f32_16x16x32_bf16 v[52:55], v[214:217], v[160:163], v[52:55]
	v_mfma_f32_16x16x32_bf16 v[40:43], v[192:195], v[168:171], v[40:43]
	v_mfma_f32_16x16x32_bf16 v[36:39], v[214:217], v[168:171], v[36:39]
	v_mfma_f32_16x16x32_bf16 v[24:27], v[192:195], v[176:179], v[24:27]
	v_mfma_f32_16x16x32_bf16 v[20:23], v[214:217], v[176:179], v[20:23]
	v_mfma_f32_16x16x32_bf16 v[8:11], v[192:195], v[184:187], v[8:11]
	v_mfma_f32_16x16x32_bf16 v[4:7], v[214:217], v[184:187], v[4:7]
	s_setprio 0
	s_andn2_b64 vcc, exec, s[22:23]
	s_mov_b64 s[26:27], -1
	s_mov_b64 s[22:23], 0
	s_mov_b64 s[24:25], 0x100
	s_barrier
	s_cbranch_vccz .LBB0_2213
	v_mov_b32_e32 v141, v0
	s_ashr_i32 s15, s14, 31
	v_readfirstlane_b32 s1, v141
	s_bfe_u32 s7, s1, 0x20006
	s_ashr_i32 s1, s1, 2
	s_and_b32 s16, s1, 0xffffffc0
	s_ashr_i32 s17, s16, 31
	s_lshl_b64 s[20:21], s[14:15], 10
	s_add_u32 s1, s56, s20
	s_addc_u32 s22, s57, s21
	s_lshl_b64 s[20:21], s[16:17], 2
	v_and_b32_e32 v142, 15, v141
	s_add_u32 s20, s1, s20
	s_addc_u32 s21, s22, s21
	v_lshlrev_b32_e32 v140, 2, v142
	global_load_dword v150, v140, s[20:21] offset:64
	global_load_dword v149, v140, s[20:21] offset:128
	global_load_dword v148, v140, s[20:21] offset:192
	global_load_dword v147, v140, s[20:21] offset:512
	global_load_dword v146, v140, s[20:21] offset:576
	global_load_dword v145, v140, s[20:21] offset:640
	global_load_dword v144, v140, s[20:21] offset:704
	v_mul_f32_e32 v129, v129, v129
	v_mul_f32_e32 v125, v125, v125
	v_mul_f32_e32 v121, v121, v121
	v_mul_f32_e32 v117, v117, v117
	v_fmac_f32_e32 v129, v128, v128
	v_mul_f32_e32 v128, v131, v131
	v_fmac_f32_e32 v125, v124, v124
	v_mul_f32_e32 v124, v127, v127
	v_fmac_f32_e32 v121, v120, v120
	v_mul_f32_e32 v120, v123, v123
	v_fmac_f32_e32 v117, v116, v116
	v_mul_f32_e32 v116, v119, v119
	v_fmac_f32_e32 v128, v130, v130
	v_fmac_f32_e32 v124, v126, v126
	v_fmac_f32_e32 v120, v122, v122
	v_fmac_f32_e32 v116, v118, v118
	v_add_f32_e32 v128, v129, v128
	v_add_f32_e32 v124, v125, v124
	v_add_f32_e32 v120, v121, v120
	v_add_f32_e32 v116, v117, v116
	v_add_f32_e32 v124, v128, v124
	v_add_f32_e32 v116, v120, v116
	v_add_f32_e32 v117, v124, v116
	ds_swizzle_b32 v118, v117 offset:swizzle(SWAP,16)
	v_and_b32_e32 v152, 64, v236
	v_xor_b32_e32 v151, 32, v236
	v_add_u32_e32 v152, 64, v152
	v_cmp_lt_i32_e32 vcc, v151, v152
	s_lshl_b32 s0, s0, 2
	s_or_b32 s0, s7, s0
	v_cndmask_b32_e32 v116, v236, v151, vcc
	s_lshl_b64 s[14:15], s[14:15], 8
	v_lshlrev_b32_e32 v116, 2, v116
	s_waitcnt lgkmcnt(0)
	v_add_f32_e32 v117, v117, v118
	s_add_u32 s1, s14, s16
	ds_bpermute_b32 v118, v116, v117
	s_addc_u32 s7, s15, s17
	v_or_b32_e32 v143, s1, v142
	s_ashr_i32 s1, s0, 31
	s_lshl_b64 s[0:1], s[0:1], 2
	v_and_b32_e32 v119, 48, v141
	s_add_u32 s0, s62, s0
	v_mov_b32_e32 v142, s7
	v_cmp_eq_u32_e64 s[16:17], 0, v119
	s_addc_u32 s1, s63, s1
	s_and_saveexec_b64 s[14:15], s[16:17]
	s_cbranch_execz .LBB0_2216
	v_mov_b32_e32 v141, v2
	v_lshl_add_u64 v[120:121], s[20:21], 0, v[140:141]
	global_load_dword v119, v[120:121], off
	s_waitcnt lgkmcnt(0)
	v_add_f32_e32 v117, v117, v118
	s_waitcnt vmcnt(0)
	v_add_f32_e32 v117, v117, v119
	v_fmamk_f32 v117, v117, 0x3c2aaaab, v231
	v_cmp_gt_f32_e32 vcc, s11, v117
	v_mul_f32_e32 v118, 0x4b800000, v117
	s_nop 0
	v_cndmask_b32_e32 v117, v117, v118, vcc
	v_rsq_f32_e32 v117, v117
	s_nop 0
	v_mul_f32_e32 v118, 0x45800000, v117
	v_cndmask_b32_e32 v117, v117, v118, vcc
	v_mad_u64_u32 v[118:119], s[20:21], v143, 48, s[0:1]
	v_mov_b32_e32 v120, v119
	v_mad_u64_u32 v[120:121], s[20:21], v142, 48, v[120:121]
	v_mov_b32_e32 v119, v120
	global_store_dword v[118:119], v117, off

.LBB0_2602:
	s_add_u32 s47, s22, 0x100
	v_mov_b32_e32 v4, 0
	s_addc_u32 s48, s23, 0
	s_mov_b32 s49, -2
	v_mov_b32_e32 v5, v4
	v_mov_b32_e32 v6, v4
	v_mov_b32_e32 v7, v4
	v_mov_b32_e32 v8, v4
	v_mov_b32_e32 v9, v4
	v_mov_b32_e32 v10, v4
	v_mov_b32_e32 v11, v4
	v_mov_b32_e32 v12, v4
	v_mov_b32_e32 v13, v4
	v_mov_b32_e32 v14, v4
	v_mov_b32_e32 v15, v4
	v_mov_b32_e32 v16, v4
	v_mov_b32_e32 v17, v4
	v_mov_b32_e32 v18, v4
	v_mov_b32_e32 v19, v4
	v_mov_b32_e32 v28, v4
	v_mov_b32_e32 v29, v4
	v_mov_b32_e32 v30, v4
	v_mov_b32_e32 v31, v4
	v_mov_b32_e32 v32, v4
	v_mov_b32_e32 v33, v4
	v_mov_b32_e32 v34, v4
	v_mov_b32_e32 v35, v4
	v_mov_b32_e32 v44, v4
	v_mov_b32_e32 v45, v4
	v_mov_b32_e32 v46, v4
	v_mov_b32_e32 v47, v4
	v_mov_b32_e32 v48, v4
	v_mov_b32_e32 v49, v4
	v_mov_b32_e32 v50, v4
	v_mov_b32_e32 v51, v4
	v_mov_b32_e32 v20, v4
	v_mov_b32_e32 v21, v4
	v_mov_b32_e32 v22, v4
	v_mov_b32_e32 v23, v4
	v_mov_b32_e32 v24, v4
	v_mov_b32_e32 v25, v4
	v_mov_b32_e32 v26, v4
	v_mov_b32_e32 v27, v4
	v_mov_b32_e32 v36, v4
	v_mov_b32_e32 v37, v4
	v_mov_b32_e32 v38, v4
	v_mov_b32_e32 v39, v4
	v_mov_b32_e32 v40, v4
	v_mov_b32_e32 v41, v4
	v_mov_b32_e32 v42, v4
	v_mov_b32_e32 v43, v4
	v_mov_b32_e32 v52, v4
	v_mov_b32_e32 v53, v4
	v_mov_b32_e32 v54, v4
	v_mov_b32_e32 v55, v4
	v_mov_b32_e32 v56, v4
	v_mov_b32_e32 v57, v4
	v_mov_b32_e32 v58, v4
	v_mov_b32_e32 v59, v4
	v_mov_b32_e32 v60, v4
	v_mov_b32_e32 v61, v4
	v_mov_b32_e32 v62, v4
	v_mov_b32_e32 v63, v4
	v_mov_b32_e32 v64, v4
	v_mov_b32_e32 v65, v4
	v_mov_b32_e32 v66, v4
	v_mov_b32_e32 v67, v4
	v_mov_b32_e32 v68, v4
	v_mov_b32_e32 v69, v4
	v_mov_b32_e32 v70, v4
	v_mov_b32_e32 v71, v4
	v_mov_b32_e32 v72, v4
	v_mov_b32_e32 v73, v4
	v_mov_b32_e32 v74, v4
	v_mov_b32_e32 v75, v4
	v_mov_b32_e32 v76, v4
	v_mov_b32_e32 v77, v4
	v_mov_b32_e32 v78, v4
	v_mov_b32_e32 v79, v4
	v_mov_b32_e32 v84, v4
	v_mov_b32_e32 v85, v4
	v_mov_b32_e32 v86, v4
	v_mov_b32_e32 v87, v4
	v_mov_b32_e32 v92, v4
	v_mov_b32_e32 v93, v4
	v_mov_b32_e32 v94, v4
	v_mov_b32_e32 v95, v4
	v_mov_b32_e32 v100, v4
	v_mov_b32_e32 v101, v4
	v_mov_b32_e32 v102, v4
	v_mov_b32_e32 v103, v4
	v_mov_b32_e32 v108, v4
	v_mov_b32_e32 v109, v4
	v_mov_b32_e32 v110, v4
	v_mov_b32_e32 v111, v4
	v_mov_b32_e32 v116, v4
	v_mov_b32_e32 v117, v4
	v_mov_b32_e32 v118, v4
	v_mov_b32_e32 v119, v4
	v_mov_b32_e32 v80, v4
	v_mov_b32_e32 v81, v4
	v_mov_b32_e32 v82, v4
	v_mov_b32_e32 v83, v4
	v_mov_b32_e32 v88, v4
	v_mov_b32_e32 v89, v4
	v_mov_b32_e32 v90, v4
	v_mov_b32_e32 v91, v4
	v_mov_b32_e32 v96, v4
	v_mov_b32_e32 v97, v4
	v_mov_b32_e32 v98, v4
	v_mov_b32_e32 v99, v4
	v_mov_b32_e32 v104, v4
	v_mov_b32_e32 v105, v4
	v_mov_b32_e32 v106, v4
	v_mov_b32_e32 v107, v4
	v_mov_b32_e32 v112, v4
	v_mov_b32_e32 v113, v4
	v_mov_b32_e32 v114, v4
	v_mov_b32_e32 v115, v4
	v_mov_b32_e32 v120, v4
	v_mov_b32_e32 v121, v4
	v_mov_b32_e32 v122, v4
	v_mov_b32_e32 v123, v4
	v_mov_b32_e32 v124, v4
	v_mov_b32_e32 v125, v4
	v_mov_b32_e32 v126, v4
	v_mov_b32_e32 v127, v4
	v_mov_b32_e32 v128, v4
	v_mov_b32_e32 v129, v4
	v_mov_b32_e32 v130, v4
	v_mov_b32_e32 v131, v4
	v_add_u32_e32 v218, 0x10000, v1
.LBB0_2603:
	s_add_u32 s18, s14, 0x100
	s_addc_u32 s19, s15, 0
	s_cmp_eq_u32 s49, 2
	s_cselect_b32 s24, s6, s18
	s_cselect_b32 s25, s7, s19
	s_cselect_b32 s20, s8, s47
	s_cselect_b32 s21, s9, s48
	s_add_u32 s22, s24, 0x80
	s_addc_u32 s23, s25, 0
	s_add_i32 s50, 0, 0x10000
	ds_read_b128 v[140:143], v218
	ds_read_b128 v[144:147], v218 offset:1024
	ds_read_b128 v[148:151], v218 offset:2048
	ds_read_b128 v[152:155], v218 offset:3072
	s_add_u32 s14, s14, 0x30080
	s_addc_u32 s15, s15, 0
	ds_read_b128 v[156:159], v3
	ds_read_b128 v[160:163], v3 offset:1024
	ds_read_b128 v[164:167], v3 offset:2048
	ds_read_b128 v[168:171], v3 offset:3072
	ds_read_b128 v[172:175], v3 offset:4096
	ds_read_b128 v[176:179], v3 offset:5120
	ds_read_b128 v[180:183], v3 offset:6144
	ds_read_b128 v[184:187], v3 offset:7168
	s_add_i32 m0, s38, 0xc000
	s_nop 0
	global_load_lds_dwordx4 v132, s[14:15]
	s_add_i32 m0, s38, 0xe000
	s_nop 0
	global_load_lds_dwordx4 v136, s[14:15]
	s_waitcnt lgkmcnt(8)
	s_barrier
	s_waitcnt lgkmcnt(0)
	s_setprio 1
	s_waitcnt lgkmcnt(0)
	v_mfma_f32_16x16x32_bf16 v[128:131], v[140:143], v[156:159], v[128:131]
	v_mfma_f32_16x16x32_bf16 v[124:127], v[148:151], v[156:159], v[124:127]
	v_mfma_f32_16x16x32_bf16 v[120:123], v[140:143], v[164:167], v[120:123]
	v_mfma_f32_16x16x32_bf16 v[112:115], v[148:151], v[164:167], v[112:115]
	v_mfma_f32_16x16x32_bf16 v[104:107], v[140:143], v[172:175], v[104:107]
	v_mfma_f32_16x16x32_bf16 v[96:99], v[148:151], v[172:175], v[96:99]
	v_mfma_f32_16x16x32_bf16 v[88:91], v[140:143], v[180:183], v[88:91]
	v_mfma_f32_16x16x32_bf16 v[80:83], v[148:151], v[180:183], v[80:83]
	v_mfma_f32_16x16x32_bf16 v[128:131], v[144:147], v[160:163], v[128:131]
	v_mfma_f32_16x16x32_bf16 v[124:127], v[152:155], v[160:163], v[124:127]
	v_mfma_f32_16x16x32_bf16 v[120:123], v[144:147], v[168:171], v[120:123]
	v_mfma_f32_16x16x32_bf16 v[112:115], v[152:155], v[168:171], v[112:115]
	v_mfma_f32_16x16x32_bf16 v[104:107], v[144:147], v[176:179], v[104:107]
	v_mfma_f32_16x16x32_bf16 v[96:99], v[152:155], v[176:179], v[96:99]
	v_mfma_f32_16x16x32_bf16 v[88:91], v[144:147], v[184:187], v[88:91]
	v_mfma_f32_16x16x32_bf16 v[80:83], v[152:155], v[184:187], v[80:83]
	s_setprio 0
	s_barrier
	s_add_i32 s51, 0, 0x14000
	s_mov_b64 s[14:15], s[20:21]
	s_add_i32 s50, s50, s37
	ds_read_b128 v[188:191], v218 offset:16384
	ds_read_b128 v[192:195], v218 offset:17408
	ds_read_b128 v[210:213], v218 offset:18432
	ds_read_b128 v[214:217], v218 offset:19456
	s_mov_b32 m0, s50
	s_nop 0
	global_load_lds_dwordx4 v134, s[14:15]
	s_add_i32 m0, s50, 0x2000
	s_nop 0
	global_load_lds_dwordx4 v138, s[14:15]
	s_barrier
	s_waitcnt lgkmcnt(0)
	s_setprio 1
	s_waitcnt lgkmcnt(0)
	v_mfma_f32_16x16x32_bf16 v[116:119], v[188:191], v[156:159], v[116:119]
	v_mfma_f32_16x16x32_bf16 v[108:111], v[210:213], v[156:159], v[108:111]
	v_mfma_f32_16x16x32_bf16 v[100:103], v[188:191], v[164:167], v[100:103]
	v_mfma_f32_16x16x32_bf16 v[92:95], v[210:213], v[164:167], v[92:95]
	v_mfma_f32_16x16x32_bf16 v[84:87], v[188:191], v[172:175], v[84:87]
	v_mfma_f32_16x16x32_bf16 v[76:79], v[210:213], v[172:175], v[76:79]
	v_mfma_f32_16x16x32_bf16 v[72:75], v[188:191], v[180:183], v[72:75]
	v_mfma_f32_16x16x32_bf16 v[68:71], v[210:213], v[180:183], v[68:71]
	v_mfma_f32_16x16x32_bf16 v[116:119], v[192:195], v[160:163], v[116:119]
	v_mfma_f32_16x16x32_bf16 v[108:111], v[214:217], v[160:163], v[108:111]
	v_mfma_f32_16x16x32_bf16 v[100:103], v[192:195], v[168:171], v[100:103]
	v_mfma_f32_16x16x32_bf16 v[92:95], v[214:217], v[168:171], v[92:95]
	v_mfma_f32_16x16x32_bf16 v[84:87], v[192:195], v[176:179], v[84:87]
	v_mfma_f32_16x16x32_bf16 v[76:79], v[214:217], v[176:179], v[76:79]
	v_mfma_f32_16x16x32_bf16 v[72:75], v[192:195], v[184:187], v[72:75]
	v_mfma_f32_16x16x32_bf16 v[68:71], v[214:217], v[184:187], v[68:71]
	s_setprio 0
	s_mov_b64 s[14:15], s[24:25]
	s_mov_b32 m0, s38
	s_barrier
	ds_read_b128 v[156:159], v3 offset:16384
	ds_read_b128 v[160:163], v3 offset:17408
	ds_read_b128 v[164:167], v3 offset:18432
	ds_read_b128 v[168:171], v3 offset:19456
	ds_read_b128 v[172:175], v3 offset:20480
	ds_read_b128 v[176:179], v3 offset:21504
	ds_read_b128 v[180:183], v3 offset:22528
	ds_read_b128 v[184:187], v3 offset:23552
	s_nop 0
	global_load_lds_dwordx4 v132, s[14:15]
	s_mov_b32 m0, s39
	s_nop 0
	global_load_lds_dwordx4 v136, s[14:15]
	s_barrier
	s_waitcnt lgkmcnt(0)
	s_setprio 1
	s_waitcnt lgkmcnt(0)
	v_mfma_f32_16x16x32_bf16 v[64:67], v[140:143], v[156:159], v[64:67]
	v_mfma_f32_16x16x32_bf16 v[60:63], v[148:151], v[156:159], v[60:63]
	v_mfma_f32_16x16x32_bf16 v[56:59], v[140:143], v[164:167], v[56:59]
	v_mfma_f32_16x16x32_bf16 v[52:55], v[148:151], v[164:167], v[52:55]
	v_mfma_f32_16x16x32_bf16 v[40:43], v[140:143], v[172:175], v[40:43]
	v_mfma_f32_16x16x32_bf16 v[36:39], v[148:151], v[172:175], v[36:39]
	v_mfma_f32_16x16x32_bf16 v[24:27], v[140:143], v[180:183], v[24:27]
	v_mfma_f32_16x16x32_bf16 v[20:23], v[148:151], v[180:183], v[20:23]
	v_mfma_f32_16x16x32_bf16 v[64:67], v[144:147], v[160:163], v[64:67]
	v_mfma_f32_16x16x32_bf16 v[60:63], v[152:155], v[160:163], v[60:63]
	v_mfma_f32_16x16x32_bf16 v[56:59], v[144:147], v[168:171], v[56:59]
	v_mfma_f32_16x16x32_bf16 v[52:55], v[152:155], v[168:171], v[52:55]
	v_mfma_f32_16x16x32_bf16 v[40:43], v[144:147], v[176:179], v[40:43]
	v_mfma_f32_16x16x32_bf16 v[36:39], v[152:155], v[176:179], v[36:39]
	v_mfma_f32_16x16x32_bf16 v[24:27], v[144:147], v[184:187], v[24:27]
	v_mfma_f32_16x16x32_bf16 v[20:23], v[152:155], v[184:187], v[20:23]
	s_setprio 0
	s_barrier
	s_add_u32 s14, s20, 0x18000
	s_addc_u32 s15, s21, 0
	s_add_i32 s50, s51, s37
	s_mov_b32 m0, s50
	s_nop 0
	global_load_lds_dwordx4 v134, s[14:15]
	s_add_i32 m0, s50, 0x2000
	s_nop 0
	global_load_lds_dwordx4 v138, s[14:15]
	s_waitcnt vmcnt(6)
	s_barrier
	s_setprio 1
	v_mfma_f32_16x16x32_bf16 v[48:51], v[188:191], v[156:159], v[48:51]
	v_mfma_f32_16x16x32_bf16 v[44:47], v[210:213], v[156:159], v[44:47]
	v_mfma_f32_16x16x32_bf16 v[32:35], v[188:191], v[164:167], v[32:35]
	v_mfma_f32_16x16x32_bf16 v[28:31], v[210:213], v[164:167], v[28:31]
	v_mfma_f32_16x16x32_bf16 v[16:19], v[188:191], v[172:175], v[16:19]
	v_mfma_f32_16x16x32_bf16 v[12:15], v[210:213], v[172:175], v[12:15]
	v_mfma_f32_16x16x32_bf16 v[8:11], v[188:191], v[180:183], v[8:11]
	v_mfma_f32_16x16x32_bf16 v[4:7], v[210:213], v[180:183], v[4:7]
	v_mfma_f32_16x16x32_bf16 v[48:51], v[192:195], v[160:163], v[48:51]
	v_mfma_f32_16x16x32_bf16 v[44:47], v[214:217], v[160:163], v[44:47]
	v_mfma_f32_16x16x32_bf16 v[32:35], v[192:195], v[168:171], v[32:35]
	v_mfma_f32_16x16x32_bf16 v[28:31], v[214:217], v[168:171], v[28:31]
	v_mfma_f32_16x16x32_bf16 v[16:19], v[192:195], v[176:179], v[16:19]
	v_mfma_f32_16x16x32_bf16 v[12:15], v[214:217], v[176:179], v[12:15]
	v_mfma_f32_16x16x32_bf16 v[8:11], v[192:195], v[184:187], v[8:11]
	v_mfma_f32_16x16x32_bf16 v[4:7], v[214:217], v[184:187], v[4:7]
	s_setprio 0
	s_add_i32 s50, 0, 0x18000
	s_barrier
	ds_read_b128 v[140:143], v218 offset:32768
	ds_read_b128 v[144:147], v218 offset:33792
	ds_read_b128 v[148:151], v218 offset:34816
	ds_read_b128 v[152:155], v218 offset:35840
	s_add_u32 s14, s24, 0x30000
	s_addc_u32 s15, s25, 0
	s_mov_b32 m0, s40
	ds_read_b128 v[156:159], v3 offset:32768
	ds_read_b128 v[160:163], v3 offset:33792
	ds_read_b128 v[164:167], v3 offset:34816
	ds_read_b128 v[168:171], v3 offset:35840
	ds_read_b128 v[172:175], v3 offset:36864
	ds_read_b128 v[176:179], v3 offset:37888
	ds_read_b128 v[180:183], v3 offset:38912
	ds_read_b128 v[184:187], v3 offset:39936
	s_nop 0
	global_load_lds_dwordx4 v132, s[14:15]
	s_mov_b32 m0, s41
	s_nop 0
	global_load_lds_dwordx4 v136, s[14:15]
	s_waitcnt lgkmcnt(8)
	s_barrier
	s_waitcnt lgkmcnt(0)
	s_setprio 1
	s_waitcnt lgkmcnt(0)
	v_mfma_f32_16x16x32_bf16 v[128:131], v[140:143], v[156:159], v[128:131]
	v_mfma_f32_16x16x32_bf16 v[124:127], v[148:151], v[156:159], v[124:127]
	v_mfma_f32_16x16x32_bf16 v[120:123], v[140:143], v[164:167], v[120:123]
	v_mfma_f32_16x16x32_bf16 v[112:115], v[148:151], v[164:167], v[112:115]
	v_mfma_f32_16x16x32_bf16 v[104:107], v[140:143], v[172:175], v[104:107]
	v_mfma_f32_16x16x32_bf16 v[96:99], v[148:151], v[172:175], v[96:99]
	v_mfma_f32_16x16x32_bf16 v[88:91], v[140:143], v[180:183], v[88:91]
	v_mfma_f32_16x16x32_bf16 v[80:83], v[148:151], v[180:183], v[80:83]
	v_mfma_f32_16x16x32_bf16 v[128:131], v[144:147], v[160:163], v[128:131]
	v_mfma_f32_16x16x32_bf16 v[124:127], v[152:155], v[160:163], v[124:127]
	v_mfma_f32_16x16x32_bf16 v[120:123], v[144:147], v[168:171], v[120:123]
	v_mfma_f32_16x16x32_bf16 v[112:115], v[152:155], v[168:171], v[112:115]
	v_mfma_f32_16x16x32_bf16 v[104:107], v[144:147], v[176:179], v[104:107]
	v_mfma_f32_16x16x32_bf16 v[96:99], v[152:155], v[176:179], v[96:99]
	v_mfma_f32_16x16x32_bf16 v[88:91], v[144:147], v[184:187], v[88:91]
	v_mfma_f32_16x16x32_bf16 v[80:83], v[152:155], v[184:187], v[80:83]
	s_setprio 0
	s_barrier
	s_add_i32 s24, 0, 0x1c000
	s_add_u32 s14, s20, 0x80
	s_addc_u32 s15, s21, 0
	s_add_i32 s25, s50, s37
	ds_read_b128 v[188:191], v218 offset:49152
	ds_read_b128 v[192:195], v218 offset:50176
	ds_read_b128 v[210:213], v218 offset:51200
	ds_read_b128 v[214:217], v218 offset:52224
	s_mov_b32 m0, s25
	s_nop 0
	global_load_lds_dwordx4 v134, s[14:15]
	s_add_i32 m0, s25, 0x2000
	s_nop 0
	global_load_lds_dwordx4 v138, s[14:15]
	s_barrier
	s_waitcnt lgkmcnt(0)
	s_setprio 1
	s_waitcnt lgkmcnt(0)
	v_mfma_f32_16x16x32_bf16 v[116:119], v[188:191], v[156:159], v[116:119]
	v_mfma_f32_16x16x32_bf16 v[108:111], v[210:213], v[156:159], v[108:111]
	v_mfma_f32_16x16x32_bf16 v[100:103], v[188:191], v[164:167], v[100:103]
	v_mfma_f32_16x16x32_bf16 v[92:95], v[210:213], v[164:167], v[92:95]
	v_mfma_f32_16x16x32_bf16 v[84:87], v[188:191], v[172:175], v[84:87]
	v_mfma_f32_16x16x32_bf16 v[76:79], v[210:213], v[172:175], v[76:79]
	v_mfma_f32_16x16x32_bf16 v[72:75], v[188:191], v[180:183], v[72:75]
	v_mfma_f32_16x16x32_bf16 v[68:71], v[210:213], v[180:183], v[68:71]
	v_mfma_f32_16x16x32_bf16 v[116:119], v[192:195], v[160:163], v[116:119]
	v_mfma_f32_16x16x32_bf16 v[108:111], v[214:217], v[160:163], v[108:111]
	v_mfma_f32_16x16x32_bf16 v[100:103], v[192:195], v[168:171], v[100:103]
	v_mfma_f32_16x16x32_bf16 v[92:95], v[214:217], v[168:171], v[92:95]
	v_mfma_f32_16x16x32_bf16 v[84:87], v[192:195], v[176:179], v[84:87]
	v_mfma_f32_16x16x32_bf16 v[76:79], v[214:217], v[176:179], v[76:79]
	v_mfma_f32_16x16x32_bf16 v[72:75], v[192:195], v[184:187], v[72:75]
	v_mfma_f32_16x16x32_bf16 v[68:71], v[214:217], v[184:187], v[68:71]
	s_setprio 0
	s_mov_b32 m0, s26
	s_barrier
	ds_read_b128 v[156:159], v3 offset:49152
	ds_read_b128 v[160:163], v3 offset:50176
	ds_read_b128 v[164:167], v3 offset:51200
	ds_read_b128 v[168:171], v3 offset:52224
	ds_read_b128 v[172:175], v3 offset:53248
	ds_read_b128 v[176:179], v3 offset:54272
	ds_read_b128 v[180:183], v3 offset:55296
	ds_read_b128 v[184:187], v3 offset:56320
	s_nop 0
	global_load_lds_dwordx4 v132, s[22:23]
	s_mov_b32 m0, s27
	s_nop 0
	global_load_lds_dwordx4 v136, s[22:23]
	s_barrier
	s_waitcnt lgkmcnt(0)
	s_setprio 1
	s_waitcnt lgkmcnt(0)
	v_mfma_f32_16x16x32_bf16 v[64:67], v[140:143], v[156:159], v[64:67]
	v_mfma_f32_16x16x32_bf16 v[60:63], v[148:151], v[156:159], v[60:63]
	v_mfma_f32_16x16x32_bf16 v[56:59], v[140:143], v[164:167], v[56:59]
	v_mfma_f32_16x16x32_bf16 v[52:55], v[148:151], v[164:167], v[52:55]
	v_mfma_f32_16x16x32_bf16 v[40:43], v[140:143], v[172:175], v[40:43]
	v_mfma_f32_16x16x32_bf16 v[36:39], v[148:151], v[172:175], v[36:39]
	v_mfma_f32_16x16x32_bf16 v[24:27], v[140:143], v[180:183], v[24:27]
	v_mfma_f32_16x16x32_bf16 v[20:23], v[148:151], v[180:183], v[20:23]
	v_mfma_f32_16x16x32_bf16 v[64:67], v[144:147], v[160:163], v[64:67]
	v_mfma_f32_16x16x32_bf16 v[60:63], v[152:155], v[160:163], v[60:63]
	v_mfma_f32_16x16x32_bf16 v[56:59], v[144:147], v[168:171], v[56:59]
	v_mfma_f32_16x16x32_bf16 v[52:55], v[152:155], v[168:171], v[52:55]
	v_mfma_f32_16x16x32_bf16 v[40:43], v[144:147], v[176:179], v[40:43]
	v_mfma_f32_16x16x32_bf16 v[36:39], v[152:155], v[176:179], v[36:39]
	v_mfma_f32_16x16x32_bf16 v[24:27], v[144:147], v[184:187], v[24:27]
	v_mfma_f32_16x16x32_bf16 v[20:23], v[152:155], v[184:187], v[20:23]
	s_setprio 0
	s_barrier
	s_add_u32 s14, s20, 0x18080
	s_addc_u32 s15, s21, 0
	s_add_i32 s20, s24, s37
	s_mov_b32 m0, s20
	s_nop 0
	global_load_lds_dwordx4 v134, s[14:15]
	s_add_i32 m0, s20, 0x2000
	s_nop 0
	global_load_lds_dwordx4 v138, s[14:15]
	s_waitcnt vmcnt(6)
	s_barrier
	s_setprio 1
	v_mfma_f32_16x16x32_bf16 v[48:51], v[188:191], v[156:159], v[48:51]
	v_mfma_f32_16x16x32_bf16 v[44:47], v[210:213], v[156:159], v[44:47]
	v_mfma_f32_16x16x32_bf16 v[32:35], v[188:191], v[164:167], v[32:35]
	v_mfma_f32_16x16x32_bf16 v[28:31], v[210:213], v[164:167], v[28:31]
	v_mfma_f32_16x16x32_bf16 v[16:19], v[188:191], v[172:175], v[16:19]
	v_mfma_f32_16x16x32_bf16 v[12:15], v[210:213], v[172:175], v[12:15]
	v_mfma_f32_16x16x32_bf16 v[8:11], v[188:191], v[180:183], v[8:11]
	v_mfma_f32_16x16x32_bf16 v[4:7], v[210:213], v[180:183], v[4:7]
	v_mfma_f32_16x16x32_bf16 v[48:51], v[192:195], v[160:163], v[48:51]
	v_mfma_f32_16x16x32_bf16 v[44:47], v[214:217], v[160:163], v[44:47]
	v_mfma_f32_16x16x32_bf16 v[32:35], v[192:195], v[168:171], v[32:35]
	v_mfma_f32_16x16x32_bf16 v[28:31], v[214:217], v[168:171], v[28:31]
	v_mfma_f32_16x16x32_bf16 v[16:19], v[192:195], v[176:179], v[16:19]
	v_mfma_f32_16x16x32_bf16 v[12:15], v[214:217], v[176:179], v[12:15]
	v_mfma_f32_16x16x32_bf16 v[8:11], v[192:195], v[184:187], v[8:11]
	v_mfma_f32_16x16x32_bf16 v[4:7], v[214:217], v[184:187], v[4:7]
	s_setprio 0
	s_add_i32 s49, s49, 2
	s_add_u32 s47, s47, 0x100
	s_addc_u32 s48, s48, 0
	s_cmp_gt_u32 s49, 3
	s_mov_b64 s[14:15], s[18:19]
	s_barrier
	s_cbranch_scc0 .LBB0_2603
	v_mov_b32_e32 v141, v0
	s_lshl_b32 s18, s46, 8
	v_readfirstlane_b32 s14, v141
	s_and_b32 s15, s14, 0xc0
	s_ashr_i32 s14, s14, 2
	s_andn2_b32 s14, s14, 63
	s_add_i32 s14, s14, s18
	v_and_or_b32 v140, v141, 15, s14
	s_lshl_b32 s14, s45, 8
	s_or_b32 s14, s15, s14
	v_lshrrev_b32_e32 v141, 1, v141
	v_cvt_pk_bf16_f32 v72, v72, v73
	v_cvt_pk_bf16_f32 v73, v74, v75
	v_cvt_pk_bf16_f32 v74, v68, v69
	v_add_u32_e32 v68, 0x80, v140
	v_and_or_b32 v142, v141, 24, s14
	v_ashrrev_i32_e32 v141, 31, v140
	v_cvt_pk_bf16_f32 v116, v116, v117
	v_cvt_pk_bf16_f32 v117, v118, v119
	v_cvt_pk_bf16_f32 v118, v108, v109
	v_or_b32_e32 v108, 16, v140
	v_ashrrev_i32_e32 v69, 31, v68
	v_cvt_pk_bf16_f32 v48, v48, v49
	v_cvt_pk_bf16_f32 v49, v50, v51
	v_cvt_pk_bf16_f32 v50, v44, v45
	v_add_u32_e32 v44, 0x90, v140
	v_lshlrev_b64 v[144:145], 11, v[140:141]
	v_ashrrev_i32_e32 v143, 31, v142
	v_ashrrev_i32_e32 v109, 31, v108
	v_cvt_pk_bf16_f32 v100, v100, v101
	v_cvt_pk_bf16_f32 v101, v102, v103
	v_cvt_pk_bf16_f32 v102, v92, v93
	v_or_b32_e32 v92, 32, v140
	v_lshlrev_b64 v[68:69], 11, v[68:69]
	v_ashrrev_i32_e32 v45, 31, v44
	v_cvt_pk_bf16_f32 v32, v32, v33
	v_cvt_pk_bf16_f32 v33, v34, v35
	v_cvt_pk_bf16_f32 v34, v28, v29
	v_add_u32_e32 v28, 0xa0, v140
	v_lshl_add_u64 v[144:145], s[0:1], 0, v[144:145]
	v_lshlrev_b64 v[142:143], 1, v[142:143]
	v_lshlrev_b64 v[108:109], 11, v[108:109]
	v_ashrrev_i32_e32 v93, 31, v92
	v_cvt_pk_bf16_f32 v84, v84, v85
	v_cvt_pk_bf16_f32 v85, v86, v87
	v_cvt_pk_bf16_f32 v86, v76, v77
	v_or_b32_e32 v76, 48, v140
	v_lshl_add_u64 v[68:69], s[0:1], 0, v[68:69]
	v_lshlrev_b64 v[44:45], 11, v[44:45]
	v_ashrrev_i32_e32 v29, 31, v28
	v_cvt_pk_bf16_f32 v16, v16, v17
	v_cvt_pk_bf16_f32 v17, v18, v19
	v_cvt_pk_bf16_f32 v18, v12, v13
	v_add_u32_e32 v12, 0xb0, v140
	v_lshl_add_u64 v[144:145], v[144:145], 0, v[142:143]
	v_cvt_pk_bf16_f32 v119, v110, v111
	v_lshl_add_u64 v[108:109], s[0:1], 0, v[108:109]
	v_lshlrev_b64 v[92:93], 11, v[92:93]
	v_ashrrev_i32_e32 v77, 31, v76
	v_lshl_add_u64 v[68:69], v[68:69], 0, v[142:143]
	v_cvt_pk_bf16_f32 v51, v46, v47
	v_lshl_add_u64 v[44:45], s[0:1], 0, v[44:45]
	v_lshlrev_b64 v[28:29], 11, v[28:29]
	v_ashrrev_i32_e32 v13, 31, v12
	global_store_dwordx4 v[144:145], v[116:119], off offset:64
	v_cvt_pk_bf16_f32 v103, v94, v95
	v_lshl_add_u64 v[92:93], s[0:1], 0, v[92:93]
	v_lshl_add_u64 v[116:117], v[108:109], 0, v[142:143]
	v_lshlrev_b64 v[76:77], 11, v[76:77]
	global_store_dwordx4 v[68:69], v[48:51], off offset:64
	v_cvt_pk_bf16_f32 v35, v30, v31
	v_lshl_add_u64 v[28:29], s[0:1], 0, v[28:29]
	v_lshl_add_u64 v[48:49], v[44:45], 0, v[142:143]
	v_lshlrev_b64 v[12:13], 11, v[12:13]
	global_store_dwordx4 v[116:117], v[100:103], off offset:64
	v_cvt_pk_bf16_f32 v87, v78, v79
	v_lshl_add_u64 v[76:77], s[0:1], 0, v[76:77]
	v_lshl_add_u64 v[100:101], v[92:93], 0, v[142:143]
	global_store_dwordx4 v[48:49], v[32:35], off offset:64
	v_cvt_pk_bf16_f32 v19, v14, v15
	v_lshl_add_u64 v[12:13], s[0:1], 0, v[12:13]
	v_lshl_add_u64 v[32:33], v[28:29], 0, v[142:143]
	v_cvt_pk_bf16_f32 v128, v128, v129
	v_cvt_pk_bf16_f32 v129, v130, v131
	v_cvt_pk_bf16_f32 v130, v124, v125
	v_cvt_pk_bf16_f32 v131, v126, v127
	v_cvt_pk_bf16_f32 v108, v120, v121
	v_cvt_pk_bf16_f32 v109, v122, v123
	v_cvt_pk_bf16_f32 v110, v112, v113
	v_cvt_pk_bf16_f32 v111, v114, v115
	v_cvt_pk_bf16_f32 v92, v104, v105
	v_cvt_pk_bf16_f32 v93, v106, v107
	v_cvt_pk_bf16_f32 v94, v96, v97
	v_cvt_pk_bf16_f32 v95, v98, v99
	global_store_dwordx4 v[100:101], v[84:87], off offset:64
	v_cvt_pk_bf16_f32 v78, v80, v81
	v_cvt_pk_bf16_f32 v79, v82, v83
	v_lshl_add_u64 v[84:85], v[76:77], 0, v[142:143]
	v_cvt_pk_bf16_f32 v76, v88, v89
	v_cvt_pk_bf16_f32 v77, v90, v91
	v_cvt_pk_bf16_f32 v75, v70, v71
	v_cvt_pk_bf16_f32 v64, v64, v65
	v_cvt_pk_bf16_f32 v65, v66, v67
	v_cvt_pk_bf16_f32 v66, v60, v61
	v_cvt_pk_bf16_f32 v67, v62, v63
	v_cvt_pk_bf16_f32 v44, v56, v57
	v_cvt_pk_bf16_f32 v45, v58, v59
	v_cvt_pk_bf16_f32 v46, v52, v53
	v_cvt_pk_bf16_f32 v47, v54, v55
	v_cvt_pk_bf16_f32 v28, v40, v41
	v_cvt_pk_bf16_f32 v29, v42, v43
	v_cvt_pk_bf16_f32 v30, v36, v37
	v_cvt_pk_bf16_f32 v31, v38, v39
	global_store_dwordx4 v[32:33], v[16:19], off offset:64
	v_cvt_pk_bf16_f32 v14, v20, v21
	v_cvt_pk_bf16_f32 v15, v22, v23
	v_lshl_add_u64 v[16:17], v[12:13], 0, v[142:143]
	v_cvt_pk_bf16_f32 v12, v24, v25
	v_cvt_pk_bf16_f32 v13, v26, v27
	v_cvt_pk_bf16_f32 v8, v8, v9
	v_cvt_pk_bf16_f32 v9, v10, v11
	v_cvt_pk_bf16_f32 v10, v4, v5
	v_cvt_pk_bf16_f32 v11, v6, v7
	s_and_b64 vcc, exec, s[16:17]
	s_mov_b32 s45, s43
	s_mov_b32 s46, s44
	s_mov_b64 s[22:23], s[8:9]
	s_mov_b64 s[14:15], s[6:7]
	global_store_dwordx4 v[144:145], v[128:131], off
	global_store_dwordx4 v[116:117], v[108:111], off
	global_store_dwordx4 v[100:101], v[92:95], off
	global_store_dwordx4 v[84:85], v[76:79], off
	global_store_dwordx4 v[84:85], v[72:75], off offset:64
	global_store_dwordx4 v[68:69], v[64:67], off
	global_store_dwordx4 v[48:49], v[44:47], off
	global_store_dwordx4 v[32:33], v[28:31], off
	global_store_dwordx4 v[16:17], v[12:15], off
	global_store_dwordx4 v[16:17], v[8:11], off offset:64
	s_cbranch_vccz .LBB0_2596
	s_waitcnt vmcnt(0)
	s_cmpk_gt_u32 s36, 0xff
	s_cbranch_scc1 .LBB0_2607
	s_barrier

.LBB0_2673:
	s_ashr_i32 s31, s30, 31
	s_lshl_b64 s[14:15], s[30:31], 19
	s_add_u32 s36, s45, s14
	s_addc_u32 s37, s46, s15
	s_and_b64 s[14:15], s[16:17], exec
	s_cselect_b32 s31, s37, s1
	s_cselect_b32 s68, s36, s0
	s_ashr_i32 s29, s28, 31
	s_lshl_b64 s[14:15], s[28:29], 19
	s_add_u32 s38, s47, s14
	s_addc_u32 s39, s48, s15
	s_and_b64 s[14:15], s[16:17], exec
	s_cselect_b32 s29, s39, s9
	s_cselect_b32 s72, s38, s8
	s_add_u32 s73, s8, 0x100
	v_mov_b32_e32 v4, 0
	s_addc_u32 s74, s9, 0
	s_mov_b32 s75, -2
	s_waitcnt lgkmcnt(0)
	v_mov_b32_e32 v5, v4
	v_mov_b32_e32 v6, v4
	v_mov_b32_e32 v7, v4
	v_mov_b32_e32 v8, v4
	v_mov_b32_e32 v9, v4
	s_waitcnt vmcnt(0)
	v_mov_b32_e32 v10, v4
	v_mov_b32_e32 v11, v4
	v_mov_b32_e32 v20, v4
	v_mov_b32_e32 v21, v4
	v_mov_b32_e32 v22, v4
	v_mov_b32_e32 v23, v4
	v_mov_b32_e32 v24, v4
	v_mov_b32_e32 v25, v4
	v_mov_b32_e32 v26, v4
	v_mov_b32_e32 v27, v4
	v_mov_b32_e32 v36, v4
	v_mov_b32_e32 v37, v4
	v_mov_b32_e32 v38, v4
	v_mov_b32_e32 v39, v4
	v_mov_b32_e32 v40, v4
	v_mov_b32_e32 v41, v4
	v_mov_b32_e32 v42, v4
	v_mov_b32_e32 v43, v4
	v_mov_b32_e32 v44, v4
	v_mov_b32_e32 v45, v4
	v_mov_b32_e32 v46, v4
	v_mov_b32_e32 v47, v4
	v_mov_b32_e32 v48, v4
	v_mov_b32_e32 v49, v4
	v_mov_b32_e32 v50, v4
	v_mov_b32_e32 v51, v4
	v_mov_b32_e32 v12, v4
	v_mov_b32_e32 v13, v4
	v_mov_b32_e32 v14, v4
	v_mov_b32_e32 v15, v4
	v_mov_b32_e32 v16, v4
	v_mov_b32_e32 v17, v4
	v_mov_b32_e32 v18, v4
	v_mov_b32_e32 v19, v4
	v_mov_b32_e32 v28, v4
	v_mov_b32_e32 v29, v4
	v_mov_b32_e32 v30, v4
	v_mov_b32_e32 v31, v4
	v_mov_b32_e32 v32, v4
	v_mov_b32_e32 v33, v4
	v_mov_b32_e32 v34, v4
	v_mov_b32_e32 v35, v4
	v_mov_b32_e32 v52, v4
	v_mov_b32_e32 v53, v4
	v_mov_b32_e32 v54, v4
	v_mov_b32_e32 v55, v4
	v_mov_b32_e32 v56, v4
	v_mov_b32_e32 v57, v4
	v_mov_b32_e32 v58, v4
	v_mov_b32_e32 v59, v4
	v_mov_b32_e32 v60, v4
	v_mov_b32_e32 v61, v4
	v_mov_b32_e32 v62, v4
	v_mov_b32_e32 v63, v4
	v_mov_b32_e32 v64, v4
	v_mov_b32_e32 v65, v4
	v_mov_b32_e32 v66, v4
	v_mov_b32_e32 v67, v4
	v_mov_b32_e32 v68, v4
	v_mov_b32_e32 v69, v4
	v_mov_b32_e32 v70, v4
	v_mov_b32_e32 v71, v4
	v_mov_b32_e32 v72, v4
	v_mov_b32_e32 v73, v4
	v_mov_b32_e32 v74, v4
	v_mov_b32_e32 v75, v4
	v_mov_b32_e32 v84, v4
	v_mov_b32_e32 v85, v4
	v_mov_b32_e32 v86, v4
	v_mov_b32_e32 v87, v4
	v_mov_b32_e32 v88, v4
	v_mov_b32_e32 v89, v4
	v_mov_b32_e32 v90, v4
	v_mov_b32_e32 v91, v4
	v_mov_b32_e32 v100, v4
	v_mov_b32_e32 v101, v4
	v_mov_b32_e32 v102, v4
	v_mov_b32_e32 v103, v4
	v_mov_b32_e32 v104, v4
	v_mov_b32_e32 v105, v4
	v_mov_b32_e32 v106, v4
	v_mov_b32_e32 v107, v4
	v_mov_b32_e32 v116, v4
	v_mov_b32_e32 v117, v4
	v_mov_b32_e32 v118, v4
	v_mov_b32_e32 v119, v4
	v_mov_b32_e32 v120, v4
	v_mov_b32_e32 v121, v4
	v_mov_b32_e32 v122, v4
	v_mov_b32_e32 v123, v4
	v_mov_b32_e32 v76, v4
	v_mov_b32_e32 v77, v4
	v_mov_b32_e32 v78, v4
	v_mov_b32_e32 v79, v4
	v_mov_b32_e32 v80, v4
	v_mov_b32_e32 v81, v4
	v_mov_b32_e32 v82, v4
	v_mov_b32_e32 v83, v4
	v_mov_b32_e32 v92, v4
	v_mov_b32_e32 v93, v4
	v_mov_b32_e32 v94, v4
	v_mov_b32_e32 v95, v4
	v_mov_b32_e32 v96, v4
	v_mov_b32_e32 v97, v4
	v_mov_b32_e32 v98, v4
	v_mov_b32_e32 v99, v4
	v_mov_b32_e32 v108, v4
	v_mov_b32_e32 v109, v4
	v_mov_b32_e32 v110, v4
	v_mov_b32_e32 v111, v4
	v_mov_b32_e32 v112, v4
	v_mov_b32_e32 v113, v4
	v_mov_b32_e32 v114, v4
	v_mov_b32_e32 v115, v4
	v_mov_b32_e32 v124, v4
	v_mov_b32_e32 v125, v4
	v_mov_b32_e32 v126, v4
	v_mov_b32_e32 v127, v4
	v_mov_b32_e32 v128, v4
	v_mov_b32_e32 v129, v4
	v_mov_b32_e32 v130, v4
	v_mov_b32_e32 v131, v4
	v_add_u32_e32 v229, 0x10000, v1
.LBB0_2674:
	s_add_u32 s8, s0, 0x100
	s_addc_u32 s9, s1, 0
	s_cmp_eq_u32 s75, 12
	s_cselect_b32 s42, s68, s8
	s_cselect_b32 s43, s31, s9
	s_cselect_b32 s40, s72, s73
	s_cselect_b32 s41, s29, s74
	s_add_u32 s14, s42, 0x80
	s_addc_u32 s15, s43, 0
	s_add_i32 s78, 0, 0x10000
	s_add_i32 s79, 0, 0x14000
	ds_read_b128 v[132:135], v229
	ds_read_b128 v[136:139], v229 offset:1024
	ds_read_b128 v[140:143], v229 offset:2048
	ds_read_b128 v[144:147], v229 offset:3072
	ds_read_b128 v[148:151], v229 offset:16384
	ds_read_b128 v[152:155], v229 offset:17408
	ds_read_b128 v[156:159], v229 offset:18432
	ds_read_b128 v[160:163], v229 offset:19456
	s_add_u32 s0, s0, 0x40080
	s_addc_u32 s1, s1, 0
	ds_read_b128 v[164:167], v3
	ds_read_b128 v[168:171], v3 offset:1024
	ds_read_b128 v[172:175], v3 offset:2048
	ds_read_b128 v[176:179], v3 offset:3072
	ds_read_b128 v[180:183], v3 offset:4096
	ds_read_b128 v[184:187], v3 offset:5120
	ds_read_b128 v[192:195], v3 offset:6144
	ds_read_b128 v[210:213], v3 offset:7168
	s_add_i32 m0, s50, 0xc000
	s_nop 0
	global_load_lds_dwordx4 v190, s[0:1]
	s_add_i32 m0, s50, 0xe000
	s_nop 0
	global_load_lds_dwordx4 v188, s[0:1]
	s_waitcnt vmcnt(8)
	s_waitcnt lgkmcnt(0)
	s_barrier
	s_setprio 1
	s_waitcnt lgkmcnt(0)
	v_mfma_f32_16x16x32_bf16 v[128:131], v[132:135], v[164:167], v[128:131]
	v_mfma_f32_16x16x32_bf16 v[124:127], v[140:143], v[164:167], v[124:127]
	v_mfma_f32_16x16x32_bf16 v[112:115], v[132:135], v[172:175], v[112:115]
	v_mfma_f32_16x16x32_bf16 v[108:111], v[140:143], v[172:175], v[108:111]
	v_mfma_f32_16x16x32_bf16 v[96:99], v[132:135], v[180:183], v[96:99]
	v_mfma_f32_16x16x32_bf16 v[92:95], v[140:143], v[180:183], v[92:95]
	v_mfma_f32_16x16x32_bf16 v[80:83], v[132:135], v[192:195], v[80:83]
	v_mfma_f32_16x16x32_bf16 v[76:79], v[140:143], v[192:195], v[76:79]
	v_mfma_f32_16x16x32_bf16 v[128:131], v[136:139], v[168:171], v[128:131]
	v_mfma_f32_16x16x32_bf16 v[124:127], v[144:147], v[168:171], v[124:127]
	v_mfma_f32_16x16x32_bf16 v[112:115], v[136:139], v[176:179], v[112:115]
	v_mfma_f32_16x16x32_bf16 v[108:111], v[144:147], v[176:179], v[108:111]
	v_mfma_f32_16x16x32_bf16 v[96:99], v[136:139], v[184:187], v[96:99]
	v_mfma_f32_16x16x32_bf16 v[92:95], v[144:147], v[184:187], v[92:95]
	v_mfma_f32_16x16x32_bf16 v[80:83], v[136:139], v[210:213], v[80:83]
	v_mfma_f32_16x16x32_bf16 v[76:79], v[144:147], v[210:213], v[76:79]
	s_setprio 0
	s_setprio 1
	v_mfma_f32_16x16x32_bf16 v[120:123], v[148:151], v[164:167], v[120:123]
	v_mfma_f32_16x16x32_bf16 v[116:119], v[156:159], v[164:167], v[116:119]
	v_mfma_f32_16x16x32_bf16 v[104:107], v[148:151], v[172:175], v[104:107]
	v_mfma_f32_16x16x32_bf16 v[100:103], v[156:159], v[172:175], v[100:103]
	v_mfma_f32_16x16x32_bf16 v[88:91], v[148:151], v[180:183], v[88:91]
	v_mfma_f32_16x16x32_bf16 v[84:87], v[156:159], v[180:183], v[84:87]
	v_mfma_f32_16x16x32_bf16 v[72:75], v[148:151], v[192:195], v[72:75]
	v_mfma_f32_16x16x32_bf16 v[68:71], v[156:159], v[192:195], v[68:71]
	v_mfma_f32_16x16x32_bf16 v[120:123], v[152:155], v[168:171], v[120:123]
	v_mfma_f32_16x16x32_bf16 v[116:119], v[160:163], v[168:171], v[116:119]
	v_mfma_f32_16x16x32_bf16 v[104:107], v[152:155], v[176:179], v[104:107]
	v_mfma_f32_16x16x32_bf16 v[100:103], v[160:163], v[176:179], v[100:103]
	v_mfma_f32_16x16x32_bf16 v[88:91], v[152:155], v[184:187], v[88:91]
	v_mfma_f32_16x16x32_bf16 v[84:87], v[160:163], v[184:187], v[84:87]
	v_mfma_f32_16x16x32_bf16 v[72:75], v[152:155], v[210:213], v[72:75]
	v_mfma_f32_16x16x32_bf16 v[68:71], v[160:163], v[210:213], v[68:71]
	s_setprio 0
	s_barrier
	s_mov_b64 s[0:1], s[40:41]
	s_add_i32 s78, s78, s49
	ds_read_b128 v[164:167], v3 offset:16384
	ds_read_b128 v[168:171], v3 offset:17408
	ds_read_b128 v[172:175], v3 offset:18432
	ds_read_b128 v[176:179], v3 offset:19456
	ds_read_b128 v[180:183], v3 offset:20480
	ds_read_b128 v[184:187], v3 offset:21504
	ds_read_b128 v[192:195], v3 offset:22528
	ds_read_b128 v[210:213], v3 offset:23552
	s_mov_b32 m0, s78
	s_nop 0
	global_load_lds_dwordx4 v190, s[0:1]
	s_add_i32 m0, s78, 0x2000
	s_nop 0
	global_load_lds_dwordx4 v188, s[0:1]
	s_add_u32 s0, s40, 0x40000
	s_addc_u32 s1, s41, 0
	s_add_i32 s78, s79, s49
	s_mov_b32 m0, s78
	s_nop 0
	global_load_lds_dwordx4 v190, s[0:1]
	s_add_i32 m0, s78, 0x2000
	s_nop 0
	global_load_lds_dwordx4 v188, s[0:1]
	s_mov_b64 s[0:1], s[42:43]
	s_mov_b32 m0, s50
	s_nop 0
	global_load_lds_dwordx4 v190, s[0:1]
	s_mov_b32 m0, s51
	s_nop 0
	global_load_lds_dwordx4 v188, s[0:1]
	s_waitcnt vmcnt(8)
	s_waitcnt lgkmcnt(0)
	s_barrier
	s_setprio 1
	s_waitcnt lgkmcnt(0)
	v_mfma_f32_16x16x32_bf16 v[64:67], v[132:135], v[164:167], v[64:67]
	v_mfma_f32_16x16x32_bf16 v[60:63], v[140:143], v[164:167], v[60:63]
	v_mfma_f32_16x16x32_bf16 v[56:59], v[132:135], v[172:175], v[56:59]
	v_mfma_f32_16x16x32_bf16 v[52:55], v[140:143], v[172:175], v[52:55]
	v_mfma_f32_16x16x32_bf16 v[32:35], v[132:135], v[180:183], v[32:35]
	v_mfma_f32_16x16x32_bf16 v[28:31], v[140:143], v[180:183], v[28:31]
	v_mfma_f32_16x16x32_bf16 v[16:19], v[132:135], v[192:195], v[16:19]
	v_mfma_f32_16x16x32_bf16 v[12:15], v[140:143], v[192:195], v[12:15]
	v_mfma_f32_16x16x32_bf16 v[64:67], v[136:139], v[168:171], v[64:67]
	v_mfma_f32_16x16x32_bf16 v[60:63], v[144:147], v[168:171], v[60:63]
	v_mfma_f32_16x16x32_bf16 v[56:59], v[136:139], v[176:179], v[56:59]
	v_mfma_f32_16x16x32_bf16 v[52:55], v[144:147], v[176:179], v[52:55]
	v_mfma_f32_16x16x32_bf16 v[32:35], v[136:139], v[184:187], v[32:35]
	v_mfma_f32_16x16x32_bf16 v[28:31], v[144:147], v[184:187], v[28:31]
	v_mfma_f32_16x16x32_bf16 v[16:19], v[136:139], v[210:213], v[16:19]
	v_mfma_f32_16x16x32_bf16 v[12:15], v[144:147], v[210:213], v[12:15]
	s_setprio 0
	s_setprio 1
	v_mfma_f32_16x16x32_bf16 v[48:51], v[148:151], v[164:167], v[48:51]
	v_mfma_f32_16x16x32_bf16 v[44:47], v[156:159], v[164:167], v[44:47]
	v_mfma_f32_16x16x32_bf16 v[40:43], v[148:151], v[172:175], v[40:43]
	v_mfma_f32_16x16x32_bf16 v[36:39], v[156:159], v[172:175], v[36:39]
	v_mfma_f32_16x16x32_bf16 v[24:27], v[148:151], v[180:183], v[24:27]
	v_mfma_f32_16x16x32_bf16 v[20:23], v[156:159], v[180:183], v[20:23]
	v_mfma_f32_16x16x32_bf16 v[8:11], v[148:151], v[192:195], v[8:11]
	v_mfma_f32_16x16x32_bf16 v[4:7], v[156:159], v[192:195], v[4:7]
	v_mfma_f32_16x16x32_bf16 v[48:51], v[152:155], v[168:171], v[48:51]
	v_mfma_f32_16x16x32_bf16 v[44:47], v[160:163], v[168:171], v[44:47]
	v_mfma_f32_16x16x32_bf16 v[40:43], v[152:155], v[176:179], v[40:43]
	v_mfma_f32_16x16x32_bf16 v[36:39], v[160:163], v[176:179], v[36:39]
	v_mfma_f32_16x16x32_bf16 v[24:27], v[152:155], v[184:187], v[24:27]
	v_mfma_f32_16x16x32_bf16 v[20:23], v[160:163], v[184:187], v[20:23]
	v_mfma_f32_16x16x32_bf16 v[8:11], v[152:155], v[210:213], v[8:11]
	v_mfma_f32_16x16x32_bf16 v[4:7], v[160:163], v[210:213], v[4:7]
	s_setprio 0
	s_barrier
	s_add_i32 s78, 0, 0x18000
	s_add_i32 s79, 0, 0x1c000
	ds_read_b128 v[132:135], v229 offset:32768
	ds_read_b128 v[136:139], v229 offset:33792
	ds_read_b128 v[140:143], v229 offset:34816
	ds_read_b128 v[144:147], v229 offset:35840
	ds_read_b128 v[148:151], v229 offset:49152
	ds_read_b128 v[152:155], v229 offset:50176
	ds_read_b128 v[156:159], v229 offset:51200
	ds_read_b128 v[160:163], v229 offset:52224
	s_add_u32 s0, s42, 0x40000
	s_addc_u32 s1, s43, 0
	s_mov_b32 m0, s52
	ds_read_b128 v[164:167], v3 offset:32768
	ds_read_b128 v[168:171], v3 offset:33792
	ds_read_b128 v[172:175], v3 offset:34816
	ds_read_b128 v[176:179], v3 offset:35840
	ds_read_b128 v[180:183], v3 offset:36864
	ds_read_b128 v[184:187], v3 offset:37888
	ds_read_b128 v[192:195], v3 offset:38912
	ds_read_b128 v[210:213], v3 offset:39936
	s_nop 0
	global_load_lds_dwordx4 v190, s[0:1]
	s_mov_b32 m0, s53
	s_nop 0
	global_load_lds_dwordx4 v188, s[0:1]
	s_waitcnt vmcnt(8)
	s_waitcnt lgkmcnt(0)
	s_barrier
	s_setprio 1
	s_waitcnt lgkmcnt(0)
	v_mfma_f32_16x16x32_bf16 v[128:131], v[132:135], v[164:167], v[128:131]
	v_mfma_f32_16x16x32_bf16 v[124:127], v[140:143], v[164:167], v[124:127]
	v_mfma_f32_16x16x32_bf16 v[112:115], v[132:135], v[172:175], v[112:115]
	v_mfma_f32_16x16x32_bf16 v[108:111], v[140:143], v[172:175], v[108:111]
	v_mfma_f32_16x16x32_bf16 v[96:99], v[132:135], v[180:183], v[96:99]
	v_mfma_f32_16x16x32_bf16 v[92:95], v[140:143], v[180:183], v[92:95]
	v_mfma_f32_16x16x32_bf16 v[80:83], v[132:135], v[192:195], v[80:83]
	v_mfma_f32_16x16x32_bf16 v[76:79], v[140:143], v[192:195], v[76:79]
	v_mfma_f32_16x16x32_bf16 v[128:131], v[136:139], v[168:171], v[128:131]
	v_mfma_f32_16x16x32_bf16 v[124:127], v[144:147], v[168:171], v[124:127]
	v_mfma_f32_16x16x32_bf16 v[112:115], v[136:139], v[176:179], v[112:115]
	v_mfma_f32_16x16x32_bf16 v[108:111], v[144:147], v[176:179], v[108:111]
	v_mfma_f32_16x16x32_bf16 v[96:99], v[136:139], v[184:187], v[96:99]
	v_mfma_f32_16x16x32_bf16 v[92:95], v[144:147], v[184:187], v[92:95]
	v_mfma_f32_16x16x32_bf16 v[80:83], v[136:139], v[210:213], v[80:83]
	v_mfma_f32_16x16x32_bf16 v[76:79], v[144:147], v[210:213], v[76:79]
	s_setprio 0
	s_setprio 1
	v_mfma_f32_16x16x32_bf16 v[120:123], v[148:151], v[164:167], v[120:123]
	v_mfma_f32_16x16x32_bf16 v[116:119], v[156:159], v[164:167], v[116:119]
	v_mfma_f32_16x16x32_bf16 v[104:107], v[148:151], v[172:175], v[104:107]
	v_mfma_f32_16x16x32_bf16 v[100:103], v[156:159], v[172:175], v[100:103]
	v_mfma_f32_16x16x32_bf16 v[88:91], v[148:151], v[180:183], v[88:91]
	v_mfma_f32_16x16x32_bf16 v[84:87], v[156:159], v[180:183], v[84:87]
	v_mfma_f32_16x16x32_bf16 v[72:75], v[148:151], v[192:195], v[72:75]
	v_mfma_f32_16x16x32_bf16 v[68:71], v[156:159], v[192:195], v[68:71]
	v_mfma_f32_16x16x32_bf16 v[120:123], v[152:155], v[168:171], v[120:123]
	v_mfma_f32_16x16x32_bf16 v[116:119], v[160:163], v[168:171], v[116:119]
	v_mfma_f32_16x16x32_bf16 v[104:107], v[152:155], v[176:179], v[104:107]
	v_mfma_f32_16x16x32_bf16 v[100:103], v[160:163], v[176:179], v[100:103]
	v_mfma_f32_16x16x32_bf16 v[88:91], v[152:155], v[184:187], v[88:91]
	v_mfma_f32_16x16x32_bf16 v[84:87], v[160:163], v[184:187], v[84:87]
	v_mfma_f32_16x16x32_bf16 v[72:75], v[152:155], v[210:213], v[72:75]
	v_mfma_f32_16x16x32_bf16 v[68:71], v[160:163], v[210:213], v[68:71]
	s_setprio 0
	s_barrier
	s_add_u32 s0, s40, 0x80
	s_addc_u32 s1, s41, 0
	s_add_i32 s42, s78, s49
	ds_read_b128 v[164:167], v3 offset:49152
	ds_read_b128 v[168:171], v3 offset:50176
	ds_read_b128 v[172:175], v3 offset:51200
	ds_read_b128 v[176:179], v3 offset:52224
	ds_read_b128 v[180:183], v3 offset:53248
	ds_read_b128 v[184:187], v3 offset:54272
	ds_read_b128 v[192:195], v3 offset:55296
	ds_read_b128 v[210:213], v3 offset:56320
	s_mov_b32 m0, s42
	s_nop 0
	global_load_lds_dwordx4 v190, s[0:1]
	s_add_i32 m0, s42, 0x2000
	s_nop 0
	global_load_lds_dwordx4 v188, s[0:1]
	s_add_u32 s0, s40, 0x40080
	s_addc_u32 s1, s41, 0
	s_add_i32 s40, s79, s49
	s_mov_b32 m0, s40
	s_nop 0
	global_load_lds_dwordx4 v190, s[0:1]
	s_add_i32 m0, s40, 0x2000
	s_nop 0
	global_load_lds_dwordx4 v188, s[0:1]
	s_mov_b32 m0, s56
	s_nop 0
	global_load_lds_dwordx4 v190, s[14:15]
	s_mov_b32 m0, s57
	s_nop 0
	global_load_lds_dwordx4 v188, s[14:15]
	s_waitcnt vmcnt(8)
	s_waitcnt lgkmcnt(0)
	s_barrier
	s_setprio 1
	s_waitcnt lgkmcnt(0)
	v_mfma_f32_16x16x32_bf16 v[64:67], v[132:135], v[164:167], v[64:67]
	v_mfma_f32_16x16x32_bf16 v[60:63], v[140:143], v[164:167], v[60:63]
	v_mfma_f32_16x16x32_bf16 v[56:59], v[132:135], v[172:175], v[56:59]
	v_mfma_f32_16x16x32_bf16 v[52:55], v[140:143], v[172:175], v[52:55]
	v_mfma_f32_16x16x32_bf16 v[32:35], v[132:135], v[180:183], v[32:35]
	v_mfma_f32_16x16x32_bf16 v[28:31], v[140:143], v[180:183], v[28:31]
	v_mfma_f32_16x16x32_bf16 v[16:19], v[132:135], v[192:195], v[16:19]
	v_mfma_f32_16x16x32_bf16 v[12:15], v[140:143], v[192:195], v[12:15]
	v_mfma_f32_16x16x32_bf16 v[64:67], v[136:139], v[168:171], v[64:67]
	v_mfma_f32_16x16x32_bf16 v[60:63], v[144:147], v[168:171], v[60:63]
	v_mfma_f32_16x16x32_bf16 v[56:59], v[136:139], v[176:179], v[56:59]
	v_mfma_f32_16x16x32_bf16 v[52:55], v[144:147], v[176:179], v[52:55]
	v_mfma_f32_16x16x32_bf16 v[32:35], v[136:139], v[184:187], v[32:35]
	v_mfma_f32_16x16x32_bf16 v[28:31], v[144:147], v[184:187], v[28:31]
	v_mfma_f32_16x16x32_bf16 v[16:19], v[136:139], v[210:213], v[16:19]
	v_mfma_f32_16x16x32_bf16 v[12:15], v[144:147], v[210:213], v[12:15]
	s_setprio 0
	s_setprio 1
	v_mfma_f32_16x16x32_bf16 v[48:51], v[148:151], v[164:167], v[48:51]
	v_mfma_f32_16x16x32_bf16 v[44:47], v[156:159], v[164:167], v[44:47]
	v_mfma_f32_16x16x32_bf16 v[40:43], v[148:151], v[172:175], v[40:43]
	v_mfma_f32_16x16x32_bf16 v[36:39], v[156:159], v[172:175], v[36:39]
	v_mfma_f32_16x16x32_bf16 v[24:27], v[148:151], v[180:183], v[24:27]
	v_mfma_f32_16x16x32_bf16 v[20:23], v[156:159], v[180:183], v[20:23]
	v_mfma_f32_16x16x32_bf16 v[8:11], v[148:151], v[192:195], v[8:11]
	v_mfma_f32_16x16x32_bf16 v[4:7], v[156:159], v[192:195], v[4:7]
	v_mfma_f32_16x16x32_bf16 v[48:51], v[152:155], v[168:171], v[48:51]
	v_mfma_f32_16x16x32_bf16 v[44:47], v[160:163], v[168:171], v[44:47]
	v_mfma_f32_16x16x32_bf16 v[40:43], v[152:155], v[176:179], v[40:43]
	v_mfma_f32_16x16x32_bf16 v[36:39], v[160:163], v[176:179], v[36:39]
	v_mfma_f32_16x16x32_bf16 v[24:27], v[152:155], v[184:187], v[24:27]
	v_mfma_f32_16x16x32_bf16 v[20:23], v[160:163], v[184:187], v[20:23]
	v_mfma_f32_16x16x32_bf16 v[8:11], v[152:155], v[210:213], v[8:11]
	v_mfma_f32_16x16x32_bf16 v[4:7], v[160:163], v[210:213], v[4:7]
	s_setprio 0
	s_barrier
	s_add_i32 s75, s75, 2
	s_add_u32 s73, s73, 0x100
	s_addc_u32 s74, s74, 0
	s_cmp_gt_u32 s75, 13
	s_mov_b64 s[0:1], s[8:9]
	s_cbranch_scc0 .LBB0_2674
	s_and_b64 vcc, exec, s[26:27]
	s_cbranch_vccz .LBB0_2677
	s_barrier

.LBB0_2740:
	v_and_b32_e32 v3, 15, v1
	v_and_b32_e32 v4, 48, v1
	v_lshlrev_b32_e32 v3, 6, v3
	v_lshlrev_b32_e32 v1, 2, v1
	v_or_b32_e32 v5, v3, v4
	v_and_b32_e32 v1, 32, v1
	s_lshl_b32 s21, s21, 12
	s_lshl_b32 s20, s20, 13
	v_bitop3_b32 v3, v3, v1, v4 bitop3:0x36
	v_bitop3_b32 v6, v5, s20, v1 bitop3:0xde
	s_and_b32 s20, s21, 0x3000
	v_or_b32_e32 v1, s20, v3
	s_add_u32 s20, s14, 0x80
	v_mov_b32_e32 v135, v2
	s_addc_u32 s21, s15, 0
	s_waitcnt vmcnt(4)
	s_barrier
	s_add_i32 m0, s42, 0x18000
	v_lshl_add_u64 v[4:5], s[20:21], 0, v[134:135]
	v_mov_b32_e32 v139, v2
	global_load_lds_dwordx4 v[4:5], off
	s_add_i32 m0, s42, 0x1a000
	v_lshl_add_u64 v[4:5], s[20:21], 0, v[138:139]
	s_add_u32 s20, s0, 0x80
	v_mov_b32_e32 v133, v2
	s_addc_u32 s21, s1, 0
	s_add_i32 s47, s42, 0x8000
	v_mov_b32_e32 v137, v2
	global_load_lds_dwordx4 v[4:5], off
	s_mov_b32 m0, s47
	v_lshl_add_u64 v[4:5], s[20:21], 0, v[132:133]
	s_add_i32 s50, s42, 0xa000
	global_load_lds_dwordx4 v[4:5], off
	v_lshl_add_u64 v[4:5], s[20:21], 0, v[136:137]
	s_add_u32 s20, s14, 0x18080
	s_mov_b32 m0, s50
	s_addc_u32 s21, s15, 0
	global_load_lds_dwordx4 v[4:5], off
	s_add_i32 m0, s42, 0x1c000
	v_lshl_add_u64 v[4:5], s[20:21], 0, v[134:135]
	global_load_lds_dwordx4 v[4:5], off
	v_lshl_add_u64 v[4:5], s[20:21], 0, v[138:139]
	s_add_i32 m0, s42, 0x1e000
	v_readlane_b32 s20, v255, 11
	global_load_lds_dwordx4 v[4:5], off
	s_add_u32 s20, s38, s20
	v_readlane_b32 s21, v255, 12
	s_waitcnt vmcnt(6)
	s_addc_u32 s21, s39, s21
	s_add_u32 s51, s20, s19
	v_mov_b32_e32 v4, 0
	s_addc_u32 s64, s21, s18
	s_mov_b32 s65, -2
	v_add_u32_e32 v3, 0, v6
	s_mov_b64 s[18:19], s[0:1]
	v_mov_b32_e32 v5, v4
	v_mov_b32_e32 v6, v4
	v_mov_b32_e32 v7, v4
	v_mov_b32_e32 v8, v4
	v_mov_b32_e32 v9, v4
	v_mov_b32_e32 v10, v4
	v_mov_b32_e32 v11, v4
	v_mov_b32_e32 v12, v4
	v_mov_b32_e32 v13, v4
	s_waitcnt vmcnt(0)
	v_mov_b32_e32 v14, v4
	v_mov_b32_e32 v15, v4
	v_mov_b32_e32 v16, v4
	v_mov_b32_e32 v17, v4
	v_mov_b32_e32 v18, v4
	v_mov_b32_e32 v19, v4
	v_mov_b32_e32 v28, v4
	v_mov_b32_e32 v29, v4
	v_mov_b32_e32 v30, v4
	v_mov_b32_e32 v31, v4
	v_mov_b32_e32 v32, v4
	v_mov_b32_e32 v33, v4
	v_mov_b32_e32 v34, v4
	v_mov_b32_e32 v35, v4
	v_mov_b32_e32 v44, v4
	v_mov_b32_e32 v45, v4
	v_mov_b32_e32 v46, v4
	v_mov_b32_e32 v47, v4
	v_mov_b32_e32 v48, v4
	v_mov_b32_e32 v49, v4
	v_mov_b32_e32 v50, v4
	v_mov_b32_e32 v51, v4
	v_mov_b32_e32 v20, v4
	v_mov_b32_e32 v21, v4
	v_mov_b32_e32 v22, v4
	v_mov_b32_e32 v23, v4
	v_mov_b32_e32 v24, v4
	v_mov_b32_e32 v25, v4
	v_mov_b32_e32 v26, v4
	v_mov_b32_e32 v27, v4
	v_mov_b32_e32 v36, v4
	v_mov_b32_e32 v37, v4
	v_mov_b32_e32 v38, v4
	v_mov_b32_e32 v39, v4
	v_mov_b32_e32 v40, v4
	v_mov_b32_e32 v41, v4
	v_mov_b32_e32 v42, v4
	v_mov_b32_e32 v43, v4
	v_mov_b32_e32 v52, v4
	v_mov_b32_e32 v53, v4
	v_mov_b32_e32 v54, v4
	v_mov_b32_e32 v55, v4
	v_mov_b32_e32 v56, v4
	v_mov_b32_e32 v57, v4
	v_mov_b32_e32 v58, v4
	v_mov_b32_e32 v59, v4
	v_mov_b32_e32 v60, v4
	v_mov_b32_e32 v61, v4
	v_mov_b32_e32 v62, v4
	v_mov_b32_e32 v63, v4
	v_mov_b32_e32 v64, v4
	v_mov_b32_e32 v65, v4
	v_mov_b32_e32 v66, v4
	v_mov_b32_e32 v67, v4
	v_mov_b32_e32 v68, v4
	v_mov_b32_e32 v69, v4
	v_mov_b32_e32 v70, v4
	v_mov_b32_e32 v71, v4
	v_mov_b32_e32 v72, v4
	v_mov_b32_e32 v73, v4
	v_mov_b32_e32 v74, v4
	v_mov_b32_e32 v75, v4
	v_mov_b32_e32 v76, v4
	v_mov_b32_e32 v77, v4
	v_mov_b32_e32 v78, v4
	v_mov_b32_e32 v79, v4
	v_mov_b32_e32 v80, v4
	v_mov_b32_e32 v81, v4
	v_mov_b32_e32 v82, v4
	v_mov_b32_e32 v83, v4
	v_mov_b32_e32 v92, v4
	v_mov_b32_e32 v93, v4
	v_mov_b32_e32 v94, v4
	v_mov_b32_e32 v95, v4
	v_mov_b32_e32 v96, v4
	v_mov_b32_e32 v97, v4
	v_mov_b32_e32 v98, v4
	v_mov_b32_e32 v99, v4
	v_mov_b32_e32 v108, v4
	v_mov_b32_e32 v109, v4
	v_mov_b32_e32 v110, v4
	v_mov_b32_e32 v111, v4
	v_mov_b32_e32 v112, v4
	v_mov_b32_e32 v113, v4
	v_mov_b32_e32 v114, v4
	v_mov_b32_e32 v115, v4
	v_mov_b32_e32 v84, v4
	v_mov_b32_e32 v85, v4
	v_mov_b32_e32 v86, v4
	v_mov_b32_e32 v87, v4
	v_mov_b32_e32 v88, v4
	v_mov_b32_e32 v89, v4
	v_mov_b32_e32 v90, v4
	v_mov_b32_e32 v91, v4
	v_mov_b32_e32 v100, v4
	v_mov_b32_e32 v101, v4
	v_mov_b32_e32 v102, v4
	v_mov_b32_e32 v103, v4
	v_mov_b32_e32 v104, v4
	v_mov_b32_e32 v105, v4
	v_mov_b32_e32 v106, v4
	v_mov_b32_e32 v107, v4
	v_mov_b32_e32 v116, v4
	v_mov_b32_e32 v117, v4
	v_mov_b32_e32 v118, v4
	v_mov_b32_e32 v119, v4
	v_mov_b32_e32 v120, v4
	v_mov_b32_e32 v121, v4
	v_mov_b32_e32 v122, v4
	v_mov_b32_e32 v123, v4
	v_mov_b32_e32 v124, v4
	v_mov_b32_e32 v125, v4
	v_mov_b32_e32 v126, v4
	v_mov_b32_e32 v127, v4
	v_mov_b32_e32 v128, v4
	v_mov_b32_e32 v129, v4
	v_mov_b32_e32 v130, v4
	v_mov_b32_e32 v131, v4
	v_add_u32_e32 v218, 0x10000, v1
	s_barrier
.LBB0_2741:
	s_add_u32 s20, s18, 0x100
	s_addc_u32 s21, s19, 0
	s_cmp_eq_u32 s65, 2
	s_cselect_b32 s22, s14, s51
	s_cselect_b32 s23, s15, s64
	s_cselect_b32 s56, s0, s20
	s_cselect_b32 s57, s1, s21
	s_add_u32 s54, s22, 0x80
	s_addc_u32 s55, s23, 0
	s_add_u32 s52, s56, 0x80
	s_addc_u32 s53, s57, 0
	s_add_i32 s67, 0, 0x10000
	ds_read_b128 v[140:143], v218
	ds_read_b128 v[144:147], v218 offset:1024
	ds_read_b128 v[148:151], v218 offset:2048
	ds_read_b128 v[152:155], v218 offset:3072
	s_add_u32 s18, s18, 0x30080
	s_addc_u32 s19, s19, 0
	ds_read_b128 v[156:159], v3
	ds_read_b128 v[160:163], v3 offset:1024
	ds_read_b128 v[164:167], v3 offset:2048
	ds_read_b128 v[168:171], v3 offset:3072
	ds_read_b128 v[172:175], v3 offset:4096
	ds_read_b128 v[176:179], v3 offset:5120
	ds_read_b128 v[180:183], v3 offset:6144
	ds_read_b128 v[184:187], v3 offset:7168
	s_add_i32 m0, s42, 0xc000
	s_nop 0
	global_load_lds_dwordx4 v132, s[18:19]
	s_add_i32 m0, s42, 0xe000
	s_nop 0
	global_load_lds_dwordx4 v136, s[18:19]
	s_waitcnt lgkmcnt(8)
	s_barrier
	s_waitcnt lgkmcnt(0)
	s_setprio 1
	s_waitcnt lgkmcnt(0)
	v_mfma_f32_16x16x32_bf16 v[128:131], v[140:143], v[156:159], v[128:131]
	v_mfma_f32_16x16x32_bf16 v[124:127], v[148:151], v[156:159], v[124:127]
	v_mfma_f32_16x16x32_bf16 v[120:123], v[140:143], v[164:167], v[120:123]
	v_mfma_f32_16x16x32_bf16 v[116:119], v[148:151], v[164:167], v[116:119]
	v_mfma_f32_16x16x32_bf16 v[104:107], v[140:143], v[172:175], v[104:107]
	v_mfma_f32_16x16x32_bf16 v[100:103], v[148:151], v[172:175], v[100:103]
	v_mfma_f32_16x16x32_bf16 v[88:91], v[140:143], v[180:183], v[88:91]
	v_mfma_f32_16x16x32_bf16 v[84:87], v[148:151], v[180:183], v[84:87]
	v_mfma_f32_16x16x32_bf16 v[128:131], v[144:147], v[160:163], v[128:131]
	v_mfma_f32_16x16x32_bf16 v[124:127], v[152:155], v[160:163], v[124:127]
	v_mfma_f32_16x16x32_bf16 v[120:123], v[144:147], v[168:171], v[120:123]
	v_mfma_f32_16x16x32_bf16 v[116:119], v[152:155], v[168:171], v[116:119]
	v_mfma_f32_16x16x32_bf16 v[104:107], v[144:147], v[176:179], v[104:107]
	v_mfma_f32_16x16x32_bf16 v[100:103], v[152:155], v[176:179], v[100:103]
	v_mfma_f32_16x16x32_bf16 v[88:91], v[144:147], v[184:187], v[88:91]
	v_mfma_f32_16x16x32_bf16 v[84:87], v[152:155], v[184:187], v[84:87]
	s_setprio 0
	s_barrier
	s_add_i32 s68, 0, 0x14000
	s_mov_b64 s[18:19], s[22:23]
	s_add_i32 s67, s67, s41
	ds_read_b128 v[188:191], v218 offset:16384
	ds_read_b128 v[192:195], v218 offset:17408
	ds_read_b128 v[210:213], v218 offset:18432
	ds_read_b128 v[214:217], v218 offset:19456
	s_mov_b32 m0, s67
	s_nop 0
	global_load_lds_dwordx4 v134, s[18:19]
	s_add_i32 m0, s67, 0x2000
	s_nop 0
	global_load_lds_dwordx4 v138, s[18:19]
	s_barrier
	s_waitcnt lgkmcnt(0)
	s_setprio 1
	s_waitcnt lgkmcnt(0)
	v_mfma_f32_16x16x32_bf16 v[112:115], v[188:191], v[156:159], v[112:115]
	v_mfma_f32_16x16x32_bf16 v[108:111], v[210:213], v[156:159], v[108:111]
	v_mfma_f32_16x16x32_bf16 v[96:99], v[188:191], v[164:167], v[96:99]
	v_mfma_f32_16x16x32_bf16 v[92:95], v[210:213], v[164:167], v[92:95]
	v_mfma_f32_16x16x32_bf16 v[80:83], v[188:191], v[172:175], v[80:83]
	v_mfma_f32_16x16x32_bf16 v[76:79], v[210:213], v[172:175], v[76:79]
	v_mfma_f32_16x16x32_bf16 v[72:75], v[188:191], v[180:183], v[72:75]
	v_mfma_f32_16x16x32_bf16 v[68:71], v[210:213], v[180:183], v[68:71]
	v_mfma_f32_16x16x32_bf16 v[112:115], v[192:195], v[160:163], v[112:115]
	v_mfma_f32_16x16x32_bf16 v[108:111], v[214:217], v[160:163], v[108:111]
	v_mfma_f32_16x16x32_bf16 v[96:99], v[192:195], v[168:171], v[96:99]
	v_mfma_f32_16x16x32_bf16 v[92:95], v[214:217], v[168:171], v[92:95]
	v_mfma_f32_16x16x32_bf16 v[80:83], v[192:195], v[176:179], v[80:83]
	v_mfma_f32_16x16x32_bf16 v[76:79], v[214:217], v[176:179], v[76:79]
	v_mfma_f32_16x16x32_bf16 v[72:75], v[192:195], v[184:187], v[72:75]
	v_mfma_f32_16x16x32_bf16 v[68:71], v[214:217], v[184:187], v[68:71]
	s_setprio 0
	s_mov_b64 s[18:19], s[56:57]
	s_mov_b32 m0, s42
	s_barrier
	ds_read_b128 v[156:159], v3 offset:16384
	ds_read_b128 v[160:163], v3 offset:17408
	ds_read_b128 v[164:167], v3 offset:18432
	ds_read_b128 v[168:171], v3 offset:19456
	ds_read_b128 v[172:175], v3 offset:20480
	ds_read_b128 v[176:179], v3 offset:21504
	ds_read_b128 v[180:183], v3 offset:22528
	ds_read_b128 v[184:187], v3 offset:23552
	s_nop 0
	global_load_lds_dwordx4 v132, s[18:19]
	s_mov_b32 m0, s43
	s_nop 0
	global_load_lds_dwordx4 v136, s[18:19]
	s_barrier
	s_waitcnt lgkmcnt(0)
	s_setprio 1
	s_waitcnt lgkmcnt(0)
	v_mfma_f32_16x16x32_bf16 v[64:67], v[140:143], v[156:159], v[64:67]
	v_mfma_f32_16x16x32_bf16 v[60:63], v[148:151], v[156:159], v[60:63]
	v_mfma_f32_16x16x32_bf16 v[56:59], v[140:143], v[164:167], v[56:59]
	v_mfma_f32_16x16x32_bf16 v[52:55], v[148:151], v[164:167], v[52:55]
	v_mfma_f32_16x16x32_bf16 v[40:43], v[140:143], v[172:175], v[40:43]
	v_mfma_f32_16x16x32_bf16 v[36:39], v[148:151], v[172:175], v[36:39]
	v_mfma_f32_16x16x32_bf16 v[24:27], v[140:143], v[180:183], v[24:27]
	v_mfma_f32_16x16x32_bf16 v[20:23], v[148:151], v[180:183], v[20:23]
	v_mfma_f32_16x16x32_bf16 v[64:67], v[144:147], v[160:163], v[64:67]
	v_mfma_f32_16x16x32_bf16 v[60:63], v[152:155], v[160:163], v[60:63]
	v_mfma_f32_16x16x32_bf16 v[56:59], v[144:147], v[168:171], v[56:59]
	v_mfma_f32_16x16x32_bf16 v[52:55], v[152:155], v[168:171], v[52:55]
	v_mfma_f32_16x16x32_bf16 v[40:43], v[144:147], v[176:179], v[40:43]
	v_mfma_f32_16x16x32_bf16 v[36:39], v[152:155], v[176:179], v[36:39]
	v_mfma_f32_16x16x32_bf16 v[24:27], v[144:147], v[184:187], v[24:27]
	v_mfma_f32_16x16x32_bf16 v[20:23], v[152:155], v[184:187], v[20:23]
	s_setprio 0
	s_barrier
	s_add_u32 s18, s22, 0x18000
	s_addc_u32 s19, s23, 0
	s_add_i32 s67, s68, s41
	s_mov_b32 m0, s67
	s_nop 0
	global_load_lds_dwordx4 v134, s[18:19]
	s_add_i32 m0, s67, 0x2000
	s_nop 0
	global_load_lds_dwordx4 v138, s[18:19]
	s_waitcnt vmcnt(6)
	s_barrier
	s_setprio 1
	v_mfma_f32_16x16x32_bf16 v[48:51], v[188:191], v[156:159], v[48:51]
	v_mfma_f32_16x16x32_bf16 v[44:47], v[210:213], v[156:159], v[44:47]
	v_mfma_f32_16x16x32_bf16 v[32:35], v[188:191], v[164:167], v[32:35]
	v_mfma_f32_16x16x32_bf16 v[28:31], v[210:213], v[164:167], v[28:31]
	v_mfma_f32_16x16x32_bf16 v[16:19], v[188:191], v[172:175], v[16:19]
	v_mfma_f32_16x16x32_bf16 v[12:15], v[210:213], v[172:175], v[12:15]
	v_mfma_f32_16x16x32_bf16 v[8:11], v[188:191], v[180:183], v[8:11]
	v_mfma_f32_16x16x32_bf16 v[4:7], v[210:213], v[180:183], v[4:7]
	v_mfma_f32_16x16x32_bf16 v[48:51], v[192:195], v[160:163], v[48:51]
	v_mfma_f32_16x16x32_bf16 v[44:47], v[214:217], v[160:163], v[44:47]
	v_mfma_f32_16x16x32_bf16 v[32:35], v[192:195], v[168:171], v[32:35]
	v_mfma_f32_16x16x32_bf16 v[28:31], v[214:217], v[168:171], v[28:31]
	v_mfma_f32_16x16x32_bf16 v[16:19], v[192:195], v[176:179], v[16:19]
	v_mfma_f32_16x16x32_bf16 v[12:15], v[214:217], v[176:179], v[12:15]
	v_mfma_f32_16x16x32_bf16 v[8:11], v[192:195], v[184:187], v[8:11]
	v_mfma_f32_16x16x32_bf16 v[4:7], v[214:217], v[184:187], v[4:7]
	s_setprio 0
	s_add_i32 s67, 0, 0x18000
	s_barrier
	ds_read_b128 v[140:143], v218 offset:32768
	ds_read_b128 v[144:147], v218 offset:33792
	ds_read_b128 v[148:151], v218 offset:34816
	ds_read_b128 v[152:155], v218 offset:35840
	s_add_u32 s18, s56, 0x30000
	s_addc_u32 s19, s57, 0
	s_mov_b32 m0, s45
	ds_read_b128 v[156:159], v3 offset:32768
	ds_read_b128 v[160:163], v3 offset:33792
	ds_read_b128 v[164:167], v3 offset:34816
	ds_read_b128 v[168:171], v3 offset:35840
	ds_read_b128 v[172:175], v3 offset:36864
	ds_read_b128 v[176:179], v3 offset:37888
	ds_read_b128 v[180:183], v3 offset:38912
	ds_read_b128 v[184:187], v3 offset:39936
	s_nop 0
	global_load_lds_dwordx4 v132, s[18:19]
	s_mov_b32 m0, s46
	s_nop 0
	global_load_lds_dwordx4 v136, s[18:19]
	s_waitcnt lgkmcnt(8)
	s_barrier
	s_waitcnt lgkmcnt(0)
	s_setprio 1
	s_waitcnt lgkmcnt(0)
	v_mfma_f32_16x16x32_bf16 v[128:131], v[140:143], v[156:159], v[128:131]
	v_mfma_f32_16x16x32_bf16 v[124:127], v[148:151], v[156:159], v[124:127]
	v_mfma_f32_16x16x32_bf16 v[120:123], v[140:143], v[164:167], v[120:123]
	v_mfma_f32_16x16x32_bf16 v[116:119], v[148:151], v[164:167], v[116:119]
	v_mfma_f32_16x16x32_bf16 v[104:107], v[140:143], v[172:175], v[104:107]
	v_mfma_f32_16x16x32_bf16 v[100:103], v[148:151], v[172:175], v[100:103]
	v_mfma_f32_16x16x32_bf16 v[88:91], v[140:143], v[180:183], v[88:91]
	v_mfma_f32_16x16x32_bf16 v[84:87], v[148:151], v[180:183], v[84:87]
	v_mfma_f32_16x16x32_bf16 v[128:131], v[144:147], v[160:163], v[128:131]
	v_mfma_f32_16x16x32_bf16 v[124:127], v[152:155], v[160:163], v[124:127]
	v_mfma_f32_16x16x32_bf16 v[120:123], v[144:147], v[168:171], v[120:123]
	v_mfma_f32_16x16x32_bf16 v[116:119], v[152:155], v[168:171], v[116:119]
	v_mfma_f32_16x16x32_bf16 v[104:107], v[144:147], v[176:179], v[104:107]
	v_mfma_f32_16x16x32_bf16 v[100:103], v[152:155], v[176:179], v[100:103]
	v_mfma_f32_16x16x32_bf16 v[88:91], v[144:147], v[184:187], v[88:91]
	v_mfma_f32_16x16x32_bf16 v[84:87], v[152:155], v[184:187], v[84:87]
	s_setprio 0
	s_barrier
	s_add_i32 s56, 0, 0x1c000
	s_add_i32 s18, s67, s41
	ds_read_b128 v[188:191], v218 offset:49152
	ds_read_b128 v[192:195], v218 offset:50176
	ds_read_b128 v[210:213], v218 offset:51200
	ds_read_b128 v[214:217], v218 offset:52224
	s_mov_b32 m0, s18
	s_nop 0
	global_load_lds_dwordx4 v134, s[54:55]
	s_add_i32 m0, s18, 0x2000
	s_nop 0
	global_load_lds_dwordx4 v138, s[54:55]
	s_barrier
	s_waitcnt lgkmcnt(0)
	s_setprio 1
	s_waitcnt lgkmcnt(0)
	v_mfma_f32_16x16x32_bf16 v[112:115], v[188:191], v[156:159], v[112:115]
	v_mfma_f32_16x16x32_bf16 v[108:111], v[210:213], v[156:159], v[108:111]
	v_mfma_f32_16x16x32_bf16 v[96:99], v[188:191], v[164:167], v[96:99]
	v_mfma_f32_16x16x32_bf16 v[92:95], v[210:213], v[164:167], v[92:95]
	v_mfma_f32_16x16x32_bf16 v[80:83], v[188:191], v[172:175], v[80:83]
	v_mfma_f32_16x16x32_bf16 v[76:79], v[210:213], v[172:175], v[76:79]
	v_mfma_f32_16x16x32_bf16 v[72:75], v[188:191], v[180:183], v[72:75]
	v_mfma_f32_16x16x32_bf16 v[68:71], v[210:213], v[180:183], v[68:71]
	v_mfma_f32_16x16x32_bf16 v[112:115], v[192:195], v[160:163], v[112:115]
	v_mfma_f32_16x16x32_bf16 v[108:111], v[214:217], v[160:163], v[108:111]
	v_mfma_f32_16x16x32_bf16 v[96:99], v[192:195], v[168:171], v[96:99]
	v_mfma_f32_16x16x32_bf16 v[92:95], v[214:217], v[168:171], v[92:95]
	v_mfma_f32_16x16x32_bf16 v[80:83], v[192:195], v[176:179], v[80:83]
	v_mfma_f32_16x16x32_bf16 v[76:79], v[214:217], v[176:179], v[76:79]
	v_mfma_f32_16x16x32_bf16 v[72:75], v[192:195], v[184:187], v[72:75]
	v_mfma_f32_16x16x32_bf16 v[68:71], v[214:217], v[184:187], v[68:71]
	s_setprio 0
	s_mov_b32 m0, s47
	s_barrier
	ds_read_b128 v[156:159], v3 offset:49152
	ds_read_b128 v[160:163], v3 offset:50176
	ds_read_b128 v[164:167], v3 offset:51200
	ds_read_b128 v[168:171], v3 offset:52224
	ds_read_b128 v[172:175], v3 offset:53248
	ds_read_b128 v[176:179], v3 offset:54272
	ds_read_b128 v[180:183], v3 offset:55296
	ds_read_b128 v[184:187], v3 offset:56320
	s_nop 0
	global_load_lds_dwordx4 v132, s[52:53]
	s_mov_b32 m0, s50
	s_nop 0
	global_load_lds_dwordx4 v136, s[52:53]
	s_barrier
	s_waitcnt lgkmcnt(0)
	s_setprio 1
	s_waitcnt lgkmcnt(0)
	v_mfma_f32_16x16x32_bf16 v[64:67], v[140:143], v[156:159], v[64:67]
	v_mfma_f32_16x16x32_bf16 v[60:63], v[148:151], v[156:159], v[60:63]
	v_mfma_f32_16x16x32_bf16 v[56:59], v[140:143], v[164:167], v[56:59]
	v_mfma_f32_16x16x32_bf16 v[52:55], v[148:151], v[164:167], v[52:55]
	v_mfma_f32_16x16x32_bf16 v[40:43], v[140:143], v[172:175], v[40:43]
	v_mfma_f32_16x16x32_bf16 v[36:39], v[148:151], v[172:175], v[36:39]
	v_mfma_f32_16x16x32_bf16 v[24:27], v[140:143], v[180:183], v[24:27]
	v_mfma_f32_16x16x32_bf16 v[20:23], v[148:151], v[180:183], v[20:23]
	v_mfma_f32_16x16x32_bf16 v[64:67], v[144:147], v[160:163], v[64:67]
	v_mfma_f32_16x16x32_bf16 v[60:63], v[152:155], v[160:163], v[60:63]
	v_mfma_f32_16x16x32_bf16 v[56:59], v[144:147], v[168:171], v[56:59]
	v_mfma_f32_16x16x32_bf16 v[52:55], v[152:155], v[168:171], v[52:55]
	v_mfma_f32_16x16x32_bf16 v[40:43], v[144:147], v[176:179], v[40:43]
	v_mfma_f32_16x16x32_bf16 v[36:39], v[152:155], v[176:179], v[36:39]
	v_mfma_f32_16x16x32_bf16 v[24:27], v[144:147], v[184:187], v[24:27]
	v_mfma_f32_16x16x32_bf16 v[20:23], v[152:155], v[184:187], v[20:23]
	s_setprio 0
	s_barrier
	s_add_u32 s18, s22, 0x18080
	s_addc_u32 s19, s23, 0
	s_add_i32 s22, s56, s41
	s_mov_b32 m0, s22
	s_nop 0
	global_load_lds_dwordx4 v134, s[18:19]
	s_add_i32 m0, s22, 0x2000
	s_nop 0
	global_load_lds_dwordx4 v138, s[18:19]
	s_waitcnt vmcnt(6)
	s_barrier
	s_setprio 1
	v_mfma_f32_16x16x32_bf16 v[48:51], v[188:191], v[156:159], v[48:51]
	v_mfma_f32_16x16x32_bf16 v[44:47], v[210:213], v[156:159], v[44:47]
	v_mfma_f32_16x16x32_bf16 v[32:35], v[188:191], v[164:167], v[32:35]
	v_mfma_f32_16x16x32_bf16 v[28:31], v[210:213], v[164:167], v[28:31]
	v_mfma_f32_16x16x32_bf16 v[16:19], v[188:191], v[172:175], v[16:19]
	v_mfma_f32_16x16x32_bf16 v[12:15], v[210:213], v[172:175], v[12:15]
	v_mfma_f32_16x16x32_bf16 v[8:11], v[188:191], v[180:183], v[8:11]
	v_mfma_f32_16x16x32_bf16 v[4:7], v[210:213], v[180:183], v[4:7]
	v_mfma_f32_16x16x32_bf16 v[48:51], v[192:195], v[160:163], v[48:51]
	v_mfma_f32_16x16x32_bf16 v[44:47], v[214:217], v[160:163], v[44:47]
	v_mfma_f32_16x16x32_bf16 v[32:35], v[192:195], v[168:171], v[32:35]
	v_mfma_f32_16x16x32_bf16 v[28:31], v[214:217], v[168:171], v[28:31]
	v_mfma_f32_16x16x32_bf16 v[16:19], v[192:195], v[176:179], v[16:19]
	v_mfma_f32_16x16x32_bf16 v[12:15], v[214:217], v[176:179], v[12:15]
	v_mfma_f32_16x16x32_bf16 v[8:11], v[192:195], v[184:187], v[8:11]
	v_mfma_f32_16x16x32_bf16 v[4:7], v[214:217], v[184:187], v[4:7]
	s_setprio 0
	s_add_i32 s65, s65, 2
	s_add_u32 s51, s51, 0x100
	s_addc_u32 s64, s64, 0
	s_cmp_gt_u32 s65, 3
	s_mov_b64 s[18:19], s[20:21]
	s_barrier
	s_cbranch_scc0 .LBB0_2741
	v_mov_b32_e32 v1, v0
	s_add_u32 s0, s38, 0xb55ec00
	s_addc_u32 s1, s39, 0
	v_readfirstlane_b32 s14, v1
	s_and_b32 s15, s14, 0xc0
	s_ashr_i32 s14, s14, 2
	s_andn2_b32 s14, s14, 63
	s_addk_i32 s14, 0x4000
	v_and_or_b32 v132, v1, 15, s14
	v_lshrrev_b32_e32 v1, 1, v1
	v_and_or_b32 v1, v1, 24, s15
	v_readlane_b32 s14, v255, 15
	v_ashrrev_i32_e32 v133, 31, v132
	v_lshlrev_b64 v[136:137], 11, v[132:133]
	v_or_b32_e32 v134, s14, v1
	v_ashrrev_i32_e32 v135, 31, v134
	v_cvt_pk_bf16_f32 v112, v112, v113
	v_cvt_pk_bf16_f32 v113, v114, v115
	v_cvt_pk_bf16_f32 v114, v108, v109
	v_or_b32_e32 v108, 16, v132
	v_lshl_add_u64 v[136:137], s[0:1], 0, v[136:137]
	v_lshlrev_b64 v[134:135], 1, v[134:135]
	v_ashrrev_i32_e32 v109, 31, v108
	v_lshl_add_u64 v[136:137], v[136:137], 0, v[134:135]
	v_cvt_pk_bf16_f32 v128, v128, v129
	v_cvt_pk_bf16_f32 v129, v130, v131
	v_cvt_pk_bf16_f32 v130, v124, v125
	v_cvt_pk_bf16_f32 v131, v126, v127
	global_store_dwordx4 v[136:137], v[128:131], off sc1
	s_nop 1
	v_lshlrev_b64 v[108:109], 11, v[108:109]
	v_cvt_pk_bf16_f32 v96, v96, v97
	v_cvt_pk_bf16_f32 v97, v98, v99
	v_cvt_pk_bf16_f32 v98, v92, v93
	v_or_b32_e32 v92, 32, v132
	v_lshl_add_u64 v[124:125], v[136:137], 0, 64
	v_cvt_pk_bf16_f32 v115, v110, v111
	global_store_dwordx4 v[124:125], v[112:115], off sc1
	s_nop 1
	v_lshl_add_u64 v[108:109], s[0:1], 0, v[108:109]
	v_ashrrev_i32_e32 v93, 31, v92
	v_lshl_add_u64 v[112:113], v[108:109], 0, v[134:135]
	v_cvt_pk_bf16_f32 v108, v120, v121
	v_cvt_pk_bf16_f32 v109, v122, v123
	v_cvt_pk_bf16_f32 v110, v116, v117
	v_cvt_pk_bf16_f32 v111, v118, v119
	global_store_dwordx4 v[112:113], v[108:111], off sc1
	s_nop 1
	v_lshlrev_b64 v[92:93], 11, v[92:93]
	v_cvt_pk_bf16_f32 v80, v80, v81
	v_cvt_pk_bf16_f32 v81, v82, v83
	v_cvt_pk_bf16_f32 v82, v76, v77
	v_or_b32_e32 v76, 48, v132
	v_lshl_add_u64 v[108:109], v[112:113], 0, 64
	v_cvt_pk_bf16_f32 v99, v94, v95
	global_store_dwordx4 v[108:109], v[96:99], off sc1
	s_nop 1
	v_lshl_add_u64 v[92:93], s[0:1], 0, v[92:93]
	v_ashrrev_i32_e32 v77, 31, v76
	v_lshl_add_u64 v[96:97], v[92:93], 0, v[134:135]
	v_cvt_pk_bf16_f32 v92, v104, v105
	v_cvt_pk_bf16_f32 v93, v106, v107
	v_cvt_pk_bf16_f32 v94, v100, v101
	v_cvt_pk_bf16_f32 v95, v102, v103
	global_store_dwordx4 v[96:97], v[92:95], off sc1
	s_nop 1
	v_lshlrev_b64 v[76:77], 11, v[76:77]
	v_lshl_add_u64 v[92:93], v[96:97], 0, 64
	v_cvt_pk_bf16_f32 v83, v78, v79
	global_store_dwordx4 v[92:93], v[80:83], off sc1
	s_nop 1
	v_lshl_add_u64 v[76:77], s[0:1], 0, v[76:77]
	v_lshl_add_u64 v[80:81], v[76:77], 0, v[134:135]
	v_cvt_pk_bf16_f32 v76, v88, v89
	v_cvt_pk_bf16_f32 v77, v90, v91
	v_cvt_pk_bf16_f32 v78, v84, v85
	v_cvt_pk_bf16_f32 v79, v86, v87
	global_store_dwordx4 v[80:81], v[76:79], off sc1
	s_nop 1
	v_lshl_add_u64 v[76:77], v[80:81], 0, 64
	v_cvt_pk_bf16_f32 v72, v72, v73
	v_cvt_pk_bf16_f32 v73, v74, v75
	v_cvt_pk_bf16_f32 v74, v68, v69
	v_cvt_pk_bf16_f32 v75, v70, v71
	global_store_dwordx4 v[76:77], v[72:75], off sc1
	s_nop 1
	s_mov_b64 s[0:1], 0x40000
	v_lshl_add_u64 v[68:69], v[136:137], 0, s[0:1]
	v_cvt_pk_bf16_f32 v64, v64, v65
	v_cvt_pk_bf16_f32 v65, v66, v67
	v_cvt_pk_bf16_f32 v66, v60, v61
	v_cvt_pk_bf16_f32 v67, v62, v63
	global_store_dwordx4 v[68:69], v[64:67], off sc1
	s_nop 1
	s_mov_b64 s[0:1], 0x40040
	v_lshl_add_u64 v[60:61], v[136:137], 0, s[0:1]
	v_cvt_pk_bf16_f32 v48, v48, v49
	v_cvt_pk_bf16_f32 v49, v50, v51
	v_cvt_pk_bf16_f32 v50, v44, v45
	v_cvt_pk_bf16_f32 v51, v46, v47
	global_store_dwordx4 v[60:61], v[48:51], off sc1
	s_nop 1
	s_mov_b64 s[0:1], 0x48000
	v_lshl_add_u64 v[48:49], v[136:137], 0, s[0:1]
	v_cvt_pk_bf16_f32 v44, v56, v57
	v_cvt_pk_bf16_f32 v45, v58, v59
	v_cvt_pk_bf16_f32 v46, v52, v53
	v_cvt_pk_bf16_f32 v47, v54, v55
	global_store_dwordx4 v[48:49], v[44:47], off sc1
	s_nop 1
	s_mov_b64 s[0:1], 0x48040
	v_lshl_add_u64 v[44:45], v[136:137], 0, s[0:1]
	v_cvt_pk_bf16_f32 v32, v32, v33
	v_cvt_pk_bf16_f32 v33, v34, v35
	v_cvt_pk_bf16_f32 v34, v28, v29
	v_cvt_pk_bf16_f32 v35, v30, v31
	global_store_dwordx4 v[44:45], v[32:35], off sc1
	s_nop 1
	s_mov_b64 s[0:1], 0x50000
	v_lshl_add_u64 v[32:33], v[136:137], 0, s[0:1]
	v_cvt_pk_bf16_f32 v28, v40, v41
	v_cvt_pk_bf16_f32 v29, v42, v43
	v_cvt_pk_bf16_f32 v30, v36, v37
	v_cvt_pk_bf16_f32 v31, v38, v39
	global_store_dwordx4 v[32:33], v[28:31], off sc1
	s_nop 1
	s_mov_b64 s[0:1], 0x50040
	v_lshl_add_u64 v[28:29], v[136:137], 0, s[0:1]
	v_cvt_pk_bf16_f32 v16, v16, v17
	v_cvt_pk_bf16_f32 v17, v18, v19
	v_cvt_pk_bf16_f32 v18, v12, v13
	v_cvt_pk_bf16_f32 v19, v14, v15
	global_store_dwordx4 v[28:29], v[16:19], off sc1
	s_nop 1
	s_mov_b64 s[0:1], 0x58000
	v_lshl_add_u64 v[16:17], v[136:137], 0, s[0:1]
	v_cvt_pk_bf16_f32 v12, v24, v25
	v_cvt_pk_bf16_f32 v13, v26, v27
	v_cvt_pk_bf16_f32 v14, v20, v21
	v_cvt_pk_bf16_f32 v15, v22, v23
	global_store_dwordx4 v[16:17], v[12:15], off sc1
	s_nop 1
	s_mov_b64 s[0:1], 0x58040
	v_lshl_add_u64 v[12:13], v[136:137], 0, s[0:1]
	v_cvt_pk_bf16_f32 v8, v8, v9
	v_cvt_pk_bf16_f32 v9, v10, v11
	v_cvt_pk_bf16_f32 v10, v4, v5
	v_cvt_pk_bf16_f32 v11, v6, v7
	global_store_dwordx4 v[12:13], v[8:11], off sc1
	s_nop 1
	s_waitcnt vmcnt(0)
	v_readlane_b32 s15, v255, 16
	s_mov_b64 s[0:1], exec
	v_readlane_b32 s14, v253, 23
	v_readlane_b32 s15, v253, 24
	s_and_b64 s[14:15], s[0:1], s[14:15]
	s_mov_b64 exec, s[14:15]
	s_cbranch_execz .LBB0_2745
	s_mov_b64 s[14:15], exec
	v_mbcnt_lo_u32_b32 v1, s14, 0
	v_mbcnt_hi_u32_b32 v1, s15, v1
	v_cmp_eq_u32_e32 vcc, 0, v1
	s_and_b64 s[18:19], exec, vcc
	s_mov_b64 exec, s[18:19]
	s_cbranch_execz .LBB0_2745
	s_bcnt1_i32_b64 s14, s[14:15]
	v_mov_b32_e32 v1, s14
	global_atomic_add v2, v1, s[8:9]

.LBB0_2765:
	v_and_b32_e32 v3, 15, v1
	v_and_b32_e32 v4, 48, v1
	v_lshlrev_b32_e32 v3, 6, v3
	v_lshlrev_b32_e32 v1, 2, v1
	v_or_b32_e32 v5, v3, v4
	v_and_b32_e32 v1, 32, v1
	s_lshl_b32 s15, s15, 12
	s_lshl_b32 s14, s14, 13
	v_bitop3_b32 v3, v3, v1, v4 bitop3:0x36
	v_bitop3_b32 v6, v5, s14, v1 bitop3:0xde
	s_and_b32 s14, s15, 0x3000
	v_or_b32_e32 v1, s14, v3
	s_add_u32 s14, s8, 0x80
	v_mov_b32_e32 v133, v2
	s_addc_u32 s15, s9, 0
	s_waitcnt vmcnt(2)
	s_barrier
	s_add_i32 m0, s42, 0x18000
	v_lshl_add_u64 v[4:5], s[14:15], 0, v[132:133]
	v_mov_b32_e32 v135, v2
	global_load_lds_dwordx4 v[4:5], off
	s_add_i32 m0, s42, 0x1a000
	v_lshl_add_u64 v[4:5], s[14:15], 0, v[134:135]
	s_add_u32 s14, s38, 0xd55ec80
	s_addc_u32 s15, s39, 0
	s_add_i32 s46, s42, 0x8000
	global_load_lds_dwordx4 v[4:5], off
	s_mov_b32 m0, s46
	v_lshl_add_u64 v[4:5], s[14:15], 0, v[132:133]
	s_add_i32 s47, s42, 0xa000
	global_load_lds_dwordx4 v[4:5], off
	v_lshl_add_u64 v[4:5], s[14:15], 0, v[134:135]
	s_add_u32 s14, s8, 0x40080
	s_mov_b32 m0, s47
	s_addc_u32 s15, s9, 0
	global_load_lds_dwordx4 v[4:5], off
	s_add_i32 m0, s42, 0x1c000
	v_lshl_add_u64 v[4:5], s[14:15], 0, v[132:133]
	global_load_lds_dwordx4 v[4:5], off
	v_lshl_add_u64 v[4:5], s[14:15], 0, v[134:135]
	s_add_i32 m0, s42, 0x1e000
	v_readlane_b32 s14, v254, 10
	global_load_lds_dwordx4 v[4:5], off
	s_waitcnt vmcnt(6)
	v_readlane_b32 s15, v254, 11
	s_add_u32 s50, s14, s34
	v_mov_b32_e32 v4, 0
	s_addc_u32 s51, s15, s35
	s_mov_b32 s56, -2
	v_add_u32_e32 v3, 0, v6
	s_mov_b64 s[14:15], s[0:1]
	v_mov_b32_e32 v5, v4
	v_mov_b32_e32 v6, v4
	v_mov_b32_e32 v7, v4
	v_mov_b32_e32 v8, v4
	v_mov_b32_e32 v9, v4
	v_mov_b32_e32 v10, v4
	v_mov_b32_e32 v11, v4
	v_mov_b32_e32 v20, v4
	v_mov_b32_e32 v21, v4
	v_mov_b32_e32 v22, v4
	v_mov_b32_e32 v23, v4
	v_mov_b32_e32 v24, v4
	v_mov_b32_e32 v25, v4
	v_mov_b32_e32 v26, v4
	v_mov_b32_e32 v27, v4
	v_mov_b32_e32 v36, v4
	v_mov_b32_e32 v37, v4
	v_mov_b32_e32 v38, v4
	v_mov_b32_e32 v39, v4
	v_mov_b32_e32 v40, v4
	v_mov_b32_e32 v41, v4
	v_mov_b32_e32 v42, v4
	v_mov_b32_e32 v43, v4
	v_mov_b32_e32 v52, v4
	v_mov_b32_e32 v53, v4
	v_mov_b32_e32 v54, v4
	v_mov_b32_e32 v55, v4
	v_mov_b32_e32 v56, v4
	v_mov_b32_e32 v57, v4
	v_mov_b32_e32 v58, v4
	v_mov_b32_e32 v59, v4
	v_mov_b32_e32 v12, v4
	v_mov_b32_e32 v13, v4
	v_mov_b32_e32 v14, v4
	v_mov_b32_e32 v15, v4
	v_mov_b32_e32 v16, v4
	v_mov_b32_e32 v17, v4
	v_mov_b32_e32 v18, v4
	v_mov_b32_e32 v19, v4
	v_mov_b32_e32 v28, v4
	v_mov_b32_e32 v29, v4
	v_mov_b32_e32 v30, v4
	v_mov_b32_e32 v31, v4
	v_mov_b32_e32 v32, v4
	v_mov_b32_e32 v33, v4
	v_mov_b32_e32 v34, v4
	v_mov_b32_e32 v35, v4
	v_mov_b32_e32 v44, v4
	v_mov_b32_e32 v45, v4
	v_mov_b32_e32 v46, v4
	v_mov_b32_e32 v47, v4
	v_mov_b32_e32 v48, v4
	v_mov_b32_e32 v49, v4
	v_mov_b32_e32 v50, v4
	v_mov_b32_e32 v51, v4
	v_mov_b32_e32 v60, v4
	v_mov_b32_e32 v61, v4
	v_mov_b32_e32 v62, v4
	v_mov_b32_e32 v63, v4
	v_mov_b32_e32 v64, v4
	v_mov_b32_e32 v65, v4
	v_mov_b32_e32 v66, v4
	v_mov_b32_e32 v67, v4
	v_mov_b32_e32 v68, v4
	v_mov_b32_e32 v69, v4
	v_mov_b32_e32 v70, v4
	v_mov_b32_e32 v71, v4
	v_mov_b32_e32 v72, v4
	v_mov_b32_e32 v73, v4
	v_mov_b32_e32 v74, v4
	v_mov_b32_e32 v75, v4
	v_mov_b32_e32 v84, v4
	v_mov_b32_e32 v85, v4
	v_mov_b32_e32 v86, v4
	v_mov_b32_e32 v87, v4
	v_mov_b32_e32 v88, v4
	v_mov_b32_e32 v89, v4
	v_mov_b32_e32 v90, v4
	v_mov_b32_e32 v91, v4
	v_mov_b32_e32 v100, v4
	v_mov_b32_e32 v101, v4
	v_mov_b32_e32 v102, v4
	v_mov_b32_e32 v103, v4
	v_mov_b32_e32 v104, v4
	v_mov_b32_e32 v105, v4
	v_mov_b32_e32 v106, v4
	v_mov_b32_e32 v107, v4
	v_mov_b32_e32 v116, v4
	v_mov_b32_e32 v117, v4
	v_mov_b32_e32 v118, v4
	v_mov_b32_e32 v119, v4
	v_mov_b32_e32 v120, v4
	v_mov_b32_e32 v121, v4
	v_mov_b32_e32 v122, v4
	v_mov_b32_e32 v123, v4
	v_mov_b32_e32 v76, v4
	v_mov_b32_e32 v77, v4
	v_mov_b32_e32 v78, v4
	v_mov_b32_e32 v79, v4
	v_mov_b32_e32 v80, v4
	v_mov_b32_e32 v81, v4
	v_mov_b32_e32 v82, v4
	v_mov_b32_e32 v83, v4
	v_mov_b32_e32 v92, v4
	v_mov_b32_e32 v93, v4
	v_mov_b32_e32 v94, v4
	v_mov_b32_e32 v95, v4
	v_mov_b32_e32 v96, v4
	v_mov_b32_e32 v97, v4
	v_mov_b32_e32 v98, v4
	v_mov_b32_e32 v99, v4
	v_mov_b32_e32 v108, v4
	v_mov_b32_e32 v109, v4
	v_mov_b32_e32 v110, v4
	v_mov_b32_e32 v111, v4
	v_mov_b32_e32 v112, v4
	v_mov_b32_e32 v113, v4
	v_mov_b32_e32 v114, v4
	v_mov_b32_e32 v115, v4
	v_mov_b32_e32 v124, v4
	v_mov_b32_e32 v125, v4
	v_mov_b32_e32 v126, v4
	v_mov_b32_e32 v127, v4
	v_mov_b32_e32 v128, v4
	v_mov_b32_e32 v129, v4
	v_mov_b32_e32 v130, v4
	v_mov_b32_e32 v131, v4
	v_add_u32_e32 v239, 0x10000, v1
	s_barrier
.LBB0_2766:
	s_add_u32 s20, s14, s50
	s_addc_u32 s21, s15, s51
	s_add_u32 s22, s20, 0xf30df100
	s_addc_u32 s23, s21, -1
	s_add_u32 s20, s14, 0x100
	s_addc_u32 s21, s15, 0
	s_cmp_eq_u32 s56, 12
	s_cselect_b32 s34, s8, s22
	s_cselect_b32 s35, s9, s23
	s_cselect_b32 s54, s0, s20
	s_cselect_b32 s55, s1, s21
	s_add_u32 s52, s34, 0x80
	s_addc_u32 s53, s35, 0
	s_add_u32 s22, s54, 0x80
	s_addc_u32 s23, s55, 0
	s_add_i32 s57, 0, 0x10000
	s_add_i32 s64, 0, 0x14000
	ds_read_b128 v[136:139], v239
	ds_read_b128 v[140:143], v239 offset:1024
	ds_read_b128 v[144:147], v239 offset:2048
	ds_read_b128 v[148:151], v239 offset:3072
	ds_read_b128 v[152:155], v239 offset:16384
	ds_read_b128 v[156:159], v239 offset:17408
	ds_read_b128 v[160:163], v239 offset:18432
	ds_read_b128 v[164:167], v239 offset:19456
	s_add_u32 s14, s14, 0x40080
	s_addc_u32 s15, s15, 0
	ds_read_b128 v[168:171], v3
	ds_read_b128 v[172:175], v3 offset:1024
	ds_read_b128 v[176:179], v3 offset:2048
	ds_read_b128 v[180:183], v3 offset:3072
	ds_read_b128 v[184:187], v3 offset:4096
	ds_read_b128 v[188:191], v3 offset:5120
	ds_read_b128 v[192:195], v3 offset:6144
	ds_read_b128 v[210:213], v3 offset:7168
	s_add_i32 m0, s42, 0xc000
	s_nop 0
	global_load_lds_dwordx4 v132, s[14:15]
	s_add_i32 m0, s42, 0xe000
	s_nop 0
	global_load_lds_dwordx4 v134, s[14:15]
	s_waitcnt vmcnt(8)
	s_waitcnt lgkmcnt(0)
	s_barrier
	s_setprio 1
	s_waitcnt lgkmcnt(0)
	v_mfma_f32_16x16x32_bf16 v[128:131], v[136:139], v[168:171], v[128:131]
	v_mfma_f32_16x16x32_bf16 v[124:127], v[144:147], v[168:171], v[124:127]
	v_mfma_f32_16x16x32_bf16 v[112:115], v[136:139], v[176:179], v[112:115]
	v_mfma_f32_16x16x32_bf16 v[108:111], v[144:147], v[176:179], v[108:111]
	v_mfma_f32_16x16x32_bf16 v[96:99], v[136:139], v[184:187], v[96:99]
	v_mfma_f32_16x16x32_bf16 v[92:95], v[144:147], v[184:187], v[92:95]
	v_mfma_f32_16x16x32_bf16 v[80:83], v[136:139], v[192:195], v[80:83]
	v_mfma_f32_16x16x32_bf16 v[76:79], v[144:147], v[192:195], v[76:79]
	v_mfma_f32_16x16x32_bf16 v[128:131], v[140:143], v[172:175], v[128:131]
	v_mfma_f32_16x16x32_bf16 v[124:127], v[148:151], v[172:175], v[124:127]
	v_mfma_f32_16x16x32_bf16 v[112:115], v[140:143], v[180:183], v[112:115]
	v_mfma_f32_16x16x32_bf16 v[108:111], v[148:151], v[180:183], v[108:111]
	v_mfma_f32_16x16x32_bf16 v[96:99], v[140:143], v[188:191], v[96:99]
	v_mfma_f32_16x16x32_bf16 v[92:95], v[148:151], v[188:191], v[92:95]
	v_mfma_f32_16x16x32_bf16 v[80:83], v[140:143], v[210:213], v[80:83]
	v_mfma_f32_16x16x32_bf16 v[76:79], v[148:151], v[210:213], v[76:79]
	s_setprio 0
	s_setprio 1
	v_mfma_f32_16x16x32_bf16 v[120:123], v[152:155], v[168:171], v[120:123]
	v_mfma_f32_16x16x32_bf16 v[116:119], v[160:163], v[168:171], v[116:119]
	v_mfma_f32_16x16x32_bf16 v[104:107], v[152:155], v[176:179], v[104:107]
	v_mfma_f32_16x16x32_bf16 v[100:103], v[160:163], v[176:179], v[100:103]
	v_mfma_f32_16x16x32_bf16 v[88:91], v[152:155], v[184:187], v[88:91]
	v_mfma_f32_16x16x32_bf16 v[84:87], v[160:163], v[184:187], v[84:87]
	v_mfma_f32_16x16x32_bf16 v[72:75], v[152:155], v[192:195], v[72:75]
	v_mfma_f32_16x16x32_bf16 v[68:71], v[160:163], v[192:195], v[68:71]
	v_mfma_f32_16x16x32_bf16 v[120:123], v[156:159], v[172:175], v[120:123]
	v_mfma_f32_16x16x32_bf16 v[116:119], v[164:167], v[172:175], v[116:119]
	v_mfma_f32_16x16x32_bf16 v[104:107], v[156:159], v[180:183], v[104:107]
	v_mfma_f32_16x16x32_bf16 v[100:103], v[164:167], v[180:183], v[100:103]
	v_mfma_f32_16x16x32_bf16 v[88:91], v[156:159], v[188:191], v[88:91]
	v_mfma_f32_16x16x32_bf16 v[84:87], v[164:167], v[188:191], v[84:87]
	v_mfma_f32_16x16x32_bf16 v[72:75], v[156:159], v[210:213], v[72:75]
	v_mfma_f32_16x16x32_bf16 v[68:71], v[164:167], v[210:213], v[68:71]
	s_setprio 0
	s_barrier
	s_mov_b64 s[14:15], s[34:35]
	s_add_i32 s57, s57, s41
	ds_read_b128 v[168:171], v3 offset:16384
	ds_read_b128 v[172:175], v3 offset:17408
	ds_read_b128 v[176:179], v3 offset:18432
	ds_read_b128 v[180:183], v3 offset:19456
	ds_read_b128 v[184:187], v3 offset:20480
	ds_read_b128 v[188:191], v3 offset:21504
	ds_read_b128 v[192:195], v3 offset:22528
	ds_read_b128 v[210:213], v3 offset:23552
	s_mov_b32 m0, s57
	s_nop 0
	global_load_lds_dwordx4 v132, s[14:15]
	s_add_i32 m0, s57, 0x2000
	s_nop 0
	global_load_lds_dwordx4 v134, s[14:15]
	s_add_u32 s14, s34, 0x40000
	s_addc_u32 s15, s35, 0
	s_add_i32 s57, s64, s41
	s_mov_b32 m0, s57
	s_nop 0
	global_load_lds_dwordx4 v132, s[14:15]
	s_add_i32 m0, s57, 0x2000
	s_nop 0
	global_load_lds_dwordx4 v134, s[14:15]
	s_mov_b64 s[14:15], s[54:55]
	s_mov_b32 m0, s42
	s_nop 0
	global_load_lds_dwordx4 v132, s[14:15]
	s_mov_b32 m0, s43
	s_nop 0
	global_load_lds_dwordx4 v134, s[14:15]
	s_waitcnt vmcnt(8)
	s_waitcnt lgkmcnt(0)
	s_barrier
	s_setprio 1
	s_waitcnt lgkmcnt(0)
	v_mfma_f32_16x16x32_bf16 v[64:67], v[136:139], v[168:171], v[64:67]
	v_mfma_f32_16x16x32_bf16 v[60:63], v[144:147], v[168:171], v[60:63]
	v_mfma_f32_16x16x32_bf16 v[48:51], v[136:139], v[176:179], v[48:51]
	v_mfma_f32_16x16x32_bf16 v[44:47], v[144:147], v[176:179], v[44:47]
	v_mfma_f32_16x16x32_bf16 v[32:35], v[136:139], v[184:187], v[32:35]
	v_mfma_f32_16x16x32_bf16 v[28:31], v[144:147], v[184:187], v[28:31]
	v_mfma_f32_16x16x32_bf16 v[16:19], v[136:139], v[192:195], v[16:19]
	v_mfma_f32_16x16x32_bf16 v[12:15], v[144:147], v[192:195], v[12:15]
	v_mfma_f32_16x16x32_bf16 v[64:67], v[140:143], v[172:175], v[64:67]
	v_mfma_f32_16x16x32_bf16 v[60:63], v[148:151], v[172:175], v[60:63]
	v_mfma_f32_16x16x32_bf16 v[48:51], v[140:143], v[180:183], v[48:51]
	v_mfma_f32_16x16x32_bf16 v[44:47], v[148:151], v[180:183], v[44:47]
	v_mfma_f32_16x16x32_bf16 v[32:35], v[140:143], v[188:191], v[32:35]
	v_mfma_f32_16x16x32_bf16 v[28:31], v[148:151], v[188:191], v[28:31]
	v_mfma_f32_16x16x32_bf16 v[16:19], v[140:143], v[210:213], v[16:19]
	v_mfma_f32_16x16x32_bf16 v[12:15], v[148:151], v[210:213], v[12:15]
	s_setprio 0
	s_setprio 1
	v_mfma_f32_16x16x32_bf16 v[56:59], v[152:155], v[168:171], v[56:59]
	v_mfma_f32_16x16x32_bf16 v[52:55], v[160:163], v[168:171], v[52:55]
	v_mfma_f32_16x16x32_bf16 v[40:43], v[152:155], v[176:179], v[40:43]
	v_mfma_f32_16x16x32_bf16 v[36:39], v[160:163], v[176:179], v[36:39]
	v_mfma_f32_16x16x32_bf16 v[24:27], v[152:155], v[184:187], v[24:27]
	v_mfma_f32_16x16x32_bf16 v[20:23], v[160:163], v[184:187], v[20:23]
	v_mfma_f32_16x16x32_bf16 v[8:11], v[152:155], v[192:195], v[8:11]
	v_mfma_f32_16x16x32_bf16 v[4:7], v[160:163], v[192:195], v[4:7]
	v_mfma_f32_16x16x32_bf16 v[56:59], v[156:159], v[172:175], v[56:59]
	v_mfma_f32_16x16x32_bf16 v[52:55], v[164:167], v[172:175], v[52:55]
	v_mfma_f32_16x16x32_bf16 v[40:43], v[156:159], v[180:183], v[40:43]
	v_mfma_f32_16x16x32_bf16 v[36:39], v[164:167], v[180:183], v[36:39]
	v_mfma_f32_16x16x32_bf16 v[24:27], v[156:159], v[188:191], v[24:27]
	v_mfma_f32_16x16x32_bf16 v[20:23], v[164:167], v[188:191], v[20:23]
	v_mfma_f32_16x16x32_bf16 v[8:11], v[156:159], v[210:213], v[8:11]
	v_mfma_f32_16x16x32_bf16 v[4:7], v[164:167], v[210:213], v[4:7]
	s_setprio 0
	s_barrier
	s_add_i32 s57, 0, 0x18000
	s_add_i32 s64, 0, 0x1c000
	ds_read_b128 v[136:139], v239 offset:32768
	ds_read_b128 v[140:143], v239 offset:33792
	ds_read_b128 v[144:147], v239 offset:34816
	ds_read_b128 v[148:151], v239 offset:35840
	ds_read_b128 v[152:155], v239 offset:49152
	ds_read_b128 v[156:159], v239 offset:50176
	ds_read_b128 v[160:163], v239 offset:51200
	ds_read_b128 v[164:167], v239 offset:52224
	s_add_u32 s14, s54, 0x40000
	s_addc_u32 s15, s55, 0
	s_mov_b32 m0, s44
	ds_read_b128 v[168:171], v3 offset:32768
	ds_read_b128 v[172:175], v3 offset:33792
	ds_read_b128 v[176:179], v3 offset:34816
	ds_read_b128 v[180:183], v3 offset:35840
	ds_read_b128 v[184:187], v3 offset:36864
	ds_read_b128 v[188:191], v3 offset:37888
	ds_read_b128 v[192:195], v3 offset:38912
	ds_read_b128 v[210:213], v3 offset:39936
	s_nop 0
	global_load_lds_dwordx4 v132, s[14:15]
	s_mov_b32 m0, s45
	s_nop 0
	global_load_lds_dwordx4 v134, s[14:15]
	s_waitcnt vmcnt(8)
	s_waitcnt lgkmcnt(0)
	s_barrier
	s_setprio 1
	s_waitcnt lgkmcnt(0)
	v_mfma_f32_16x16x32_bf16 v[128:131], v[136:139], v[168:171], v[128:131]
	v_mfma_f32_16x16x32_bf16 v[124:127], v[144:147], v[168:171], v[124:127]
	v_mfma_f32_16x16x32_bf16 v[112:115], v[136:139], v[176:179], v[112:115]
	v_mfma_f32_16x16x32_bf16 v[108:111], v[144:147], v[176:179], v[108:111]
	v_mfma_f32_16x16x32_bf16 v[96:99], v[136:139], v[184:187], v[96:99]
	v_mfma_f32_16x16x32_bf16 v[92:95], v[144:147], v[184:187], v[92:95]
	v_mfma_f32_16x16x32_bf16 v[80:83], v[136:139], v[192:195], v[80:83]
	v_mfma_f32_16x16x32_bf16 v[76:79], v[144:147], v[192:195], v[76:79]
	v_mfma_f32_16x16x32_bf16 v[128:131], v[140:143], v[172:175], v[128:131]
	v_mfma_f32_16x16x32_bf16 v[124:127], v[148:151], v[172:175], v[124:127]
	v_mfma_f32_16x16x32_bf16 v[112:115], v[140:143], v[180:183], v[112:115]
	v_mfma_f32_16x16x32_bf16 v[108:111], v[148:151], v[180:183], v[108:111]
	v_mfma_f32_16x16x32_bf16 v[96:99], v[140:143], v[188:191], v[96:99]
	v_mfma_f32_16x16x32_bf16 v[92:95], v[148:151], v[188:191], v[92:95]
	v_mfma_f32_16x16x32_bf16 v[80:83], v[140:143], v[210:213], v[80:83]
	v_mfma_f32_16x16x32_bf16 v[76:79], v[148:151], v[210:213], v[76:79]
	s_setprio 0
	s_setprio 1
	v_mfma_f32_16x16x32_bf16 v[120:123], v[152:155], v[168:171], v[120:123]
	v_mfma_f32_16x16x32_bf16 v[116:119], v[160:163], v[168:171], v[116:119]
	v_mfma_f32_16x16x32_bf16 v[104:107], v[152:155], v[176:179], v[104:107]
	v_mfma_f32_16x16x32_bf16 v[100:103], v[160:163], v[176:179], v[100:103]
	v_mfma_f32_16x16x32_bf16 v[88:91], v[152:155], v[184:187], v[88:91]
	v_mfma_f32_16x16x32_bf16 v[84:87], v[160:163], v[184:187], v[84:87]
	v_mfma_f32_16x16x32_bf16 v[72:75], v[152:155], v[192:195], v[72:75]
	v_mfma_f32_16x16x32_bf16 v[68:71], v[160:163], v[192:195], v[68:71]
	v_mfma_f32_16x16x32_bf16 v[120:123], v[156:159], v[172:175], v[120:123]
	v_mfma_f32_16x16x32_bf16 v[116:119], v[164:167], v[172:175], v[116:119]
	v_mfma_f32_16x16x32_bf16 v[104:107], v[156:159], v[180:183], v[104:107]
	v_mfma_f32_16x16x32_bf16 v[100:103], v[164:167], v[180:183], v[100:103]
	v_mfma_f32_16x16x32_bf16 v[88:91], v[156:159], v[188:191], v[88:91]
	v_mfma_f32_16x16x32_bf16 v[84:87], v[164:167], v[188:191], v[84:87]
	v_mfma_f32_16x16x32_bf16 v[72:75], v[156:159], v[210:213], v[72:75]
	v_mfma_f32_16x16x32_bf16 v[68:71], v[164:167], v[210:213], v[68:71]
	s_setprio 0
	s_barrier
	s_add_i32 s14, s57, s41
	ds_read_b128 v[168:171], v3 offset:49152
	ds_read_b128 v[172:175], v3 offset:50176
	ds_read_b128 v[176:179], v3 offset:51200
	ds_read_b128 v[180:183], v3 offset:52224
	ds_read_b128 v[184:187], v3 offset:53248
	ds_read_b128 v[188:191], v3 offset:54272
	ds_read_b128 v[192:195], v3 offset:55296
	ds_read_b128 v[210:213], v3 offset:56320
	s_mov_b32 m0, s14
	s_nop 0
	global_load_lds_dwordx4 v132, s[52:53]
	s_add_i32 m0, s14, 0x2000
	s_add_u32 s14, s34, 0x40080
	s_addc_u32 s15, s35, 0
	s_add_i32 s34, s64, s41
	global_load_lds_dwordx4 v134, s[52:53]
	s_mov_b32 m0, s34
	s_nop 0
	global_load_lds_dwordx4 v132, s[14:15]
	s_add_i32 m0, s34, 0x2000
	s_nop 0
	global_load_lds_dwordx4 v134, s[14:15]
	s_mov_b32 m0, s46
	s_nop 0
	global_load_lds_dwordx4 v132, s[22:23]
	s_mov_b32 m0, s47
	s_nop 0
	global_load_lds_dwordx4 v134, s[22:23]
	s_waitcnt vmcnt(8)
	s_waitcnt lgkmcnt(0)
	s_barrier
	s_setprio 1
	s_waitcnt lgkmcnt(0)
	v_mfma_f32_16x16x32_bf16 v[64:67], v[136:139], v[168:171], v[64:67]
	v_mfma_f32_16x16x32_bf16 v[60:63], v[144:147], v[168:171], v[60:63]
	v_mfma_f32_16x16x32_bf16 v[48:51], v[136:139], v[176:179], v[48:51]
	v_mfma_f32_16x16x32_bf16 v[44:47], v[144:147], v[176:179], v[44:47]
	v_mfma_f32_16x16x32_bf16 v[32:35], v[136:139], v[184:187], v[32:35]
	v_mfma_f32_16x16x32_bf16 v[28:31], v[144:147], v[184:187], v[28:31]
	v_mfma_f32_16x16x32_bf16 v[16:19], v[136:139], v[192:195], v[16:19]
	v_mfma_f32_16x16x32_bf16 v[12:15], v[144:147], v[192:195], v[12:15]
	v_mfma_f32_16x16x32_bf16 v[64:67], v[140:143], v[172:175], v[64:67]
	v_mfma_f32_16x16x32_bf16 v[60:63], v[148:151], v[172:175], v[60:63]
	v_mfma_f32_16x16x32_bf16 v[48:51], v[140:143], v[180:183], v[48:51]
	v_mfma_f32_16x16x32_bf16 v[44:47], v[148:151], v[180:183], v[44:47]
	v_mfma_f32_16x16x32_bf16 v[32:35], v[140:143], v[188:191], v[32:35]
	v_mfma_f32_16x16x32_bf16 v[28:31], v[148:151], v[188:191], v[28:31]
	v_mfma_f32_16x16x32_bf16 v[16:19], v[140:143], v[210:213], v[16:19]
	v_mfma_f32_16x16x32_bf16 v[12:15], v[148:151], v[210:213], v[12:15]
	s_setprio 0
	s_setprio 1
	v_mfma_f32_16x16x32_bf16 v[56:59], v[152:155], v[168:171], v[56:59]
	v_mfma_f32_16x16x32_bf16 v[52:55], v[160:163], v[168:171], v[52:55]
	v_mfma_f32_16x16x32_bf16 v[40:43], v[152:155], v[176:179], v[40:43]
	v_mfma_f32_16x16x32_bf16 v[36:39], v[160:163], v[176:179], v[36:39]
	v_mfma_f32_16x16x32_bf16 v[24:27], v[152:155], v[184:187], v[24:27]
	v_mfma_f32_16x16x32_bf16 v[20:23], v[160:163], v[184:187], v[20:23]
	v_mfma_f32_16x16x32_bf16 v[8:11], v[152:155], v[192:195], v[8:11]
	v_mfma_f32_16x16x32_bf16 v[4:7], v[160:163], v[192:195], v[4:7]
	v_mfma_f32_16x16x32_bf16 v[56:59], v[156:159], v[172:175], v[56:59]
	v_mfma_f32_16x16x32_bf16 v[52:55], v[164:167], v[172:175], v[52:55]
	v_mfma_f32_16x16x32_bf16 v[40:43], v[156:159], v[180:183], v[40:43]
	v_mfma_f32_16x16x32_bf16 v[36:39], v[164:167], v[180:183], v[36:39]
	v_mfma_f32_16x16x32_bf16 v[24:27], v[156:159], v[188:191], v[24:27]
	v_mfma_f32_16x16x32_bf16 v[20:23], v[164:167], v[188:191], v[20:23]
	v_mfma_f32_16x16x32_bf16 v[8:11], v[156:159], v[210:213], v[8:11]
	v_mfma_f32_16x16x32_bf16 v[4:7], v[164:167], v[210:213], v[4:7]
	s_setprio 0
	s_barrier
	s_add_i32 s56, s56, 2
	s_cmp_gt_u32 s56, 13
	s_mov_b64 s[14:15], s[20:21]
	s_cbranch_scc0 .LBB0_2766
	s_cmpk_lt_u32 s40, 0x100
	s_cbranch_scc0 .LBB0_2769
	s_barrier

.LBB0_2832:
	s_ashr_i32 s75, s74, 31
	s_xor_b64 s[86:87], s[0:1], -1
	s_lshl_b64 s[14:15], s[74:75], 19
	s_add_u32 s80, s34, s14
	s_addc_u32 s81, s35, s15
	s_and_b64 s[14:15], s[0:1], exec
	s_cselect_b32 s64, s9, s81
	s_cselect_b32 s65, s8, s80
	s_ashr_i32 s63, s62, 31
	s_lshl_b64 s[14:15], s[62:63], 19
	s_add_u32 s82, s46, s14
	s_addc_u32 s83, s47, s15
	s_and_b64 s[14:15], s[0:1], exec
	s_cselect_b32 s63, s17, s83
	s_cselect_b32 s67, s16, s82
	v_mov_b32_e32 v4, 0
	s_cmp_lg_u32 s74, 64
	s_mov_b32 s75, 0
	s_cselect_b64 s[14:15], -1, 0
	v_mov_b32_e32 v5, v4
	v_mov_b32_e32 v6, v4
	v_mov_b32_e32 v7, v4
	v_mov_b32_e32 v12, v4
	v_mov_b32_e32 v13, v4
	v_mov_b32_e32 v14, v4
	v_mov_b32_e32 v15, v4
	v_mov_b32_e32 v20, v4
	v_mov_b32_e32 v21, v4
	v_mov_b32_e32 v22, v4
	v_mov_b32_e32 v23, v4
	v_mov_b32_e32 v28, v4
	v_mov_b32_e32 v29, v4
	v_mov_b32_e32 v30, v4
	v_mov_b32_e32 v31, v4
	v_mov_b32_e32 v36, v4
	v_mov_b32_e32 v37, v4
	v_mov_b32_e32 v38, v4
	v_mov_b32_e32 v39, v4
	v_mov_b32_e32 v44, v4
	v_mov_b32_e32 v45, v4
	v_mov_b32_e32 v46, v4
	v_mov_b32_e32 v47, v4
	v_mov_b32_e32 v52, v4
	v_mov_b32_e32 v53, v4
	v_mov_b32_e32 v54, v4
	v_mov_b32_e32 v55, v4
	v_mov_b32_e32 v60, v4
	v_mov_b32_e32 v61, v4
	v_mov_b32_e32 v62, v4
	v_mov_b32_e32 v63, v4
	v_mov_b32_e32 v8, v4
	v_mov_b32_e32 v9, v4
	v_mov_b32_e32 v10, v4
	v_mov_b32_e32 v11, v4
	v_mov_b32_e32 v16, v4
	v_mov_b32_e32 v17, v4
	v_mov_b32_e32 v18, v4
	v_mov_b32_e32 v19, v4
	v_mov_b32_e32 v24, v4
	v_mov_b32_e32 v25, v4
	v_mov_b32_e32 v26, v4
	v_mov_b32_e32 v27, v4
	v_mov_b32_e32 v32, v4
	v_mov_b32_e32 v33, v4
	v_mov_b32_e32 v34, v4
	v_mov_b32_e32 v35, v4
	v_mov_b32_e32 v40, v4
	v_mov_b32_e32 v41, v4
	v_mov_b32_e32 v42, v4
	v_mov_b32_e32 v43, v4
	v_mov_b32_e32 v48, v4
	v_mov_b32_e32 v49, v4
	v_mov_b32_e32 v50, v4
	v_mov_b32_e32 v51, v4
	v_mov_b32_e32 v56, v4
	v_mov_b32_e32 v57, v4
	v_mov_b32_e32 v58, v4
	v_mov_b32_e32 v59, v4
	v_mov_b32_e32 v64, v4
	v_mov_b32_e32 v65, v4
	v_mov_b32_e32 v66, v4
	v_mov_b32_e32 v67, v4
	v_mov_b32_e32 v68, v4
	v_mov_b32_e32 v69, v4
	v_mov_b32_e32 v70, v4
	v_mov_b32_e32 v71, v4
	v_mov_b32_e32 v76, v4
	v_mov_b32_e32 v77, v4
	v_mov_b32_e32 v78, v4
	v_mov_b32_e32 v79, v4
	v_mov_b32_e32 v84, v4
	v_mov_b32_e32 v85, v4
	v_mov_b32_e32 v86, v4
	v_mov_b32_e32 v87, v4
	v_mov_b32_e32 v92, v4
	v_mov_b32_e32 v93, v4
	v_mov_b32_e32 v94, v4
	v_mov_b32_e32 v95, v4
	v_mov_b32_e32 v100, v4
	v_mov_b32_e32 v101, v4
	v_mov_b32_e32 v102, v4
	v_mov_b32_e32 v103, v4
	v_mov_b32_e32 v108, v4
	v_mov_b32_e32 v109, v4
	v_mov_b32_e32 v110, v4
	v_mov_b32_e32 v111, v4
	v_mov_b32_e32 v116, v4
	v_mov_b32_e32 v117, v4
	v_mov_b32_e32 v118, v4
	v_mov_b32_e32 v119, v4
	v_mov_b32_e32 v120, v4
	v_mov_b32_e32 v121, v4
	v_mov_b32_e32 v122, v4
	v_mov_b32_e32 v123, v4
	v_mov_b32_e32 v72, v4
	v_mov_b32_e32 v73, v4
	v_mov_b32_e32 v74, v4
	v_mov_b32_e32 v75, v4
	v_mov_b32_e32 v80, v4
	v_mov_b32_e32 v81, v4
	v_mov_b32_e32 v82, v4
	v_mov_b32_e32 v83, v4
	v_mov_b32_e32 v88, v4
	v_mov_b32_e32 v89, v4
	v_mov_b32_e32 v90, v4
	v_mov_b32_e32 v91, v4
	v_mov_b32_e32 v96, v4
	v_mov_b32_e32 v97, v4
	v_mov_b32_e32 v98, v4
	v_mov_b32_e32 v99, v4
	v_mov_b32_e32 v104, v4
	v_mov_b32_e32 v105, v4
	v_mov_b32_e32 v106, v4
	v_mov_b32_e32 v107, v4
	v_mov_b32_e32 v112, v4
	v_mov_b32_e32 v113, v4
	v_mov_b32_e32 v114, v4
	v_mov_b32_e32 v115, v4
	v_mov_b32_e32 v124, v4
	v_mov_b32_e32 v125, v4
	v_mov_b32_e32 v126, v4
	v_mov_b32_e32 v127, v4
	v_mov_b32_e32 v128, v4
	v_mov_b32_e32 v129, v4
	v_mov_b32_e32 v130, v4
	v_mov_b32_e32 v131, v4
	v_add_u32_e32 v222, 0x10000, v1
	s_branch .LBB0_2837

.Lffn1_pf_skip:
	s_lshl_b32 s78, s75, 7
	s_add_u32 s88, s8, s78
	s_addc_u32 s89, s9, 0
	s_add_u32 s79, s88, 0x100
	s_addc_u32 s84, s89, 0
	s_and_b64 s[72:73], s[52:53], exec
	s_cselect_b32 s91, s84, s64
	s_cselect_b32 s90, s79, s65
	s_add_u32 s72, s16, s78
	s_addc_u32 s73, s17, 0
	s_add_u32 s72, s72, 0x100
	s_addc_u32 s73, s73, 0
	s_and_b64 s[52:53], s[52:53], exec
	s_cselect_b32 s73, s73, s63
	s_cselect_b32 s72, s72, s67
	s_add_u32 s52, s90, 0x80
	s_addc_u32 s53, s91, 0
	s_add_u32 s78, s72, 0x80
	s_addc_u32 s79, s73, 0
	s_add_i32 s84, 0, 0x10000
	s_add_i32 s85, 0, 0x14000
	ds_read_b128 v[136:139], v222
	ds_read_b128 v[140:143], v222 offset:1024
	ds_read_b128 v[144:147], v222 offset:2048
	ds_read_b128 v[148:151], v222 offset:3072
	ds_read_b128 v[152:155], v222 offset:16384
	ds_read_b128 v[156:159], v222 offset:17408
	ds_read_b128 v[160:163], v222 offset:18432
	ds_read_b128 v[164:167], v222 offset:19456
	s_add_u32 s88, s88, 0x40080
	s_addc_u32 s89, s89, 0
	ds_read_b128 v[168:171], v3
	ds_read_b128 v[172:175], v3 offset:1024
	ds_read_b128 v[176:179], v3 offset:2048
	ds_read_b128 v[180:183], v3 offset:3072
	ds_read_b128 v[184:187], v3 offset:4096
	ds_read_b128 v[188:191], v3 offset:5120
	ds_read_b128 v[192:195], v3 offset:6144
	ds_read_b128 v[210:213], v3 offset:7168
	s_add_i32 m0, s95, 0xc000
	s_nop 0
	global_load_lds_dwordx4 v132, s[88:89]
	s_add_i32 m0, s95, 0xe000
	s_nop 0
	global_load_lds_dwordx4 v134, s[88:89]
	s_waitcnt vmcnt(8)
	s_waitcnt lgkmcnt(0)
	s_barrier
	s_setprio 1
	s_waitcnt lgkmcnt(0)
	v_mfma_f32_16x16x32_bf16 v[128:131], v[136:139], v[168:171], v[128:131]
	v_mfma_f32_16x16x32_bf16 v[124:127], v[144:147], v[168:171], v[124:127]
	v_mfma_f32_16x16x32_bf16 v[112:115], v[136:139], v[176:179], v[112:115]
	v_mfma_f32_16x16x32_bf16 v[104:107], v[144:147], v[176:179], v[104:107]
	v_mfma_f32_16x16x32_bf16 v[96:99], v[136:139], v[184:187], v[96:99]
	v_mfma_f32_16x16x32_bf16 v[88:91], v[144:147], v[184:187], v[88:91]
	v_mfma_f32_16x16x32_bf16 v[80:83], v[136:139], v[192:195], v[80:83]
	v_mfma_f32_16x16x32_bf16 v[72:75], v[144:147], v[192:195], v[72:75]
	v_mfma_f32_16x16x32_bf16 v[128:131], v[140:143], v[172:175], v[128:131]
	v_mfma_f32_16x16x32_bf16 v[124:127], v[148:151], v[172:175], v[124:127]
	v_mfma_f32_16x16x32_bf16 v[112:115], v[140:143], v[180:183], v[112:115]
	v_mfma_f32_16x16x32_bf16 v[104:107], v[148:151], v[180:183], v[104:107]
	v_mfma_f32_16x16x32_bf16 v[96:99], v[140:143], v[188:191], v[96:99]
	v_mfma_f32_16x16x32_bf16 v[88:91], v[148:151], v[188:191], v[88:91]
	v_mfma_f32_16x16x32_bf16 v[80:83], v[140:143], v[210:213], v[80:83]
	v_mfma_f32_16x16x32_bf16 v[72:75], v[148:151], v[210:213], v[72:75]
	s_setprio 0
	s_setprio 1
	v_mfma_f32_16x16x32_bf16 v[120:123], v[152:155], v[168:171], v[120:123]
	v_mfma_f32_16x16x32_bf16 v[116:119], v[160:163], v[168:171], v[116:119]
	v_mfma_f32_16x16x32_bf16 v[108:111], v[152:155], v[176:179], v[108:111]
	v_mfma_f32_16x16x32_bf16 v[100:103], v[160:163], v[176:179], v[100:103]
	v_mfma_f32_16x16x32_bf16 v[92:95], v[152:155], v[184:187], v[92:95]
	v_mfma_f32_16x16x32_bf16 v[84:87], v[160:163], v[184:187], v[84:87]
	v_mfma_f32_16x16x32_bf16 v[76:79], v[152:155], v[192:195], v[76:79]
	v_mfma_f32_16x16x32_bf16 v[68:71], v[160:163], v[192:195], v[68:71]
	v_mfma_f32_16x16x32_bf16 v[120:123], v[156:159], v[172:175], v[120:123]
	v_mfma_f32_16x16x32_bf16 v[116:119], v[164:167], v[172:175], v[116:119]
	v_mfma_f32_16x16x32_bf16 v[108:111], v[156:159], v[180:183], v[108:111]
	v_mfma_f32_16x16x32_bf16 v[100:103], v[164:167], v[180:183], v[100:103]
	v_mfma_f32_16x16x32_bf16 v[92:95], v[156:159], v[188:191], v[92:95]
	v_mfma_f32_16x16x32_bf16 v[84:87], v[164:167], v[188:191], v[84:87]
	v_mfma_f32_16x16x32_bf16 v[76:79], v[156:159], v[210:213], v[76:79]
	v_mfma_f32_16x16x32_bf16 v[68:71], v[164:167], v[210:213], v[68:71]
	s_setprio 0
	s_barrier
	s_mov_b64 s[88:89], s[72:73]
	s_add_i32 s92, s84, s94
	ds_read_b128 v[168:171], v3 offset:16384
	ds_read_b128 v[172:175], v3 offset:17408
	ds_read_b128 v[176:179], v3 offset:18432
	ds_read_b128 v[180:183], v3 offset:19456
	ds_read_b128 v[184:187], v3 offset:20480
	ds_read_b128 v[188:191], v3 offset:21504
	ds_read_b128 v[192:195], v3 offset:22528
	ds_read_b128 v[210:213], v3 offset:23552
	s_mov_b32 m0, s92
	s_nop 0
	global_load_lds_dwordx4 v132, s[88:89]
	s_add_i32 m0, s92, 0x2000
	s_nop 0
	global_load_lds_dwordx4 v134, s[88:89]
	s_add_u32 s88, s72, 0x40000
	s_addc_u32 s89, s73, 0
	s_add_i32 s92, s85, s94
	s_mov_b32 m0, s92
	s_nop 0
	global_load_lds_dwordx4 v132, s[88:89]
	s_add_i32 m0, s92, 0x2000
	s_nop 0
	global_load_lds_dwordx4 v134, s[88:89]
	s_mov_b64 s[88:89], s[90:91]
	s_mov_b32 m0, s95
	s_nop 0
	global_load_lds_dwordx4 v132, s[88:89]
	s_mov_b32 m0, s40
	s_nop 0
	global_load_lds_dwordx4 v134, s[88:89]
	s_waitcnt vmcnt(8)
	s_waitcnt lgkmcnt(0)
	s_barrier
	s_setprio 1
	s_waitcnt lgkmcnt(0)
	v_mfma_f32_16x16x32_bf16 v[64:67], v[136:139], v[168:171], v[64:67]
	v_mfma_f32_16x16x32_bf16 v[56:59], v[144:147], v[168:171], v[56:59]
	v_mfma_f32_16x16x32_bf16 v[48:51], v[136:139], v[176:179], v[48:51]
	v_mfma_f32_16x16x32_bf16 v[40:43], v[144:147], v[176:179], v[40:43]
	v_mfma_f32_16x16x32_bf16 v[32:35], v[136:139], v[184:187], v[32:35]
	v_mfma_f32_16x16x32_bf16 v[24:27], v[144:147], v[184:187], v[24:27]
	v_mfma_f32_16x16x32_bf16 v[16:19], v[136:139], v[192:195], v[16:19]
	v_mfma_f32_16x16x32_bf16 v[8:11], v[144:147], v[192:195], v[8:11]
	v_mfma_f32_16x16x32_bf16 v[64:67], v[140:143], v[172:175], v[64:67]
	v_mfma_f32_16x16x32_bf16 v[56:59], v[148:151], v[172:175], v[56:59]
	v_mfma_f32_16x16x32_bf16 v[48:51], v[140:143], v[180:183], v[48:51]
	v_mfma_f32_16x16x32_bf16 v[40:43], v[148:151], v[180:183], v[40:43]
	v_mfma_f32_16x16x32_bf16 v[32:35], v[140:143], v[188:191], v[32:35]
	v_mfma_f32_16x16x32_bf16 v[24:27], v[148:151], v[188:191], v[24:27]
	v_mfma_f32_16x16x32_bf16 v[16:19], v[140:143], v[210:213], v[16:19]
	v_mfma_f32_16x16x32_bf16 v[8:11], v[148:151], v[210:213], v[8:11]
	s_setprio 0
	s_setprio 1
	v_mfma_f32_16x16x32_bf16 v[60:63], v[152:155], v[168:171], v[60:63]
	v_mfma_f32_16x16x32_bf16 v[52:55], v[160:163], v[168:171], v[52:55]
	v_mfma_f32_16x16x32_bf16 v[44:47], v[152:155], v[176:179], v[44:47]
	v_mfma_f32_16x16x32_bf16 v[36:39], v[160:163], v[176:179], v[36:39]
	v_mfma_f32_16x16x32_bf16 v[28:31], v[152:155], v[184:187], v[28:31]
	v_mfma_f32_16x16x32_bf16 v[20:23], v[160:163], v[184:187], v[20:23]
	v_mfma_f32_16x16x32_bf16 v[12:15], v[152:155], v[192:195], v[12:15]
	v_mfma_f32_16x16x32_bf16 v[4:7], v[160:163], v[192:195], v[4:7]
	v_mfma_f32_16x16x32_bf16 v[60:63], v[156:159], v[172:175], v[60:63]
	v_mfma_f32_16x16x32_bf16 v[52:55], v[164:167], v[172:175], v[52:55]
	v_mfma_f32_16x16x32_bf16 v[44:47], v[156:159], v[180:183], v[44:47]
	v_mfma_f32_16x16x32_bf16 v[36:39], v[164:167], v[180:183], v[36:39]
	v_mfma_f32_16x16x32_bf16 v[28:31], v[156:159], v[188:191], v[28:31]
	v_mfma_f32_16x16x32_bf16 v[20:23], v[164:167], v[188:191], v[20:23]
	v_mfma_f32_16x16x32_bf16 v[12:15], v[156:159], v[210:213], v[12:15]
	v_mfma_f32_16x16x32_bf16 v[4:7], v[164:167], v[210:213], v[4:7]
	s_setprio 0
	s_barrier
	s_add_i32 s88, 0, 0x18000
	s_add_i32 s89, 0, 0x1c000
	ds_read_b128 v[136:139], v222 offset:32768
	ds_read_b128 v[140:143], v222 offset:33792
	ds_read_b128 v[144:147], v222 offset:34816
	ds_read_b128 v[148:151], v222 offset:35840
	ds_read_b128 v[152:155], v222 offset:49152
	ds_read_b128 v[156:159], v222 offset:50176
	ds_read_b128 v[160:163], v222 offset:51200
	ds_read_b128 v[164:167], v222 offset:52224
	s_add_u32 s90, s90, 0x40000
	s_addc_u32 s91, s91, 0
	s_mov_b32 m0, s41
	ds_read_b128 v[168:171], v3 offset:32768
	ds_read_b128 v[172:175], v3 offset:33792
	ds_read_b128 v[176:179], v3 offset:34816
	ds_read_b128 v[180:183], v3 offset:35840
	ds_read_b128 v[184:187], v3 offset:36864
	ds_read_b128 v[188:191], v3 offset:37888
	ds_read_b128 v[192:195], v3 offset:38912
	ds_read_b128 v[210:213], v3 offset:39936
	s_nop 0
	global_load_lds_dwordx4 v132, s[90:91]
	s_mov_b32 m0, s42
	s_nop 0
	global_load_lds_dwordx4 v134, s[90:91]
	s_waitcnt vmcnt(8)
	s_waitcnt lgkmcnt(0)
	s_barrier
	s_setprio 1
	s_waitcnt lgkmcnt(0)
	v_mfma_f32_16x16x32_bf16 v[128:131], v[136:139], v[168:171], v[128:131]
	v_mfma_f32_16x16x32_bf16 v[124:127], v[144:147], v[168:171], v[124:127]
	v_mfma_f32_16x16x32_bf16 v[112:115], v[136:139], v[176:179], v[112:115]
	v_mfma_f32_16x16x32_bf16 v[104:107], v[144:147], v[176:179], v[104:107]
	v_mfma_f32_16x16x32_bf16 v[96:99], v[136:139], v[184:187], v[96:99]
	v_mfma_f32_16x16x32_bf16 v[88:91], v[144:147], v[184:187], v[88:91]
	v_mfma_f32_16x16x32_bf16 v[80:83], v[136:139], v[192:195], v[80:83]
	v_mfma_f32_16x16x32_bf16 v[72:75], v[144:147], v[192:195], v[72:75]
	v_mfma_f32_16x16x32_bf16 v[128:131], v[140:143], v[172:175], v[128:131]
	v_mfma_f32_16x16x32_bf16 v[124:127], v[148:151], v[172:175], v[124:127]
	v_mfma_f32_16x16x32_bf16 v[112:115], v[140:143], v[180:183], v[112:115]
	v_mfma_f32_16x16x32_bf16 v[104:107], v[148:151], v[180:183], v[104:107]
	v_mfma_f32_16x16x32_bf16 v[96:99], v[140:143], v[188:191], v[96:99]
	v_mfma_f32_16x16x32_bf16 v[88:91], v[148:151], v[188:191], v[88:91]
	v_mfma_f32_16x16x32_bf16 v[80:83], v[140:143], v[210:213], v[80:83]
	v_mfma_f32_16x16x32_bf16 v[72:75], v[148:151], v[210:213], v[72:75]
	s_setprio 0
	s_setprio 1
	v_mfma_f32_16x16x32_bf16 v[120:123], v[152:155], v[168:171], v[120:123]
	v_mfma_f32_16x16x32_bf16 v[116:119], v[160:163], v[168:171], v[116:119]
	v_mfma_f32_16x16x32_bf16 v[108:111], v[152:155], v[176:179], v[108:111]
	v_mfma_f32_16x16x32_bf16 v[100:103], v[160:163], v[176:179], v[100:103]
	v_mfma_f32_16x16x32_bf16 v[92:95], v[152:155], v[184:187], v[92:95]
	v_mfma_f32_16x16x32_bf16 v[84:87], v[160:163], v[184:187], v[84:87]
	v_mfma_f32_16x16x32_bf16 v[76:79], v[152:155], v[192:195], v[76:79]
	v_mfma_f32_16x16x32_bf16 v[68:71], v[160:163], v[192:195], v[68:71]
	v_mfma_f32_16x16x32_bf16 v[120:123], v[156:159], v[172:175], v[120:123]
	v_mfma_f32_16x16x32_bf16 v[116:119], v[164:167], v[172:175], v[116:119]
	v_mfma_f32_16x16x32_bf16 v[108:111], v[156:159], v[180:183], v[108:111]
	v_mfma_f32_16x16x32_bf16 v[100:103], v[164:167], v[180:183], v[100:103]
	v_mfma_f32_16x16x32_bf16 v[92:95], v[156:159], v[188:191], v[92:95]
	v_mfma_f32_16x16x32_bf16 v[84:87], v[164:167], v[188:191], v[84:87]
	v_mfma_f32_16x16x32_bf16 v[76:79], v[156:159], v[210:213], v[76:79]
	v_mfma_f32_16x16x32_bf16 v[68:71], v[164:167], v[210:213], v[68:71]
	s_setprio 0
	s_barrier
	s_add_i32 s90, s88, s94
	ds_read_b128 v[168:171], v3 offset:49152
	ds_read_b128 v[172:175], v3 offset:50176
	ds_read_b128 v[176:179], v3 offset:51200
	ds_read_b128 v[180:183], v3 offset:52224
	ds_read_b128 v[184:187], v3 offset:53248
	ds_read_b128 v[188:191], v3 offset:54272
	ds_read_b128 v[192:195], v3 offset:55296
	ds_read_b128 v[210:213], v3 offset:56320
	s_mov_b32 m0, s90
	s_nop 0
	global_load_lds_dwordx4 v132, s[78:79]
	s_add_i32 m0, s90, 0x2000
	s_add_u32 s72, s72, 0x40080
	s_addc_u32 s73, s73, 0
	global_load_lds_dwordx4 v134, s[78:79]
	s_add_i32 s78, s89, s94
	s_mov_b32 m0, s78
	s_nop 0
	global_load_lds_dwordx4 v132, s[72:73]
	s_add_i32 m0, s78, 0x2000
	s_nop 0
	global_load_lds_dwordx4 v134, s[72:73]
	s_mov_b32 m0, s43
	s_nop 0
	global_load_lds_dwordx4 v132, s[52:53]
	s_mov_b32 m0, s97
	s_nop 0
	global_load_lds_dwordx4 v134, s[52:53]
	s_waitcnt vmcnt(8)
	s_waitcnt lgkmcnt(0)
	s_barrier
	s_setprio 1
	s_waitcnt lgkmcnt(0)
	v_mfma_f32_16x16x32_bf16 v[64:67], v[136:139], v[168:171], v[64:67]
	v_mfma_f32_16x16x32_bf16 v[56:59], v[144:147], v[168:171], v[56:59]
	v_mfma_f32_16x16x32_bf16 v[48:51], v[136:139], v[176:179], v[48:51]
	v_mfma_f32_16x16x32_bf16 v[40:43], v[144:147], v[176:179], v[40:43]
	v_mfma_f32_16x16x32_bf16 v[32:35], v[136:139], v[184:187], v[32:35]
	v_mfma_f32_16x16x32_bf16 v[24:27], v[144:147], v[184:187], v[24:27]
	v_mfma_f32_16x16x32_bf16 v[16:19], v[136:139], v[192:195], v[16:19]
	v_mfma_f32_16x16x32_bf16 v[8:11], v[144:147], v[192:195], v[8:11]
	v_mfma_f32_16x16x32_bf16 v[64:67], v[140:143], v[172:175], v[64:67]
	v_mfma_f32_16x16x32_bf16 v[56:59], v[148:151], v[172:175], v[56:59]
	v_mfma_f32_16x16x32_bf16 v[48:51], v[140:143], v[180:183], v[48:51]
	v_mfma_f32_16x16x32_bf16 v[40:43], v[148:151], v[180:183], v[40:43]
	v_mfma_f32_16x16x32_bf16 v[32:35], v[140:143], v[188:191], v[32:35]
	v_mfma_f32_16x16x32_bf16 v[24:27], v[148:151], v[188:191], v[24:27]
	v_mfma_f32_16x16x32_bf16 v[16:19], v[140:143], v[210:213], v[16:19]
	v_mfma_f32_16x16x32_bf16 v[8:11], v[148:151], v[210:213], v[8:11]
	s_setprio 0
	s_setprio 1
	v_mfma_f32_16x16x32_bf16 v[60:63], v[152:155], v[168:171], v[60:63]
	v_mfma_f32_16x16x32_bf16 v[52:55], v[160:163], v[168:171], v[52:55]
	v_mfma_f32_16x16x32_bf16 v[44:47], v[152:155], v[176:179], v[44:47]
	v_mfma_f32_16x16x32_bf16 v[36:39], v[160:163], v[176:179], v[36:39]
	v_mfma_f32_16x16x32_bf16 v[28:31], v[152:155], v[184:187], v[28:31]
	v_mfma_f32_16x16x32_bf16 v[20:23], v[160:163], v[184:187], v[20:23]
	v_mfma_f32_16x16x32_bf16 v[12:15], v[152:155], v[192:195], v[12:15]
	v_mfma_f32_16x16x32_bf16 v[4:7], v[160:163], v[192:195], v[4:7]
	v_mfma_f32_16x16x32_bf16 v[60:63], v[156:159], v[172:175], v[60:63]
	v_mfma_f32_16x16x32_bf16 v[52:55], v[164:167], v[172:175], v[52:55]
	v_mfma_f32_16x16x32_bf16 v[44:47], v[156:159], v[180:183], v[44:47]
	v_mfma_f32_16x16x32_bf16 v[36:39], v[164:167], v[180:183], v[36:39]
	v_mfma_f32_16x16x32_bf16 v[28:31], v[156:159], v[188:191], v[28:31]
	v_mfma_f32_16x16x32_bf16 v[20:23], v[164:167], v[188:191], v[20:23]
	v_mfma_f32_16x16x32_bf16 v[12:15], v[156:159], v[210:213], v[12:15]
	v_mfma_f32_16x16x32_bf16 v[4:7], v[164:167], v[210:213], v[4:7]
	s_setprio 0
	s_barrier
	s_add_i32 s52, s75, 2
	s_cmp_gt_u32 s75, 13
	s_mov_b32 s75, s52
	s_cbranch_scc1 .LBB0_2848

.LBB0_3049:
	s_ashr_i32 s9, s8, 31
	s_lshl_b64 s[16:17], s[8:9], 17
	s_add_u32 s20, s54, s16
	s_addc_u32 s21, s55, s17
	s_and_b64 s[16:17], s[24:25], exec
	v_mov_b32_e32 v4, 0
	s_cselect_b32 s1, s21, s15
	s_cselect_b32 s9, s20, s14
	s_mov_b64 s[24:25], 0
	s_mov_b64 s[16:17], -1
	s_mov_b64 s[26:27], 0
	s_waitcnt lgkmcnt(0)
	v_mov_b32_e32 v5, v4
	v_mov_b32_e32 v6, v4
	v_mov_b32_e32 v7, v4
	v_mov_b32_e32 v8, v4
	v_mov_b32_e32 v9, v4
	v_mov_b32_e32 v10, v4
	v_mov_b32_e32 v11, v4
	v_mov_b32_e32 v20, v4
	v_mov_b32_e32 v21, v4
	v_mov_b32_e32 v22, v4
	v_mov_b32_e32 v23, v4
	v_mov_b32_e32 v24, v4
	v_mov_b32_e32 v25, v4
	v_mov_b32_e32 v26, v4
	v_mov_b32_e32 v27, v4
	v_mov_b32_e32 v36, v4
	v_mov_b32_e32 v37, v4
	v_mov_b32_e32 v38, v4
	v_mov_b32_e32 v39, v4
	v_mov_b32_e32 v40, v4
	v_mov_b32_e32 v41, v4
	v_mov_b32_e32 v42, v4
	v_mov_b32_e32 v43, v4
	v_mov_b32_e32 v52, v4
	v_mov_b32_e32 v53, v4
	v_mov_b32_e32 v54, v4
	v_mov_b32_e32 v55, v4
	v_mov_b32_e32 v56, v4
	v_mov_b32_e32 v57, v4
	v_mov_b32_e32 v58, v4
	v_mov_b32_e32 v59, v4
	v_mov_b32_e32 v12, v4
	v_mov_b32_e32 v13, v4
	v_mov_b32_e32 v14, v4
	v_mov_b32_e32 v15, v4
	v_mov_b32_e32 v16, v4
	v_mov_b32_e32 v17, v4
	v_mov_b32_e32 v18, v4
	v_mov_b32_e32 v19, v4
	v_mov_b32_e32 v28, v4
	v_mov_b32_e32 v29, v4
	v_mov_b32_e32 v30, v4
	v_mov_b32_e32 v31, v4
	v_mov_b32_e32 v32, v4
	v_mov_b32_e32 v33, v4
	v_mov_b32_e32 v34, v4
	v_mov_b32_e32 v35, v4
	v_mov_b32_e32 v44, v4
	v_mov_b32_e32 v45, v4
	v_mov_b32_e32 v46, v4
	v_mov_b32_e32 v47, v4
	v_mov_b32_e32 v48, v4
	v_mov_b32_e32 v49, v4
	v_mov_b32_e32 v50, v4
	v_mov_b32_e32 v51, v4
	v_mov_b32_e32 v60, v4
	v_mov_b32_e32 v61, v4
	v_mov_b32_e32 v62, v4
	v_mov_b32_e32 v63, v4
	v_mov_b32_e32 v64, v4
	v_mov_b32_e32 v65, v4
	v_mov_b32_e32 v66, v4
	v_mov_b32_e32 v67, v4
	v_mov_b32_e32 v68, v4
	v_mov_b32_e32 v69, v4
	v_mov_b32_e32 v70, v4
	v_mov_b32_e32 v71, v4
	v_mov_b32_e32 v72, v4
	v_mov_b32_e32 v73, v4
	v_mov_b32_e32 v74, v4
	v_mov_b32_e32 v75, v4
	v_mov_b32_e32 v84, v4
	v_mov_b32_e32 v85, v4
	v_mov_b32_e32 v86, v4
	v_mov_b32_e32 v87, v4
	v_mov_b32_e32 v88, v4
	v_mov_b32_e32 v89, v4
	v_mov_b32_e32 v90, v4
	v_mov_b32_e32 v91, v4
	v_mov_b32_e32 v100, v4
	v_mov_b32_e32 v101, v4
	v_mov_b32_e32 v102, v4
	v_mov_b32_e32 v103, v4
	v_mov_b32_e32 v104, v4
	v_mov_b32_e32 v105, v4
	v_mov_b32_e32 v106, v4
	v_mov_b32_e32 v107, v4
	v_mov_b32_e32 v116, v4
	v_mov_b32_e32 v117, v4
	v_mov_b32_e32 v118, v4
	v_mov_b32_e32 v119, v4
	v_mov_b32_e32 v120, v4
	v_mov_b32_e32 v121, v4
	v_mov_b32_e32 v122, v4
	v_mov_b32_e32 v123, v4
	v_mov_b32_e32 v76, v4
	v_mov_b32_e32 v77, v4
	v_mov_b32_e32 v78, v4
	v_mov_b32_e32 v79, v4
	v_mov_b32_e32 v80, v4
	v_mov_b32_e32 v81, v4
	v_mov_b32_e32 v82, v4
	v_mov_b32_e32 v83, v4
	v_mov_b32_e32 v92, v4
	v_mov_b32_e32 v93, v4
	v_mov_b32_e32 v94, v4
	v_mov_b32_e32 v95, v4
	v_mov_b32_e32 v96, v4
	v_mov_b32_e32 v97, v4
	v_mov_b32_e32 v98, v4
	v_mov_b32_e32 v99, v4
	v_mov_b32_e32 v108, v4
	v_mov_b32_e32 v109, v4
	v_mov_b32_e32 v110, v4
	v_mov_b32_e32 v111, v4
	v_mov_b32_e32 v112, v4
	v_mov_b32_e32 v113, v4
	v_mov_b32_e32 v114, v4
	v_mov_b32_e32 v115, v4
	v_mov_b32_e32 v124, v4
	v_mov_b32_e32 v125, v4
	v_mov_b32_e32 v126, v4
	v_mov_b32_e32 v127, v4
	v_mov_b32_e32 v128, v4
	v_mov_b32_e32 v129, v4
	v_mov_b32_e32 v130, v4
	v_mov_b32_e32 v131, v4
	v_add_u32_e32 v218, 0x10000, v1
	s_waitcnt vmcnt(0)
.LBB0_3050:
	s_add_u32 s30, s22, s24
	s_addc_u32 s31, s23, s25
	s_add_u32 s40, s30, 0x100
	s_addc_u32 s41, s31, 0
	s_and_b64 s[28:29], s[26:27], exec
	s_cselect_b32 s43, s19, s41
	s_cselect_b32 s42, s18, s40
	s_add_u32 s24, s14, s24
	s_addc_u32 s25, s15, s25
	s_add_u32 s28, s24, 0x100
	s_addc_u32 s29, s25, 0
	s_add_u32 s24, s42, 0x80
	s_addc_u32 s25, s43, 0
	s_and_b64 s[26:27], s[26:27], exec
	s_cselect_b32 s45, s1, s29
	s_cselect_b32 s44, s9, s28
	s_add_u32 s46, s30, 0x12080
	s_addc_u32 s47, s31, 0
	s_add_i32 s95, s84, s57
	s_add_i32 m0, s63, 0xc000
	s_add_i32 s97, s63, 0xe000
	s_add_i32 s94, s95, 0x2000
	s_add_u32 s40, s44, 0x10000
	s_addc_u32 s41, s45, 0
	s_add_i32 s93, s85, s57
	s_add_i32 s92, s93, 0x2000
	s_add_u32 s30, s42, 0x12000
	ds_read_b128 v[140:143], v218
	ds_read_b128 v[144:147], v218 offset:1024
	ds_read_b128 v[148:151], v218 offset:2048
	ds_read_b128 v[152:155], v218 offset:3072
	s_addc_u32 s31, s43, 0
	s_add_u32 s28, s44, 0x80
	s_addc_u32 s29, s45, 0
	s_add_i32 s91, s88, s57
	s_add_i32 s90, s91, 0x2000
	s_add_u32 s26, s44, 0x10080
	s_addc_u32 s27, s45, 0
	s_add_i32 s87, s89, s57
	s_add_i32 s86, s87, 0x2000
	ds_read_b128 v[156:159], v3
	ds_read_b128 v[160:163], v3 offset:1024
	ds_read_b128 v[164:167], v3 offset:2048
	ds_read_b128 v[168:171], v3 offset:3072
	ds_read_b128 v[172:175], v3 offset:4096
	ds_read_b128 v[176:179], v3 offset:5120
	ds_read_b128 v[180:183], v3 offset:6144
	ds_read_b128 v[184:187], v3 offset:7168
	s_nop 0
	global_load_lds_dwordx4 v132, s[46:47]
	s_mov_b32 m0, s97
	s_nop 0
	global_load_lds_dwordx4 v136, s[46:47]
	s_waitcnt lgkmcnt(8)
	s_barrier
	s_waitcnt lgkmcnt(0)
	s_setprio 1
	s_waitcnt lgkmcnt(0)
	v_mfma_f32_16x16x32_bf16 v[128:131], v[140:143], v[156:159], v[128:131]
	v_mfma_f32_16x16x32_bf16 v[124:127], v[148:151], v[156:159], v[124:127]
	v_mfma_f32_16x16x32_bf16 v[112:115], v[140:143], v[164:167], v[112:115]
	v_mfma_f32_16x16x32_bf16 v[108:111], v[148:151], v[164:167], v[108:111]
	v_mfma_f32_16x16x32_bf16 v[96:99], v[140:143], v[172:175], v[96:99]
	v_mfma_f32_16x16x32_bf16 v[92:95], v[148:151], v[172:175], v[92:95]
	v_mfma_f32_16x16x32_bf16 v[80:83], v[140:143], v[180:183], v[80:83]
	v_mfma_f32_16x16x32_bf16 v[76:79], v[148:151], v[180:183], v[76:79]
	v_mfma_f32_16x16x32_bf16 v[128:131], v[144:147], v[160:163], v[128:131]
	v_mfma_f32_16x16x32_bf16 v[124:127], v[152:155], v[160:163], v[124:127]
	v_mfma_f32_16x16x32_bf16 v[112:115], v[144:147], v[168:171], v[112:115]
	v_mfma_f32_16x16x32_bf16 v[108:111], v[152:155], v[168:171], v[108:111]
	v_mfma_f32_16x16x32_bf16 v[96:99], v[144:147], v[176:179], v[96:99]
	v_mfma_f32_16x16x32_bf16 v[92:95], v[152:155], v[176:179], v[92:95]
	v_mfma_f32_16x16x32_bf16 v[80:83], v[144:147], v[184:187], v[80:83]
	v_mfma_f32_16x16x32_bf16 v[76:79], v[152:155], v[184:187], v[76:79]
	s_setprio 0
	s_barrier
	s_mov_b32 m0, s95
	ds_read_b128 v[188:191], v218 offset:16384
	ds_read_b128 v[192:195], v218 offset:17408
	ds_read_b128 v[210:213], v218 offset:18432
	ds_read_b128 v[214:217], v218 offset:19456
	s_nop 0
	global_load_lds_dwordx4 v134, s[44:45]
	s_mov_b32 m0, s94
	s_nop 0
	global_load_lds_dwordx4 v138, s[44:45]
	s_barrier
	s_waitcnt lgkmcnt(0)
	s_setprio 1
	s_waitcnt lgkmcnt(0)
	v_mfma_f32_16x16x32_bf16 v[120:123], v[188:191], v[156:159], v[120:123]
	v_mfma_f32_16x16x32_bf16 v[116:119], v[210:213], v[156:159], v[116:119]
	v_mfma_f32_16x16x32_bf16 v[104:107], v[188:191], v[164:167], v[104:107]
	v_mfma_f32_16x16x32_bf16 v[100:103], v[210:213], v[164:167], v[100:103]
	v_mfma_f32_16x16x32_bf16 v[88:91], v[188:191], v[172:175], v[88:91]
	v_mfma_f32_16x16x32_bf16 v[84:87], v[210:213], v[172:175], v[84:87]
	v_mfma_f32_16x16x32_bf16 v[72:75], v[188:191], v[180:183], v[72:75]
	v_mfma_f32_16x16x32_bf16 v[68:71], v[210:213], v[180:183], v[68:71]
	v_mfma_f32_16x16x32_bf16 v[120:123], v[192:195], v[160:163], v[120:123]
	v_mfma_f32_16x16x32_bf16 v[116:119], v[214:217], v[160:163], v[116:119]
	v_mfma_f32_16x16x32_bf16 v[104:107], v[192:195], v[168:171], v[104:107]
	v_mfma_f32_16x16x32_bf16 v[100:103], v[214:217], v[168:171], v[100:103]
	v_mfma_f32_16x16x32_bf16 v[88:91], v[192:195], v[176:179], v[88:91]
	v_mfma_f32_16x16x32_bf16 v[84:87], v[214:217], v[176:179], v[84:87]
	v_mfma_f32_16x16x32_bf16 v[72:75], v[192:195], v[184:187], v[72:75]
	v_mfma_f32_16x16x32_bf16 v[68:71], v[214:217], v[184:187], v[68:71]
	s_setprio 0
	s_mov_b32 m0, s63
	s_barrier
	ds_read_b128 v[156:159], v3 offset:16384
	ds_read_b128 v[160:163], v3 offset:17408
	ds_read_b128 v[164:167], v3 offset:18432
	ds_read_b128 v[168:171], v3 offset:19456
	ds_read_b128 v[172:175], v3 offset:20480
	ds_read_b128 v[176:179], v3 offset:21504
	ds_read_b128 v[180:183], v3 offset:22528
	ds_read_b128 v[184:187], v3 offset:23552
	s_nop 0
	global_load_lds_dwordx4 v132, s[42:43]
	s_mov_b32 m0, s64
	s_nop 0
	global_load_lds_dwordx4 v136, s[42:43]
	s_barrier
	s_waitcnt lgkmcnt(0)
	s_setprio 1
	s_waitcnt lgkmcnt(0)
	v_mfma_f32_16x16x32_bf16 v[64:67], v[140:143], v[156:159], v[64:67]
	v_mfma_f32_16x16x32_bf16 v[60:63], v[148:151], v[156:159], v[60:63]
	v_mfma_f32_16x16x32_bf16 v[48:51], v[140:143], v[164:167], v[48:51]
	v_mfma_f32_16x16x32_bf16 v[44:47], v[148:151], v[164:167], v[44:47]
	v_mfma_f32_16x16x32_bf16 v[32:35], v[140:143], v[172:175], v[32:35]
	v_mfma_f32_16x16x32_bf16 v[28:31], v[148:151], v[172:175], v[28:31]
	v_mfma_f32_16x16x32_bf16 v[16:19], v[140:143], v[180:183], v[16:19]
	v_mfma_f32_16x16x32_bf16 v[12:15], v[148:151], v[180:183], v[12:15]
	v_mfma_f32_16x16x32_bf16 v[64:67], v[144:147], v[160:163], v[64:67]
	v_mfma_f32_16x16x32_bf16 v[60:63], v[152:155], v[160:163], v[60:63]
	v_mfma_f32_16x16x32_bf16 v[48:51], v[144:147], v[168:171], v[48:51]
	v_mfma_f32_16x16x32_bf16 v[44:47], v[152:155], v[168:171], v[44:47]
	v_mfma_f32_16x16x32_bf16 v[32:35], v[144:147], v[176:179], v[32:35]
	v_mfma_f32_16x16x32_bf16 v[28:31], v[152:155], v[176:179], v[28:31]
	v_mfma_f32_16x16x32_bf16 v[16:19], v[144:147], v[184:187], v[16:19]
	v_mfma_f32_16x16x32_bf16 v[12:15], v[152:155], v[184:187], v[12:15]
	s_setprio 0
	s_barrier
	s_mov_b32 m0, s93
	s_nop 0
	global_load_lds_dwordx4 v134, s[40:41]
	s_mov_b32 m0, s92
	s_nop 0
	global_load_lds_dwordx4 v138, s[40:41]
	s_waitcnt vmcnt(6)
	s_barrier
	s_setprio 1
	v_mfma_f32_16x16x32_bf16 v[56:59], v[188:191], v[156:159], v[56:59]
	v_mfma_f32_16x16x32_bf16 v[52:55], v[210:213], v[156:159], v[52:55]
	v_mfma_f32_16x16x32_bf16 v[40:43], v[188:191], v[164:167], v[40:43]
	v_mfma_f32_16x16x32_bf16 v[36:39], v[210:213], v[164:167], v[36:39]
	v_mfma_f32_16x16x32_bf16 v[24:27], v[188:191], v[172:175], v[24:27]
	v_mfma_f32_16x16x32_bf16 v[20:23], v[210:213], v[172:175], v[20:23]
	v_mfma_f32_16x16x32_bf16 v[8:11], v[188:191], v[180:183], v[8:11]
	v_mfma_f32_16x16x32_bf16 v[4:7], v[210:213], v[180:183], v[4:7]
	v_mfma_f32_16x16x32_bf16 v[56:59], v[192:195], v[160:163], v[56:59]
	v_mfma_f32_16x16x32_bf16 v[52:55], v[214:217], v[160:163], v[52:55]
	v_mfma_f32_16x16x32_bf16 v[40:43], v[192:195], v[168:171], v[40:43]
	v_mfma_f32_16x16x32_bf16 v[36:39], v[214:217], v[168:171], v[36:39]
	v_mfma_f32_16x16x32_bf16 v[24:27], v[192:195], v[176:179], v[24:27]
	v_mfma_f32_16x16x32_bf16 v[20:23], v[214:217], v[176:179], v[20:23]
	v_mfma_f32_16x16x32_bf16 v[8:11], v[192:195], v[184:187], v[8:11]
	v_mfma_f32_16x16x32_bf16 v[4:7], v[214:217], v[184:187], v[4:7]
	s_setprio 0
	s_barrier
	ds_read_b128 v[140:143], v218 offset:32768
	ds_read_b128 v[144:147], v218 offset:33792
	ds_read_b128 v[148:151], v218 offset:34816
	ds_read_b128 v[152:155], v218 offset:35840
	s_mov_b32 m0, s65
	ds_read_b128 v[156:159], v3 offset:32768
	ds_read_b128 v[160:163], v3 offset:33792
	ds_read_b128 v[164:167], v3 offset:34816
	ds_read_b128 v[168:171], v3 offset:35840
	ds_read_b128 v[172:175], v3 offset:36864
	ds_read_b128 v[176:179], v3 offset:37888
	ds_read_b128 v[180:183], v3 offset:38912
	ds_read_b128 v[184:187], v3 offset:39936
	s_nop 0
	global_load_lds_dwordx4 v132, s[30:31]
	s_mov_b32 m0, s67
	s_nop 0
	global_load_lds_dwordx4 v136, s[30:31]
	s_waitcnt lgkmcnt(8)
	s_barrier
	s_waitcnt lgkmcnt(0)
	s_setprio 1
	s_waitcnt lgkmcnt(0)
	v_mfma_f32_16x16x32_bf16 v[128:131], v[140:143], v[156:159], v[128:131]
	v_mfma_f32_16x16x32_bf16 v[124:127], v[148:151], v[156:159], v[124:127]
	v_mfma_f32_16x16x32_bf16 v[112:115], v[140:143], v[164:167], v[112:115]
	v_mfma_f32_16x16x32_bf16 v[108:111], v[148:151], v[164:167], v[108:111]
	v_mfma_f32_16x16x32_bf16 v[96:99], v[140:143], v[172:175], v[96:99]
	v_mfma_f32_16x16x32_bf16 v[92:95], v[148:151], v[172:175], v[92:95]
	v_mfma_f32_16x16x32_bf16 v[80:83], v[140:143], v[180:183], v[80:83]
	v_mfma_f32_16x16x32_bf16 v[76:79], v[148:151], v[180:183], v[76:79]
	v_mfma_f32_16x16x32_bf16 v[128:131], v[144:147], v[160:163], v[128:131]
	v_mfma_f32_16x16x32_bf16 v[124:127], v[152:155], v[160:163], v[124:127]
	v_mfma_f32_16x16x32_bf16 v[112:115], v[144:147], v[168:171], v[112:115]
	v_mfma_f32_16x16x32_bf16 v[108:111], v[152:155], v[168:171], v[108:111]
	v_mfma_f32_16x16x32_bf16 v[96:99], v[144:147], v[176:179], v[96:99]
	v_mfma_f32_16x16x32_bf16 v[92:95], v[152:155], v[176:179], v[92:95]
	v_mfma_f32_16x16x32_bf16 v[80:83], v[144:147], v[184:187], v[80:83]
	v_mfma_f32_16x16x32_bf16 v[76:79], v[152:155], v[184:187], v[76:79]
	s_setprio 0
	s_barrier
	s_mov_b32 m0, s91
	ds_read_b128 v[188:191], v218 offset:49152
	ds_read_b128 v[192:195], v218 offset:50176
	ds_read_b128 v[210:213], v218 offset:51200
	ds_read_b128 v[214:217], v218 offset:52224
	s_nop 0
	global_load_lds_dwordx4 v134, s[28:29]
	s_mov_b32 m0, s90
	s_nop 0
	global_load_lds_dwordx4 v138, s[28:29]
	s_barrier
	s_waitcnt lgkmcnt(0)
	s_setprio 1
	s_waitcnt lgkmcnt(0)
	v_mfma_f32_16x16x32_bf16 v[120:123], v[188:191], v[156:159], v[120:123]
	v_mfma_f32_16x16x32_bf16 v[116:119], v[210:213], v[156:159], v[116:119]
	v_mfma_f32_16x16x32_bf16 v[104:107], v[188:191], v[164:167], v[104:107]
	v_mfma_f32_16x16x32_bf16 v[100:103], v[210:213], v[164:167], v[100:103]
	v_mfma_f32_16x16x32_bf16 v[88:91], v[188:191], v[172:175], v[88:91]
	v_mfma_f32_16x16x32_bf16 v[84:87], v[210:213], v[172:175], v[84:87]
	v_mfma_f32_16x16x32_bf16 v[72:75], v[188:191], v[180:183], v[72:75]
	v_mfma_f32_16x16x32_bf16 v[68:71], v[210:213], v[180:183], v[68:71]
	v_mfma_f32_16x16x32_bf16 v[120:123], v[192:195], v[160:163], v[120:123]
	v_mfma_f32_16x16x32_bf16 v[116:119], v[214:217], v[160:163], v[116:119]
	v_mfma_f32_16x16x32_bf16 v[104:107], v[192:195], v[168:171], v[104:107]
	v_mfma_f32_16x16x32_bf16 v[100:103], v[214:217], v[168:171], v[100:103]
	v_mfma_f32_16x16x32_bf16 v[88:91], v[192:195], v[176:179], v[88:91]
	v_mfma_f32_16x16x32_bf16 v[84:87], v[214:217], v[176:179], v[84:87]
	v_mfma_f32_16x16x32_bf16 v[72:75], v[192:195], v[184:187], v[72:75]
	v_mfma_f32_16x16x32_bf16 v[68:71], v[214:217], v[184:187], v[68:71]
	s_setprio 0
	s_mov_b32 m0, s75
	s_barrier
	ds_read_b128 v[156:159], v3 offset:49152
	ds_read_b128 v[160:163], v3 offset:50176
	ds_read_b128 v[164:167], v3 offset:51200
	ds_read_b128 v[168:171], v3 offset:52224
	ds_read_b128 v[172:175], v3 offset:53248
	ds_read_b128 v[176:179], v3 offset:54272
	ds_read_b128 v[180:183], v3 offset:55296
	ds_read_b128 v[184:187], v3 offset:56320
	s_nop 0
	global_load_lds_dwordx4 v132, s[24:25]
	s_mov_b32 m0, s78
	s_nop 0
	global_load_lds_dwordx4 v136, s[24:25]
	s_barrier
	s_waitcnt lgkmcnt(0)
	s_setprio 1
	s_waitcnt lgkmcnt(0)
	v_mfma_f32_16x16x32_bf16 v[64:67], v[140:143], v[156:159], v[64:67]
	v_mfma_f32_16x16x32_bf16 v[60:63], v[148:151], v[156:159], v[60:63]
	v_mfma_f32_16x16x32_bf16 v[48:51], v[140:143], v[164:167], v[48:51]
	v_mfma_f32_16x16x32_bf16 v[44:47], v[148:151], v[164:167], v[44:47]
	v_mfma_f32_16x16x32_bf16 v[32:35], v[140:143], v[172:175], v[32:35]
	v_mfma_f32_16x16x32_bf16 v[28:31], v[148:151], v[172:175], v[28:31]
	v_mfma_f32_16x16x32_bf16 v[16:19], v[140:143], v[180:183], v[16:19]
	v_mfma_f32_16x16x32_bf16 v[12:15], v[148:151], v[180:183], v[12:15]
	v_mfma_f32_16x16x32_bf16 v[64:67], v[144:147], v[160:163], v[64:67]
	v_mfma_f32_16x16x32_bf16 v[60:63], v[152:155], v[160:163], v[60:63]
	v_mfma_f32_16x16x32_bf16 v[48:51], v[144:147], v[168:171], v[48:51]
	v_mfma_f32_16x16x32_bf16 v[44:47], v[152:155], v[168:171], v[44:47]
	v_mfma_f32_16x16x32_bf16 v[32:35], v[144:147], v[176:179], v[32:35]
	v_mfma_f32_16x16x32_bf16 v[28:31], v[152:155], v[176:179], v[28:31]
	v_mfma_f32_16x16x32_bf16 v[16:19], v[144:147], v[184:187], v[16:19]
	v_mfma_f32_16x16x32_bf16 v[12:15], v[152:155], v[184:187], v[12:15]
	s_setprio 0
	s_barrier
	s_mov_b32 m0, s87
	s_nop 0
	global_load_lds_dwordx4 v134, s[26:27]
	s_mov_b32 m0, s86
	s_nop 0
	global_load_lds_dwordx4 v138, s[26:27]
	s_waitcnt vmcnt(6)
	s_barrier
	s_setprio 1
	v_mfma_f32_16x16x32_bf16 v[56:59], v[188:191], v[156:159], v[56:59]
	v_mfma_f32_16x16x32_bf16 v[52:55], v[210:213], v[156:159], v[52:55]
	v_mfma_f32_16x16x32_bf16 v[40:43], v[188:191], v[164:167], v[40:43]
	v_mfma_f32_16x16x32_bf16 v[36:39], v[210:213], v[164:167], v[36:39]
	v_mfma_f32_16x16x32_bf16 v[24:27], v[188:191], v[172:175], v[24:27]
	v_mfma_f32_16x16x32_bf16 v[20:23], v[210:213], v[172:175], v[20:23]
	v_mfma_f32_16x16x32_bf16 v[8:11], v[188:191], v[180:183], v[8:11]
	v_mfma_f32_16x16x32_bf16 v[4:7], v[210:213], v[180:183], v[4:7]
	v_mfma_f32_16x16x32_bf16 v[56:59], v[192:195], v[160:163], v[56:59]
	v_mfma_f32_16x16x32_bf16 v[52:55], v[214:217], v[160:163], v[52:55]
	v_mfma_f32_16x16x32_bf16 v[40:43], v[192:195], v[168:171], v[40:43]
	v_mfma_f32_16x16x32_bf16 v[36:39], v[214:217], v[168:171], v[36:39]
	v_mfma_f32_16x16x32_bf16 v[24:27], v[192:195], v[176:179], v[24:27]
	v_mfma_f32_16x16x32_bf16 v[20:23], v[214:217], v[176:179], v[20:23]
	v_mfma_f32_16x16x32_bf16 v[8:11], v[192:195], v[184:187], v[8:11]
	v_mfma_f32_16x16x32_bf16 v[4:7], v[214:217], v[184:187], v[4:7]
	s_setprio 0
	s_andn2_b64 vcc, exec, s[16:17]
	s_mov_b64 s[26:27], -1
	s_mov_b64 s[16:17], 0
	s_mov_b64 s[24:25], 0x100
	s_barrier
	s_cbranch_vccz .LBB0_3050
	v_mov_b32_e32 v141, v0
	s_ashr_i32 s1, s0, 31
	v_readfirstlane_b32 s9, v141
	s_bfe_u32 s24, s9, 0x20006
	s_ashr_i32 s9, s9, 2
	s_and_b32 s14, s9, 0xffffffc0
	s_ashr_i32 s15, s14, 31
	s_lshl_b64 s[16:17], s[0:1], 10
	s_add_u32 s9, s68, s16
	s_addc_u32 s23, s72, s17
	s_lshl_b64 s[16:17], s[14:15], 2
	v_and_b32_e32 v142, 15, v141
	s_add_u32 s22, s9, s16
	s_addc_u32 s23, s23, s17
	v_lshlrev_b32_e32 v140, 2, v142
	global_load_dword v150, v140, s[22:23] offset:64
	global_load_dword v149, v140, s[22:23] offset:128
	global_load_dword v148, v140, s[22:23] offset:192
	global_load_dword v147, v140, s[22:23] offset:512
	global_load_dword v146, v140, s[22:23] offset:576
	global_load_dword v145, v140, s[22:23] offset:640
	global_load_dword v144, v140, s[22:23] offset:704
	v_mul_f32_e32 v129, v129, v129
	v_mul_f32_e32 v125, v125, v125
	v_mul_f32_e32 v121, v121, v121
	v_mul_f32_e32 v117, v117, v117
	v_fmac_f32_e32 v129, v128, v128
	v_mul_f32_e32 v128, v131, v131
	v_fmac_f32_e32 v125, v124, v124
	v_mul_f32_e32 v124, v127, v127
	v_fmac_f32_e32 v121, v120, v120
	v_mul_f32_e32 v120, v123, v123
	v_fmac_f32_e32 v117, v116, v116
	v_mul_f32_e32 v116, v119, v119
	v_fmac_f32_e32 v128, v130, v130
	v_fmac_f32_e32 v124, v126, v126
	v_fmac_f32_e32 v120, v122, v122
	v_fmac_f32_e32 v116, v118, v118
	v_add_f32_e32 v128, v129, v128
	v_add_f32_e32 v124, v125, v124
	v_add_f32_e32 v120, v121, v120
	v_add_f32_e32 v116, v117, v116
	v_add_f32_e32 v124, v128, v124
	v_add_f32_e32 v116, v120, v116
	v_add_f32_e32 v117, v124, v116
	ds_swizzle_b32 v118, v117 offset:swizzle(SWAP,16)
	v_and_b32_e32 v152, 64, v236
	v_xor_b32_e32 v151, 32, v236
	v_add_u32_e32 v152, 64, v152
	v_cmp_lt_i32_e32 vcc, v151, v152
	s_lshl_b32 s9, s83, 2
	s_or_b32 s24, s24, s9
	v_cndmask_b32_e32 v116, v236, v151, vcc
	s_lshl_b64 s[0:1], s[0:1], 8
	v_lshlrev_b32_e32 v116, 2, v116
	s_waitcnt lgkmcnt(0)
	v_add_f32_e32 v117, v117, v118
	s_add_u32 s0, s0, s14
	ds_bpermute_b32 v118, v116, v117
	s_addc_u32 s1, s1, s15
	s_ashr_i32 s25, s24, 31
	v_or_b32_e32 v143, s0, v142
	v_mov_b32_e32 v142, s1
	s_lshl_b64 s[0:1], s[24:25], 2
	v_and_b32_e32 v119, 48, v141
	s_add_u32 s0, s73, s0
	v_cmp_eq_u32_e64 s[16:17], 0, v119
	s_addc_u32 s1, s74, s1
	s_and_saveexec_b64 s[14:15], s[16:17]
	s_cbranch_execz .LBB0_3053
	v_mov_b32_e32 v141, v2
	v_lshl_add_u64 v[120:121], s[22:23], 0, v[140:141]
	global_load_dword v119, v[120:121], off
	s_waitcnt lgkmcnt(0)
	v_add_f32_e32 v117, v117, v118
	s_waitcnt vmcnt(0)
	v_add_f32_e32 v117, v117, v119
	v_fmamk_f32 v117, v117, 0x3c2aaaab, v231
	v_cmp_gt_f32_e32 vcc, s11, v117
	v_mul_f32_e32 v118, 0x4b800000, v117
	s_nop 0
	v_cndmask_b32_e32 v117, v117, v118, vcc
	v_rsq_f32_e32 v117, v117
	s_nop 0
	v_mul_f32_e32 v118, 0x45800000, v117
	v_cndmask_b32_e32 v117, v117, v118, vcc
	v_mad_u64_u32 v[118:119], s[22:23], v143, 48, s[0:1]
	v_mov_b32_e32 v120, v119
	v_mad_u64_u32 v[120:121], s[22:23], v142, 48, v[120:121]
	v_mov_b32_e32 v119, v120
	global_store_dword v[118:119], v117, off

.LBB0_3087:
	v_and_b32_e32 v3, 15, v1
	v_and_b32_e32 v4, 48, v1
	v_lshlrev_b32_e32 v3, 6, v3
	v_lshlrev_b32_e32 v1, 2, v1
	v_or_b32_e32 v5, v3, v4
	v_and_b32_e32 v1, 32, v1
	s_lshl_b32 s16, s16, 12
	s_lshl_b32 s15, s15, 13
	v_bitop3_b32 v6, v5, s15, v1 bitop3:0xde
	s_and_b32 s15, s16, 0x3000
	s_add_u32 s16, s6, 0x80
	v_mov_b32_e32 v133, v2
	s_addc_u32 s17, s7, 0
	v_bitop3_b32 v3, v3, v1, v4 bitop3:0x36
	s_waitcnt vmcnt(2)
	s_barrier
	s_add_i32 m0, s41, 0x18000
	v_lshl_add_u64 v[4:5], s[16:17], 0, v[132:133]
	v_mov_b32_e32 v135, v2
	global_load_lds_dwordx4 v[4:5], off
	s_add_i32 m0, s41, 0x1a000
	v_lshl_add_u64 v[4:5], s[16:17], 0, v[134:135]
	s_add_u32 s16, s38, 0x12ddec80
	s_addc_u32 s17, s39, 0
	s_add_i32 s38, s41, 0x8000
	global_load_lds_dwordx4 v[4:5], off
	s_mov_b32 m0, s38
	v_lshl_add_u64 v[4:5], s[16:17], 0, v[132:133]
	s_add_i32 s39, s41, 0xa000
	global_load_lds_dwordx4 v[4:5], off
	v_lshl_add_u64 v[4:5], s[16:17], 0, v[134:135]
	s_add_u32 s16, s6, 0xb0080
	s_mov_b32 m0, s39
	s_addc_u32 s17, s7, 0
	global_load_lds_dwordx4 v[4:5], off
	s_add_i32 m0, s41, 0x1c000
	v_lshl_add_u64 v[4:5], s[16:17], 0, v[132:133]
	global_load_lds_dwordx4 v[4:5], off
	v_lshl_add_u64 v[4:5], s[16:17], 0, v[134:135]
	s_add_i32 m0, s41, 0x1e000
	v_or_b32_e32 v1, s15, v3
	global_load_lds_dwordx4 v[4:5], off
	s_waitcnt vmcnt(6)
	v_readlane_b32 s15, v254, 29
	s_add_u32 s45, s15, s40
	v_readlane_b32 s15, v254, 28
	v_mov_b32_e32 v4, 0
	s_addc_u32 s46, s15, s14
	s_mov_b32 s47, -2
	v_add_u32_e32 v3, 0, v6
	s_mov_b64 s[14:15], s[0:1]
	v_mov_b32_e32 v5, v4
	v_mov_b32_e32 v6, v4
	v_mov_b32_e32 v7, v4
	v_mov_b32_e32 v8, v4
	v_mov_b32_e32 v9, v4
	v_mov_b32_e32 v10, v4
	v_mov_b32_e32 v11, v4
	v_mov_b32_e32 v20, v4
	v_mov_b32_e32 v21, v4
	v_mov_b32_e32 v22, v4
	v_mov_b32_e32 v23, v4
	v_mov_b32_e32 v24, v4
	v_mov_b32_e32 v25, v4
	v_mov_b32_e32 v26, v4
	v_mov_b32_e32 v27, v4
	v_mov_b32_e32 v36, v4
	v_mov_b32_e32 v37, v4
	v_mov_b32_e32 v38, v4
	v_mov_b32_e32 v39, v4
	v_mov_b32_e32 v40, v4
	v_mov_b32_e32 v41, v4
	v_mov_b32_e32 v42, v4
	v_mov_b32_e32 v43, v4
	v_mov_b32_e32 v52, v4
	v_mov_b32_e32 v53, v4
	v_mov_b32_e32 v54, v4
	v_mov_b32_e32 v55, v4
	v_mov_b32_e32 v56, v4
	v_mov_b32_e32 v57, v4
	v_mov_b32_e32 v58, v4
	v_mov_b32_e32 v59, v4
	v_mov_b32_e32 v12, v4
	v_mov_b32_e32 v13, v4
	v_mov_b32_e32 v14, v4
	v_mov_b32_e32 v15, v4
	v_mov_b32_e32 v16, v4
	v_mov_b32_e32 v17, v4
	v_mov_b32_e32 v18, v4
	v_mov_b32_e32 v19, v4
	v_mov_b32_e32 v28, v4
	v_mov_b32_e32 v29, v4
	v_mov_b32_e32 v30, v4
	v_mov_b32_e32 v31, v4
	v_mov_b32_e32 v32, v4
	v_mov_b32_e32 v33, v4
	v_mov_b32_e32 v34, v4
	v_mov_b32_e32 v35, v4
	v_mov_b32_e32 v44, v4
	v_mov_b32_e32 v45, v4
	v_mov_b32_e32 v46, v4
	v_mov_b32_e32 v47, v4
	v_mov_b32_e32 v48, v4
	v_mov_b32_e32 v49, v4
	v_mov_b32_e32 v50, v4
	v_mov_b32_e32 v51, v4
	v_mov_b32_e32 v60, v4
	v_mov_b32_e32 v61, v4
	v_mov_b32_e32 v62, v4
	v_mov_b32_e32 v63, v4
	v_mov_b32_e32 v64, v4
	v_mov_b32_e32 v65, v4
	v_mov_b32_e32 v66, v4
	v_mov_b32_e32 v67, v4
	v_mov_b32_e32 v68, v4
	v_mov_b32_e32 v69, v4
	v_mov_b32_e32 v70, v4
	v_mov_b32_e32 v71, v4
	v_mov_b32_e32 v72, v4
	v_mov_b32_e32 v73, v4
	v_mov_b32_e32 v74, v4
	v_mov_b32_e32 v75, v4
	v_mov_b32_e32 v84, v4
	v_mov_b32_e32 v85, v4
	v_mov_b32_e32 v86, v4
	v_mov_b32_e32 v87, v4
	v_mov_b32_e32 v88, v4
	v_mov_b32_e32 v89, v4
	v_mov_b32_e32 v90, v4
	v_mov_b32_e32 v91, v4
	v_mov_b32_e32 v100, v4
	v_mov_b32_e32 v101, v4
	v_mov_b32_e32 v102, v4
	v_mov_b32_e32 v103, v4
	v_mov_b32_e32 v104, v4
	v_mov_b32_e32 v105, v4
	v_mov_b32_e32 v106, v4
	v_mov_b32_e32 v107, v4
	v_mov_b32_e32 v116, v4
	v_mov_b32_e32 v117, v4
	v_mov_b32_e32 v118, v4
	v_mov_b32_e32 v119, v4
	v_mov_b32_e32 v120, v4
	v_mov_b32_e32 v121, v4
	v_mov_b32_e32 v122, v4
	v_mov_b32_e32 v123, v4
	v_mov_b32_e32 v76, v4
	v_mov_b32_e32 v77, v4
	v_mov_b32_e32 v78, v4
	v_mov_b32_e32 v79, v4
	v_mov_b32_e32 v80, v4
	v_mov_b32_e32 v81, v4
	v_mov_b32_e32 v82, v4
	v_mov_b32_e32 v83, v4
	v_mov_b32_e32 v92, v4
	v_mov_b32_e32 v93, v4
	v_mov_b32_e32 v94, v4
	v_mov_b32_e32 v95, v4
	v_mov_b32_e32 v96, v4
	v_mov_b32_e32 v97, v4
	v_mov_b32_e32 v98, v4
	v_mov_b32_e32 v99, v4
	v_mov_b32_e32 v108, v4
	v_mov_b32_e32 v109, v4
	v_mov_b32_e32 v110, v4
	v_mov_b32_e32 v111, v4
	v_mov_b32_e32 v112, v4
	v_mov_b32_e32 v113, v4
	v_mov_b32_e32 v114, v4
	v_mov_b32_e32 v115, v4
	v_mov_b32_e32 v124, v4
	v_mov_b32_e32 v125, v4
	v_mov_b32_e32 v126, v4
	v_mov_b32_e32 v127, v4
	v_mov_b32_e32 v128, v4
	v_mov_b32_e32 v129, v4
	v_mov_b32_e32 v130, v4
	v_mov_b32_e32 v131, v4
	v_add_u32_e32 v239, 0x10000, v1
	s_barrier
	s_waitcnt vmcnt(0)
.LBB0_3088:
	s_add_u32 s16, s14, s45
	s_addc_u32 s17, s15, s46
	s_add_u32 s20, s16, 0xf0c5f100
	s_addc_u32 s21, s17, -1
	s_add_u32 s16, s14, 0x100
	ds_read_b128 v[136:139], v239
	ds_read_b128 v[140:143], v239 offset:1024
	ds_read_b128 v[144:147], v239 offset:2048
	ds_read_b128 v[148:151], v239 offset:3072
	ds_read_b128 v[152:155], v239 offset:16384
	ds_read_b128 v[156:159], v239 offset:17408
	ds_read_b128 v[160:163], v239 offset:18432
	ds_read_b128 v[164:167], v239 offset:19456
	s_addc_u32 s17, s15, 0
	s_cmp_eq_u32 s47, 40
	s_cselect_b32 s20, s6, s20
	s_cselect_b32 s21, s7, s21
	s_cselect_b32 s26, s0, s16
	s_cselect_b32 s27, s1, s17
	s_add_u32 s24, s20, 0x80
	s_addc_u32 s25, s21, 0
	s_add_u32 s22, s26, 0x80
	s_addc_u32 s23, s27, 0
	s_add_u32 s14, s14, 0xb0080
	s_addc_u32 s15, s15, 0
	ds_read_b128 v[168:171], v3
	ds_read_b128 v[172:175], v3 offset:1024
	ds_read_b128 v[176:179], v3 offset:2048
	ds_read_b128 v[180:183], v3 offset:3072
	ds_read_b128 v[184:187], v3 offset:4096
	ds_read_b128 v[188:191], v3 offset:5120
	ds_read_b128 v[192:195], v3 offset:6144
	ds_read_b128 v[210:213], v3 offset:7168
	s_add_i32 m0, s41, 0xc000
	s_nop 0
	global_load_lds_dwordx4 v132, s[14:15]
	s_add_i32 m0, s41, 0xe000
	s_nop 0
	global_load_lds_dwordx4 v134, s[14:15]
	s_waitcnt vmcnt(8)
	s_waitcnt lgkmcnt(0)
	s_barrier
	s_setprio 1
	s_waitcnt lgkmcnt(0)
	v_mfma_f32_16x16x32_bf16 v[128:131], v[136:139], v[168:171], v[128:131]
	v_mfma_f32_16x16x32_bf16 v[124:127], v[144:147], v[168:171], v[124:127]
	v_mfma_f32_16x16x32_bf16 v[112:115], v[136:139], v[176:179], v[112:115]
	v_mfma_f32_16x16x32_bf16 v[108:111], v[144:147], v[176:179], v[108:111]
	v_mfma_f32_16x16x32_bf16 v[96:99], v[136:139], v[184:187], v[96:99]
	v_mfma_f32_16x16x32_bf16 v[92:95], v[144:147], v[184:187], v[92:95]
	v_mfma_f32_16x16x32_bf16 v[80:83], v[136:139], v[192:195], v[80:83]
	v_mfma_f32_16x16x32_bf16 v[76:79], v[144:147], v[192:195], v[76:79]
	v_mfma_f32_16x16x32_bf16 v[128:131], v[140:143], v[172:175], v[128:131]
	v_mfma_f32_16x16x32_bf16 v[124:127], v[148:151], v[172:175], v[124:127]
	v_mfma_f32_16x16x32_bf16 v[112:115], v[140:143], v[180:183], v[112:115]
	v_mfma_f32_16x16x32_bf16 v[108:111], v[148:151], v[180:183], v[108:111]
	v_mfma_f32_16x16x32_bf16 v[96:99], v[140:143], v[188:191], v[96:99]
	v_mfma_f32_16x16x32_bf16 v[92:95], v[148:151], v[188:191], v[92:95]
	v_mfma_f32_16x16x32_bf16 v[80:83], v[140:143], v[210:213], v[80:83]
	v_mfma_f32_16x16x32_bf16 v[76:79], v[148:151], v[210:213], v[76:79]
	s_setprio 0
	s_setprio 1
	v_mfma_f32_16x16x32_bf16 v[120:123], v[152:155], v[168:171], v[120:123]
	v_mfma_f32_16x16x32_bf16 v[116:119], v[160:163], v[168:171], v[116:119]
	v_mfma_f32_16x16x32_bf16 v[104:107], v[152:155], v[176:179], v[104:107]
	v_mfma_f32_16x16x32_bf16 v[100:103], v[160:163], v[176:179], v[100:103]
	v_mfma_f32_16x16x32_bf16 v[88:91], v[152:155], v[184:187], v[88:91]
	v_mfma_f32_16x16x32_bf16 v[84:87], v[160:163], v[184:187], v[84:87]
	v_mfma_f32_16x16x32_bf16 v[72:75], v[152:155], v[192:195], v[72:75]
	v_mfma_f32_16x16x32_bf16 v[68:71], v[160:163], v[192:195], v[68:71]
	v_mfma_f32_16x16x32_bf16 v[120:123], v[156:159], v[172:175], v[120:123]
	v_mfma_f32_16x16x32_bf16 v[116:119], v[164:167], v[172:175], v[116:119]
	v_mfma_f32_16x16x32_bf16 v[104:107], v[156:159], v[180:183], v[104:107]
	v_mfma_f32_16x16x32_bf16 v[100:103], v[164:167], v[180:183], v[100:103]
	v_mfma_f32_16x16x32_bf16 v[88:91], v[156:159], v[188:191], v[88:91]
	v_mfma_f32_16x16x32_bf16 v[84:87], v[164:167], v[188:191], v[84:87]
	v_mfma_f32_16x16x32_bf16 v[72:75], v[156:159], v[210:213], v[72:75]
	v_mfma_f32_16x16x32_bf16 v[68:71], v[164:167], v[210:213], v[68:71]
	s_setprio 0
	s_barrier
	s_mov_b64 s[14:15], s[20:21]
	s_add_i32 s48, s84, s29
	ds_read_b128 v[168:171], v3 offset:16384
	ds_read_b128 v[172:175], v3 offset:17408
	ds_read_b128 v[176:179], v3 offset:18432
	ds_read_b128 v[180:183], v3 offset:19456
	ds_read_b128 v[184:187], v3 offset:20480
	ds_read_b128 v[188:191], v3 offset:21504
	ds_read_b128 v[192:195], v3 offset:22528
	ds_read_b128 v[210:213], v3 offset:23552
	s_mov_b32 m0, s48
	s_nop 0
	global_load_lds_dwordx4 v132, s[14:15]
	s_add_i32 m0, s48, 0x2000
	s_nop 0
	global_load_lds_dwordx4 v134, s[14:15]
	s_add_u32 s14, s20, 0xb0000
	s_addc_u32 s15, s21, 0
	s_add_i32 s48, s85, s29
	s_mov_b32 m0, s48
	s_nop 0
	global_load_lds_dwordx4 v132, s[14:15]
	s_add_i32 m0, s48, 0x2000
	s_nop 0
	global_load_lds_dwordx4 v134, s[14:15]
	s_mov_b64 s[14:15], s[26:27]
	s_mov_b32 m0, s41
	s_nop 0
	global_load_lds_dwordx4 v132, s[14:15]
	s_mov_b32 m0, s42
	s_nop 0
	global_load_lds_dwordx4 v134, s[14:15]
	s_waitcnt vmcnt(8)
	s_waitcnt lgkmcnt(0)
	s_barrier
	s_setprio 1
	s_waitcnt lgkmcnt(0)
	v_mfma_f32_16x16x32_bf16 v[64:67], v[136:139], v[168:171], v[64:67]
	v_mfma_f32_16x16x32_bf16 v[60:63], v[144:147], v[168:171], v[60:63]
	v_mfma_f32_16x16x32_bf16 v[48:51], v[136:139], v[176:179], v[48:51]
	v_mfma_f32_16x16x32_bf16 v[44:47], v[144:147], v[176:179], v[44:47]
	v_mfma_f32_16x16x32_bf16 v[32:35], v[136:139], v[184:187], v[32:35]
	v_mfma_f32_16x16x32_bf16 v[28:31], v[144:147], v[184:187], v[28:31]
	v_mfma_f32_16x16x32_bf16 v[16:19], v[136:139], v[192:195], v[16:19]
	v_mfma_f32_16x16x32_bf16 v[12:15], v[144:147], v[192:195], v[12:15]
	v_mfma_f32_16x16x32_bf16 v[64:67], v[140:143], v[172:175], v[64:67]
	v_mfma_f32_16x16x32_bf16 v[60:63], v[148:151], v[172:175], v[60:63]
	v_mfma_f32_16x16x32_bf16 v[48:51], v[140:143], v[180:183], v[48:51]
	v_mfma_f32_16x16x32_bf16 v[44:47], v[148:151], v[180:183], v[44:47]
	v_mfma_f32_16x16x32_bf16 v[32:35], v[140:143], v[188:191], v[32:35]
	v_mfma_f32_16x16x32_bf16 v[28:31], v[148:151], v[188:191], v[28:31]
	v_mfma_f32_16x16x32_bf16 v[16:19], v[140:143], v[210:213], v[16:19]
	v_mfma_f32_16x16x32_bf16 v[12:15], v[148:151], v[210:213], v[12:15]
	s_setprio 0
	s_setprio 1
	v_mfma_f32_16x16x32_bf16 v[56:59], v[152:155], v[168:171], v[56:59]
	v_mfma_f32_16x16x32_bf16 v[52:55], v[160:163], v[168:171], v[52:55]
	v_mfma_f32_16x16x32_bf16 v[40:43], v[152:155], v[176:179], v[40:43]
	v_mfma_f32_16x16x32_bf16 v[36:39], v[160:163], v[176:179], v[36:39]
	v_mfma_f32_16x16x32_bf16 v[24:27], v[152:155], v[184:187], v[24:27]
	v_mfma_f32_16x16x32_bf16 v[20:23], v[160:163], v[184:187], v[20:23]
	v_mfma_f32_16x16x32_bf16 v[8:11], v[152:155], v[192:195], v[8:11]
	v_mfma_f32_16x16x32_bf16 v[4:7], v[160:163], v[192:195], v[4:7]
	v_mfma_f32_16x16x32_bf16 v[56:59], v[156:159], v[172:175], v[56:59]
	v_mfma_f32_16x16x32_bf16 v[52:55], v[164:167], v[172:175], v[52:55]
	v_mfma_f32_16x16x32_bf16 v[40:43], v[156:159], v[180:183], v[40:43]
	v_mfma_f32_16x16x32_bf16 v[36:39], v[164:167], v[180:183], v[36:39]
	v_mfma_f32_16x16x32_bf16 v[24:27], v[156:159], v[188:191], v[24:27]
	v_mfma_f32_16x16x32_bf16 v[20:23], v[164:167], v[188:191], v[20:23]
	v_mfma_f32_16x16x32_bf16 v[8:11], v[156:159], v[210:213], v[8:11]
	v_mfma_f32_16x16x32_bf16 v[4:7], v[164:167], v[210:213], v[4:7]
	s_setprio 0
	s_barrier
	ds_read_b128 v[136:139], v239 offset:32768
	ds_read_b128 v[140:143], v239 offset:33792
	ds_read_b128 v[144:147], v239 offset:34816
	ds_read_b128 v[148:151], v239 offset:35840
	ds_read_b128 v[152:155], v239 offset:49152
	ds_read_b128 v[156:159], v239 offset:50176
	ds_read_b128 v[160:163], v239 offset:51200
	ds_read_b128 v[164:167], v239 offset:52224
	s_add_u32 s14, s26, 0xb0000
	s_addc_u32 s15, s27, 0
	s_mov_b32 m0, s43
	ds_read_b128 v[168:171], v3 offset:32768
	ds_read_b128 v[172:175], v3 offset:33792
	ds_read_b128 v[176:179], v3 offset:34816
	ds_read_b128 v[180:183], v3 offset:35840
	ds_read_b128 v[184:187], v3 offset:36864
	ds_read_b128 v[188:191], v3 offset:37888
	ds_read_b128 v[192:195], v3 offset:38912
	ds_read_b128 v[210:213], v3 offset:39936
	s_nop 0
	global_load_lds_dwordx4 v132, s[14:15]
	s_mov_b32 m0, s44
	s_nop 0
	global_load_lds_dwordx4 v134, s[14:15]
	s_waitcnt vmcnt(8)
	s_waitcnt lgkmcnt(0)
	s_barrier
	s_setprio 1
	s_waitcnt lgkmcnt(0)
	v_mfma_f32_16x16x32_bf16 v[128:131], v[136:139], v[168:171], v[128:131]
	v_mfma_f32_16x16x32_bf16 v[124:127], v[144:147], v[168:171], v[124:127]
	v_mfma_f32_16x16x32_bf16 v[112:115], v[136:139], v[176:179], v[112:115]
	v_mfma_f32_16x16x32_bf16 v[108:111], v[144:147], v[176:179], v[108:111]
	v_mfma_f32_16x16x32_bf16 v[96:99], v[136:139], v[184:187], v[96:99]
	v_mfma_f32_16x16x32_bf16 v[92:95], v[144:147], v[184:187], v[92:95]
	v_mfma_f32_16x16x32_bf16 v[80:83], v[136:139], v[192:195], v[80:83]
	v_mfma_f32_16x16x32_bf16 v[76:79], v[144:147], v[192:195], v[76:79]
	v_mfma_f32_16x16x32_bf16 v[128:131], v[140:143], v[172:175], v[128:131]
	v_mfma_f32_16x16x32_bf16 v[124:127], v[148:151], v[172:175], v[124:127]
	v_mfma_f32_16x16x32_bf16 v[112:115], v[140:143], v[180:183], v[112:115]
	v_mfma_f32_16x16x32_bf16 v[108:111], v[148:151], v[180:183], v[108:111]
	v_mfma_f32_16x16x32_bf16 v[96:99], v[140:143], v[188:191], v[96:99]
	v_mfma_f32_16x16x32_bf16 v[92:95], v[148:151], v[188:191], v[92:95]
	v_mfma_f32_16x16x32_bf16 v[80:83], v[140:143], v[210:213], v[80:83]
	v_mfma_f32_16x16x32_bf16 v[76:79], v[148:151], v[210:213], v[76:79]
	s_setprio 0
	s_setprio 1
	v_mfma_f32_16x16x32_bf16 v[120:123], v[152:155], v[168:171], v[120:123]
	v_mfma_f32_16x16x32_bf16 v[116:119], v[160:163], v[168:171], v[116:119]
	v_mfma_f32_16x16x32_bf16 v[104:107], v[152:155], v[176:179], v[104:107]
	v_mfma_f32_16x16x32_bf16 v[100:103], v[160:163], v[176:179], v[100:103]
	v_mfma_f32_16x16x32_bf16 v[88:91], v[152:155], v[184:187], v[88:91]
	v_mfma_f32_16x16x32_bf16 v[84:87], v[160:163], v[184:187], v[84:87]
	v_mfma_f32_16x16x32_bf16 v[72:75], v[152:155], v[192:195], v[72:75]
	v_mfma_f32_16x16x32_bf16 v[68:71], v[160:163], v[192:195], v[68:71]
	v_mfma_f32_16x16x32_bf16 v[120:123], v[156:159], v[172:175], v[120:123]
	v_mfma_f32_16x16x32_bf16 v[116:119], v[164:167], v[172:175], v[116:119]
	v_mfma_f32_16x16x32_bf16 v[104:107], v[156:159], v[180:183], v[104:107]
	v_mfma_f32_16x16x32_bf16 v[100:103], v[164:167], v[180:183], v[100:103]
	v_mfma_f32_16x16x32_bf16 v[88:91], v[156:159], v[188:191], v[88:91]
	v_mfma_f32_16x16x32_bf16 v[84:87], v[164:167], v[188:191], v[84:87]
	v_mfma_f32_16x16x32_bf16 v[72:75], v[156:159], v[210:213], v[72:75]
	v_mfma_f32_16x16x32_bf16 v[68:71], v[164:167], v[210:213], v[68:71]
	s_setprio 0
	s_barrier
	s_add_i32 s14, s88, s29
	ds_read_b128 v[168:171], v3 offset:49152
	ds_read_b128 v[172:175], v3 offset:50176
	ds_read_b128 v[176:179], v3 offset:51200
	ds_read_b128 v[180:183], v3 offset:52224
	ds_read_b128 v[184:187], v3 offset:53248
	ds_read_b128 v[188:191], v3 offset:54272
	ds_read_b128 v[192:195], v3 offset:55296
	ds_read_b128 v[210:213], v3 offset:56320
	s_mov_b32 m0, s14
	s_nop 0
	global_load_lds_dwordx4 v132, s[24:25]
	s_add_i32 m0, s14, 0x2000
	s_add_u32 s14, s20, 0xb0080
	s_addc_u32 s15, s21, 0
	s_add_i32 s20, s89, s29
	global_load_lds_dwordx4 v134, s[24:25]
	s_mov_b32 m0, s20
	s_nop 0
	global_load_lds_dwordx4 v132, s[14:15]
	s_add_i32 m0, s20, 0x2000
	s_nop 0
	global_load_lds_dwordx4 v134, s[14:15]
	s_mov_b32 m0, s38
	s_nop 0
	global_load_lds_dwordx4 v132, s[22:23]
	s_mov_b32 m0, s39
	s_nop 0
	global_load_lds_dwordx4 v134, s[22:23]
	s_waitcnt vmcnt(8)
	s_waitcnt lgkmcnt(0)
	s_barrier
	s_setprio 1
	s_waitcnt lgkmcnt(0)
	v_mfma_f32_16x16x32_bf16 v[64:67], v[136:139], v[168:171], v[64:67]
	v_mfma_f32_16x16x32_bf16 v[60:63], v[144:147], v[168:171], v[60:63]
	v_mfma_f32_16x16x32_bf16 v[48:51], v[136:139], v[176:179], v[48:51]
	v_mfma_f32_16x16x32_bf16 v[44:47], v[144:147], v[176:179], v[44:47]
	v_mfma_f32_16x16x32_bf16 v[32:35], v[136:139], v[184:187], v[32:35]
	v_mfma_f32_16x16x32_bf16 v[28:31], v[144:147], v[184:187], v[28:31]
	v_mfma_f32_16x16x32_bf16 v[16:19], v[136:139], v[192:195], v[16:19]
	v_mfma_f32_16x16x32_bf16 v[12:15], v[144:147], v[192:195], v[12:15]
	v_mfma_f32_16x16x32_bf16 v[64:67], v[140:143], v[172:175], v[64:67]
	v_mfma_f32_16x16x32_bf16 v[60:63], v[148:151], v[172:175], v[60:63]
	v_mfma_f32_16x16x32_bf16 v[48:51], v[140:143], v[180:183], v[48:51]
	v_mfma_f32_16x16x32_bf16 v[44:47], v[148:151], v[180:183], v[44:47]
	v_mfma_f32_16x16x32_bf16 v[32:35], v[140:143], v[188:191], v[32:35]
	v_mfma_f32_16x16x32_bf16 v[28:31], v[148:151], v[188:191], v[28:31]
	v_mfma_f32_16x16x32_bf16 v[16:19], v[140:143], v[210:213], v[16:19]
	v_mfma_f32_16x16x32_bf16 v[12:15], v[148:151], v[210:213], v[12:15]
	s_setprio 0
	s_setprio 1
	v_mfma_f32_16x16x32_bf16 v[56:59], v[152:155], v[168:171], v[56:59]
	v_mfma_f32_16x16x32_bf16 v[52:55], v[160:163], v[168:171], v[52:55]
	v_mfma_f32_16x16x32_bf16 v[40:43], v[152:155], v[176:179], v[40:43]
	v_mfma_f32_16x16x32_bf16 v[36:39], v[160:163], v[176:179], v[36:39]
	v_mfma_f32_16x16x32_bf16 v[24:27], v[152:155], v[184:187], v[24:27]
	v_mfma_f32_16x16x32_bf16 v[20:23], v[160:163], v[184:187], v[20:23]
	v_mfma_f32_16x16x32_bf16 v[8:11], v[152:155], v[192:195], v[8:11]
	v_mfma_f32_16x16x32_bf16 v[4:7], v[160:163], v[192:195], v[4:7]
	v_mfma_f32_16x16x32_bf16 v[56:59], v[156:159], v[172:175], v[56:59]
	v_mfma_f32_16x16x32_bf16 v[52:55], v[164:167], v[172:175], v[52:55]
	v_mfma_f32_16x16x32_bf16 v[40:43], v[156:159], v[180:183], v[40:43]
	v_mfma_f32_16x16x32_bf16 v[36:39], v[164:167], v[180:183], v[36:39]
	v_mfma_f32_16x16x32_bf16 v[24:27], v[156:159], v[188:191], v[24:27]
	v_mfma_f32_16x16x32_bf16 v[20:23], v[164:167], v[188:191], v[20:23]
	v_mfma_f32_16x16x32_bf16 v[8:11], v[156:159], v[210:213], v[8:11]
	v_mfma_f32_16x16x32_bf16 v[4:7], v[164:167], v[210:213], v[4:7]
	s_setprio 0
	s_barrier
	s_add_i32 s47, s47, 2
	s_cmp_gt_u32 s47, 41
	s_mov_b64 s[14:15], s[16:17]
	s_cbranch_scc0 .LBB0_3088
	s_cmpk_lt_u32 s28, 0x100
	s_cbranch_scc0 .LBB0_3091
	s_barrier

.LBB0_3198:
	s_add_u32 s62, s8, 0x100
	v_mov_b32_e32 v4, 0
	s_addc_u32 s63, s9, 0
	s_mov_b32 s64, -2
	s_waitcnt lgkmcnt(0)
	v_mov_b32_e32 v5, v4
	v_mov_b32_e32 v6, v4
	v_mov_b32_e32 v7, v4
	v_mov_b32_e32 v8, v4
	v_mov_b32_e32 v9, v4
	v_mov_b32_e32 v10, v4
	v_mov_b32_e32 v11, v4
	v_mov_b32_e32 v20, v4
	v_mov_b32_e32 v21, v4
	v_mov_b32_e32 v22, v4
	v_mov_b32_e32 v23, v4
	v_mov_b32_e32 v24, v4
	v_mov_b32_e32 v25, v4
	v_mov_b32_e32 v26, v4
	v_mov_b32_e32 v27, v4
	v_mov_b32_e32 v36, v4
	v_mov_b32_e32 v37, v4
	v_mov_b32_e32 v38, v4
	v_mov_b32_e32 v39, v4
	v_mov_b32_e32 v40, v4
	v_mov_b32_e32 v41, v4
	v_mov_b32_e32 v42, v4
	v_mov_b32_e32 v43, v4
	v_mov_b32_e32 v52, v4
	v_mov_b32_e32 v53, v4
	v_mov_b32_e32 v54, v4
	v_mov_b32_e32 v55, v4
	v_mov_b32_e32 v56, v4
	v_mov_b32_e32 v57, v4
	v_mov_b32_e32 v58, v4
	v_mov_b32_e32 v59, v4
	v_mov_b32_e32 v12, v4
	v_mov_b32_e32 v13, v4
	v_mov_b32_e32 v14, v4
	v_mov_b32_e32 v15, v4
	v_mov_b32_e32 v16, v4
	v_mov_b32_e32 v17, v4
	v_mov_b32_e32 v18, v4
	v_mov_b32_e32 v19, v4
	v_mov_b32_e32 v28, v4
	v_mov_b32_e32 v29, v4
	v_mov_b32_e32 v30, v4
	v_mov_b32_e32 v31, v4
	v_mov_b32_e32 v32, v4
	v_mov_b32_e32 v33, v4
	v_mov_b32_e32 v34, v4
	v_mov_b32_e32 v35, v4
	v_mov_b32_e32 v44, v4
	v_mov_b32_e32 v45, v4
	v_mov_b32_e32 v46, v4
	v_mov_b32_e32 v47, v4
	v_mov_b32_e32 v48, v4
	v_mov_b32_e32 v49, v4
	v_mov_b32_e32 v50, v4
	v_mov_b32_e32 v51, v4
	v_mov_b32_e32 v60, v4
	v_mov_b32_e32 v61, v4
	v_mov_b32_e32 v62, v4
	v_mov_b32_e32 v63, v4
	v_mov_b32_e32 v64, v4
	v_mov_b32_e32 v65, v4
	v_mov_b32_e32 v66, v4
	v_mov_b32_e32 v67, v4
	v_mov_b32_e32 v68, v4
	v_mov_b32_e32 v69, v4
	v_mov_b32_e32 v70, v4
	v_mov_b32_e32 v71, v4
	v_mov_b32_e32 v72, v4
	v_mov_b32_e32 v73, v4
	v_mov_b32_e32 v74, v4
	v_mov_b32_e32 v75, v4
	v_mov_b32_e32 v84, v4
	v_mov_b32_e32 v85, v4
	v_mov_b32_e32 v86, v4
	v_mov_b32_e32 v87, v4
	v_mov_b32_e32 v88, v4
	v_mov_b32_e32 v89, v4
	v_mov_b32_e32 v90, v4
	v_mov_b32_e32 v91, v4
	v_mov_b32_e32 v100, v4
	v_mov_b32_e32 v101, v4
	v_mov_b32_e32 v102, v4
	v_mov_b32_e32 v103, v4
	v_mov_b32_e32 v104, v4
	v_mov_b32_e32 v105, v4
	v_mov_b32_e32 v106, v4
	v_mov_b32_e32 v107, v4
	v_mov_b32_e32 v116, v4
	v_mov_b32_e32 v117, v4
	v_mov_b32_e32 v118, v4
	v_mov_b32_e32 v119, v4
	v_mov_b32_e32 v120, v4
	v_mov_b32_e32 v121, v4
	v_mov_b32_e32 v122, v4
	v_mov_b32_e32 v123, v4
	v_mov_b32_e32 v76, v4
	v_mov_b32_e32 v77, v4
	v_mov_b32_e32 v78, v4
	v_mov_b32_e32 v79, v4
	v_mov_b32_e32 v80, v4
	v_mov_b32_e32 v81, v4
	v_mov_b32_e32 v82, v4
	v_mov_b32_e32 v83, v4
	v_mov_b32_e32 v92, v4
	v_mov_b32_e32 v93, v4
	v_mov_b32_e32 v94, v4
	v_mov_b32_e32 v95, v4
	v_mov_b32_e32 v96, v4
	v_mov_b32_e32 v97, v4
	v_mov_b32_e32 v98, v4
	v_mov_b32_e32 v99, v4
	v_mov_b32_e32 v108, v4
	v_mov_b32_e32 v109, v4
	v_mov_b32_e32 v110, v4
	v_mov_b32_e32 v111, v4
	v_mov_b32_e32 v112, v4
	v_mov_b32_e32 v113, v4
	v_mov_b32_e32 v114, v4
	v_mov_b32_e32 v115, v4
	v_mov_b32_e32 v124, v4
	v_mov_b32_e32 v125, v4
	v_mov_b32_e32 v126, v4
	v_mov_b32_e32 v127, v4
	v_mov_b32_e32 v128, v4
	v_mov_b32_e32 v129, v4
	v_mov_b32_e32 v130, v4
	v_mov_b32_e32 v131, v4
	v_add_u32_e32 v229, 0x10000, v1
.LBB0_3199:
	ds_read_b128 v[132:135], v229
	ds_read_b128 v[136:139], v229 offset:1024
	ds_read_b128 v[140:143], v229 offset:2048
	ds_read_b128 v[144:147], v229 offset:3072
	ds_read_b128 v[148:151], v229 offset:16384
	ds_read_b128 v[152:155], v229 offset:17408
	ds_read_b128 v[156:159], v229 offset:18432
	ds_read_b128 v[160:163], v229 offset:19456
	s_add_u32 s8, s0, 0x100
	s_addc_u32 s9, s1, 0
	s_cmp_eq_u32 s64, 40
	s_cselect_b32 s40, s34, s8
	s_cselect_b32 s41, s35, s9
	s_cselect_b32 s38, s36, s62
	s_cselect_b32 s39, s37, s63
	s_add_u32 s16, s40, 0x80
	s_addc_u32 s17, s41, 0
	s_add_u32 s0, s0, 0xb0080
	s_addc_u32 s1, s1, 0
	ds_read_b128 v[164:167], v3
	ds_read_b128 v[168:171], v3 offset:1024
	ds_read_b128 v[172:175], v3 offset:2048
	ds_read_b128 v[176:179], v3 offset:3072
	ds_read_b128 v[180:183], v3 offset:4096
	ds_read_b128 v[184:187], v3 offset:5120
	ds_read_b128 v[192:195], v3 offset:6144
	ds_read_b128 v[210:213], v3 offset:7168
	s_add_i32 m0, s47, 0xc000
	s_nop 0
	global_load_lds_dwordx4 v190, s[0:1]
	s_add_i32 m0, s47, 0xe000
	s_nop 0
	global_load_lds_dwordx4 v188, s[0:1]
	s_waitcnt vmcnt(8)
	s_waitcnt lgkmcnt(0)
	s_barrier
	s_setprio 1
	s_waitcnt lgkmcnt(0)
	v_mfma_f32_16x16x32_bf16 v[128:131], v[132:135], v[164:167], v[128:131]
	v_mfma_f32_16x16x32_bf16 v[124:127], v[140:143], v[164:167], v[124:127]
	v_mfma_f32_16x16x32_bf16 v[112:115], v[132:135], v[172:175], v[112:115]
	v_mfma_f32_16x16x32_bf16 v[108:111], v[140:143], v[172:175], v[108:111]
	v_mfma_f32_16x16x32_bf16 v[96:99], v[132:135], v[180:183], v[96:99]
	v_mfma_f32_16x16x32_bf16 v[92:95], v[140:143], v[180:183], v[92:95]
	v_mfma_f32_16x16x32_bf16 v[80:83], v[132:135], v[192:195], v[80:83]
	v_mfma_f32_16x16x32_bf16 v[76:79], v[140:143], v[192:195], v[76:79]
	v_mfma_f32_16x16x32_bf16 v[128:131], v[136:139], v[168:171], v[128:131]
	v_mfma_f32_16x16x32_bf16 v[124:127], v[144:147], v[168:171], v[124:127]
	v_mfma_f32_16x16x32_bf16 v[112:115], v[136:139], v[176:179], v[112:115]
	v_mfma_f32_16x16x32_bf16 v[108:111], v[144:147], v[176:179], v[108:111]
	v_mfma_f32_16x16x32_bf16 v[96:99], v[136:139], v[184:187], v[96:99]
	v_mfma_f32_16x16x32_bf16 v[92:95], v[144:147], v[184:187], v[92:95]
	v_mfma_f32_16x16x32_bf16 v[80:83], v[136:139], v[210:213], v[80:83]
	v_mfma_f32_16x16x32_bf16 v[76:79], v[144:147], v[210:213], v[76:79]
	s_setprio 0
	s_setprio 1
	v_mfma_f32_16x16x32_bf16 v[120:123], v[148:151], v[164:167], v[120:123]
	v_mfma_f32_16x16x32_bf16 v[116:119], v[156:159], v[164:167], v[116:119]
	v_mfma_f32_16x16x32_bf16 v[104:107], v[148:151], v[172:175], v[104:107]
	v_mfma_f32_16x16x32_bf16 v[100:103], v[156:159], v[172:175], v[100:103]
	v_mfma_f32_16x16x32_bf16 v[88:91], v[148:151], v[180:183], v[88:91]
	v_mfma_f32_16x16x32_bf16 v[84:87], v[156:159], v[180:183], v[84:87]
	v_mfma_f32_16x16x32_bf16 v[72:75], v[148:151], v[192:195], v[72:75]
	v_mfma_f32_16x16x32_bf16 v[68:71], v[156:159], v[192:195], v[68:71]
	v_mfma_f32_16x16x32_bf16 v[120:123], v[152:155], v[168:171], v[120:123]
	v_mfma_f32_16x16x32_bf16 v[116:119], v[160:163], v[168:171], v[116:119]
	v_mfma_f32_16x16x32_bf16 v[104:107], v[152:155], v[176:179], v[104:107]
	v_mfma_f32_16x16x32_bf16 v[100:103], v[160:163], v[176:179], v[100:103]
	v_mfma_f32_16x16x32_bf16 v[88:91], v[152:155], v[184:187], v[88:91]
	v_mfma_f32_16x16x32_bf16 v[84:87], v[160:163], v[184:187], v[84:87]
	v_mfma_f32_16x16x32_bf16 v[72:75], v[152:155], v[210:213], v[72:75]
	v_mfma_f32_16x16x32_bf16 v[68:71], v[160:163], v[210:213], v[68:71]
	s_setprio 0
	s_barrier
	s_mov_b64 s[0:1], s[38:39]
	s_add_i32 s65, s84, s44
	ds_read_b128 v[164:167], v3 offset:16384
	ds_read_b128 v[168:171], v3 offset:17408
	ds_read_b128 v[172:175], v3 offset:18432
	ds_read_b128 v[176:179], v3 offset:19456
	ds_read_b128 v[180:183], v3 offset:20480
	ds_read_b128 v[184:187], v3 offset:21504
	ds_read_b128 v[192:195], v3 offset:22528
	ds_read_b128 v[210:213], v3 offset:23552
	s_mov_b32 m0, s65
	s_nop 0
	global_load_lds_dwordx4 v190, s[0:1]
	s_add_i32 m0, s65, 0x2000
	s_nop 0
	global_load_lds_dwordx4 v188, s[0:1]
	s_add_u32 s0, s38, 0xb0000
	s_addc_u32 s1, s39, 0
	s_add_i32 s65, s85, s44
	s_mov_b32 m0, s65
	s_nop 0
	global_load_lds_dwordx4 v190, s[0:1]
	s_add_i32 m0, s65, 0x2000
	s_nop 0
	global_load_lds_dwordx4 v188, s[0:1]
	s_mov_b64 s[0:1], s[40:41]
	s_mov_b32 m0, s47
	s_nop 0
	global_load_lds_dwordx4 v190, s[0:1]
	s_mov_b32 m0, s48
	s_nop 0
	global_load_lds_dwordx4 v188, s[0:1]
	s_waitcnt vmcnt(8)
	s_waitcnt lgkmcnt(0)
	s_barrier
	s_setprio 1
	s_waitcnt lgkmcnt(0)
	v_mfma_f32_16x16x32_bf16 v[64:67], v[132:135], v[164:167], v[64:67]
	v_mfma_f32_16x16x32_bf16 v[60:63], v[140:143], v[164:167], v[60:63]
	v_mfma_f32_16x16x32_bf16 v[48:51], v[132:135], v[172:175], v[48:51]
	v_mfma_f32_16x16x32_bf16 v[44:47], v[140:143], v[172:175], v[44:47]
	v_mfma_f32_16x16x32_bf16 v[32:35], v[132:135], v[180:183], v[32:35]
	v_mfma_f32_16x16x32_bf16 v[28:31], v[140:143], v[180:183], v[28:31]
	v_mfma_f32_16x16x32_bf16 v[16:19], v[132:135], v[192:195], v[16:19]
	v_mfma_f32_16x16x32_bf16 v[12:15], v[140:143], v[192:195], v[12:15]
	v_mfma_f32_16x16x32_bf16 v[64:67], v[136:139], v[168:171], v[64:67]
	v_mfma_f32_16x16x32_bf16 v[60:63], v[144:147], v[168:171], v[60:63]
	v_mfma_f32_16x16x32_bf16 v[48:51], v[136:139], v[176:179], v[48:51]
	v_mfma_f32_16x16x32_bf16 v[44:47], v[144:147], v[176:179], v[44:47]
	v_mfma_f32_16x16x32_bf16 v[32:35], v[136:139], v[184:187], v[32:35]
	v_mfma_f32_16x16x32_bf16 v[28:31], v[144:147], v[184:187], v[28:31]
	v_mfma_f32_16x16x32_bf16 v[16:19], v[136:139], v[210:213], v[16:19]
	v_mfma_f32_16x16x32_bf16 v[12:15], v[144:147], v[210:213], v[12:15]
	s_setprio 0
	s_setprio 1
	v_mfma_f32_16x16x32_bf16 v[56:59], v[148:151], v[164:167], v[56:59]
	v_mfma_f32_16x16x32_bf16 v[52:55], v[156:159], v[164:167], v[52:55]
	v_mfma_f32_16x16x32_bf16 v[40:43], v[148:151], v[172:175], v[40:43]
	v_mfma_f32_16x16x32_bf16 v[36:39], v[156:159], v[172:175], v[36:39]
	v_mfma_f32_16x16x32_bf16 v[24:27], v[148:151], v[180:183], v[24:27]
	v_mfma_f32_16x16x32_bf16 v[20:23], v[156:159], v[180:183], v[20:23]
	v_mfma_f32_16x16x32_bf16 v[8:11], v[148:151], v[192:195], v[8:11]
	v_mfma_f32_16x16x32_bf16 v[4:7], v[156:159], v[192:195], v[4:7]
	v_mfma_f32_16x16x32_bf16 v[56:59], v[152:155], v[168:171], v[56:59]
	v_mfma_f32_16x16x32_bf16 v[52:55], v[160:163], v[168:171], v[52:55]
	v_mfma_f32_16x16x32_bf16 v[40:43], v[152:155], v[176:179], v[40:43]
	v_mfma_f32_16x16x32_bf16 v[36:39], v[160:163], v[176:179], v[36:39]
	v_mfma_f32_16x16x32_bf16 v[24:27], v[152:155], v[184:187], v[24:27]
	v_mfma_f32_16x16x32_bf16 v[20:23], v[160:163], v[184:187], v[20:23]
	v_mfma_f32_16x16x32_bf16 v[8:11], v[152:155], v[210:213], v[8:11]
	v_mfma_f32_16x16x32_bf16 v[4:7], v[160:163], v[210:213], v[4:7]
	s_setprio 0
	s_barrier
	ds_read_b128 v[132:135], v229 offset:32768
	ds_read_b128 v[136:139], v229 offset:33792
	ds_read_b128 v[140:143], v229 offset:34816
	ds_read_b128 v[144:147], v229 offset:35840
	ds_read_b128 v[148:151], v229 offset:49152
	ds_read_b128 v[152:155], v229 offset:50176
	ds_read_b128 v[156:159], v229 offset:51200
	ds_read_b128 v[160:163], v229 offset:52224
	s_add_u32 s0, s40, 0xb0000
	s_addc_u32 s1, s41, 0
	s_mov_b32 m0, s49
	ds_read_b128 v[164:167], v3 offset:32768
	ds_read_b128 v[168:171], v3 offset:33792
	ds_read_b128 v[172:175], v3 offset:34816
	ds_read_b128 v[176:179], v3 offset:35840
	ds_read_b128 v[180:183], v3 offset:36864
	ds_read_b128 v[184:187], v3 offset:37888
	ds_read_b128 v[192:195], v3 offset:38912
	ds_read_b128 v[210:213], v3 offset:39936
	s_nop 0
	global_load_lds_dwordx4 v190, s[0:1]
	s_mov_b32 m0, s50
	s_nop 0
	global_load_lds_dwordx4 v188, s[0:1]
	s_waitcnt vmcnt(8)
	s_waitcnt lgkmcnt(0)
	s_barrier
	s_setprio 1
	s_waitcnt lgkmcnt(0)
	v_mfma_f32_16x16x32_bf16 v[128:131], v[132:135], v[164:167], v[128:131]
	v_mfma_f32_16x16x32_bf16 v[124:127], v[140:143], v[164:167], v[124:127]
	v_mfma_f32_16x16x32_bf16 v[112:115], v[132:135], v[172:175], v[112:115]
	v_mfma_f32_16x16x32_bf16 v[108:111], v[140:143], v[172:175], v[108:111]
	v_mfma_f32_16x16x32_bf16 v[96:99], v[132:135], v[180:183], v[96:99]
	v_mfma_f32_16x16x32_bf16 v[92:95], v[140:143], v[180:183], v[92:95]
	v_mfma_f32_16x16x32_bf16 v[80:83], v[132:135], v[192:195], v[80:83]
	v_mfma_f32_16x16x32_bf16 v[76:79], v[140:143], v[192:195], v[76:79]
	v_mfma_f32_16x16x32_bf16 v[128:131], v[136:139], v[168:171], v[128:131]
	v_mfma_f32_16x16x32_bf16 v[124:127], v[144:147], v[168:171], v[124:127]
	v_mfma_f32_16x16x32_bf16 v[112:115], v[136:139], v[176:179], v[112:115]
	v_mfma_f32_16x16x32_bf16 v[108:111], v[144:147], v[176:179], v[108:111]
	v_mfma_f32_16x16x32_bf16 v[96:99], v[136:139], v[184:187], v[96:99]
	v_mfma_f32_16x16x32_bf16 v[92:95], v[144:147], v[184:187], v[92:95]
	v_mfma_f32_16x16x32_bf16 v[80:83], v[136:139], v[210:213], v[80:83]
	v_mfma_f32_16x16x32_bf16 v[76:79], v[144:147], v[210:213], v[76:79]
	s_setprio 0
	s_setprio 1
	v_mfma_f32_16x16x32_bf16 v[120:123], v[148:151], v[164:167], v[120:123]
	v_mfma_f32_16x16x32_bf16 v[116:119], v[156:159], v[164:167], v[116:119]
	v_mfma_f32_16x16x32_bf16 v[104:107], v[148:151], v[172:175], v[104:107]
	v_mfma_f32_16x16x32_bf16 v[100:103], v[156:159], v[172:175], v[100:103]
	v_mfma_f32_16x16x32_bf16 v[88:91], v[148:151], v[180:183], v[88:91]
	v_mfma_f32_16x16x32_bf16 v[84:87], v[156:159], v[180:183], v[84:87]
	v_mfma_f32_16x16x32_bf16 v[72:75], v[148:151], v[192:195], v[72:75]
	v_mfma_f32_16x16x32_bf16 v[68:71], v[156:159], v[192:195], v[68:71]
	v_mfma_f32_16x16x32_bf16 v[120:123], v[152:155], v[168:171], v[120:123]
	v_mfma_f32_16x16x32_bf16 v[116:119], v[160:163], v[168:171], v[116:119]
	v_mfma_f32_16x16x32_bf16 v[104:107], v[152:155], v[176:179], v[104:107]
	v_mfma_f32_16x16x32_bf16 v[100:103], v[160:163], v[176:179], v[100:103]
	v_mfma_f32_16x16x32_bf16 v[88:91], v[152:155], v[184:187], v[88:91]
	v_mfma_f32_16x16x32_bf16 v[84:87], v[160:163], v[184:187], v[84:87]
	v_mfma_f32_16x16x32_bf16 v[72:75], v[152:155], v[210:213], v[72:75]
	v_mfma_f32_16x16x32_bf16 v[68:71], v[160:163], v[210:213], v[68:71]
	s_setprio 0
	s_barrier
	s_add_u32 s0, s38, 0x80
	s_addc_u32 s1, s39, 0
	s_add_i32 s40, s88, s44
	ds_read_b128 v[164:167], v3 offset:49152
	ds_read_b128 v[168:171], v3 offset:50176
	ds_read_b128 v[172:175], v3 offset:51200
	ds_read_b128 v[176:179], v3 offset:52224
	ds_read_b128 v[180:183], v3 offset:53248
	ds_read_b128 v[184:187], v3 offset:54272
	ds_read_b128 v[192:195], v3 offset:55296
	ds_read_b128 v[210:213], v3 offset:56320
	s_mov_b32 m0, s40
	s_nop 0
	global_load_lds_dwordx4 v190, s[0:1]
	s_add_i32 m0, s40, 0x2000
	s_nop 0
	global_load_lds_dwordx4 v188, s[0:1]
	s_add_u32 s0, s38, 0xb0080
	s_addc_u32 s1, s39, 0
	s_add_i32 s38, s89, s44
	s_mov_b32 m0, s38
	s_nop 0
	global_load_lds_dwordx4 v190, s[0:1]
	s_add_i32 m0, s38, 0x2000
	s_nop 0
	global_load_lds_dwordx4 v188, s[0:1]
	s_mov_b32 m0, s51
	s_nop 0
	global_load_lds_dwordx4 v190, s[16:17]
	s_mov_b32 m0, s52
	s_nop 0
	global_load_lds_dwordx4 v188, s[16:17]
	s_waitcnt vmcnt(8)
	s_waitcnt lgkmcnt(0)
	s_barrier
	s_setprio 1
	s_waitcnt lgkmcnt(0)
	v_mfma_f32_16x16x32_bf16 v[64:67], v[132:135], v[164:167], v[64:67]
	v_mfma_f32_16x16x32_bf16 v[60:63], v[140:143], v[164:167], v[60:63]
	v_mfma_f32_16x16x32_bf16 v[48:51], v[132:135], v[172:175], v[48:51]
	v_mfma_f32_16x16x32_bf16 v[44:47], v[140:143], v[172:175], v[44:47]
	v_mfma_f32_16x16x32_bf16 v[32:35], v[132:135], v[180:183], v[32:35]
	v_mfma_f32_16x16x32_bf16 v[28:31], v[140:143], v[180:183], v[28:31]
	v_mfma_f32_16x16x32_bf16 v[16:19], v[132:135], v[192:195], v[16:19]
	v_mfma_f32_16x16x32_bf16 v[12:15], v[140:143], v[192:195], v[12:15]
	v_mfma_f32_16x16x32_bf16 v[64:67], v[136:139], v[168:171], v[64:67]
	v_mfma_f32_16x16x32_bf16 v[60:63], v[144:147], v[168:171], v[60:63]
	v_mfma_f32_16x16x32_bf16 v[48:51], v[136:139], v[176:179], v[48:51]
	v_mfma_f32_16x16x32_bf16 v[44:47], v[144:147], v[176:179], v[44:47]
	v_mfma_f32_16x16x32_bf16 v[32:35], v[136:139], v[184:187], v[32:35]
	v_mfma_f32_16x16x32_bf16 v[28:31], v[144:147], v[184:187], v[28:31]
	v_mfma_f32_16x16x32_bf16 v[16:19], v[136:139], v[210:213], v[16:19]
	v_mfma_f32_16x16x32_bf16 v[12:15], v[144:147], v[210:213], v[12:15]
	s_setprio 0
	s_setprio 1
	v_mfma_f32_16x16x32_bf16 v[56:59], v[148:151], v[164:167], v[56:59]
	v_mfma_f32_16x16x32_bf16 v[52:55], v[156:159], v[164:167], v[52:55]
	v_mfma_f32_16x16x32_bf16 v[40:43], v[148:151], v[172:175], v[40:43]
	v_mfma_f32_16x16x32_bf16 v[36:39], v[156:159], v[172:175], v[36:39]
	v_mfma_f32_16x16x32_bf16 v[24:27], v[148:151], v[180:183], v[24:27]
	v_mfma_f32_16x16x32_bf16 v[20:23], v[156:159], v[180:183], v[20:23]
	v_mfma_f32_16x16x32_bf16 v[8:11], v[148:151], v[192:195], v[8:11]
	v_mfma_f32_16x16x32_bf16 v[4:7], v[156:159], v[192:195], v[4:7]
	v_mfma_f32_16x16x32_bf16 v[56:59], v[152:155], v[168:171], v[56:59]
	v_mfma_f32_16x16x32_bf16 v[52:55], v[160:163], v[168:171], v[52:55]
	v_mfma_f32_16x16x32_bf16 v[40:43], v[152:155], v[176:179], v[40:43]
	v_mfma_f32_16x16x32_bf16 v[36:39], v[160:163], v[176:179], v[36:39]
	v_mfma_f32_16x16x32_bf16 v[24:27], v[152:155], v[184:187], v[24:27]
	v_mfma_f32_16x16x32_bf16 v[20:23], v[160:163], v[184:187], v[20:23]
	v_mfma_f32_16x16x32_bf16 v[8:11], v[152:155], v[210:213], v[8:11]
	v_mfma_f32_16x16x32_bf16 v[4:7], v[160:163], v[210:213], v[4:7]
	s_setprio 0
	s_barrier
	s_add_i32 s64, s64, 2
	s_add_u32 s62, s62, 0x100
	s_addc_u32 s63, s63, 0
	s_cmp_gt_u32 s64, 41
	s_mov_b64 s[0:1], s[8:9]
	s_cbranch_scc0 .LBB0_3199
	s_and_b64 vcc, exec, s[26:27]
	s_cbranch_vccz .LBB0_3202
	s_barrier
